# selection v2: output rows staged in LDS and written as 128x16B, radix passes without exec switching
# speedup vs baseline: 1.0712x; 1.0236x over previous
; DI int t5_bucket(int n) {
;   if (n < 16) return n;
;   int lg = 16 + (int)(logf((float)n / 16.f) / logf(8.f) * 16.f);
;   return lg < 31 ? lg : 31;
; }
; __global__ void __launch_bounds__(NTHREADS) mega(Params p) {
;     ...
;   for (int l = 0; l < 4; ++l) {
;     for (int rep = 0; rep < REP_P1; ++rep) {
;       for (int j = blockIdx.x; j < 66 * 48; j += gridDim.x) inproj_tile(p, l, j / 48, j % 48, lds);
;       if (l < 3 && rep == 0) {
;         const int nbusy = 66 * 48 - (66 * 48 / (int)gridDim.x) * (int)gridDim.x;
;         const int nidle = (int)gridDim.x - nbusy;
;         if ((int)blockIdx.x >= nbusy && nidle > 0) conv_weights(p, l + 1, lds, (int)blockIdx.x - nbusy, nidle, 1536);
;       }
;       xcd_barrier(xb);
;     }
;     for (int rep = 0; rep < REP_P2; ++rep) {
;       constexpr int NTK = 2 * 2052, NUP = 66 * 14, NJ = NTK + NUP + 16;
;       int pending = 0, par = 0;
;       if (threadIdx.x == 0) pending = (int)atomicAdd(p.ctr + l * 2 + 8 * rep, 1u);
.LBB0_316:
	s_or_b64 exec, exec, s[0:1]
	v_readlane_b32 s52, v241, 40
	s_cmpk_lt_i32 s35, 0xc60
	v_readlane_b32 s56, v241, 44
	s_cselect_b64 s[0:1], -1, 0
	v_readlane_b32 s57, v241, 45
	s_add_u32 s94, s56, 0x200
	v_writelane_b32 v240, s0, 17
	s_addc_u32 s95, s57, 0
	v_cvt_f32_u32_e32 v0, v152
	v_writelane_b32 v240, s1, 18
	s_add_u32 s0, s56, 0x1000
	s_addc_u32 s1, s57, 0
	v_writelane_b32 v240, s0, 19
	v_mul_f32_e32 v0, 0x3d800000, v0
	s_mov_b32 s89, 0x7f800000
	v_writelane_b32 v240, s1, 20
	s_add_u32 s0, s56, 0x1100
	s_addc_u32 s1, s57, 0
	v_writelane_b32 v240, s0, 21
	v_mov_b32_e32 v188, 0x41b17218
	s_mov_b32 s6, 0x40051592
	v_writelane_b32 v240, s1, 22
	s_add_u32 s0, s56, 0x1200
	s_addc_u32 s1, s57, 0
	v_writelane_b32 v240, s0, 23
	v_readlane_b32 s58, v241, 46
	v_writelane_b32 v240, s1, 24
	s_mov_b32 s0, 0x800000
	v_cmp_gt_f32_e32 vcc, s0, v0
	s_add_u32 s0, s56, 0x1300
	s_addc_u32 s1, s57, 0
	v_cndmask_b32_e64 v1, 0, 32, vcc
	v_ldexp_f32 v0, v0, v1
	v_log_f32_e32 v0, v0
	v_writelane_b32 v240, s0, 25
	s_cmp_eq_u32 s5, 15
	v_readlane_b32 s48, v241, 28
	v_writelane_b32 v240, s1, 26
	s_mov_b32 s0, 0x3f317217
	v_mul_f32_e32 v1, 0x3f317217, v0
	v_fma_f32 v1, v0, s0, -v1
	v_fmac_f32_e32 v1, 0x3377d1cf, v0
	v_fmac_f32_e32 v1, 0x3f317217, v0
	v_cmp_lt_f32_e64 s[0:1], |v0|, s89
	v_readlane_b32 s49, v241, 29
	v_readlane_b32 s38, v241, 18
	v_cndmask_b32_e64 v0, v0, v1, s[0:1]
	v_cndmask_b32_e32 v1, 0, v188, vcc
	v_sub_f32_e32 v4, v0, v1
	v_div_scale_f32 v0, s[0:1], s6, s6, v4
	s_cselect_b64 s[0:1], -1, 0
	s_nop 0
	v_writelane_b32 v240, s0, 27
	s_cmp_eq_u32 s5, 14
	v_rcp_f32_e32 v1, v0
	v_writelane_b32 v240, s1, 28
	s_cselect_b64 s[0:1], -1, 0
	v_writelane_b32 v240, s0, 29
	s_cmp_eq_u32 s5, 13
	v_fma_f32 v2, -v0, v1, 1.0
	v_writelane_b32 v240, s1, 30
	s_cselect_b64 s[0:1], -1, 0
	v_writelane_b32 v240, s0, 31
	s_cmp_eq_u32 s5, 12
	v_fmac_f32_e32 v1, v2, v1
	v_writelane_b32 v240, s1, 32
	s_cselect_b64 s[0:1], -1, 0
	v_writelane_b32 v240, s0, 33
	s_cmp_eq_u32 s5, 11
	v_div_scale_f32 v2, vcc, v4, s6, v4
	v_writelane_b32 v240, s1, 34
	s_cselect_b64 s[0:1], -1, 0
	v_writelane_b32 v240, s0, 35
	s_cmp_eq_u32 s5, 10
	v_mul_f32_e32 v3, v2, v1
	v_writelane_b32 v240, s1, 36
	s_cselect_b64 s[0:1], -1, 0
	v_writelane_b32 v240, s0, 37
	s_cmp_eq_u32 s5, 9
	v_fma_f32 v5, -v0, v3, v2
	v_writelane_b32 v240, s1, 38
	s_cselect_b64 s[0:1], -1, 0
	v_writelane_b32 v240, s0, 39
	s_cmp_eq_u32 s5, 8
	v_fmac_f32_e32 v3, v5, v1
	v_writelane_b32 v240, s1, 40
	s_cselect_b64 s[0:1], -1, 0
	v_writelane_b32 v240, s0, 41
	s_cmp_eq_u32 s5, 7
	v_fma_f32 v0, -v0, v3, v2
	v_writelane_b32 v240, s1, 42
	s_cselect_b64 s[0:1], -1, 0
	v_writelane_b32 v240, s0, 43
	s_cmp_eq_u32 s5, 6
	v_div_fmas_f32 v5, v0, v1, v3
	v_writelane_b32 v240, s1, 44
	s_cselect_b64 s[0:1], -1, 0
	v_writelane_b32 v240, s0, 45
	s_cmp_eq_u32 s5, 5
	v_lshlrev_b32_e32 v0, 1, v152
	v_writelane_b32 v240, s1, 46
	s_cselect_b64 s[0:1], -1, 0
	v_writelane_b32 v240, s0, 47
	s_cmp_eq_u32 s5, 4
	v_and_b32_e32 v1, 7, v152
	v_writelane_b32 v240, s1, 48
	s_cselect_b64 s[0:1], -1, 0
	v_writelane_b32 v240, s0, 49
	s_cmp_eq_u32 s5, 3
	v_readlane_b32 s39, v241, 19
	v_writelane_b32 v240, s1, 50
	s_cselect_b64 s[0:1], -1, 0
	v_writelane_b32 v240, s0, 51
	s_cmp_eq_u32 s5, 2
	v_mov_b32_e32 v3, 0
	v_writelane_b32 v240, s1, 52
	s_cselect_b64 s[0:1], -1, 0
	v_writelane_b32 v240, s0, 53
	s_cmp_eq_u32 s5, 1
	v_readlane_b32 s53, v241, 41
	v_writelane_b32 v240, s1, 54
	s_cselect_b64 s[0:1], -1, 0
	v_writelane_b32 v240, s0, 55
	s_cmp_eq_u32 s5, 0
	v_cmp_gt_u32_e32 vcc, 16, v152
	v_writelane_b32 v240, s1, 56
	s_cselect_b64 s[0:1], -1, 0
	v_writelane_b32 v240, s0, 57
	v_readlane_b32 s59, v241, 47
	v_readlane_b32 s46, v241, 26
	v_writelane_b32 v240, s1, 58
	s_lshl_b32 s0, s4, 2
	s_add_u32 s0, s56, s0
	s_addc_u32 s1, s57, 0
	s_add_u32 s2, s0, 0x1400
	s_addc_u32 s3, s1, 0
	v_writelane_b32 v240, s2, 59
	s_add_u32 s0, s0, 0x2400
	s_addc_u32 s1, s1, 0
	v_writelane_b32 v240, s3, 60
	v_writelane_b32 v240, s0, 61
	v_readlane_b32 s47, v241, 27
	s_movk_i32 s33, 0x80
	v_writelane_b32 v240, s1, 62
	s_movk_i32 s0, 0x7f0
	v_and_or_b32 v0, v0, s0, v1
	s_add_u32 s0, s56, 0x3400
	s_addc_u32 s1, s57, 0
	v_writelane_b32 v240, s0, 63
	v_lshlrev_b32_e32 v2, 2, v0
	v_writelane_b32 v239, s1, 0
	s_add_u32 s0, s56, 0x3500
	s_addc_u32 s1, s57, 0
	s_add_i32 s7, 0, 0x23000
	s_add_i32 s4, 0, 0x23400
	v_writelane_b32 v239, s0, 1
	s_cmpk_lt_i32 s35, 0x200
	v_writelane_b32 v239, s1, 2
	s_cselect_b64 s[0:1], -1, 0
	v_writelane_b32 v239, s0, 3
	s_add_i32 s3, s35, 0x5c0
	v_mov_b32_e32 v192, 0x3ecc95a3
	v_writelane_b32 v239, s1, 4
	v_sub_co_u32_e64 v1, s[0:1], s35, 64
	s_xor_b64 s[0:1], s[0:1], -1
	s_nop 0
	v_writelane_b32 v239, s0, 5
	v_mov_b32_e32 v193, 0x260
	v_mov_b32_e32 v194, 1
	v_writelane_b32 v239, s1, 6
	s_sub_i32 s0, s58, 64
	s_cmpk_lt_i32 s35, 0x290
	v_writelane_b32 v239, s0, 7
	s_cselect_b64 s[0:1], -1, 0
	v_writelane_b32 v239, s0, 8
	s_cmp_gt_i32 s35, 63
	v_mov_b32_e32 v195, -1
	v_writelane_b32 v239, s1, 9
	s_cselect_b64 s[0:1], -1, 0
	v_writelane_b32 v239, s0, 10
	s_cmpk_gt_u32 s3, 0x7ff
	v_mov_b32_e32 v196, 0x3727c5ac
	v_writelane_b32 v239, s1, 11
	s_cselect_b64 s[0:1], -1, 0
	v_writelane_b32 v239, s0, 12
	s_cmpk_gt_u32 s3, 0x82f
	s_cselect_b64 s[8:9], -1, 0
	v_writelane_b32 v239, s1, 13
	s_mul_hi_i32 s0, s3, 0x2aaaaaab
	s_lshr_b32 s1, s0, 31
	s_ashr_i32 s0, s0, 4
	s_add_i32 s5, s0, s1
	s_lshr_b32 s0, s35, 1
	s_and_b32 s0, s0, 6
	s_lshr_b32 s1, s35, 5
	v_writelane_b32 v239, s8, 14
	s_or_b32 s2, s0, s1
	s_add_i32 s0, s35, 0xfffffd90
	v_writelane_b32 v239, s9, 15
	s_lshr_b32 s0, s0, 4
	v_writelane_b32 v239, s0, 16
	s_and_b32 s0, s3, 0xff
	s_mulk_i32 s0, 0xab
; DI int t5_bucket(int n) {
;   if (n < 16) return n;
;   int lg = 16 + (int)(logf((float)n / 16.f) / logf(8.f) * 16.f);
;   return lg < 31 ? lg : 31;
; }
; __global__ void __launch_bounds__(NTHREADS) mega(Params p) {
;     ...
;         const int nbusy = 66 * 48 - (66 * 48 / (int)gridDim.x) * (int)gridDim.x;
;         const int nidle = (int)gridDim.x - nbusy;
;         if ((int)blockIdx.x >= nbusy && nidle > 0) conv_weights(p, l + 1, lds, (int)blockIdx.x - nbusy, nidle, 1536);
	s_lshr_b32 s0, s0, 11
	v_writelane_b32 v239, s0, 17
	s_mul_i32 s0, s0, 12
	s_sub_i32 s0, s3, s0
	s_and_b32 s0, s0, 0xff
	v_writelane_b32 v239, s0, 18
	v_readfirstlane_b32 s0, v1
	s_lshr_b32 s0, s0, 4
	v_mov_b32_e32 v197, 0x7f800000
	v_writelane_b32 v239, s0, 19
	v_writelane_b32 v239, s5, 20
	s_mul_i32 s0, s5, 0x60
	v_writelane_b32 v239, s3, 21
	s_sub_i32 s0, s3, s0
	v_writelane_b32 v239, s0, 22
	s_lshl_b32 s0, s35, 4
	s_and_b32 s1, s0, 0x100
	s_and_b32 s0, s35, 15
	v_writelane_b32 v239, s0, 23
	v_writelane_b32 v239, s1, 24
	s_bitset1_b32 s1, 14
	s_and_b32 s0, s35, 3
	v_writelane_b32 v239, s1, 25
	s_lshl_b32 s1, s1, 12
	s_add_u32 s1, s48, s1
	s_addc_u32 s3, s49, 0
	s_lshl_b32 s5, s0, 10
	s_add_u32 s8, s1, s5
	s_addc_u32 s9, s3, 0
	s_lshl_b32 s1, s2, 19
	s_add_u32 s1, s38, s1
	v_writelane_b32 v239, s8, 26
	s_addc_u32 s3, s39, 0
	s_add_u32 s1, s1, s5
	v_writelane_b32 v239, s9, 27
	v_writelane_b32 v239, s1, 28
	v_readlane_b32 s16, v241, 8
	v_readlane_b32 s17, v241, 9
	s_addc_u32 s1, s3, 0
	v_writelane_b32 v239, s1, 29
	v_lshl_add_u64 v[154:155], s[16:17], 0, v[2:3]
	v_sub_co_u32_e64 v2, s[0:1], s0, 1
	s_xor_b64 s[0:1], s[0:1], -1
	s_nop 0
	v_writelane_b32 v239, s0, 30
	v_lshlrev_b64 v[0:1], 21, v[2:3]
	v_lshl_add_u64 v[0:1], s[52:53], 0, v[0:1]
	v_writelane_b32 v239, s1, 31
	s_lshl_b32 s0, s2, 7
	s_mov_b32 s1, s61
	v_writelane_b32 v239, s0, 32
	v_writelane_b32 v239, s1, 33
	s_lshl_b64 s[0:1], s[0:1], 2
	v_lshl_add_u64 v[156:157], v[0:1], 0, s[0:1]
	v_div_fixup_f32 v0, v5, s6, v4
	v_mul_f32_e32 v0, 0x41800000, v0
	v_cvt_i32_f32_e32 v0, v0
	s_add_u32 s0, s74, s0
	s_addc_u32 s1, s75, s1
	v_writelane_b32 v239, s0, 34
	v_min_i32_e32 v0, 15, v0
	v_add_u32_e32 v0, 16, v0
	v_writelane_b32 v239, s1, 35
	s_abs_i32 s0, s58
	v_cndmask_b32_e32 v189, v0, v152, vcc
	v_cvt_f32_u32_e32 v0, s0
	s_sub_i32 s1, 0, s0
	s_mov_b32 s18, s76
	v_mov_b32_e32 v199, 0x43000000
	v_rcp_iflag_f32_e32 v0, v0
	v_mov_b32_e32 v200, 0x43800000
	v_bfrev_b32_e32 v201, 0.5
	v_mov_b32_e32 v202, 0x70
	v_mul_f32_e32 v0, 0x4f7ffffe, v0
	v_cvt_u32_f32_e32 v0, v0
	v_mov_b32_e32 v203, 0xf149f2ca
	v_mov_b32_e32 v204, 0x1200
	v_mov_b32_e32 v205, 0x80
	v_readfirstlane_b32 s2, v0
	s_mul_i32 s1, s1, s2
	s_mul_hi_u32 s1, s2, s1
	s_add_i32 s2, s2, s1
	s_mul_hi_u32 s1, s2, 0xc60
	s_mul_i32 s1, s1, s0
	s_sub_i32 s1, 0xc60, s1
	s_sub_i32 s2, s1, s0
	s_cmp_ge_u32 s1, s0
	s_cselect_b32 s1, s2, s1
	s_sub_i32 s2, s1, s0
	s_cmp_ge_u32 s1, s0
	s_cselect_b32 s5, s2, s1
	s_sub_i32 s91, s58, s5
	s_cmp_ge_i32 s35, s5
	s_cselect_b64 s[0:1], -1, 0
	s_cmp_gt_i32 s91, 0
	s_cselect_b64 s[2:3], -1, 0
	s_and_b64 s[0:1], s[0:1], s[2:3]
	v_writelane_b32 v239, s0, 36
	s_sub_i32 s2, s35, s5
	v_lshlrev_b32_e32 v0, 2, v152
	v_writelane_b32 v239, s1, 37
	s_mul_i32 s0, s59, s58
	s_mul_i32 s96, s0, s28
	s_sext_i32_i16 s0, s2
	s_cmpk_lt_i32 s2, 0x600
	s_mulk_i32 s0, 0x2aab
	v_add_u32_e32 v190, s4, v0
	s_cselect_b64 s[4:5], -1, 0
	s_lshr_b32 s1, s0, 31
	s_ashr_i32 s0, s0, 20
	s_add_i32 s0, s0, s1
	s_sext_i32_i16 s1, s0
	s_mulk_i32 s0, 0x60
	s_sub_i32 s0, s2, s0
	v_writelane_b32 v239, s4, 38
	s_sext_i32_i16 s0, s0
	s_lshl_b32 s1, s1, 6
	v_writelane_b32 v239, s5, 39
	s_lshl_b32 s0, s0, 6
	v_writelane_b32 v239, s7, 40
	s_cmpk_gt_u32 s0, 0x5ff
	v_writelane_b32 v239, s2, 41
	s_cselect_b64 s[2:3], -1, 0
	v_writelane_b32 v239, s2, 42
	s_cmpk_gt_u32 s0, 0x6ff
	v_add_u32_e32 v191, s7, v0
	v_writelane_b32 v239, s3, 43
	s_cselect_b64 s[2:3], -1, 0
	v_writelane_b32 v239, s2, 44
	s_cmpk_gt_u32 s0, 0x77f
	v_mov_b32_e32 v206, 0x1a00
	v_writelane_b32 v239, s3, 45
	s_cselect_b64 s[2:3], -1, 0
; DI int map_in(int n) {
;   if (n < 512) return n;
;   if (n < 1024) return n;
;   if (n < 1536) return 1544 + (n - 1024);
;   if (n < 1792) return 2056 + (n - 1536);
;   if (n < 1920) return 2312 + (n - 1792);
;   if (n < 2432) return 2472 + (n - 1920);
;   if (n < 2944) return 2984 + (n - 2432);
;   if (n < 3072) return 3496 + (n - 2944);
;   if (n < 3200) return 3624 + (n - 3072);
;   if (n < 3712) return 3752 + (n - 3200);
;   if (n < 4224) return 4336 + (n - 3712);
;   if (n < 4736) return 4848 + (n - 4224);
;   if (n < 4864) return 5360 + (n - 4736);
;   if (n < 5376) return 5616 + (n - 4864);
;   if (n < 5408) return 2440 + (n - 5376);
;   if (n < 5472) return 4264 + (n - 5408);
;   if (n < 5480) return 1536 + (n - 5472);
;   if (n < 5488) return 4328 + (n - 5480);
;   if (n < 5504) return -1;
;   if (n < 6016) return 1024 + (n - 5504);
;   return 5488 + (n - 6016);
; }
; DI void conv_weights(const Params& p, int l, char* lds, int t_first, int t_stride, int t_end) {
;     ...
;     else if (tI < 2048) { int u = tI - 1536; kind = 1; kt = u / 16; ntile = u % 16; src = p.w_out + (size_t)l * 2048 * DM; ldsrc = DM; d.K = 2048; d.dst = p.Wt_out + (size_t)(l & 1) * DM * 2048; }
;     else if (tI < 2096) { int u = tI - 2048; kind = 2; kt = u / 12; ntile = u % 12; src = p.w_uq + (size_t)l * 256 * 768; ldsrc = 768; d.K = 256; d.dst = p.Wt_uq; ksc = p.gq + l * 256; }
;     else { int u = tI - 2096; kind = 3; kt = u / 16; ntile = u % 16; src = p.w_ukv + (size_t)l * 128 * 1024; ldsrc = 1024; d.K = 128; d.dst = p.Wt_ukv; ksc = p.gkv + l * 128; }
;     d.k0 = kt * 64; d.n0 = ntile * 64;
;     const int n = d.n0 + nn_l;
;     int sc;
;     if (kind == 0) sc = map_in(n);
;     else if (kind == 3) sc = (n < 512) ? ((n >> 6) * 128 + (n & 63)) : (((n - 512) >> 6) * 128 + 64 + (n & 63));
;     else sc = n;
	v_writelane_b32 v239, s2, 46
	s_cmpk_gt_u32 s0, 0x97f
	v_mbcnt_lo_u32_b32 v0, -1, 0
	v_writelane_b32 v239, s3, 47
	s_cselect_b64 s[2:3], -1, 0
	v_writelane_b32 v239, s2, 48
	s_cmpk_gt_u32 s0, 0xb7f
	v_mbcnt_hi_u32_b32 v198, -1, v0
	v_writelane_b32 v239, s3, 49
	s_cselect_b64 s[2:3], -1, 0
	v_writelane_b32 v239, s2, 50
	s_cmpk_gt_u32 s0, 0xbff
	s_mov_b32 s60, 0x20000
	v_writelane_b32 v239, s3, 51
	s_cselect_b64 s[2:3], -1, 0
	v_writelane_b32 v239, s2, 52
	s_cmpk_gt_u32 s0, 0xc7f
	s_movk_i32 s57, 0x90
	v_writelane_b32 v239, s3, 53
	s_cselect_b64 s[2:3], -1, 0
	v_writelane_b32 v239, s2, 54
	s_cmpk_gt_u32 s0, 0xe7f
	s_movk_i32 s53, 0x2a00
	v_writelane_b32 v239, s3, 55
	s_cselect_b64 s[2:3], -1, 0
	v_writelane_b32 v239, s2, 56
	s_cmpk_gt_u32 s0, 0x107f
	s_movk_i32 s86, 0x6f
	v_writelane_b32 v239, s3, 57
	s_cselect_b64 s[2:3], -1, 0
	v_writelane_b32 v239, s2, 58
	s_cmpk_gt_u32 s0, 0x127f
	s_mov_b32 s38, 0
	v_writelane_b32 v239, s3, 59
	s_cselect_b64 s[2:3], -1, 0
	v_writelane_b32 v239, s2, 60
	s_cmpk_gt_u32 s0, 0x12ff
	s_mov_b32 s52, 0x3e38aa3b
	v_writelane_b32 v239, s3, 61
	s_cselect_b64 s[2:3], -1, 0
	v_writelane_b32 v239, s2, 62
	s_cmpk_gt_u32 s0, 0x14ff
	s_mov_b64 s[54:55], 0x100
	v_writelane_b32 v239, s3, 63
	s_cselect_b64 s[2:3], -1, 0
	v_writelane_b32 v238, s2, 0
	s_cmpk_gt_u32 s0, 0x157f
	v_writelane_b32 v238, s3, 1
	s_cselect_b64 s[2:3], -1, 0
	v_writelane_b32 v238, s2, 2
	s_cmpk_gt_u32 s0, 0x177f
	v_writelane_b32 v238, s3, 3
	v_writelane_b32 v238, s0, 4
	s_cselect_b64 s[2:3], -1, 0
	v_writelane_b32 v238, s2, 5
	s_or_b32 s0, s1, 8
	s_ashr_i32 s19, s76, 31
	v_writelane_b32 v238, s3, 6
	v_writelane_b32 v238, s0, 7
	s_or_b32 s0, s1, 16
	v_writelane_b32 v238, s0, 8
	s_or_b32 s0, s1, 24
	v_writelane_b32 v238, s0, 9
	s_or_b32 s0, s1, 32
	v_writelane_b32 v238, s0, 10
	s_or_b32 s0, s1, 40
	v_writelane_b32 v238, s0, 11
	s_or_b32 s0, s1, 48
	v_writelane_b32 v238, s0, 12
	v_writelane_b32 v238, s1, 13
	s_or_b32 s0, s1, 56
	v_writelane_b32 v238, s0, 14
	s_lshl_b32 s0, s35, 1
	v_writelane_b32 v238, s0, 15
	v_writelane_b32 v238, s35, 16
	s_lshl_b32 s0, s35, 7
	v_writelane_b32 v238, s0, 17
	s_lshl_b32 s0, s58, 1
	v_writelane_b32 v238, s0, 18
	v_readlane_b32 s0, v241, 48
	s_add_i32 s1, s0, 0xffffff80
	v_writelane_b32 v238, s1, 19
	s_add_i32 s0, s0, s76
	v_writelane_b32 v238, s0, 20
	s_lshl_b64 s[0:1], s[18:19], 12
	v_writelane_b32 v238, s0, 21
	v_writelane_b32 v238, s1, 22
	s_add_u32 s0, s46, 0x400
	s_addc_u32 s1, s47, 0
	v_writelane_b32 v238, s0, 23
	s_add_i32 s59, 0, 0x16800
	v_writelane_b32 v238, s1, 24
	s_add_i32 s1, 0, 0xd800
	v_writelane_b32 v238, s1, 25
	s_add_i32 s1, 0, 0x10000
	v_writelane_b32 v238, s1, 26
	s_add_i32 s1, 0, 0x400
	s_movk_i32 s0, 0x100
	v_writelane_b32 v238, s1, 27
	s_add_i32 s1, 0, 0x23010
	v_writelane_b32 v238, s1, 28
	v_cmp_gt_u32_e64 s[0:1], s0, v152
	s_nop 0
	s_nop 0
	v_writelane_b32 v238, s0, 29
	s_nop 0
	s_nop 0
	v_writelane_b32 v238, s1, 30
	v_cmp_gt_u32_e64 s[0:1], s33, v152
	s_nop 0
	s_nop 0
	v_writelane_b32 v238, s0, 31
	v_writelane_b32 v238, s1, 32
	s_lshl_b64 s[0:1], s[18:19], 11
	v_writelane_b32 v238, s0, 33
	v_writelane_b32 v238, s1, 34
	s_mov_b64 s[0:1], 0
	v_writelane_b32 v238, s0, 35
	v_writelane_b32 v238, s1, 36
	v_writelane_b32 v238, s92, 37
	v_readlane_b32 s22, v241, 14
	v_writelane_b32 v238, s93, 38
	v_writelane_b32 v238, s94, 39
	v_readlane_b32 s23, v241, 15
	s_nop 0
	v_writelane_b32 v238, s95, 40
	v_writelane_b32 v238, s91, 41
	v_writelane_b32 v238, s96, 42
	v_writelane_b32 v238, s18, 43
	s_nop 1
	v_writelane_b32 v238, s19, 44
	s_branch .LBB0_320

; #define MFMA32(a, b, c) __builtin_amdgcn_mfma_f32_32x32x16_bf16((a), (b), (c), 0, 0, 0)
; DI void topk_job(const Params& p, int b, int t0, char* lds) {
;     ...
;         bf16x8 b0[4], b1[4];
; #pragma unroll
;         for (int ks = 0; ks < 4; ++ks) {
;           b0[ks] = *(const bf16x8*)(wb + r * 144 + ks * 32 + h * 16);
;           b1[ks] = *(const bf16x8*)(wb + (32 + r) * 144 + ks * 32 + h * 16);
;         }
;         __builtin_amdgcn_sched_barrier(0);
;         f32x16 a0, a1;
; #pragma unroll
;         for (int e = 0; e < 16; ++e) { a0[e] = 0.f; a1[e] = 0.f; }
; #pragma unroll
;         for (int ks = 0; ks < 4; ++ks) { a0 = MFMA32(af[ks], b0[ks], a0); a1 = MFMA32(af[ks], b1[ks], a1); }
;         const int key = c * 64 + lane;
; #pragma unroll
;         for (int qi = 0; qi < 4; ++qi) {
;           f32x2 pp2 = {0.f, 0.f};
; #pragma unroll
;           for (int e = 0; e < 4; ++e) {
;             const f32x2 rl = {fmaxf(a0[4 * qi + e], 0.f), fmaxf(a1[4 * qi + e], 0.f)};
;             const f32x2 wv = {iw[qi][e], iw[qi][e]};
;             pp2 += rl * wv;
;           }
;           const float p0 = pp2[0], p1 = pp2[1];
;           const u32x2 sw = __builtin_amdgcn_permlane32_swap(__float_as_uint(p0), __float_as_uint(p1), false, false);
;           float mine = __uint_as_float(sw[0]) + __uint_as_float(sw[1]);
;           mine += 0.0f;
;           unsigned u = __float_as_uint(mine);
;           u = (u & 0x80000000u) ? ~u : (u | 0x80000000u);
;           if (key > t0 + qi || key < LEAD) u = 0u;
;           sc[i][qi] = u;
;         }
;         if (more) {
; #pragma unroll
;           for (int j = 0; j < 8; ++j) *(u32x4*)(wb + (lrow + 8 * j) * 144 + lpc * 16) = st[j];
.LBB0_657:
	s_or_b64 exec, exec, s[2:3]
	ds_read_b128 v[4:7], v210 offset:16384
	ds_read_b128 v[102:105], v210 offset:16416
	s_waitcnt vmcnt(8)
	ds_read_b128 v[8:11], v210 offset:20992
	ds_read_b128 v[106:109], v210 offset:21024
	ds_read_b128 v[110:113], v210 offset:16448
	ds_read_b128 v[114:117], v210 offset:16480
	ds_read_b128 v[118:121], v210 offset:21056
	ds_read_b128 v[122:125], v210 offset:21088
	s_waitcnt lgkmcnt(7)
	v_mfma_f32_32x32x16_bf16 v[20:35], v[64:67], v[4:7], 0
	s_sub_i32 s2, 0x209d, s23
	s_sub_i32 s10, 0x209e, s23
	s_waitcnt lgkmcnt(5)
	v_mfma_f32_32x32x16_bf16 v[4:19], v[64:67], v[8:11], 0
	v_mfma_f32_32x32x16_bf16 v[20:35], v[60:63], v[102:105], v[20:35]
	v_lshl_or_b32 v104, v134, 6, v101
	v_cmp_gt_i32_e32 vcc, s25, v104
	v_cmp_lt_i32_e64 s[6:7], s24, v104
	v_cmp_lt_i32_e64 s[2:3], s2, v104
	v_cmp_lt_i32_e64 s[14:15], s10, v104
	v_cmp_lt_i32_e64 s[10:11], s22, v104
	s_waitcnt lgkmcnt(4)
	v_mfma_f32_32x32x16_bf16 v[4:19], v[60:63], v[106:109], v[4:19]
	s_waitcnt lgkmcnt(3)
	v_mfma_f32_32x32x16_bf16 v[20:35], v[56:59], v[110:113], v[20:35]
	s_waitcnt lgkmcnt(1)
	v_mfma_f32_32x32x16_bf16 v[4:19], v[56:59], v[118:121], v[4:19]
	v_mfma_f32_32x32x16_bf16 v[20:35], v[52:55], v[114:117], v[20:35]
	s_waitcnt lgkmcnt(0)
	v_mfma_f32_32x32x16_bf16 v[4:19], v[52:55], v[122:125], v[4:19]
	s_nop 9
	v_max_f32_e32 v102, 0, v20
	v_max_f32_e32 v20, 0, v22
	v_max_f32_e32 v103, 0, v4
	v_pk_fma_f32 v[102:103], v[48:49], v[102:103], 0 op_sel_hi:[0,1,0]
	v_max_f32_e32 v4, 0, v21
	v_max_f32_e32 v5, 0, v5
	v_pk_fma_f32 v[4:5], v[48:49], v[4:5], v[102:103] op_sel:[1,0,0]
	v_max_f32_e32 v21, 0, v6
	v_pk_fma_f32 v[4:5], v[50:51], v[20:21], v[4:5] op_sel_hi:[0,1,1]
	v_max_f32_e32 v6, 0, v23
	v_max_f32_e32 v7, 0, v7
	v_mov_b32_e32 v20, v51
	v_pk_fma_f32 v[4:5], v[20:21], v[6:7], v[4:5] op_sel_hi:[0,1,1]
	v_mov_b32_e32 v6, v5
	v_max_f32_e32 v20, 0, v24
	v_max_f32_e32 v21, 0, v8
	v_max_f32_e32 v8, 0, v25
	v_pk_fma_f32 v[20:21], v[44:45], v[20:21], 0 op_sel_hi:[0,1,0]
	v_max_f32_e32 v9, 0, v9
	v_pk_fma_f32 v[8:9], v[44:45], v[8:9], v[20:21] op_sel:[1,0,0]
	v_max_f32_e32 v20, 0, v26
	v_max_f32_e32 v21, 0, v10
	v_max_f32_e32 v10, 0, v27
	v_pk_fma_f32 v[8:9], v[46:47], v[20:21], v[8:9] op_sel_hi:[0,1,1]
	v_max_f32_e32 v11, 0, v11
	v_mov_b32_e32 v20, v47
	v_pk_fma_f32 v[8:9], v[20:21], v[10:11], v[8:9] op_sel_hi:[0,1,1]
	v_mov_b32_e32 v7, v9
	s_nop 1
	v_permlane32_swap_b32_e32 v8, v7
	v_permlane32_swap_b32_e32 v4, v6
	v_mov_b32_e32 v5, v8
	v_pk_add_f32 v[4:5], v[4:5], v[6:7]
	v_max_f32_e32 v6, 0, v28
	v_max_f32_e32 v7, 0, v12
	v_pk_fma_f32 v[6:7], v[40:41], v[6:7], 0 op_sel_hi:[0,1,0]
	v_max_f32_e32 v8, 0, v29
	v_max_f32_e32 v9, 0, v13
	v_pk_fma_f32 v[6:7], v[40:41], v[8:9], v[6:7] op_sel:[1,0,0]
	v_max_f32_e32 v8, 0, v30
	v_max_f32_e32 v9, 0, v14
	v_pk_fma_f32 v[6:7], v[42:43], v[8:9], v[6:7] op_sel_hi:[0,1,1]
	v_max_f32_e32 v8, 0, v31
	v_max_f32_e32 v9, 0, v15
	v_mov_b32_e32 v10, v43
	v_pk_fma_f32 v[6:7], v[10:11], v[8:9], v[6:7] op_sel_hi:[0,1,1]
	v_mov_b32_e32 v8, v7
	v_max_f32_e32 v10, 0, v32
	v_max_f32_e32 v11, 0, v16
	v_max_f32_e32 v12, 0, v33
	v_pk_fma_f32 v[10:11], v[36:37], v[10:11], 0 op_sel_hi:[0,1,0]
	v_max_f32_e32 v13, 0, v17
	v_pk_fma_f32 v[10:11], v[36:37], v[12:13], v[10:11] op_sel:[1,0,0]
	v_max_f32_e32 v12, 0, v34
	v_max_f32_e32 v13, 0, v18
	v_pk_fma_f32 v[10:11], v[38:39], v[12:13], v[10:11] op_sel_hi:[0,1,1]
	v_max_f32_e32 v12, 0, v35
	v_max_f32_e32 v13, 0, v19
	v_mov_b32_e32 v14, v39
	v_pk_fma_f32 v[10:11], v[14:15], v[12:13], v[10:11] op_sel_hi:[0,1,1]
	v_mov_b32_e32 v9, v11
	s_nop 1
	v_permlane32_swap_b32_e32 v10, v9
	v_permlane32_swap_b32_e32 v6, v8
	v_mov_b32_e32 v7, v10
	v_pk_add_f32 v[6:7], v[6:7], v[8:9]
	v_pk_add_f32 v[4:5], v[4:5], 0 op_sel_hi:[1,0]
	v_pk_add_f32 v[6:7], v[6:7], 0 op_sel_hi:[1,0]
	v_cmp_gt_i32_e64 s[4:5], 0, v4
	v_cmp_gt_i32_e64 s[8:9], 0, v5
	v_cmp_gt_i32_e64 s[12:13], 0, v6
	v_cmp_gt_i32_e64 s[16:17], 0, v7
	s_and_saveexec_b64 s[20:21], s[0:1]
	s_cbranch_execz .LBB0_659
	v_mad_u32_u24 v8, v209, s57, v2
	s_waitcnt vmcnt(0)
	ds_write_b128 v8, v[68:71] offset:16384
	ds_write_b128 v8, v[72:75] offset:17536
	ds_write_b128 v8, v[76:79] offset:18688
	ds_write_b128 v8, v[80:83] offset:19840
	ds_write_b128 v8, v[84:87] offset:20992
	ds_write_b128 v8, v[88:91] offset:22144
	ds_write_b128 v8, v[92:95] offset:23296
	ds_write_b128 v8, v[96:99] offset:24448

; #define MFMA32(a, b, c) __builtin_amdgcn_mfma_f32_32x32x16_bf16((a), (b), (c), 0, 0, 0)
; DI void topk_job(const Params& p, int b, int t0, char* lds) {
;     ...
;         bf16x8 b0[4], b1[4];
; #pragma unroll
;         for (int ks = 0; ks < 4; ++ks) {
;           b0[ks] = *(const bf16x8*)(wb + r * 144 + ks * 32 + h * 16);
;           b1[ks] = *(const bf16x8*)(wb + (32 + r) * 144 + ks * 32 + h * 16);
;         }
;         __builtin_amdgcn_sched_barrier(0);
;         f32x16 a0, a1;
; #pragma unroll
;         for (int e = 0; e < 16; ++e) { a0[e] = 0.f; a1[e] = 0.f; }
; #pragma unroll
;         for (int ks = 0; ks < 4; ++ks) { a0 = MFMA32(af[ks], b0[ks], a0); a1 = MFMA32(af[ks], b1[ks], a1); }
;         const int key = c * 64 + lane;
; #pragma unroll
;         for (int qi = 0; qi < 4; ++qi) {
;           f32x2 pp2 = {0.f, 0.f};
; #pragma unroll
;           for (int e = 0; e < 4; ++e) {
;             const f32x2 rl = {fmaxf(a0[4 * qi + e], 0.f), fmaxf(a1[4 * qi + e], 0.f)};
;             const f32x2 wv = {iw[qi][e], iw[qi][e]};
;             pp2 += rl * wv;
;           }
;           const float p0 = pp2[0], p1 = pp2[1];
;           const u32x2 sw = __builtin_amdgcn_permlane32_swap(__float_as_uint(p0), __float_as_uint(p1), false, false);
;           float mine = __uint_as_float(sw[0]) + __uint_as_float(sw[1]);
;           mine += 0.0f;
;           unsigned u = __float_as_uint(mine);
;           u = (u & 0x80000000u) ? ~u : (u | 0x80000000u);
;           if (key > t0 + qi || key < LEAD) u = 0u;
;           sc[i][qi] = u;
;         }
;         if (more) {
; #pragma unroll
;           for (int j = 0; j < 8; ++j) *(u32x4*)(wb + (lrow + 8 * j) * 144 + lpc * 16) = st[j];
.LBB0_663:
	s_or_b64 exec, exec, s[2:3]
	ds_read_b128 v[4:7], v210 offset:16384
	ds_read_b128 v[102:105], v210 offset:16416
	s_waitcnt vmcnt(8)
	ds_read_b128 v[8:11], v210 offset:20992
	ds_read_b128 v[106:109], v210 offset:21024
	ds_read_b128 v[110:113], v210 offset:16448
	ds_read_b128 v[114:117], v210 offset:16480
	ds_read_b128 v[118:121], v210 offset:21056
	ds_read_b128 v[122:125], v210 offset:21088
	s_waitcnt lgkmcnt(7)
	v_mfma_f32_32x32x16_bf16 v[20:35], v[64:67], v[4:7], 0
	s_sub_i32 s2, 0x209d, s23
	s_sub_i32 s10, 0x209e, s23
	s_waitcnt lgkmcnt(5)
	v_mfma_f32_32x32x16_bf16 v[4:19], v[64:67], v[8:11], 0
	v_mfma_f32_32x32x16_bf16 v[20:35], v[60:63], v[102:105], v[20:35]
	v_lshl_or_b32 v104, v132, 6, v101
	v_cmp_gt_i32_e32 vcc, s25, v104
	v_cmp_lt_i32_e64 s[6:7], s24, v104
	v_cmp_lt_i32_e64 s[2:3], s2, v104
	v_cmp_lt_i32_e64 s[14:15], s10, v104
	v_cmp_lt_i32_e64 s[10:11], s22, v104
	s_waitcnt lgkmcnt(4)
	v_mfma_f32_32x32x16_bf16 v[4:19], v[60:63], v[106:109], v[4:19]
	s_waitcnt lgkmcnt(3)
	v_mfma_f32_32x32x16_bf16 v[20:35], v[56:59], v[110:113], v[20:35]
	s_waitcnt lgkmcnt(1)
	v_mfma_f32_32x32x16_bf16 v[4:19], v[56:59], v[118:121], v[4:19]
	v_mfma_f32_32x32x16_bf16 v[20:35], v[52:55], v[114:117], v[20:35]
	s_waitcnt lgkmcnt(0)
	v_mfma_f32_32x32x16_bf16 v[4:19], v[52:55], v[122:125], v[4:19]
	s_nop 9
	v_max_f32_e32 v102, 0, v20
	v_max_f32_e32 v20, 0, v22
	v_max_f32_e32 v103, 0, v4
	v_pk_fma_f32 v[102:103], v[48:49], v[102:103], 0 op_sel_hi:[0,1,0]
	v_max_f32_e32 v4, 0, v21
	v_max_f32_e32 v5, 0, v5
	v_pk_fma_f32 v[4:5], v[48:49], v[4:5], v[102:103] op_sel:[1,0,0]
	v_max_f32_e32 v21, 0, v6
	v_pk_fma_f32 v[4:5], v[50:51], v[20:21], v[4:5] op_sel_hi:[0,1,1]
	v_max_f32_e32 v6, 0, v23
	v_max_f32_e32 v7, 0, v7
	v_mov_b32_e32 v20, v51
	v_pk_fma_f32 v[4:5], v[20:21], v[6:7], v[4:5] op_sel_hi:[0,1,1]
	v_mov_b32_e32 v6, v5
	v_max_f32_e32 v20, 0, v24
	v_max_f32_e32 v21, 0, v8
	v_max_f32_e32 v8, 0, v25
	v_pk_fma_f32 v[20:21], v[44:45], v[20:21], 0 op_sel_hi:[0,1,0]
	v_max_f32_e32 v9, 0, v9
	v_pk_fma_f32 v[8:9], v[44:45], v[8:9], v[20:21] op_sel:[1,0,0]
	v_max_f32_e32 v20, 0, v26
	v_max_f32_e32 v21, 0, v10
	v_max_f32_e32 v10, 0, v27
	v_pk_fma_f32 v[8:9], v[46:47], v[20:21], v[8:9] op_sel_hi:[0,1,1]
	v_max_f32_e32 v11, 0, v11
	v_mov_b32_e32 v20, v47
	v_pk_fma_f32 v[8:9], v[20:21], v[10:11], v[8:9] op_sel_hi:[0,1,1]
	v_mov_b32_e32 v7, v9
	s_nop 1
	v_permlane32_swap_b32_e32 v8, v7
	v_permlane32_swap_b32_e32 v4, v6
	v_mov_b32_e32 v5, v8
	v_pk_add_f32 v[4:5], v[4:5], v[6:7]
	v_max_f32_e32 v6, 0, v28
	v_max_f32_e32 v7, 0, v12
	v_pk_fma_f32 v[6:7], v[40:41], v[6:7], 0 op_sel_hi:[0,1,0]
	v_max_f32_e32 v8, 0, v29
	v_max_f32_e32 v9, 0, v13
	v_pk_fma_f32 v[6:7], v[40:41], v[8:9], v[6:7] op_sel:[1,0,0]
	v_max_f32_e32 v8, 0, v30
	v_max_f32_e32 v9, 0, v14
	v_pk_fma_f32 v[6:7], v[42:43], v[8:9], v[6:7] op_sel_hi:[0,1,1]
	v_max_f32_e32 v8, 0, v31
	v_max_f32_e32 v9, 0, v15
	v_mov_b32_e32 v10, v43
	v_pk_fma_f32 v[6:7], v[10:11], v[8:9], v[6:7] op_sel_hi:[0,1,1]
	v_mov_b32_e32 v8, v7
	v_max_f32_e32 v10, 0, v32
	v_max_f32_e32 v11, 0, v16
	v_max_f32_e32 v12, 0, v33
	v_pk_fma_f32 v[10:11], v[36:37], v[10:11], 0 op_sel_hi:[0,1,0]
	v_max_f32_e32 v13, 0, v17
	v_pk_fma_f32 v[10:11], v[36:37], v[12:13], v[10:11] op_sel:[1,0,0]
	v_max_f32_e32 v12, 0, v34
	v_max_f32_e32 v13, 0, v18
	v_pk_fma_f32 v[10:11], v[38:39], v[12:13], v[10:11] op_sel_hi:[0,1,1]
	v_max_f32_e32 v12, 0, v35
	v_max_f32_e32 v13, 0, v19
	v_mov_b32_e32 v14, v39
	v_pk_fma_f32 v[10:11], v[14:15], v[12:13], v[10:11] op_sel_hi:[0,1,1]
	v_mov_b32_e32 v9, v11
	s_nop 1
	v_permlane32_swap_b32_e32 v10, v9
	v_permlane32_swap_b32_e32 v6, v8
	v_mov_b32_e32 v7, v10
	v_pk_add_f32 v[6:7], v[6:7], v[8:9]
	v_pk_add_f32 v[4:5], v[4:5], 0 op_sel_hi:[1,0]
	v_pk_add_f32 v[6:7], v[6:7], 0 op_sel_hi:[1,0]
	v_cmp_gt_i32_e64 s[4:5], 0, v4
	v_cmp_gt_i32_e64 s[8:9], 0, v5
	v_cmp_gt_i32_e64 s[12:13], 0, v6
	v_cmp_gt_i32_e64 s[16:17], 0, v7
	s_and_saveexec_b64 s[20:21], s[0:1]
	s_cbranch_execz .LBB0_665
	v_mad_u32_u24 v8, v209, s57, v2
	s_waitcnt vmcnt(0)
	ds_write_b128 v8, v[68:71] offset:16384
	ds_write_b128 v8, v[72:75] offset:17536
	ds_write_b128 v8, v[76:79] offset:18688
	ds_write_b128 v8, v[80:83] offset:19840
	ds_write_b128 v8, v[84:87] offset:20992
	ds_write_b128 v8, v[88:91] offset:22144
	ds_write_b128 v8, v[92:95] offset:23296
	ds_write_b128 v8, v[96:99] offset:24448

; #define MFMA32(a, b, c) __builtin_amdgcn_mfma_f32_32x32x16_bf16((a), (b), (c), 0, 0, 0)
; DI void topk_job(const Params& p, int b, int t0, char* lds) {
;     ...
;         bf16x8 b0[4], b1[4];
; #pragma unroll
;         for (int ks = 0; ks < 4; ++ks) {
;           b0[ks] = *(const bf16x8*)(wb + r * 144 + ks * 32 + h * 16);
;           b1[ks] = *(const bf16x8*)(wb + (32 + r) * 144 + ks * 32 + h * 16);
;         }
;         __builtin_amdgcn_sched_barrier(0);
;         f32x16 a0, a1;
; #pragma unroll
;         for (int e = 0; e < 16; ++e) { a0[e] = 0.f; a1[e] = 0.f; }
; #pragma unroll
;         for (int ks = 0; ks < 4; ++ks) { a0 = MFMA32(af[ks], b0[ks], a0); a1 = MFMA32(af[ks], b1[ks], a1); }
;         const int key = c * 64 + lane;
; #pragma unroll
;         for (int qi = 0; qi < 4; ++qi) {
;           f32x2 pp2 = {0.f, 0.f};
; #pragma unroll
;           for (int e = 0; e < 4; ++e) {
;             const f32x2 rl = {fmaxf(a0[4 * qi + e], 0.f), fmaxf(a1[4 * qi + e], 0.f)};
;             const f32x2 wv = {iw[qi][e], iw[qi][e]};
;             pp2 += rl * wv;
;           }
;           const float p0 = pp2[0], p1 = pp2[1];
;           const u32x2 sw = __builtin_amdgcn_permlane32_swap(__float_as_uint(p0), __float_as_uint(p1), false, false);
;           float mine = __uint_as_float(sw[0]) + __uint_as_float(sw[1]);
;           mine += 0.0f;
;           unsigned u = __float_as_uint(mine);
;           u = (u & 0x80000000u) ? ~u : (u | 0x80000000u);
;           if (key > t0 + qi || key < LEAD) u = 0u;
;           sc[i][qi] = u;
;         }
;         if (more) {
; #pragma unroll
;           for (int j = 0; j < 8; ++j) *(u32x4*)(wb + (lrow + 8 * j) * 144 + lpc * 16) = st[j];
.LBB0_669:
	s_or_b64 exec, exec, s[2:3]
	ds_read_b128 v[4:7], v210 offset:16384
	ds_read_b128 v[102:105], v210 offset:16416
	s_waitcnt vmcnt(8)
	ds_read_b128 v[8:11], v210 offset:20992
	ds_read_b128 v[106:109], v210 offset:21024
	ds_read_b128 v[110:113], v210 offset:16448
	ds_read_b128 v[114:117], v210 offset:16480
	ds_read_b128 v[118:121], v210 offset:21056
	ds_read_b128 v[122:125], v210 offset:21088
	s_waitcnt lgkmcnt(7)
	v_mfma_f32_32x32x16_bf16 v[20:35], v[64:67], v[4:7], 0
	s_sub_i32 s2, 0x209d, s23
	s_sub_i32 s10, 0x209e, s23
	s_waitcnt lgkmcnt(5)
	v_mfma_f32_32x32x16_bf16 v[4:19], v[64:67], v[8:11], 0
	v_mfma_f32_32x32x16_bf16 v[20:35], v[60:63], v[102:105], v[20:35]
	v_lshl_or_b32 v104, v130, 6, v101
	v_cmp_gt_i32_e32 vcc, s25, v104
	v_cmp_lt_i32_e64 s[6:7], s24, v104
	v_cmp_lt_i32_e64 s[2:3], s2, v104
	v_cmp_lt_i32_e64 s[14:15], s10, v104
	v_cmp_lt_i32_e64 s[10:11], s22, v104
	s_waitcnt lgkmcnt(4)
	v_mfma_f32_32x32x16_bf16 v[4:19], v[60:63], v[106:109], v[4:19]
	s_waitcnt lgkmcnt(3)
	v_mfma_f32_32x32x16_bf16 v[20:35], v[56:59], v[110:113], v[20:35]
	s_waitcnt lgkmcnt(1)
	v_mfma_f32_32x32x16_bf16 v[4:19], v[56:59], v[118:121], v[4:19]
	v_mfma_f32_32x32x16_bf16 v[20:35], v[52:55], v[114:117], v[20:35]
	s_waitcnt lgkmcnt(0)
	v_mfma_f32_32x32x16_bf16 v[4:19], v[52:55], v[122:125], v[4:19]
	s_nop 9
	v_max_f32_e32 v102, 0, v20
	v_max_f32_e32 v20, 0, v22
	v_max_f32_e32 v103, 0, v4
	v_pk_fma_f32 v[102:103], v[48:49], v[102:103], 0 op_sel_hi:[0,1,0]
	v_max_f32_e32 v4, 0, v21
	v_max_f32_e32 v5, 0, v5
	v_pk_fma_f32 v[4:5], v[48:49], v[4:5], v[102:103] op_sel:[1,0,0]
	v_max_f32_e32 v21, 0, v6
	v_pk_fma_f32 v[4:5], v[50:51], v[20:21], v[4:5] op_sel_hi:[0,1,1]
	v_max_f32_e32 v6, 0, v23
	v_max_f32_e32 v7, 0, v7
	v_mov_b32_e32 v20, v51
	v_pk_fma_f32 v[4:5], v[20:21], v[6:7], v[4:5] op_sel_hi:[0,1,1]
	v_mov_b32_e32 v6, v5
	v_max_f32_e32 v20, 0, v24
	v_max_f32_e32 v21, 0, v8
	v_max_f32_e32 v8, 0, v25
	v_pk_fma_f32 v[20:21], v[44:45], v[20:21], 0 op_sel_hi:[0,1,0]
	v_max_f32_e32 v9, 0, v9
	v_pk_fma_f32 v[8:9], v[44:45], v[8:9], v[20:21] op_sel:[1,0,0]
	v_max_f32_e32 v20, 0, v26
	v_max_f32_e32 v21, 0, v10
	v_max_f32_e32 v10, 0, v27
	v_pk_fma_f32 v[8:9], v[46:47], v[20:21], v[8:9] op_sel_hi:[0,1,1]
	v_max_f32_e32 v11, 0, v11
	v_mov_b32_e32 v20, v47
	v_pk_fma_f32 v[8:9], v[20:21], v[10:11], v[8:9] op_sel_hi:[0,1,1]
	v_mov_b32_e32 v7, v9
	s_nop 1
	v_permlane32_swap_b32_e32 v8, v7
	v_permlane32_swap_b32_e32 v4, v6
	v_mov_b32_e32 v5, v8
	v_pk_add_f32 v[4:5], v[4:5], v[6:7]
	v_max_f32_e32 v6, 0, v28
	v_max_f32_e32 v7, 0, v12
	v_pk_fma_f32 v[6:7], v[40:41], v[6:7], 0 op_sel_hi:[0,1,0]
	v_max_f32_e32 v8, 0, v29
	v_max_f32_e32 v9, 0, v13
	v_pk_fma_f32 v[6:7], v[40:41], v[8:9], v[6:7] op_sel:[1,0,0]
	v_max_f32_e32 v8, 0, v30
	v_max_f32_e32 v9, 0, v14
	v_pk_fma_f32 v[6:7], v[42:43], v[8:9], v[6:7] op_sel_hi:[0,1,1]
	v_max_f32_e32 v8, 0, v31
	v_max_f32_e32 v9, 0, v15
	v_mov_b32_e32 v10, v43
	v_pk_fma_f32 v[6:7], v[10:11], v[8:9], v[6:7] op_sel_hi:[0,1,1]
	v_mov_b32_e32 v8, v7
	v_max_f32_e32 v10, 0, v32
	v_max_f32_e32 v11, 0, v16
	v_max_f32_e32 v12, 0, v33
	v_pk_fma_f32 v[10:11], v[36:37], v[10:11], 0 op_sel_hi:[0,1,0]
	v_max_f32_e32 v13, 0, v17
	v_pk_fma_f32 v[10:11], v[36:37], v[12:13], v[10:11] op_sel:[1,0,0]
	v_max_f32_e32 v12, 0, v34
	v_max_f32_e32 v13, 0, v18
	v_pk_fma_f32 v[10:11], v[38:39], v[12:13], v[10:11] op_sel_hi:[0,1,1]
	v_max_f32_e32 v12, 0, v35
	v_max_f32_e32 v13, 0, v19
	v_mov_b32_e32 v14, v39
	v_pk_fma_f32 v[10:11], v[14:15], v[12:13], v[10:11] op_sel_hi:[0,1,1]
	v_mov_b32_e32 v9, v11
	s_nop 1
	v_permlane32_swap_b32_e32 v10, v9
	v_permlane32_swap_b32_e32 v6, v8
	v_mov_b32_e32 v7, v10
	v_pk_add_f32 v[6:7], v[6:7], v[8:9]
	v_pk_add_f32 v[4:5], v[4:5], 0 op_sel_hi:[1,0]
	v_pk_add_f32 v[6:7], v[6:7], 0 op_sel_hi:[1,0]
	v_cmp_gt_i32_e64 s[4:5], 0, v4
	v_cmp_gt_i32_e64 s[8:9], 0, v5
	v_cmp_gt_i32_e64 s[12:13], 0, v6
	v_cmp_gt_i32_e64 s[16:17], 0, v7
	s_and_saveexec_b64 s[20:21], s[0:1]
	s_cbranch_execz .LBB0_671
	v_mad_u32_u24 v8, v209, s57, v2
	s_waitcnt vmcnt(0)
	ds_write_b128 v8, v[68:71] offset:16384
	ds_write_b128 v8, v[72:75] offset:17536
	ds_write_b128 v8, v[76:79] offset:18688
	ds_write_b128 v8, v[80:83] offset:19840
	ds_write_b128 v8, v[84:87] offset:20992
	ds_write_b128 v8, v[88:91] offset:22144
	ds_write_b128 v8, v[92:95] offset:23296
	ds_write_b128 v8, v[96:99] offset:24448

; #define MFMA32(a, b, c) __builtin_amdgcn_mfma_f32_32x32x16_bf16((a), (b), (c), 0, 0, 0)
; DI void topk_job(const Params& p, int b, int t0, char* lds) {
;     ...
;         bf16x8 b0[4], b1[4];
; #pragma unroll
;         for (int ks = 0; ks < 4; ++ks) {
;           b0[ks] = *(const bf16x8*)(wb + r * 144 + ks * 32 + h * 16);
;           b1[ks] = *(const bf16x8*)(wb + (32 + r) * 144 + ks * 32 + h * 16);
;         }
;         __builtin_amdgcn_sched_barrier(0);
;         f32x16 a0, a1;
; #pragma unroll
;         for (int e = 0; e < 16; ++e) { a0[e] = 0.f; a1[e] = 0.f; }
; #pragma unroll
;         for (int ks = 0; ks < 4; ++ks) { a0 = MFMA32(af[ks], b0[ks], a0); a1 = MFMA32(af[ks], b1[ks], a1); }
;         const int key = c * 64 + lane;
; #pragma unroll
;         for (int qi = 0; qi < 4; ++qi) {
;           f32x2 pp2 = {0.f, 0.f};
; #pragma unroll
;           for (int e = 0; e < 4; ++e) {
;             const f32x2 rl = {fmaxf(a0[4 * qi + e], 0.f), fmaxf(a1[4 * qi + e], 0.f)};
;             const f32x2 wv = {iw[qi][e], iw[qi][e]};
;             pp2 += rl * wv;
;           }
;           const float p0 = pp2[0], p1 = pp2[1];
;           const u32x2 sw = __builtin_amdgcn_permlane32_swap(__float_as_uint(p0), __float_as_uint(p1), false, false);
;           float mine = __uint_as_float(sw[0]) + __uint_as_float(sw[1]);
;           mine += 0.0f;
;           unsigned u = __float_as_uint(mine);
;           u = (u & 0x80000000u) ? ~u : (u | 0x80000000u);
;           if (key > t0 + qi || key < LEAD) u = 0u;
;           sc[i][qi] = u;
;         }
;         if (more) {
; #pragma unroll
;           for (int j = 0; j < 8; ++j) *(u32x4*)(wb + (lrow + 8 * j) * 144 + lpc * 16) = st[j];
.LBB0_675:
	s_or_b64 exec, exec, s[2:3]
	ds_read_b128 v[4:7], v210 offset:16384
	ds_read_b128 v[102:105], v210 offset:16416
	s_waitcnt vmcnt(8)
	ds_read_b128 v[8:11], v210 offset:20992
	ds_read_b128 v[106:109], v210 offset:21024
	ds_read_b128 v[110:113], v210 offset:16448
	ds_read_b128 v[114:117], v210 offset:16480
	ds_read_b128 v[118:121], v210 offset:21056
	ds_read_b128 v[122:125], v210 offset:21088
	s_waitcnt lgkmcnt(7)
	v_mfma_f32_32x32x16_bf16 v[20:35], v[64:67], v[4:7], 0
	s_sub_i32 s2, 0x209d, s23
	s_sub_i32 s10, 0x209e, s23
	s_waitcnt lgkmcnt(5)
	v_mfma_f32_32x32x16_bf16 v[4:19], v[64:67], v[8:11], 0
	v_mfma_f32_32x32x16_bf16 v[20:35], v[60:63], v[102:105], v[20:35]
	v_lshl_or_b32 v104, v128, 6, v101
	v_cmp_gt_i32_e32 vcc, s25, v104
	v_cmp_lt_i32_e64 s[6:7], s24, v104
	v_cmp_lt_i32_e64 s[2:3], s2, v104
	v_cmp_lt_i32_e64 s[14:15], s10, v104
	v_cmp_lt_i32_e64 s[10:11], s22, v104
	s_waitcnt lgkmcnt(4)
	v_mfma_f32_32x32x16_bf16 v[4:19], v[60:63], v[106:109], v[4:19]
	s_waitcnt lgkmcnt(3)
	v_mfma_f32_32x32x16_bf16 v[20:35], v[56:59], v[110:113], v[20:35]
	s_waitcnt lgkmcnt(1)
	v_mfma_f32_32x32x16_bf16 v[4:19], v[56:59], v[118:121], v[4:19]
	v_mfma_f32_32x32x16_bf16 v[20:35], v[52:55], v[114:117], v[20:35]
	s_waitcnt lgkmcnt(0)
	v_mfma_f32_32x32x16_bf16 v[4:19], v[52:55], v[122:125], v[4:19]
	s_nop 9
	v_max_f32_e32 v102, 0, v20
	v_max_f32_e32 v20, 0, v22
	v_max_f32_e32 v103, 0, v4
	v_pk_fma_f32 v[102:103], v[48:49], v[102:103], 0 op_sel_hi:[0,1,0]
	v_max_f32_e32 v4, 0, v21
	v_max_f32_e32 v5, 0, v5
	v_pk_fma_f32 v[4:5], v[48:49], v[4:5], v[102:103] op_sel:[1,0,0]
	v_max_f32_e32 v21, 0, v6
	v_pk_fma_f32 v[4:5], v[50:51], v[20:21], v[4:5] op_sel_hi:[0,1,1]
	v_max_f32_e32 v6, 0, v23
	v_max_f32_e32 v7, 0, v7
	v_mov_b32_e32 v20, v51
	v_pk_fma_f32 v[4:5], v[20:21], v[6:7], v[4:5] op_sel_hi:[0,1,1]
	v_mov_b32_e32 v6, v5
	v_max_f32_e32 v20, 0, v24
	v_max_f32_e32 v21, 0, v8
	v_max_f32_e32 v8, 0, v25
	v_pk_fma_f32 v[20:21], v[44:45], v[20:21], 0 op_sel_hi:[0,1,0]
	v_max_f32_e32 v9, 0, v9
	v_pk_fma_f32 v[8:9], v[44:45], v[8:9], v[20:21] op_sel:[1,0,0]
	v_max_f32_e32 v20, 0, v26
	v_max_f32_e32 v21, 0, v10
	v_max_f32_e32 v10, 0, v27
	v_pk_fma_f32 v[8:9], v[46:47], v[20:21], v[8:9] op_sel_hi:[0,1,1]
	v_max_f32_e32 v11, 0, v11
	v_mov_b32_e32 v20, v47
	v_pk_fma_f32 v[8:9], v[20:21], v[10:11], v[8:9] op_sel_hi:[0,1,1]
	v_mov_b32_e32 v7, v9
	s_nop 1
	v_permlane32_swap_b32_e32 v8, v7
	v_permlane32_swap_b32_e32 v4, v6
	v_mov_b32_e32 v5, v8
	v_pk_add_f32 v[4:5], v[4:5], v[6:7]
	v_max_f32_e32 v6, 0, v28
	v_max_f32_e32 v7, 0, v12
	v_pk_fma_f32 v[6:7], v[40:41], v[6:7], 0 op_sel_hi:[0,1,0]
	v_max_f32_e32 v8, 0, v29
	v_max_f32_e32 v9, 0, v13
	v_pk_fma_f32 v[6:7], v[40:41], v[8:9], v[6:7] op_sel:[1,0,0]
	v_max_f32_e32 v8, 0, v30
	v_max_f32_e32 v9, 0, v14
	v_pk_fma_f32 v[6:7], v[42:43], v[8:9], v[6:7] op_sel_hi:[0,1,1]
	v_max_f32_e32 v8, 0, v31
	v_max_f32_e32 v9, 0, v15
	v_mov_b32_e32 v10, v43
	v_pk_fma_f32 v[6:7], v[10:11], v[8:9], v[6:7] op_sel_hi:[0,1,1]
	v_mov_b32_e32 v8, v7
	v_max_f32_e32 v10, 0, v32
	v_max_f32_e32 v11, 0, v16
	v_max_f32_e32 v12, 0, v33
	v_pk_fma_f32 v[10:11], v[36:37], v[10:11], 0 op_sel_hi:[0,1,0]
	v_max_f32_e32 v13, 0, v17
	v_pk_fma_f32 v[10:11], v[36:37], v[12:13], v[10:11] op_sel:[1,0,0]
	v_max_f32_e32 v12, 0, v34
	v_max_f32_e32 v13, 0, v18
	v_pk_fma_f32 v[10:11], v[38:39], v[12:13], v[10:11] op_sel_hi:[0,1,1]
	v_max_f32_e32 v12, 0, v35
	v_max_f32_e32 v13, 0, v19
	v_mov_b32_e32 v14, v39
	v_pk_fma_f32 v[10:11], v[14:15], v[12:13], v[10:11] op_sel_hi:[0,1,1]
	v_mov_b32_e32 v9, v11
	s_nop 1
	v_permlane32_swap_b32_e32 v10, v9
	v_permlane32_swap_b32_e32 v6, v8
	v_mov_b32_e32 v7, v10
	v_pk_add_f32 v[6:7], v[6:7], v[8:9]
	v_pk_add_f32 v[4:5], v[4:5], 0 op_sel_hi:[1,0]
	v_pk_add_f32 v[6:7], v[6:7], 0 op_sel_hi:[1,0]
	v_cmp_gt_i32_e64 s[4:5], 0, v4
	v_cmp_gt_i32_e64 s[8:9], 0, v5
	v_cmp_gt_i32_e64 s[12:13], 0, v6
	v_cmp_gt_i32_e64 s[16:17], 0, v7
	s_and_saveexec_b64 s[20:21], s[0:1]
	s_cbranch_execz .LBB0_677
	v_mad_u32_u24 v8, v209, s57, v2
	s_waitcnt vmcnt(0)
	ds_write_b128 v8, v[68:71] offset:16384
	ds_write_b128 v8, v[72:75] offset:17536
	ds_write_b128 v8, v[76:79] offset:18688
	ds_write_b128 v8, v[80:83] offset:19840
	ds_write_b128 v8, v[84:87] offset:20992
	ds_write_b128 v8, v[88:91] offset:22144
	ds_write_b128 v8, v[92:95] offset:23296
	ds_write_b128 v8, v[96:99] offset:24448

; #define MFMA32(a, b, c) __builtin_amdgcn_mfma_f32_32x32x16_bf16((a), (b), (c), 0, 0, 0)
; DI void topk_job(const Params& p, int b, int t0, char* lds) {
;     ...
;         bf16x8 b0[4], b1[4];
; #pragma unroll
;         for (int ks = 0; ks < 4; ++ks) {
;           b0[ks] = *(const bf16x8*)(wb + r * 144 + ks * 32 + h * 16);
;           b1[ks] = *(const bf16x8*)(wb + (32 + r) * 144 + ks * 32 + h * 16);
;         }
;         __builtin_amdgcn_sched_barrier(0);
;         f32x16 a0, a1;
; #pragma unroll
;         for (int e = 0; e < 16; ++e) { a0[e] = 0.f; a1[e] = 0.f; }
; #pragma unroll
;         for (int ks = 0; ks < 4; ++ks) { a0 = MFMA32(af[ks], b0[ks], a0); a1 = MFMA32(af[ks], b1[ks], a1); }
;         const int key = c * 64 + lane;
; #pragma unroll
;         for (int qi = 0; qi < 4; ++qi) {
;           f32x2 pp2 = {0.f, 0.f};
; #pragma unroll
;           for (int e = 0; e < 4; ++e) {
;             const f32x2 rl = {fmaxf(a0[4 * qi + e], 0.f), fmaxf(a1[4 * qi + e], 0.f)};
;             const f32x2 wv = {iw[qi][e], iw[qi][e]};
;             pp2 += rl * wv;
;           }
;           const float p0 = pp2[0], p1 = pp2[1];
;           const u32x2 sw = __builtin_amdgcn_permlane32_swap(__float_as_uint(p0), __float_as_uint(p1), false, false);
;           float mine = __uint_as_float(sw[0]) + __uint_as_float(sw[1]);
;           mine += 0.0f;
;           unsigned u = __float_as_uint(mine);
;           u = (u & 0x80000000u) ? ~u : (u | 0x80000000u);
;           if (key > t0 + qi || key < LEAD) u = 0u;
;           sc[i][qi] = u;
;         }
;         if (more) {
; #pragma unroll
;           for (int j = 0; j < 8; ++j) *(u32x4*)(wb + (lrow + 8 * j) * 144 + lpc * 16) = st[j];
.LBB0_681:
	s_or_b64 exec, exec, s[2:3]
	ds_read_b128 v[4:7], v210 offset:16384
	ds_read_b128 v[102:105], v210 offset:16416
	s_waitcnt vmcnt(8)
	ds_read_b128 v[8:11], v210 offset:20992
	ds_read_b128 v[106:109], v210 offset:21024
	ds_read_b128 v[110:113], v210 offset:16448
	ds_read_b128 v[114:117], v210 offset:16480
	ds_read_b128 v[118:121], v210 offset:21056
	ds_read_b128 v[140:143], v210 offset:21088
	s_waitcnt lgkmcnt(7)
	v_mfma_f32_32x32x16_bf16 v[20:35], v[64:67], v[4:7], 0
	s_sub_i32 s2, 0x209d, s23
	s_sub_i32 s10, 0x209e, s23
	s_waitcnt lgkmcnt(5)
	v_mfma_f32_32x32x16_bf16 v[4:19], v[64:67], v[8:11], 0
	v_mfma_f32_32x32x16_bf16 v[20:35], v[60:63], v[102:105], v[20:35]
	v_lshl_or_b32 v104, v126, 6, v101
	v_cmp_gt_i32_e32 vcc, s25, v104
	v_cmp_lt_i32_e64 s[6:7], s24, v104
	v_cmp_lt_i32_e64 s[2:3], s2, v104
	v_cmp_lt_i32_e64 s[14:15], s10, v104
	v_cmp_lt_i32_e64 s[10:11], s22, v104
	s_waitcnt lgkmcnt(4)
	v_mfma_f32_32x32x16_bf16 v[4:19], v[60:63], v[106:109], v[4:19]
	s_waitcnt lgkmcnt(3)
	v_mfma_f32_32x32x16_bf16 v[20:35], v[56:59], v[110:113], v[20:35]
	s_waitcnt lgkmcnt(1)
	v_mfma_f32_32x32x16_bf16 v[4:19], v[56:59], v[118:121], v[4:19]
	v_mfma_f32_32x32x16_bf16 v[20:35], v[52:55], v[114:117], v[20:35]
	s_waitcnt lgkmcnt(0)
	v_mfma_f32_32x32x16_bf16 v[4:19], v[52:55], v[140:143], v[4:19]
	s_nop 9
	v_max_f32_e32 v102, 0, v20
	v_max_f32_e32 v20, 0, v22
	v_max_f32_e32 v103, 0, v4
	v_pk_fma_f32 v[102:103], v[48:49], v[102:103], 0 op_sel_hi:[0,1,0]
	v_max_f32_e32 v4, 0, v21
	v_max_f32_e32 v5, 0, v5
	v_pk_fma_f32 v[4:5], v[48:49], v[4:5], v[102:103] op_sel:[1,0,0]
	v_max_f32_e32 v21, 0, v6
	v_pk_fma_f32 v[4:5], v[50:51], v[20:21], v[4:5] op_sel_hi:[0,1,1]
	v_max_f32_e32 v6, 0, v23
	v_max_f32_e32 v7, 0, v7
	v_mov_b32_e32 v20, v51
	v_pk_fma_f32 v[4:5], v[20:21], v[6:7], v[4:5] op_sel_hi:[0,1,1]
	v_mov_b32_e32 v6, v5
	v_max_f32_e32 v20, 0, v24
	v_max_f32_e32 v21, 0, v8
	v_max_f32_e32 v8, 0, v25
	v_pk_fma_f32 v[20:21], v[44:45], v[20:21], 0 op_sel_hi:[0,1,0]
	v_max_f32_e32 v9, 0, v9
	v_pk_fma_f32 v[8:9], v[44:45], v[8:9], v[20:21] op_sel:[1,0,0]
	v_max_f32_e32 v20, 0, v26
	v_max_f32_e32 v21, 0, v10
	v_max_f32_e32 v10, 0, v27
	v_pk_fma_f32 v[8:9], v[46:47], v[20:21], v[8:9] op_sel_hi:[0,1,1]
	v_max_f32_e32 v11, 0, v11
	v_mov_b32_e32 v20, v47
	v_pk_fma_f32 v[8:9], v[20:21], v[10:11], v[8:9] op_sel_hi:[0,1,1]
	v_mov_b32_e32 v7, v9
	s_nop 1
	v_permlane32_swap_b32_e32 v8, v7
	v_permlane32_swap_b32_e32 v4, v6
	v_mov_b32_e32 v5, v8
	v_pk_add_f32 v[4:5], v[4:5], v[6:7]
	v_max_f32_e32 v6, 0, v28
	v_max_f32_e32 v7, 0, v12
	v_pk_fma_f32 v[6:7], v[40:41], v[6:7], 0 op_sel_hi:[0,1,0]
	v_max_f32_e32 v8, 0, v29
	v_max_f32_e32 v9, 0, v13
	v_pk_fma_f32 v[6:7], v[40:41], v[8:9], v[6:7] op_sel:[1,0,0]
	v_max_f32_e32 v8, 0, v30
	v_max_f32_e32 v9, 0, v14
	v_pk_fma_f32 v[6:7], v[42:43], v[8:9], v[6:7] op_sel_hi:[0,1,1]
	v_max_f32_e32 v8, 0, v31
	v_max_f32_e32 v9, 0, v15
	v_mov_b32_e32 v10, v43
	v_pk_fma_f32 v[6:7], v[10:11], v[8:9], v[6:7] op_sel_hi:[0,1,1]
	v_mov_b32_e32 v8, v7
	v_max_f32_e32 v10, 0, v32
	v_max_f32_e32 v11, 0, v16
	v_max_f32_e32 v12, 0, v33
	v_pk_fma_f32 v[10:11], v[36:37], v[10:11], 0 op_sel_hi:[0,1,0]
	v_max_f32_e32 v13, 0, v17
	v_pk_fma_f32 v[10:11], v[36:37], v[12:13], v[10:11] op_sel:[1,0,0]
	v_max_f32_e32 v12, 0, v34
	v_max_f32_e32 v13, 0, v18
	v_pk_fma_f32 v[10:11], v[38:39], v[12:13], v[10:11] op_sel_hi:[0,1,1]
	v_max_f32_e32 v12, 0, v35
	v_max_f32_e32 v13, 0, v19
	v_mov_b32_e32 v14, v39
	v_pk_fma_f32 v[10:11], v[14:15], v[12:13], v[10:11] op_sel_hi:[0,1,1]
	v_mov_b32_e32 v9, v11
	s_nop 1
	v_permlane32_swap_b32_e32 v10, v9
	v_permlane32_swap_b32_e32 v6, v8
	v_mov_b32_e32 v7, v10
	v_pk_add_f32 v[6:7], v[6:7], v[8:9]
	v_pk_add_f32 v[4:5], v[4:5], 0 op_sel_hi:[1,0]
	v_pk_add_f32 v[6:7], v[6:7], 0 op_sel_hi:[1,0]
	v_cmp_gt_i32_e64 s[4:5], 0, v4
	v_cmp_gt_i32_e64 s[8:9], 0, v5
	v_cmp_gt_i32_e64 s[12:13], 0, v6
	v_cmp_gt_i32_e64 s[16:17], 0, v7
	s_and_saveexec_b64 s[20:21], s[0:1]
	s_cbranch_execz .LBB0_683
	v_mad_u32_u24 v8, v209, s57, v2
	s_waitcnt vmcnt(0)
	ds_write_b128 v8, v[68:71] offset:16384
	ds_write_b128 v8, v[72:75] offset:17536
	ds_write_b128 v8, v[76:79] offset:18688
	ds_write_b128 v8, v[80:83] offset:19840
	ds_write_b128 v8, v[84:87] offset:20992
	ds_write_b128 v8, v[88:91] offset:22144
	ds_write_b128 v8, v[92:95] offset:23296
	ds_write_b128 v8, v[96:99] offset:24448

; #define MFMA32(a, b, c) __builtin_amdgcn_mfma_f32_32x32x16_bf16((a), (b), (c), 0, 0, 0)
; DI void topk_job(const Params& p, int b, int t0, char* lds) {
;     ...
;         bf16x8 b0[4], b1[4];
; #pragma unroll
;         for (int ks = 0; ks < 4; ++ks) {
;           b0[ks] = *(const bf16x8*)(wb + r * 144 + ks * 32 + h * 16);
;           b1[ks] = *(const bf16x8*)(wb + (32 + r) * 144 + ks * 32 + h * 16);
;         }
;         __builtin_amdgcn_sched_barrier(0);
;         f32x16 a0, a1;
; #pragma unroll
;         for (int e = 0; e < 16; ++e) { a0[e] = 0.f; a1[e] = 0.f; }
; #pragma unroll
;         for (int ks = 0; ks < 4; ++ks) { a0 = MFMA32(af[ks], b0[ks], a0); a1 = MFMA32(af[ks], b1[ks], a1); }
;         const int key = c * 64 + lane;
; #pragma unroll
;         for (int qi = 0; qi < 4; ++qi) {
;           f32x2 pp2 = {0.f, 0.f};
; #pragma unroll
;           for (int e = 0; e < 4; ++e) {
;             const f32x2 rl = {fmaxf(a0[4 * qi + e], 0.f), fmaxf(a1[4 * qi + e], 0.f)};
;             const f32x2 wv = {iw[qi][e], iw[qi][e]};
;             pp2 += rl * wv;
;           }
;           const float p0 = pp2[0], p1 = pp2[1];
;           const u32x2 sw = __builtin_amdgcn_permlane32_swap(__float_as_uint(p0), __float_as_uint(p1), false, false);
;           float mine = __uint_as_float(sw[0]) + __uint_as_float(sw[1]);
;           mine += 0.0f;
;           unsigned u = __float_as_uint(mine);
;           u = (u & 0x80000000u) ? ~u : (u | 0x80000000u);
;           if (key > t0 + qi || key < LEAD) u = 0u;
;           sc[i][qi] = u;
;         }
;         if (more) {
; #pragma unroll
;           for (int j = 0; j < 8; ++j) *(u32x4*)(wb + (lrow + 8 * j) * 144 + lpc * 16) = st[j];
.LBB0_687:
	s_or_b64 exec, exec, s[2:3]
	ds_read_b128 v[4:7], v210 offset:16384
	ds_read_b128 v[102:105], v210 offset:16416
	s_waitcnt vmcnt(8)
	ds_read_b128 v[8:11], v210 offset:20992
	ds_read_b128 v[106:109], v210 offset:21024
	ds_read_b128 v[110:113], v210 offset:16448
	ds_read_b128 v[114:117], v210 offset:16480
	ds_read_b128 v[118:121], v210 offset:21056
	ds_read_b128 v[140:143], v210 offset:21088
	s_waitcnt lgkmcnt(7)
	v_mfma_f32_32x32x16_bf16 v[20:35], v[64:67], v[4:7], 0
	s_sub_i32 s2, 0x209d, s23
	s_sub_i32 s10, 0x209e, s23
	s_waitcnt lgkmcnt(5)
	v_mfma_f32_32x32x16_bf16 v[4:19], v[64:67], v[8:11], 0
	v_mfma_f32_32x32x16_bf16 v[20:35], v[60:63], v[102:105], v[20:35]
	v_lshl_or_b32 v104, v124, 6, v101
	v_cmp_gt_i32_e32 vcc, s25, v104
	v_cmp_lt_i32_e64 s[6:7], s24, v104
	v_cmp_lt_i32_e64 s[2:3], s2, v104
	v_cmp_lt_i32_e64 s[14:15], s10, v104
	v_cmp_lt_i32_e64 s[10:11], s22, v104
	s_waitcnt lgkmcnt(4)
	v_mfma_f32_32x32x16_bf16 v[4:19], v[60:63], v[106:109], v[4:19]
	s_waitcnt lgkmcnt(3)
	v_mfma_f32_32x32x16_bf16 v[20:35], v[56:59], v[110:113], v[20:35]
	s_waitcnt lgkmcnt(1)
	v_mfma_f32_32x32x16_bf16 v[4:19], v[56:59], v[118:121], v[4:19]
	v_mfma_f32_32x32x16_bf16 v[20:35], v[52:55], v[114:117], v[20:35]
	s_waitcnt lgkmcnt(0)
	v_mfma_f32_32x32x16_bf16 v[4:19], v[52:55], v[140:143], v[4:19]
	s_nop 9
	v_max_f32_e32 v102, 0, v20
	v_max_f32_e32 v20, 0, v22
	v_max_f32_e32 v103, 0, v4
	v_pk_fma_f32 v[102:103], v[48:49], v[102:103], 0 op_sel_hi:[0,1,0]
	v_max_f32_e32 v4, 0, v21
	v_max_f32_e32 v5, 0, v5
	v_pk_fma_f32 v[4:5], v[48:49], v[4:5], v[102:103] op_sel:[1,0,0]
	v_max_f32_e32 v21, 0, v6
	v_pk_fma_f32 v[4:5], v[50:51], v[20:21], v[4:5] op_sel_hi:[0,1,1]
	v_max_f32_e32 v6, 0, v23
	v_max_f32_e32 v7, 0, v7
	v_mov_b32_e32 v20, v51
	v_pk_fma_f32 v[4:5], v[20:21], v[6:7], v[4:5] op_sel_hi:[0,1,1]
	v_mov_b32_e32 v6, v5
	v_max_f32_e32 v20, 0, v24
	v_max_f32_e32 v21, 0, v8
	v_max_f32_e32 v8, 0, v25
	v_pk_fma_f32 v[20:21], v[44:45], v[20:21], 0 op_sel_hi:[0,1,0]
	v_max_f32_e32 v9, 0, v9
	v_pk_fma_f32 v[8:9], v[44:45], v[8:9], v[20:21] op_sel:[1,0,0]
	v_max_f32_e32 v20, 0, v26
	v_max_f32_e32 v21, 0, v10
	v_max_f32_e32 v10, 0, v27
	v_pk_fma_f32 v[8:9], v[46:47], v[20:21], v[8:9] op_sel_hi:[0,1,1]
	v_max_f32_e32 v11, 0, v11
	v_mov_b32_e32 v20, v47
	v_pk_fma_f32 v[8:9], v[20:21], v[10:11], v[8:9] op_sel_hi:[0,1,1]
	v_mov_b32_e32 v7, v9
	s_nop 1
	v_permlane32_swap_b32_e32 v8, v7
	v_permlane32_swap_b32_e32 v4, v6
	v_mov_b32_e32 v5, v8
	v_pk_add_f32 v[4:5], v[4:5], v[6:7]
	v_max_f32_e32 v6, 0, v28
	v_max_f32_e32 v7, 0, v12
	v_pk_fma_f32 v[6:7], v[40:41], v[6:7], 0 op_sel_hi:[0,1,0]
	v_max_f32_e32 v8, 0, v29
	v_max_f32_e32 v9, 0, v13
	v_pk_fma_f32 v[6:7], v[40:41], v[8:9], v[6:7] op_sel:[1,0,0]
	v_max_f32_e32 v8, 0, v30
	v_max_f32_e32 v9, 0, v14
	v_pk_fma_f32 v[6:7], v[42:43], v[8:9], v[6:7] op_sel_hi:[0,1,1]
	v_max_f32_e32 v8, 0, v31
	v_max_f32_e32 v9, 0, v15
	v_mov_b32_e32 v10, v43
	v_pk_fma_f32 v[6:7], v[10:11], v[8:9], v[6:7] op_sel_hi:[0,1,1]
	v_mov_b32_e32 v8, v7
	v_max_f32_e32 v10, 0, v32
	v_max_f32_e32 v11, 0, v16
	v_max_f32_e32 v12, 0, v33
	v_pk_fma_f32 v[10:11], v[36:37], v[10:11], 0 op_sel_hi:[0,1,0]
	v_max_f32_e32 v13, 0, v17
	v_pk_fma_f32 v[10:11], v[36:37], v[12:13], v[10:11] op_sel:[1,0,0]
	v_max_f32_e32 v12, 0, v34
	v_max_f32_e32 v13, 0, v18
	v_pk_fma_f32 v[10:11], v[38:39], v[12:13], v[10:11] op_sel_hi:[0,1,1]
	v_max_f32_e32 v12, 0, v35
	v_max_f32_e32 v13, 0, v19
	v_mov_b32_e32 v14, v39
	v_pk_fma_f32 v[10:11], v[14:15], v[12:13], v[10:11] op_sel_hi:[0,1,1]
	v_mov_b32_e32 v9, v11
	s_nop 1
	v_permlane32_swap_b32_e32 v10, v9
	v_permlane32_swap_b32_e32 v6, v8
	v_mov_b32_e32 v7, v10
	v_pk_add_f32 v[6:7], v[6:7], v[8:9]
	v_pk_add_f32 v[4:5], v[4:5], 0 op_sel_hi:[1,0]
	v_pk_add_f32 v[6:7], v[6:7], 0 op_sel_hi:[1,0]
	v_cmp_gt_i32_e64 s[4:5], 0, v4
	v_cmp_gt_i32_e64 s[8:9], 0, v5
	v_cmp_gt_i32_e64 s[12:13], 0, v6
	v_cmp_gt_i32_e64 s[16:17], 0, v7
	s_and_saveexec_b64 s[20:21], s[0:1]
	s_cbranch_execz .LBB0_689
	v_mad_u32_u24 v8, v209, s57, v2
	s_waitcnt vmcnt(0)
	ds_write_b128 v8, v[68:71] offset:16384
	ds_write_b128 v8, v[72:75] offset:17536
	ds_write_b128 v8, v[76:79] offset:18688
	ds_write_b128 v8, v[80:83] offset:19840
	ds_write_b128 v8, v[84:87] offset:20992
	ds_write_b128 v8, v[88:91] offset:22144
	ds_write_b128 v8, v[92:95] offset:23296
	ds_write_b128 v8, v[96:99] offset:24448

; #define MFMA32(a, b, c) __builtin_amdgcn_mfma_f32_32x32x16_bf16((a), (b), (c), 0, 0, 0)
; DI void topk_job(const Params& p, int b, int t0, char* lds) {
;     ...
;         bf16x8 b0[4], b1[4];
; #pragma unroll
;         for (int ks = 0; ks < 4; ++ks) {
;           b0[ks] = *(const bf16x8*)(wb + r * 144 + ks * 32 + h * 16);
;           b1[ks] = *(const bf16x8*)(wb + (32 + r) * 144 + ks * 32 + h * 16);
;         }
;         __builtin_amdgcn_sched_barrier(0);
;         f32x16 a0, a1;
; #pragma unroll
;         for (int e = 0; e < 16; ++e) { a0[e] = 0.f; a1[e] = 0.f; }
; #pragma unroll
;         for (int ks = 0; ks < 4; ++ks) { a0 = MFMA32(af[ks], b0[ks], a0); a1 = MFMA32(af[ks], b1[ks], a1); }
;         const int key = c * 64 + lane;
; #pragma unroll
;         for (int qi = 0; qi < 4; ++qi) {
;           f32x2 pp2 = {0.f, 0.f};
; #pragma unroll
;           for (int e = 0; e < 4; ++e) {
;             const f32x2 rl = {fmaxf(a0[4 * qi + e], 0.f), fmaxf(a1[4 * qi + e], 0.f)};
;             const f32x2 wv = {iw[qi][e], iw[qi][e]};
;             pp2 += rl * wv;
;           }
;           const float p0 = pp2[0], p1 = pp2[1];
;           const u32x2 sw = __builtin_amdgcn_permlane32_swap(__float_as_uint(p0), __float_as_uint(p1), false, false);
;           float mine = __uint_as_float(sw[0]) + __uint_as_float(sw[1]);
;           mine += 0.0f;
;           unsigned u = __float_as_uint(mine);
;           u = (u & 0x80000000u) ? ~u : (u | 0x80000000u);
;           if (key > t0 + qi || key < LEAD) u = 0u;
;           sc[i][qi] = u;
;         }
;         if (more) {
; #pragma unroll
;           for (int j = 0; j < 8; ++j) *(u32x4*)(wb + (lrow + 8 * j) * 144 + lpc * 16) = st[j];
.LBB0_693:
	s_or_b64 exec, exec, s[2:3]
	ds_read_b128 v[4:7], v210 offset:16384
	ds_read_b128 v[102:105], v210 offset:16416
	s_waitcnt vmcnt(8)
	ds_read_b128 v[8:11], v210 offset:20992
	ds_read_b128 v[106:109], v210 offset:21024
	ds_read_b128 v[110:113], v210 offset:16448
	ds_read_b128 v[114:117], v210 offset:16480
	ds_read_b128 v[140:143], v210 offset:21056
	ds_read_b128 v[144:147], v210 offset:21088
	s_waitcnt lgkmcnt(7)
	v_mfma_f32_32x32x16_bf16 v[20:35], v[64:67], v[4:7], 0
	s_sub_i32 s2, 0x209d, s23
	s_sub_i32 s10, 0x209e, s23
	s_waitcnt lgkmcnt(5)
	v_mfma_f32_32x32x16_bf16 v[4:19], v[64:67], v[8:11], 0
	v_mfma_f32_32x32x16_bf16 v[20:35], v[60:63], v[102:105], v[20:35]
	v_lshl_or_b32 v104, v122, 6, v101
	v_cmp_gt_i32_e32 vcc, s25, v104
	v_cmp_lt_i32_e64 s[6:7], s24, v104
	v_cmp_lt_i32_e64 s[2:3], s2, v104
	v_cmp_lt_i32_e64 s[14:15], s10, v104
	v_cmp_lt_i32_e64 s[10:11], s22, v104
	s_waitcnt lgkmcnt(4)
	v_mfma_f32_32x32x16_bf16 v[4:19], v[60:63], v[106:109], v[4:19]
	s_waitcnt lgkmcnt(3)
	v_mfma_f32_32x32x16_bf16 v[20:35], v[56:59], v[110:113], v[20:35]
	s_waitcnt lgkmcnt(1)
	v_mfma_f32_32x32x16_bf16 v[4:19], v[56:59], v[140:143], v[4:19]
	v_mfma_f32_32x32x16_bf16 v[20:35], v[52:55], v[114:117], v[20:35]
	s_waitcnt lgkmcnt(0)
	v_mfma_f32_32x32x16_bf16 v[4:19], v[52:55], v[144:147], v[4:19]
	s_nop 9
	v_max_f32_e32 v102, 0, v20
	v_max_f32_e32 v20, 0, v22
	v_max_f32_e32 v103, 0, v4
	v_pk_fma_f32 v[102:103], v[48:49], v[102:103], 0 op_sel_hi:[0,1,0]
	v_max_f32_e32 v4, 0, v21
	v_max_f32_e32 v5, 0, v5
	v_pk_fma_f32 v[4:5], v[48:49], v[4:5], v[102:103] op_sel:[1,0,0]
	v_max_f32_e32 v21, 0, v6
	v_pk_fma_f32 v[4:5], v[50:51], v[20:21], v[4:5] op_sel_hi:[0,1,1]
	v_max_f32_e32 v6, 0, v23
	v_max_f32_e32 v7, 0, v7
	v_mov_b32_e32 v20, v51
	v_pk_fma_f32 v[4:5], v[20:21], v[6:7], v[4:5] op_sel_hi:[0,1,1]
	v_mov_b32_e32 v6, v5
	v_max_f32_e32 v20, 0, v24
	v_max_f32_e32 v21, 0, v8
	v_max_f32_e32 v8, 0, v25
	v_pk_fma_f32 v[20:21], v[44:45], v[20:21], 0 op_sel_hi:[0,1,0]
	v_max_f32_e32 v9, 0, v9
	v_pk_fma_f32 v[8:9], v[44:45], v[8:9], v[20:21] op_sel:[1,0,0]
	v_max_f32_e32 v20, 0, v26
	v_max_f32_e32 v21, 0, v10
	v_max_f32_e32 v10, 0, v27
	v_pk_fma_f32 v[8:9], v[46:47], v[20:21], v[8:9] op_sel_hi:[0,1,1]
	v_max_f32_e32 v11, 0, v11
	v_mov_b32_e32 v20, v47
	v_pk_fma_f32 v[8:9], v[20:21], v[10:11], v[8:9] op_sel_hi:[0,1,1]
	v_mov_b32_e32 v7, v9
	s_nop 1
	v_permlane32_swap_b32_e32 v8, v7
	v_permlane32_swap_b32_e32 v4, v6
	v_mov_b32_e32 v5, v8
	v_pk_add_f32 v[4:5], v[4:5], v[6:7]
	v_max_f32_e32 v6, 0, v28
	v_max_f32_e32 v7, 0, v12
	v_pk_fma_f32 v[6:7], v[40:41], v[6:7], 0 op_sel_hi:[0,1,0]
	v_max_f32_e32 v8, 0, v29
	v_max_f32_e32 v9, 0, v13
	v_pk_fma_f32 v[6:7], v[40:41], v[8:9], v[6:7] op_sel:[1,0,0]
	v_max_f32_e32 v8, 0, v30
	v_max_f32_e32 v9, 0, v14
	v_pk_fma_f32 v[6:7], v[42:43], v[8:9], v[6:7] op_sel_hi:[0,1,1]
	v_max_f32_e32 v8, 0, v31
	v_max_f32_e32 v9, 0, v15
	v_mov_b32_e32 v10, v43
	v_pk_fma_f32 v[6:7], v[10:11], v[8:9], v[6:7] op_sel_hi:[0,1,1]
	v_mov_b32_e32 v8, v7
	v_max_f32_e32 v10, 0, v32
	v_max_f32_e32 v11, 0, v16
	v_max_f32_e32 v12, 0, v33
	v_pk_fma_f32 v[10:11], v[36:37], v[10:11], 0 op_sel_hi:[0,1,0]
	v_max_f32_e32 v13, 0, v17
	v_pk_fma_f32 v[10:11], v[36:37], v[12:13], v[10:11] op_sel:[1,0,0]
	v_max_f32_e32 v12, 0, v34
	v_max_f32_e32 v13, 0, v18
	v_pk_fma_f32 v[10:11], v[38:39], v[12:13], v[10:11] op_sel_hi:[0,1,1]
	v_max_f32_e32 v12, 0, v35
	v_max_f32_e32 v13, 0, v19
	v_mov_b32_e32 v14, v39
	v_pk_fma_f32 v[10:11], v[14:15], v[12:13], v[10:11] op_sel_hi:[0,1,1]
	v_mov_b32_e32 v9, v11
	s_nop 1
	v_permlane32_swap_b32_e32 v10, v9
	v_permlane32_swap_b32_e32 v6, v8
	v_mov_b32_e32 v7, v10
	v_pk_add_f32 v[6:7], v[6:7], v[8:9]
	v_pk_add_f32 v[4:5], v[4:5], 0 op_sel_hi:[1,0]
	v_pk_add_f32 v[6:7], v[6:7], 0 op_sel_hi:[1,0]
	v_cmp_gt_i32_e64 s[4:5], 0, v4
	v_cmp_gt_i32_e64 s[8:9], 0, v5
	v_cmp_gt_i32_e64 s[12:13], 0, v6
	v_cmp_gt_i32_e64 s[16:17], 0, v7
	s_and_saveexec_b64 s[20:21], s[0:1]
	s_cbranch_execz .LBB0_695
	v_mad_u32_u24 v8, v209, s57, v2
	s_waitcnt vmcnt(0)
	ds_write_b128 v8, v[68:71] offset:16384
	ds_write_b128 v8, v[72:75] offset:17536
	ds_write_b128 v8, v[76:79] offset:18688
	ds_write_b128 v8, v[80:83] offset:19840
	ds_write_b128 v8, v[84:87] offset:20992
	ds_write_b128 v8, v[88:91] offset:22144
	ds_write_b128 v8, v[92:95] offset:23296
	ds_write_b128 v8, v[96:99] offset:24448

; #define MFMA32(a, b, c) __builtin_amdgcn_mfma_f32_32x32x16_bf16((a), (b), (c), 0, 0, 0)
; DI void topk_job(const Params& p, int b, int t0, char* lds) {
;     ...
;         bf16x8 b0[4], b1[4];
; #pragma unroll
;         for (int ks = 0; ks < 4; ++ks) {
;           b0[ks] = *(const bf16x8*)(wb + r * 144 + ks * 32 + h * 16);
;           b1[ks] = *(const bf16x8*)(wb + (32 + r) * 144 + ks * 32 + h * 16);
;         }
;         __builtin_amdgcn_sched_barrier(0);
;         f32x16 a0, a1;
; #pragma unroll
;         for (int e = 0; e < 16; ++e) { a0[e] = 0.f; a1[e] = 0.f; }
; #pragma unroll
;         for (int ks = 0; ks < 4; ++ks) { a0 = MFMA32(af[ks], b0[ks], a0); a1 = MFMA32(af[ks], b1[ks], a1); }
;         const int key = c * 64 + lane;
; #pragma unroll
;         for (int qi = 0; qi < 4; ++qi) {
;           f32x2 pp2 = {0.f, 0.f};
; #pragma unroll
;           for (int e = 0; e < 4; ++e) {
;             const f32x2 rl = {fmaxf(a0[4 * qi + e], 0.f), fmaxf(a1[4 * qi + e], 0.f)};
;             const f32x2 wv = {iw[qi][e], iw[qi][e]};
;             pp2 += rl * wv;
;           }
;           const float p0 = pp2[0], p1 = pp2[1];
;           const u32x2 sw = __builtin_amdgcn_permlane32_swap(__float_as_uint(p0), __float_as_uint(p1), false, false);
;           float mine = __uint_as_float(sw[0]) + __uint_as_float(sw[1]);
;           mine += 0.0f;
;           unsigned u = __float_as_uint(mine);
;           u = (u & 0x80000000u) ? ~u : (u | 0x80000000u);
;           if (key > t0 + qi || key < LEAD) u = 0u;
;           sc[i][qi] = u;
;         }
;         if (more) {
; #pragma unroll
;           for (int j = 0; j < 8; ++j) *(u32x4*)(wb + (lrow + 8 * j) * 144 + lpc * 16) = st[j];
.LBB0_699:
	s_or_b64 exec, exec, s[2:3]
	ds_read_b128 v[4:7], v210 offset:16384
	ds_read_b128 v[102:105], v210 offset:16416
	s_waitcnt vmcnt(8)
	ds_read_b128 v[8:11], v210 offset:20992
	ds_read_b128 v[106:109], v210 offset:21024
	ds_read_b128 v[110:113], v210 offset:16448
	ds_read_b128 v[114:117], v210 offset:16480
	ds_read_b128 v[140:143], v210 offset:21056
	ds_read_b128 v[162:165], v210 offset:21088
	s_waitcnt lgkmcnt(7)
	v_mfma_f32_32x32x16_bf16 v[20:35], v[64:67], v[4:7], 0
	s_sub_i32 s2, 0x209d, s23
	s_sub_i32 s10, 0x209e, s23
	s_waitcnt lgkmcnt(5)
	v_mfma_f32_32x32x16_bf16 v[4:19], v[64:67], v[8:11], 0
	v_mfma_f32_32x32x16_bf16 v[20:35], v[60:63], v[102:105], v[20:35]
	v_lshl_or_b32 v104, v120, 6, v101
	v_cmp_gt_i32_e32 vcc, s25, v104
	v_cmp_lt_i32_e64 s[6:7], s24, v104
	v_cmp_lt_i32_e64 s[2:3], s2, v104
	v_cmp_lt_i32_e64 s[14:15], s10, v104
	v_cmp_lt_i32_e64 s[10:11], s22, v104
	s_waitcnt lgkmcnt(4)
	v_mfma_f32_32x32x16_bf16 v[4:19], v[60:63], v[106:109], v[4:19]
	s_waitcnt lgkmcnt(3)
	v_mfma_f32_32x32x16_bf16 v[20:35], v[56:59], v[110:113], v[20:35]
	s_waitcnt lgkmcnt(1)
	v_mfma_f32_32x32x16_bf16 v[4:19], v[56:59], v[140:143], v[4:19]
	v_mfma_f32_32x32x16_bf16 v[20:35], v[52:55], v[114:117], v[20:35]
	s_waitcnt lgkmcnt(0)
	v_mfma_f32_32x32x16_bf16 v[4:19], v[52:55], v[162:165], v[4:19]
	s_nop 9
	v_max_f32_e32 v102, 0, v20
	v_max_f32_e32 v20, 0, v22
	v_max_f32_e32 v103, 0, v4
	v_pk_fma_f32 v[102:103], v[48:49], v[102:103], 0 op_sel_hi:[0,1,0]
	v_max_f32_e32 v4, 0, v21
	v_max_f32_e32 v5, 0, v5
	v_pk_fma_f32 v[4:5], v[48:49], v[4:5], v[102:103] op_sel:[1,0,0]
	v_max_f32_e32 v21, 0, v6
	v_pk_fma_f32 v[4:5], v[50:51], v[20:21], v[4:5] op_sel_hi:[0,1,1]
	v_max_f32_e32 v6, 0, v23
	v_max_f32_e32 v7, 0, v7
	v_mov_b32_e32 v20, v51
	v_pk_fma_f32 v[4:5], v[20:21], v[6:7], v[4:5] op_sel_hi:[0,1,1]
	v_mov_b32_e32 v6, v5
	v_max_f32_e32 v20, 0, v24
	v_max_f32_e32 v21, 0, v8
	v_max_f32_e32 v8, 0, v25
	v_pk_fma_f32 v[20:21], v[44:45], v[20:21], 0 op_sel_hi:[0,1,0]
	v_max_f32_e32 v9, 0, v9
	v_pk_fma_f32 v[8:9], v[44:45], v[8:9], v[20:21] op_sel:[1,0,0]
	v_max_f32_e32 v20, 0, v26
	v_max_f32_e32 v21, 0, v10
	v_max_f32_e32 v10, 0, v27
	v_pk_fma_f32 v[8:9], v[46:47], v[20:21], v[8:9] op_sel_hi:[0,1,1]
	v_max_f32_e32 v11, 0, v11
	v_mov_b32_e32 v20, v47
	v_pk_fma_f32 v[8:9], v[20:21], v[10:11], v[8:9] op_sel_hi:[0,1,1]
	v_mov_b32_e32 v7, v9
	s_nop 1
	v_permlane32_swap_b32_e32 v8, v7
	v_permlane32_swap_b32_e32 v4, v6
	v_mov_b32_e32 v5, v8
	v_pk_add_f32 v[4:5], v[4:5], v[6:7]
	v_max_f32_e32 v6, 0, v28
	v_max_f32_e32 v7, 0, v12
	v_pk_fma_f32 v[6:7], v[40:41], v[6:7], 0 op_sel_hi:[0,1,0]
	v_max_f32_e32 v8, 0, v29
	v_max_f32_e32 v9, 0, v13
	v_pk_fma_f32 v[6:7], v[40:41], v[8:9], v[6:7] op_sel:[1,0,0]
	v_max_f32_e32 v8, 0, v30
	v_max_f32_e32 v9, 0, v14
	v_pk_fma_f32 v[6:7], v[42:43], v[8:9], v[6:7] op_sel_hi:[0,1,1]
	v_max_f32_e32 v8, 0, v31
	v_max_f32_e32 v9, 0, v15
	v_mov_b32_e32 v10, v43
	v_pk_fma_f32 v[6:7], v[10:11], v[8:9], v[6:7] op_sel_hi:[0,1,1]
	v_mov_b32_e32 v8, v7
	v_max_f32_e32 v10, 0, v32
	v_max_f32_e32 v11, 0, v16
	v_max_f32_e32 v12, 0, v33
	v_pk_fma_f32 v[10:11], v[36:37], v[10:11], 0 op_sel_hi:[0,1,0]
	v_max_f32_e32 v13, 0, v17
	v_pk_fma_f32 v[10:11], v[36:37], v[12:13], v[10:11] op_sel:[1,0,0]
	v_max_f32_e32 v12, 0, v34
	v_max_f32_e32 v13, 0, v18
	v_pk_fma_f32 v[10:11], v[38:39], v[12:13], v[10:11] op_sel_hi:[0,1,1]
	v_max_f32_e32 v12, 0, v35
	v_max_f32_e32 v13, 0, v19
	v_mov_b32_e32 v14, v39
	v_pk_fma_f32 v[10:11], v[14:15], v[12:13], v[10:11] op_sel_hi:[0,1,1]
	v_mov_b32_e32 v9, v11
	s_nop 1
	v_permlane32_swap_b32_e32 v10, v9
	v_permlane32_swap_b32_e32 v6, v8
	v_mov_b32_e32 v7, v10
	v_pk_add_f32 v[6:7], v[6:7], v[8:9]
	v_pk_add_f32 v[4:5], v[4:5], 0 op_sel_hi:[1,0]
	v_pk_add_f32 v[6:7], v[6:7], 0 op_sel_hi:[1,0]
	v_cmp_gt_i32_e64 s[4:5], 0, v4
	v_cmp_gt_i32_e64 s[8:9], 0, v5
	v_cmp_gt_i32_e64 s[12:13], 0, v6
	v_cmp_gt_i32_e64 s[16:17], 0, v7
	s_and_saveexec_b64 s[20:21], s[0:1]
	s_cbranch_execz .LBB0_701
	v_mad_u32_u24 v8, v209, s57, v2
	s_waitcnt vmcnt(0)
	ds_write_b128 v8, v[68:71] offset:16384
	ds_write_b128 v8, v[72:75] offset:17536
	ds_write_b128 v8, v[76:79] offset:18688
	ds_write_b128 v8, v[80:83] offset:19840
	ds_write_b128 v8, v[84:87] offset:20992
	ds_write_b128 v8, v[88:91] offset:22144
	ds_write_b128 v8, v[92:95] offset:23296
	ds_write_b128 v8, v[96:99] offset:24448

; #define MFMA32(a, b, c) __builtin_amdgcn_mfma_f32_32x32x16_bf16((a), (b), (c), 0, 0, 0)
; DI void topk_job(const Params& p, int b, int t0, char* lds) {
;     ...
;         bf16x8 b0[4], b1[4];
; #pragma unroll
;         for (int ks = 0; ks < 4; ++ks) {
;           b0[ks] = *(const bf16x8*)(wb + r * 144 + ks * 32 + h * 16);
;           b1[ks] = *(const bf16x8*)(wb + (32 + r) * 144 + ks * 32 + h * 16);
;         }
;         __builtin_amdgcn_sched_barrier(0);
;         f32x16 a0, a1;
; #pragma unroll
;         for (int e = 0; e < 16; ++e) { a0[e] = 0.f; a1[e] = 0.f; }
; #pragma unroll
;         for (int ks = 0; ks < 4; ++ks) { a0 = MFMA32(af[ks], b0[ks], a0); a1 = MFMA32(af[ks], b1[ks], a1); }
;         const int key = c * 64 + lane;
; #pragma unroll
;         for (int qi = 0; qi < 4; ++qi) {
;           f32x2 pp2 = {0.f, 0.f};
; #pragma unroll
;           for (int e = 0; e < 4; ++e) {
;             const f32x2 rl = {fmaxf(a0[4 * qi + e], 0.f), fmaxf(a1[4 * qi + e], 0.f)};
;             const f32x2 wv = {iw[qi][e], iw[qi][e]};
;             pp2 += rl * wv;
;           }
;           const float p0 = pp2[0], p1 = pp2[1];
;           const u32x2 sw = __builtin_amdgcn_permlane32_swap(__float_as_uint(p0), __float_as_uint(p1), false, false);
;           float mine = __uint_as_float(sw[0]) + __uint_as_float(sw[1]);
;           mine += 0.0f;
;           unsigned u = __float_as_uint(mine);
;           u = (u & 0x80000000u) ? ~u : (u | 0x80000000u);
;           if (key > t0 + qi || key < LEAD) u = 0u;
;           sc[i][qi] = u;
;         }
;         if (more) {
; #pragma unroll
;           for (int j = 0; j < 8; ++j) *(u32x4*)(wb + (lrow + 8 * j) * 144 + lpc * 16) = st[j];
.LBB0_705:
	s_or_b64 exec, exec, s[2:3]
	ds_read_b128 v[4:7], v210 offset:16384
	ds_read_b128 v[102:105], v210 offset:16416
	s_waitcnt vmcnt(8)
	ds_read_b128 v[8:11], v210 offset:20992
	ds_read_b128 v[106:109], v210 offset:21024
	ds_read_b128 v[110:113], v210 offset:16448
	ds_read_b128 v[140:143], v210 offset:16480
	ds_read_b128 v[162:165], v210 offset:21056
	ds_read_b128 v[176:179], v210 offset:21088
	s_waitcnt lgkmcnt(7)
	v_mfma_f32_32x32x16_bf16 v[20:35], v[64:67], v[4:7], 0
	s_sub_i32 s2, 0x209d, s23
	s_sub_i32 s10, 0x209e, s23
	s_waitcnt lgkmcnt(5)
	v_mfma_f32_32x32x16_bf16 v[4:19], v[64:67], v[8:11], 0
	v_mfma_f32_32x32x16_bf16 v[20:35], v[60:63], v[102:105], v[20:35]
	v_lshl_or_b32 v104, v118, 6, v101
	v_cmp_gt_i32_e32 vcc, s25, v104
	v_cmp_lt_i32_e64 s[6:7], s24, v104
	v_cmp_lt_i32_e64 s[2:3], s2, v104
	v_cmp_lt_i32_e64 s[14:15], s10, v104
	v_cmp_lt_i32_e64 s[10:11], s22, v104
	s_waitcnt lgkmcnt(4)
	v_mfma_f32_32x32x16_bf16 v[4:19], v[60:63], v[106:109], v[4:19]
	s_waitcnt lgkmcnt(3)
	v_mfma_f32_32x32x16_bf16 v[20:35], v[56:59], v[110:113], v[20:35]
	s_waitcnt lgkmcnt(1)
	v_mfma_f32_32x32x16_bf16 v[4:19], v[56:59], v[162:165], v[4:19]
	v_mfma_f32_32x32x16_bf16 v[20:35], v[52:55], v[140:143], v[20:35]
	s_waitcnt lgkmcnt(0)
	v_mfma_f32_32x32x16_bf16 v[4:19], v[52:55], v[176:179], v[4:19]
	s_nop 9
	v_max_f32_e32 v102, 0, v20
	v_max_f32_e32 v20, 0, v22
	v_max_f32_e32 v103, 0, v4
	v_pk_fma_f32 v[102:103], v[48:49], v[102:103], 0 op_sel_hi:[0,1,0]
	v_max_f32_e32 v4, 0, v21
	v_max_f32_e32 v5, 0, v5
	v_pk_fma_f32 v[4:5], v[48:49], v[4:5], v[102:103] op_sel:[1,0,0]
	v_max_f32_e32 v21, 0, v6
	v_pk_fma_f32 v[4:5], v[50:51], v[20:21], v[4:5] op_sel_hi:[0,1,1]
	v_max_f32_e32 v6, 0, v23
	v_max_f32_e32 v7, 0, v7
	v_mov_b32_e32 v20, v51
	v_pk_fma_f32 v[4:5], v[20:21], v[6:7], v[4:5] op_sel_hi:[0,1,1]
	v_mov_b32_e32 v6, v5
	v_max_f32_e32 v20, 0, v24
	v_max_f32_e32 v21, 0, v8
	v_max_f32_e32 v8, 0, v25
	v_pk_fma_f32 v[20:21], v[44:45], v[20:21], 0 op_sel_hi:[0,1,0]
	v_max_f32_e32 v9, 0, v9
	v_pk_fma_f32 v[8:9], v[44:45], v[8:9], v[20:21] op_sel:[1,0,0]
	v_max_f32_e32 v20, 0, v26
	v_max_f32_e32 v21, 0, v10
	v_max_f32_e32 v10, 0, v27
	v_pk_fma_f32 v[8:9], v[46:47], v[20:21], v[8:9] op_sel_hi:[0,1,1]
	v_max_f32_e32 v11, 0, v11
	v_mov_b32_e32 v20, v47
	v_pk_fma_f32 v[8:9], v[20:21], v[10:11], v[8:9] op_sel_hi:[0,1,1]
	v_mov_b32_e32 v7, v9
	s_nop 1
	v_permlane32_swap_b32_e32 v8, v7
	v_permlane32_swap_b32_e32 v4, v6
	v_mov_b32_e32 v5, v8
	v_pk_add_f32 v[4:5], v[4:5], v[6:7]
	v_max_f32_e32 v6, 0, v28
	v_max_f32_e32 v7, 0, v12
	v_pk_fma_f32 v[6:7], v[40:41], v[6:7], 0 op_sel_hi:[0,1,0]
	v_max_f32_e32 v8, 0, v29
	v_max_f32_e32 v9, 0, v13
	v_pk_fma_f32 v[6:7], v[40:41], v[8:9], v[6:7] op_sel:[1,0,0]
	v_max_f32_e32 v8, 0, v30
	v_max_f32_e32 v9, 0, v14
	v_pk_fma_f32 v[6:7], v[42:43], v[8:9], v[6:7] op_sel_hi:[0,1,1]
	v_max_f32_e32 v8, 0, v31
	v_max_f32_e32 v9, 0, v15
	v_mov_b32_e32 v10, v43
	v_pk_fma_f32 v[6:7], v[10:11], v[8:9], v[6:7] op_sel_hi:[0,1,1]
	v_mov_b32_e32 v8, v7
	v_max_f32_e32 v10, 0, v32
	v_max_f32_e32 v11, 0, v16
	v_max_f32_e32 v12, 0, v33
	v_pk_fma_f32 v[10:11], v[36:37], v[10:11], 0 op_sel_hi:[0,1,0]
	v_max_f32_e32 v13, 0, v17
	v_pk_fma_f32 v[10:11], v[36:37], v[12:13], v[10:11] op_sel:[1,0,0]
	v_max_f32_e32 v12, 0, v34
	v_max_f32_e32 v13, 0, v18
	v_pk_fma_f32 v[10:11], v[38:39], v[12:13], v[10:11] op_sel_hi:[0,1,1]
	v_max_f32_e32 v12, 0, v35
	v_max_f32_e32 v13, 0, v19
	v_mov_b32_e32 v14, v39
	v_pk_fma_f32 v[10:11], v[14:15], v[12:13], v[10:11] op_sel_hi:[0,1,1]
	v_mov_b32_e32 v9, v11
	s_nop 1
	v_permlane32_swap_b32_e32 v10, v9
	v_permlane32_swap_b32_e32 v6, v8
	v_mov_b32_e32 v7, v10
	v_pk_add_f32 v[6:7], v[6:7], v[8:9]
	v_pk_add_f32 v[4:5], v[4:5], 0 op_sel_hi:[1,0]
	v_pk_add_f32 v[6:7], v[6:7], 0 op_sel_hi:[1,0]
	v_cmp_gt_i32_e64 s[4:5], 0, v4
	v_cmp_gt_i32_e64 s[8:9], 0, v5
	v_cmp_gt_i32_e64 s[12:13], 0, v6
	v_cmp_gt_i32_e64 s[16:17], 0, v7
	s_and_saveexec_b64 s[20:21], s[0:1]
	s_cbranch_execz .LBB0_707
	v_mad_u32_u24 v8, v209, s57, v2
	s_waitcnt vmcnt(0)
	ds_write_b128 v8, v[68:71] offset:16384
	ds_write_b128 v8, v[72:75] offset:17536
	ds_write_b128 v8, v[76:79] offset:18688
	ds_write_b128 v8, v[80:83] offset:19840
	ds_write_b128 v8, v[84:87] offset:20992
	ds_write_b128 v8, v[88:91] offset:22144
	ds_write_b128 v8, v[92:95] offset:23296
	ds_write_b128 v8, v[96:99] offset:24448

; #define MFMA32(a, b, c) __builtin_amdgcn_mfma_f32_32x32x16_bf16((a), (b), (c), 0, 0, 0)
; DI void topk_job(const Params& p, int b, int t0, char* lds) {
;     ...
;         bf16x8 b0[4], b1[4];
; #pragma unroll
;         for (int ks = 0; ks < 4; ++ks) {
;           b0[ks] = *(const bf16x8*)(wb + r * 144 + ks * 32 + h * 16);
;           b1[ks] = *(const bf16x8*)(wb + (32 + r) * 144 + ks * 32 + h * 16);
;         }
;         __builtin_amdgcn_sched_barrier(0);
;         f32x16 a0, a1;
; #pragma unroll
;         for (int e = 0; e < 16; ++e) { a0[e] = 0.f; a1[e] = 0.f; }
; #pragma unroll
;         for (int ks = 0; ks < 4; ++ks) { a0 = MFMA32(af[ks], b0[ks], a0); a1 = MFMA32(af[ks], b1[ks], a1); }
;         const int key = c * 64 + lane;
; #pragma unroll
;         for (int qi = 0; qi < 4; ++qi) {
;           f32x2 pp2 = {0.f, 0.f};
; #pragma unroll
;           for (int e = 0; e < 4; ++e) {
;             const f32x2 rl = {fmaxf(a0[4 * qi + e], 0.f), fmaxf(a1[4 * qi + e], 0.f)};
;             const f32x2 wv = {iw[qi][e], iw[qi][e]};
;             pp2 += rl * wv;
;           }
;           const float p0 = pp2[0], p1 = pp2[1];
;           const u32x2 sw = __builtin_amdgcn_permlane32_swap(__float_as_uint(p0), __float_as_uint(p1), false, false);
;           float mine = __uint_as_float(sw[0]) + __uint_as_float(sw[1]);
;           mine += 0.0f;
;           unsigned u = __float_as_uint(mine);
;           u = (u & 0x80000000u) ? ~u : (u | 0x80000000u);
;           if (key > t0 + qi || key < LEAD) u = 0u;
;           sc[i][qi] = u;
;         }
;         if (more) {
; #pragma unroll
;           for (int j = 0; j < 8; ++j) *(u32x4*)(wb + (lrow + 8 * j) * 144 + lpc * 16) = st[j];
.LBB0_711:
	s_or_b64 exec, exec, s[2:3]
	ds_read_b128 v[4:7], v210 offset:16384
	ds_read_b128 v[102:105], v210 offset:16416
	s_waitcnt vmcnt(8)
	ds_read_b128 v[8:11], v210 offset:20992
	ds_read_b128 v[106:109], v210 offset:21024
	ds_read_b128 v[140:143], v210 offset:16448
	ds_read_b128 v[176:179], v210 offset:16480
	ds_read_b128 v[212:215], v210 offset:21056
	ds_read_b128 v[216:219], v210 offset:21088
	s_waitcnt lgkmcnt(7)
	v_mfma_f32_32x32x16_bf16 v[20:35], v[64:67], v[4:7], 0
	s_sub_i32 s2, 0x209d, s23
	s_sub_i32 s10, 0x209e, s23
	s_waitcnt lgkmcnt(5)
	v_mfma_f32_32x32x16_bf16 v[4:19], v[64:67], v[8:11], 0
	v_mfma_f32_32x32x16_bf16 v[20:35], v[60:63], v[102:105], v[20:35]
	v_lshl_or_b32 v104, v114, 6, v101
	v_cmp_gt_i32_e32 vcc, s25, v104
	v_cmp_lt_i32_e64 s[6:7], s24, v104
	v_cmp_lt_i32_e64 s[2:3], s2, v104
	v_cmp_lt_i32_e64 s[14:15], s10, v104
	v_cmp_lt_i32_e64 s[10:11], s22, v104
	s_waitcnt lgkmcnt(4)
	v_mfma_f32_32x32x16_bf16 v[4:19], v[60:63], v[106:109], v[4:19]
	s_waitcnt lgkmcnt(3)
	v_mfma_f32_32x32x16_bf16 v[20:35], v[56:59], v[140:143], v[20:35]
	s_waitcnt lgkmcnt(1)
	v_mfma_f32_32x32x16_bf16 v[4:19], v[56:59], v[212:215], v[4:19]
	v_mfma_f32_32x32x16_bf16 v[20:35], v[52:55], v[176:179], v[20:35]
	s_waitcnt lgkmcnt(0)
	v_mfma_f32_32x32x16_bf16 v[4:19], v[52:55], v[216:219], v[4:19]
	s_nop 9
	v_max_f32_e32 v102, 0, v20
	v_max_f32_e32 v20, 0, v22
	v_max_f32_e32 v103, 0, v4
	v_pk_fma_f32 v[102:103], v[48:49], v[102:103], 0 op_sel_hi:[0,1,0]
	v_max_f32_e32 v4, 0, v21
	v_max_f32_e32 v5, 0, v5
	v_pk_fma_f32 v[4:5], v[48:49], v[4:5], v[102:103] op_sel:[1,0,0]
	v_max_f32_e32 v21, 0, v6
	v_pk_fma_f32 v[4:5], v[50:51], v[20:21], v[4:5] op_sel_hi:[0,1,1]
	v_max_f32_e32 v6, 0, v23
	v_max_f32_e32 v7, 0, v7
	v_mov_b32_e32 v20, v51
	v_pk_fma_f32 v[4:5], v[20:21], v[6:7], v[4:5] op_sel_hi:[0,1,1]
	v_mov_b32_e32 v6, v5
	v_max_f32_e32 v20, 0, v24
	v_max_f32_e32 v21, 0, v8
	v_max_f32_e32 v8, 0, v25
	v_pk_fma_f32 v[20:21], v[44:45], v[20:21], 0 op_sel_hi:[0,1,0]
	v_max_f32_e32 v9, 0, v9
	v_pk_fma_f32 v[8:9], v[44:45], v[8:9], v[20:21] op_sel:[1,0,0]
	v_max_f32_e32 v20, 0, v26
	v_max_f32_e32 v21, 0, v10
	v_max_f32_e32 v10, 0, v27
	v_pk_fma_f32 v[8:9], v[46:47], v[20:21], v[8:9] op_sel_hi:[0,1,1]
	v_max_f32_e32 v11, 0, v11
	v_mov_b32_e32 v20, v47
	v_pk_fma_f32 v[8:9], v[20:21], v[10:11], v[8:9] op_sel_hi:[0,1,1]
	v_mov_b32_e32 v7, v9
	s_nop 1
	v_permlane32_swap_b32_e32 v8, v7
	v_permlane32_swap_b32_e32 v4, v6
	v_mov_b32_e32 v5, v8
	v_pk_add_f32 v[4:5], v[4:5], v[6:7]
	v_max_f32_e32 v6, 0, v28
	v_max_f32_e32 v7, 0, v12
	v_pk_fma_f32 v[6:7], v[40:41], v[6:7], 0 op_sel_hi:[0,1,0]
	v_max_f32_e32 v8, 0, v29
	v_max_f32_e32 v9, 0, v13
	v_pk_fma_f32 v[6:7], v[40:41], v[8:9], v[6:7] op_sel:[1,0,0]
	v_max_f32_e32 v8, 0, v30
	v_max_f32_e32 v9, 0, v14
	v_pk_fma_f32 v[6:7], v[42:43], v[8:9], v[6:7] op_sel_hi:[0,1,1]
	v_max_f32_e32 v8, 0, v31
	v_max_f32_e32 v9, 0, v15
	v_mov_b32_e32 v10, v43
	v_pk_fma_f32 v[6:7], v[10:11], v[8:9], v[6:7] op_sel_hi:[0,1,1]
	v_mov_b32_e32 v8, v7
	v_max_f32_e32 v10, 0, v32
	v_max_f32_e32 v11, 0, v16
	v_max_f32_e32 v12, 0, v33
	v_pk_fma_f32 v[10:11], v[36:37], v[10:11], 0 op_sel_hi:[0,1,0]
	v_max_f32_e32 v13, 0, v17
	v_pk_fma_f32 v[10:11], v[36:37], v[12:13], v[10:11] op_sel:[1,0,0]
	v_max_f32_e32 v12, 0, v34
	v_max_f32_e32 v13, 0, v18
	v_pk_fma_f32 v[10:11], v[38:39], v[12:13], v[10:11] op_sel_hi:[0,1,1]
	v_max_f32_e32 v12, 0, v35
	v_max_f32_e32 v13, 0, v19
	v_mov_b32_e32 v14, v39
	v_pk_fma_f32 v[10:11], v[14:15], v[12:13], v[10:11] op_sel_hi:[0,1,1]
	v_mov_b32_e32 v9, v11
	s_nop 1
	v_permlane32_swap_b32_e32 v10, v9
	v_permlane32_swap_b32_e32 v6, v8
	v_mov_b32_e32 v7, v10
	v_pk_add_f32 v[6:7], v[6:7], v[8:9]
	v_pk_add_f32 v[4:5], v[4:5], 0 op_sel_hi:[1,0]
	v_pk_add_f32 v[6:7], v[6:7], 0 op_sel_hi:[1,0]
	v_cmp_gt_i32_e64 s[4:5], 0, v4
	v_cmp_gt_i32_e64 s[8:9], 0, v5
	v_cmp_gt_i32_e64 s[12:13], 0, v6
	v_cmp_gt_i32_e64 s[16:17], 0, v7
	s_and_saveexec_b64 s[20:21], s[0:1]
	s_cbranch_execz .LBB0_713
	v_mad_u32_u24 v8, v209, s57, v2
	s_waitcnt vmcnt(0)
	ds_write_b128 v8, v[68:71] offset:16384
	ds_write_b128 v8, v[72:75] offset:17536
	ds_write_b128 v8, v[76:79] offset:18688
	ds_write_b128 v8, v[80:83] offset:19840
	ds_write_b128 v8, v[84:87] offset:20992
	ds_write_b128 v8, v[88:91] offset:22144
	ds_write_b128 v8, v[92:95] offset:23296
	ds_write_b128 v8, v[96:99] offset:24448

; #define MFMA32(a, b, c) __builtin_amdgcn_mfma_f32_32x32x16_bf16((a), (b), (c), 0, 0, 0)
; DI void topk_job(const Params& p, int b, int t0, char* lds) {
;     ...
;         bf16x8 b0[4], b1[4];
; #pragma unroll
;         for (int ks = 0; ks < 4; ++ks) {
;           b0[ks] = *(const bf16x8*)(wb + r * 144 + ks * 32 + h * 16);
;           b1[ks] = *(const bf16x8*)(wb + (32 + r) * 144 + ks * 32 + h * 16);
;         }
;         __builtin_amdgcn_sched_barrier(0);
;         f32x16 a0, a1;
; #pragma unroll
;         for (int e = 0; e < 16; ++e) { a0[e] = 0.f; a1[e] = 0.f; }
; #pragma unroll
;         for (int ks = 0; ks < 4; ++ks) { a0 = MFMA32(af[ks], b0[ks], a0); a1 = MFMA32(af[ks], b1[ks], a1); }
;         const int key = c * 64 + lane;
; #pragma unroll
;         for (int qi = 0; qi < 4; ++qi) {
;           f32x2 pp2 = {0.f, 0.f};
; #pragma unroll
;           for (int e = 0; e < 4; ++e) {
;             const f32x2 rl = {fmaxf(a0[4 * qi + e], 0.f), fmaxf(a1[4 * qi + e], 0.f)};
;             const f32x2 wv = {iw[qi][e], iw[qi][e]};
;             pp2 += rl * wv;
;           }
;           const float p0 = pp2[0], p1 = pp2[1];
;           const u32x2 sw = __builtin_amdgcn_permlane32_swap(__float_as_uint(p0), __float_as_uint(p1), false, false);
;           float mine = __uint_as_float(sw[0]) + __uint_as_float(sw[1]);
;           mine += 0.0f;
;           unsigned u = __float_as_uint(mine);
;           u = (u & 0x80000000u) ? ~u : (u | 0x80000000u);
;           if (key > t0 + qi || key < LEAD) u = 0u;
;           sc[i][qi] = u;
;         }
;         if (more) {
; #pragma unroll
;           for (int j = 0; j < 8; ++j) *(u32x4*)(wb + (lrow + 8 * j) * 144 + lpc * 16) = st[j];
.LBB0_717:
	s_or_b64 exec, exec, s[2:3]
	ds_read_b128 v[4:7], v210 offset:16384
	ds_read_b128 v[102:105], v210 offset:16416
	s_waitcnt vmcnt(8)
	ds_read_b128 v[8:11], v210 offset:20992
	ds_read_b128 v[106:109], v210 offset:21024
	ds_read_b128 v[176:179], v210 offset:16448
	ds_read_b128 v[212:215], v210 offset:16480
	ds_read_b128 v[216:219], v210 offset:21056
	ds_read_b128 v[220:223], v210 offset:21088
	s_waitcnt lgkmcnt(7)
	v_mfma_f32_32x32x16_bf16 v[20:35], v[64:67], v[4:7], 0
	s_sub_i32 s2, 0x209d, s23
	s_sub_i32 s10, 0x209e, s23
	s_waitcnt lgkmcnt(5)
	v_mfma_f32_32x32x16_bf16 v[4:19], v[64:67], v[8:11], 0
	v_mfma_f32_32x32x16_bf16 v[20:35], v[60:63], v[102:105], v[20:35]
	v_lshl_or_b32 v104, v112, 6, v101
	v_cmp_gt_i32_e32 vcc, s25, v104
	v_cmp_lt_i32_e64 s[6:7], s24, v104
	v_cmp_lt_i32_e64 s[2:3], s2, v104
	v_cmp_lt_i32_e64 s[14:15], s10, v104
	v_cmp_lt_i32_e64 s[10:11], s22, v104
	s_waitcnt lgkmcnt(4)
	v_mfma_f32_32x32x16_bf16 v[4:19], v[60:63], v[106:109], v[4:19]
	s_waitcnt lgkmcnt(3)
	v_mfma_f32_32x32x16_bf16 v[20:35], v[56:59], v[176:179], v[20:35]
	s_waitcnt lgkmcnt(1)
	v_mfma_f32_32x32x16_bf16 v[4:19], v[56:59], v[216:219], v[4:19]
	v_mfma_f32_32x32x16_bf16 v[20:35], v[52:55], v[212:215], v[20:35]
	s_waitcnt lgkmcnt(0)
	v_mfma_f32_32x32x16_bf16 v[4:19], v[52:55], v[220:223], v[4:19]
	s_nop 9
	v_max_f32_e32 v102, 0, v20
	v_max_f32_e32 v20, 0, v22
	v_max_f32_e32 v103, 0, v4
	v_pk_fma_f32 v[102:103], v[48:49], v[102:103], 0 op_sel_hi:[0,1,0]
	v_max_f32_e32 v4, 0, v21
	v_max_f32_e32 v5, 0, v5
	v_pk_fma_f32 v[4:5], v[48:49], v[4:5], v[102:103] op_sel:[1,0,0]
	v_max_f32_e32 v21, 0, v6
	v_pk_fma_f32 v[4:5], v[50:51], v[20:21], v[4:5] op_sel_hi:[0,1,1]
	v_max_f32_e32 v6, 0, v23
	v_max_f32_e32 v7, 0, v7
	v_mov_b32_e32 v20, v51
	v_pk_fma_f32 v[4:5], v[20:21], v[6:7], v[4:5] op_sel_hi:[0,1,1]
	v_mov_b32_e32 v6, v5
	v_max_f32_e32 v20, 0, v24
	v_max_f32_e32 v21, 0, v8
	v_max_f32_e32 v8, 0, v25
	v_pk_fma_f32 v[20:21], v[44:45], v[20:21], 0 op_sel_hi:[0,1,0]
	v_max_f32_e32 v9, 0, v9
	v_pk_fma_f32 v[8:9], v[44:45], v[8:9], v[20:21] op_sel:[1,0,0]
	v_max_f32_e32 v20, 0, v26
	v_max_f32_e32 v21, 0, v10
	v_max_f32_e32 v10, 0, v27
	v_pk_fma_f32 v[8:9], v[46:47], v[20:21], v[8:9] op_sel_hi:[0,1,1]
	v_max_f32_e32 v11, 0, v11
	v_mov_b32_e32 v20, v47
	v_pk_fma_f32 v[8:9], v[20:21], v[10:11], v[8:9] op_sel_hi:[0,1,1]
	v_mov_b32_e32 v7, v9
	s_nop 1
	v_permlane32_swap_b32_e32 v8, v7
	v_permlane32_swap_b32_e32 v4, v6
	v_mov_b32_e32 v5, v8
	v_pk_add_f32 v[4:5], v[4:5], v[6:7]
	v_max_f32_e32 v6, 0, v28
	v_max_f32_e32 v7, 0, v12
	v_pk_fma_f32 v[6:7], v[40:41], v[6:7], 0 op_sel_hi:[0,1,0]
	v_max_f32_e32 v8, 0, v29
	v_max_f32_e32 v9, 0, v13
	v_pk_fma_f32 v[6:7], v[40:41], v[8:9], v[6:7] op_sel:[1,0,0]
	v_max_f32_e32 v8, 0, v30
	v_max_f32_e32 v9, 0, v14
	v_pk_fma_f32 v[6:7], v[42:43], v[8:9], v[6:7] op_sel_hi:[0,1,1]
	v_max_f32_e32 v8, 0, v31
	v_max_f32_e32 v9, 0, v15
	v_mov_b32_e32 v10, v43
	v_pk_fma_f32 v[6:7], v[10:11], v[8:9], v[6:7] op_sel_hi:[0,1,1]
	v_mov_b32_e32 v8, v7
	v_max_f32_e32 v10, 0, v32
	v_max_f32_e32 v11, 0, v16
	v_max_f32_e32 v12, 0, v33
	v_pk_fma_f32 v[10:11], v[36:37], v[10:11], 0 op_sel_hi:[0,1,0]
	v_max_f32_e32 v13, 0, v17
	v_pk_fma_f32 v[10:11], v[36:37], v[12:13], v[10:11] op_sel:[1,0,0]
	v_max_f32_e32 v12, 0, v34
	v_max_f32_e32 v13, 0, v18
	v_pk_fma_f32 v[10:11], v[38:39], v[12:13], v[10:11] op_sel_hi:[0,1,1]
	v_max_f32_e32 v12, 0, v35
	v_max_f32_e32 v13, 0, v19
	v_mov_b32_e32 v14, v39
	v_pk_fma_f32 v[10:11], v[14:15], v[12:13], v[10:11] op_sel_hi:[0,1,1]
	v_mov_b32_e32 v9, v11
	s_nop 1
	v_permlane32_swap_b32_e32 v10, v9
	v_permlane32_swap_b32_e32 v6, v8
	v_mov_b32_e32 v7, v10
	v_pk_add_f32 v[6:7], v[6:7], v[8:9]
	v_pk_add_f32 v[4:5], v[4:5], 0 op_sel_hi:[1,0]
	v_pk_add_f32 v[6:7], v[6:7], 0 op_sel_hi:[1,0]
	v_cmp_gt_i32_e64 s[4:5], 0, v4
	v_cmp_gt_i32_e64 s[8:9], 0, v5
	v_cmp_gt_i32_e64 s[12:13], 0, v6
	v_cmp_gt_i32_e64 s[16:17], 0, v7
	s_and_saveexec_b64 s[20:21], s[0:1]
	s_cbranch_execz .LBB0_719
	v_mad_u32_u24 v8, v209, s57, v2
	s_waitcnt vmcnt(0)
	ds_write_b128 v8, v[68:71] offset:16384
	ds_write_b128 v8, v[72:75] offset:17536
	ds_write_b128 v8, v[76:79] offset:18688
	ds_write_b128 v8, v[80:83] offset:19840
	ds_write_b128 v8, v[84:87] offset:20992
	ds_write_b128 v8, v[88:91] offset:22144
	ds_write_b128 v8, v[92:95] offset:23296
	ds_write_b128 v8, v[96:99] offset:24448

; #define MFMA32(a, b, c) __builtin_amdgcn_mfma_f32_32x32x16_bf16((a), (b), (c), 0, 0, 0)
; DI void topk_job(const Params& p, int b, int t0, char* lds) {
;     ...
;         bf16x8 b0[4], b1[4];
; #pragma unroll
;         for (int ks = 0; ks < 4; ++ks) {
;           b0[ks] = *(const bf16x8*)(wb + r * 144 + ks * 32 + h * 16);
;           b1[ks] = *(const bf16x8*)(wb + (32 + r) * 144 + ks * 32 + h * 16);
;         }
;         __builtin_amdgcn_sched_barrier(0);
;         f32x16 a0, a1;
; #pragma unroll
;         for (int e = 0; e < 16; ++e) { a0[e] = 0.f; a1[e] = 0.f; }
; #pragma unroll
;         for (int ks = 0; ks < 4; ++ks) { a0 = MFMA32(af[ks], b0[ks], a0); a1 = MFMA32(af[ks], b1[ks], a1); }
;         const int key = c * 64 + lane;
; #pragma unroll
;         for (int qi = 0; qi < 4; ++qi) {
;           f32x2 pp2 = {0.f, 0.f};
; #pragma unroll
;           for (int e = 0; e < 4; ++e) {
;             const f32x2 rl = {fmaxf(a0[4 * qi + e], 0.f), fmaxf(a1[4 * qi + e], 0.f)};
;             const f32x2 wv = {iw[qi][e], iw[qi][e]};
;             pp2 += rl * wv;
;           }
;           const float p0 = pp2[0], p1 = pp2[1];
;           const u32x2 sw = __builtin_amdgcn_permlane32_swap(__float_as_uint(p0), __float_as_uint(p1), false, false);
;           float mine = __uint_as_float(sw[0]) + __uint_as_float(sw[1]);
;           mine += 0.0f;
;           unsigned u = __float_as_uint(mine);
;           u = (u & 0x80000000u) ? ~u : (u | 0x80000000u);
;           if (key > t0 + qi || key < LEAD) u = 0u;
;           sc[i][qi] = u;
;         }
;         if (more) {
; #pragma unroll
;           for (int j = 0; j < 8; ++j) *(u32x4*)(wb + (lrow + 8 * j) * 144 + lpc * 16) = st[j];
.LBB0_723:
	s_or_b64 exec, exec, s[2:3]
	ds_read_b128 v[4:7], v210 offset:16384
	ds_read_b128 v[102:105], v210 offset:16416
	s_waitcnt vmcnt(8)
	ds_read_b128 v[8:11], v210 offset:20992
	ds_read_b128 v[106:109], v210 offset:21024
	ds_read_b128 v[212:215], v210 offset:16448
	ds_read_b128 v[216:219], v210 offset:16480
	ds_read_b128 v[220:223], v210 offset:21056
	ds_read_b128 v[224:227], v210 offset:21088
	s_waitcnt lgkmcnt(7)
	v_mfma_f32_32x32x16_bf16 v[20:35], v[64:67], v[4:7], 0
	s_sub_i32 s2, 0x209d, s23
	s_sub_i32 s10, 0x209e, s23
	s_waitcnt lgkmcnt(5)
	v_mfma_f32_32x32x16_bf16 v[4:19], v[64:67], v[8:11], 0
	v_mfma_f32_32x32x16_bf16 v[20:35], v[60:63], v[102:105], v[20:35]
	v_lshl_or_b32 v104, v116, 6, v101
	v_cmp_gt_i32_e32 vcc, s25, v104
	v_cmp_lt_i32_e64 s[6:7], s24, v104
	v_cmp_lt_i32_e64 s[2:3], s2, v104
	v_cmp_lt_i32_e64 s[14:15], s10, v104
	v_cmp_lt_i32_e64 s[10:11], s22, v104
	s_waitcnt lgkmcnt(4)
	v_mfma_f32_32x32x16_bf16 v[4:19], v[60:63], v[106:109], v[4:19]
	s_waitcnt lgkmcnt(3)
	v_mfma_f32_32x32x16_bf16 v[20:35], v[56:59], v[212:215], v[20:35]
	s_waitcnt lgkmcnt(1)
	v_mfma_f32_32x32x16_bf16 v[4:19], v[56:59], v[220:223], v[4:19]
	v_mfma_f32_32x32x16_bf16 v[20:35], v[52:55], v[216:219], v[20:35]
	s_waitcnt lgkmcnt(0)
	v_mfma_f32_32x32x16_bf16 v[4:19], v[52:55], v[224:227], v[4:19]
	s_nop 9
	v_max_f32_e32 v102, 0, v20
	v_max_f32_e32 v20, 0, v22
	v_max_f32_e32 v103, 0, v4
	v_pk_fma_f32 v[102:103], v[48:49], v[102:103], 0 op_sel_hi:[0,1,0]
	v_max_f32_e32 v4, 0, v21
	v_max_f32_e32 v5, 0, v5
	v_pk_fma_f32 v[4:5], v[48:49], v[4:5], v[102:103] op_sel:[1,0,0]
	v_max_f32_e32 v21, 0, v6
	v_pk_fma_f32 v[4:5], v[50:51], v[20:21], v[4:5] op_sel_hi:[0,1,1]
	v_max_f32_e32 v6, 0, v23
	v_max_f32_e32 v7, 0, v7
	v_mov_b32_e32 v20, v51
	v_pk_fma_f32 v[4:5], v[20:21], v[6:7], v[4:5] op_sel_hi:[0,1,1]
	v_mov_b32_e32 v6, v5
	v_max_f32_e32 v20, 0, v24
	v_max_f32_e32 v21, 0, v8
	v_max_f32_e32 v8, 0, v25
	v_pk_fma_f32 v[20:21], v[44:45], v[20:21], 0 op_sel_hi:[0,1,0]
	v_max_f32_e32 v9, 0, v9
	v_pk_fma_f32 v[8:9], v[44:45], v[8:9], v[20:21] op_sel:[1,0,0]
	v_max_f32_e32 v20, 0, v26
	v_max_f32_e32 v21, 0, v10
	v_max_f32_e32 v10, 0, v27
	v_pk_fma_f32 v[8:9], v[46:47], v[20:21], v[8:9] op_sel_hi:[0,1,1]
	v_max_f32_e32 v11, 0, v11
	v_mov_b32_e32 v20, v47
	v_pk_fma_f32 v[8:9], v[20:21], v[10:11], v[8:9] op_sel_hi:[0,1,1]
	v_mov_b32_e32 v7, v9
	s_nop 1
	v_permlane32_swap_b32_e32 v8, v7
	v_permlane32_swap_b32_e32 v4, v6
	v_mov_b32_e32 v5, v8
	v_pk_add_f32 v[4:5], v[4:5], v[6:7]
	v_max_f32_e32 v6, 0, v28
	v_max_f32_e32 v7, 0, v12
	v_pk_fma_f32 v[6:7], v[40:41], v[6:7], 0 op_sel_hi:[0,1,0]
	v_max_f32_e32 v8, 0, v29
	v_max_f32_e32 v9, 0, v13
	v_pk_fma_f32 v[6:7], v[40:41], v[8:9], v[6:7] op_sel:[1,0,0]
	v_max_f32_e32 v8, 0, v30
	v_max_f32_e32 v9, 0, v14
	v_pk_fma_f32 v[6:7], v[42:43], v[8:9], v[6:7] op_sel_hi:[0,1,1]
	v_max_f32_e32 v8, 0, v31
	v_max_f32_e32 v9, 0, v15
	v_mov_b32_e32 v10, v43
	v_pk_fma_f32 v[6:7], v[10:11], v[8:9], v[6:7] op_sel_hi:[0,1,1]
	v_mov_b32_e32 v8, v7
	v_max_f32_e32 v10, 0, v32
	v_max_f32_e32 v11, 0, v16
	v_max_f32_e32 v12, 0, v33
	v_pk_fma_f32 v[10:11], v[36:37], v[10:11], 0 op_sel_hi:[0,1,0]
	v_max_f32_e32 v13, 0, v17
	v_pk_fma_f32 v[10:11], v[36:37], v[12:13], v[10:11] op_sel:[1,0,0]
	v_max_f32_e32 v12, 0, v34
	v_max_f32_e32 v13, 0, v18
	v_pk_fma_f32 v[10:11], v[38:39], v[12:13], v[10:11] op_sel_hi:[0,1,1]
	v_max_f32_e32 v12, 0, v35
	v_max_f32_e32 v13, 0, v19
	v_mov_b32_e32 v14, v39
	v_pk_fma_f32 v[10:11], v[14:15], v[12:13], v[10:11] op_sel_hi:[0,1,1]
	v_mov_b32_e32 v9, v11
	s_nop 1
	v_permlane32_swap_b32_e32 v10, v9
	v_permlane32_swap_b32_e32 v6, v8
	v_mov_b32_e32 v7, v10
	v_pk_add_f32 v[6:7], v[6:7], v[8:9]
	v_pk_add_f32 v[4:5], v[4:5], 0 op_sel_hi:[1,0]
	v_pk_add_f32 v[6:7], v[6:7], 0 op_sel_hi:[1,0]
	v_cmp_gt_i32_e64 s[4:5], 0, v4
	v_cmp_gt_i32_e64 s[8:9], 0, v5
	v_cmp_gt_i32_e64 s[12:13], 0, v6
	v_cmp_gt_i32_e64 s[16:17], 0, v7
	s_and_saveexec_b64 s[20:21], s[0:1]
	s_cbranch_execz .LBB0_725
	v_mad_u32_u24 v8, v209, s57, v2
	s_waitcnt vmcnt(0)
	ds_write_b128 v8, v[68:71] offset:16384
	ds_write_b128 v8, v[72:75] offset:17536
	ds_write_b128 v8, v[76:79] offset:18688
	ds_write_b128 v8, v[80:83] offset:19840
	ds_write_b128 v8, v[84:87] offset:20992
	ds_write_b128 v8, v[88:91] offset:22144
	ds_write_b128 v8, v[92:95] offset:23296
	ds_write_b128 v8, v[96:99] offset:24448

; #define MFMA32(a, b, c) __builtin_amdgcn_mfma_f32_32x32x16_bf16((a), (b), (c), 0, 0, 0)
; DI void topk_job(const Params& p, int b, int t0, char* lds) {
;     ...
;         bf16x8 b0[4], b1[4];
; #pragma unroll
;         for (int ks = 0; ks < 4; ++ks) {
;           b0[ks] = *(const bf16x8*)(wb + r * 144 + ks * 32 + h * 16);
;           b1[ks] = *(const bf16x8*)(wb + (32 + r) * 144 + ks * 32 + h * 16);
;         }
;         __builtin_amdgcn_sched_barrier(0);
;         f32x16 a0, a1;
; #pragma unroll
;         for (int e = 0; e < 16; ++e) { a0[e] = 0.f; a1[e] = 0.f; }
; #pragma unroll
;         for (int ks = 0; ks < 4; ++ks) { a0 = MFMA32(af[ks], b0[ks], a0); a1 = MFMA32(af[ks], b1[ks], a1); }
;         const int key = c * 64 + lane;
; #pragma unroll
;         for (int qi = 0; qi < 4; ++qi) {
;           f32x2 pp2 = {0.f, 0.f};
; #pragma unroll
;           for (int e = 0; e < 4; ++e) {
;             const f32x2 rl = {fmaxf(a0[4 * qi + e], 0.f), fmaxf(a1[4 * qi + e], 0.f)};
;             const f32x2 wv = {iw[qi][e], iw[qi][e]};
;             pp2 += rl * wv;
;           }
;           const float p0 = pp2[0], p1 = pp2[1];
;           const u32x2 sw = __builtin_amdgcn_permlane32_swap(__float_as_uint(p0), __float_as_uint(p1), false, false);
;           float mine = __uint_as_float(sw[0]) + __uint_as_float(sw[1]);
;           mine += 0.0f;
;           unsigned u = __float_as_uint(mine);
;           u = (u & 0x80000000u) ? ~u : (u | 0x80000000u);
;           if (key > t0 + qi || key < LEAD) u = 0u;
;           sc[i][qi] = u;
;         }
;         if (more) {
; #pragma unroll
;           for (int j = 0; j < 8; ++j) *(u32x4*)(wb + (lrow + 8 * j) * 144 + lpc * 16) = st[j];
.LBB0_729:
	s_or_b64 exec, exec, s[2:3]
	ds_read_b128 v[4:7], v210 offset:16384
	ds_read_b128 v[102:105], v210 offset:16416
	s_waitcnt vmcnt(8)
	ds_read_b128 v[8:11], v210 offset:20992
	ds_read_b128 v[212:215], v210 offset:21024
	ds_read_b128 v[216:219], v210 offset:16448
	ds_read_b128 v[220:223], v210 offset:16480
	ds_read_b128 v[224:227], v210 offset:21056
	ds_read_b128 v[228:231], v210 offset:21088
	s_waitcnt lgkmcnt(7)
	v_mfma_f32_32x32x16_bf16 v[20:35], v[64:67], v[4:7], 0
	s_sub_i32 s2, 0x209d, s23
	s_sub_i32 s10, 0x209e, s23
	s_waitcnt lgkmcnt(5)
	v_mfma_f32_32x32x16_bf16 v[4:19], v[64:67], v[8:11], 0
	v_mfma_f32_32x32x16_bf16 v[20:35], v[60:63], v[102:105], v[20:35]
	v_lshl_or_b32 v104, v110, 6, v101
	v_cmp_gt_i32_e32 vcc, s25, v104
	v_cmp_lt_i32_e64 s[6:7], s24, v104
	v_cmp_lt_i32_e64 s[2:3], s2, v104
	v_cmp_lt_i32_e64 s[14:15], s10, v104
	v_cmp_lt_i32_e64 s[10:11], s22, v104
	s_waitcnt lgkmcnt(4)
	v_mfma_f32_32x32x16_bf16 v[4:19], v[60:63], v[212:215], v[4:19]
	s_waitcnt lgkmcnt(3)
	v_mfma_f32_32x32x16_bf16 v[20:35], v[56:59], v[216:219], v[20:35]
	s_waitcnt lgkmcnt(1)
	v_mfma_f32_32x32x16_bf16 v[4:19], v[56:59], v[224:227], v[4:19]
	v_mfma_f32_32x32x16_bf16 v[20:35], v[52:55], v[220:223], v[20:35]
	s_waitcnt lgkmcnt(0)
	v_mfma_f32_32x32x16_bf16 v[4:19], v[52:55], v[228:231], v[4:19]
	s_nop 9
	v_max_f32_e32 v102, 0, v20
	v_max_f32_e32 v20, 0, v22
	v_max_f32_e32 v103, 0, v4
	v_pk_fma_f32 v[102:103], v[48:49], v[102:103], 0 op_sel_hi:[0,1,0]
	v_max_f32_e32 v4, 0, v21
	v_max_f32_e32 v5, 0, v5
	v_pk_fma_f32 v[4:5], v[48:49], v[4:5], v[102:103] op_sel:[1,0,0]
	v_max_f32_e32 v21, 0, v6
	v_pk_fma_f32 v[4:5], v[50:51], v[20:21], v[4:5] op_sel_hi:[0,1,1]
	v_max_f32_e32 v6, 0, v23
	v_max_f32_e32 v7, 0, v7
	v_mov_b32_e32 v20, v51
	v_pk_fma_f32 v[4:5], v[20:21], v[6:7], v[4:5] op_sel_hi:[0,1,1]
	v_mov_b32_e32 v6, v5
	v_max_f32_e32 v20, 0, v24
	v_max_f32_e32 v21, 0, v8
	v_max_f32_e32 v8, 0, v25
	v_pk_fma_f32 v[20:21], v[44:45], v[20:21], 0 op_sel_hi:[0,1,0]
	v_max_f32_e32 v9, 0, v9
	v_pk_fma_f32 v[8:9], v[44:45], v[8:9], v[20:21] op_sel:[1,0,0]
	v_max_f32_e32 v20, 0, v26
	v_max_f32_e32 v21, 0, v10
	v_max_f32_e32 v10, 0, v27
	v_pk_fma_f32 v[8:9], v[46:47], v[20:21], v[8:9] op_sel_hi:[0,1,1]
	v_max_f32_e32 v11, 0, v11
	v_mov_b32_e32 v20, v47
	v_pk_fma_f32 v[8:9], v[20:21], v[10:11], v[8:9] op_sel_hi:[0,1,1]
	v_mov_b32_e32 v7, v9
	s_nop 1
	v_permlane32_swap_b32_e32 v8, v7
	v_permlane32_swap_b32_e32 v4, v6
	v_mov_b32_e32 v5, v8
	v_pk_add_f32 v[4:5], v[4:5], v[6:7]
	v_max_f32_e32 v6, 0, v28
	v_max_f32_e32 v7, 0, v12
	v_pk_fma_f32 v[6:7], v[40:41], v[6:7], 0 op_sel_hi:[0,1,0]
	v_max_f32_e32 v8, 0, v29
	v_max_f32_e32 v9, 0, v13
	v_pk_fma_f32 v[6:7], v[40:41], v[8:9], v[6:7] op_sel:[1,0,0]
	v_max_f32_e32 v8, 0, v30
	v_max_f32_e32 v9, 0, v14
	v_pk_fma_f32 v[6:7], v[42:43], v[8:9], v[6:7] op_sel_hi:[0,1,1]
	v_max_f32_e32 v8, 0, v31
	v_max_f32_e32 v9, 0, v15
	v_mov_b32_e32 v10, v43
	v_pk_fma_f32 v[6:7], v[10:11], v[8:9], v[6:7] op_sel_hi:[0,1,1]
	v_mov_b32_e32 v8, v7
	v_max_f32_e32 v10, 0, v32
	v_max_f32_e32 v11, 0, v16
	v_max_f32_e32 v12, 0, v33
	v_pk_fma_f32 v[10:11], v[36:37], v[10:11], 0 op_sel_hi:[0,1,0]
	v_max_f32_e32 v13, 0, v17
	v_pk_fma_f32 v[10:11], v[36:37], v[12:13], v[10:11] op_sel:[1,0,0]
	v_max_f32_e32 v12, 0, v34
	v_max_f32_e32 v13, 0, v18
	v_pk_fma_f32 v[10:11], v[38:39], v[12:13], v[10:11] op_sel_hi:[0,1,1]
	v_max_f32_e32 v12, 0, v35
	v_max_f32_e32 v13, 0, v19
	v_mov_b32_e32 v14, v39
	v_pk_fma_f32 v[10:11], v[14:15], v[12:13], v[10:11] op_sel_hi:[0,1,1]
	v_mov_b32_e32 v9, v11
	s_nop 1
	v_permlane32_swap_b32_e32 v10, v9
	v_permlane32_swap_b32_e32 v6, v8
	v_mov_b32_e32 v7, v10
	v_pk_add_f32 v[6:7], v[6:7], v[8:9]
	v_pk_add_f32 v[4:5], v[4:5], 0 op_sel_hi:[1,0]
	v_pk_add_f32 v[6:7], v[6:7], 0 op_sel_hi:[1,0]
	v_cmp_gt_i32_e64 s[4:5], 0, v4
	v_cmp_gt_i32_e64 s[8:9], 0, v5
	v_cmp_gt_i32_e64 s[12:13], 0, v6
	v_cmp_gt_i32_e64 s[16:17], 0, v7
	s_and_saveexec_b64 s[20:21], s[0:1]
	s_cbranch_execz .LBB0_731
	v_mad_u32_u24 v8, v209, s57, v2
	s_waitcnt vmcnt(0)
	ds_write_b128 v8, v[68:71] offset:16384
	ds_write_b128 v8, v[72:75] offset:17536
	ds_write_b128 v8, v[76:79] offset:18688
	ds_write_b128 v8, v[80:83] offset:19840
	ds_write_b128 v8, v[84:87] offset:20992
	ds_write_b128 v8, v[88:91] offset:22144
	ds_write_b128 v8, v[92:95] offset:23296
	ds_write_b128 v8, v[96:99] offset:24448

; #define MFMA32(a, b, c) __builtin_amdgcn_mfma_f32_32x32x16_bf16((a), (b), (c), 0, 0, 0)
; DI void topk_job(const Params& p, int b, int t0, char* lds) {
;     ...
;         bf16x8 b0[4], b1[4];
; #pragma unroll
;         for (int ks = 0; ks < 4; ++ks) {
;           b0[ks] = *(const bf16x8*)(wb + r * 144 + ks * 32 + h * 16);
;           b1[ks] = *(const bf16x8*)(wb + (32 + r) * 144 + ks * 32 + h * 16);
;         }
;         __builtin_amdgcn_sched_barrier(0);
;         f32x16 a0, a1;
; #pragma unroll
;         for (int e = 0; e < 16; ++e) { a0[e] = 0.f; a1[e] = 0.f; }
; #pragma unroll
;         for (int ks = 0; ks < 4; ++ks) { a0 = MFMA32(af[ks], b0[ks], a0); a1 = MFMA32(af[ks], b1[ks], a1); }
;         const int key = c * 64 + lane;
; #pragma unroll
;         for (int qi = 0; qi < 4; ++qi) {
;           f32x2 pp2 = {0.f, 0.f};
; #pragma unroll
;           for (int e = 0; e < 4; ++e) {
;             const f32x2 rl = {fmaxf(a0[4 * qi + e], 0.f), fmaxf(a1[4 * qi + e], 0.f)};
;             const f32x2 wv = {iw[qi][e], iw[qi][e]};
;             pp2 += rl * wv;
;           }
;           const float p0 = pp2[0], p1 = pp2[1];
;           const u32x2 sw = __builtin_amdgcn_permlane32_swap(__float_as_uint(p0), __float_as_uint(p1), false, false);
;           float mine = __uint_as_float(sw[0]) + __uint_as_float(sw[1]);
;           mine += 0.0f;
;           unsigned u = __float_as_uint(mine);
;           u = (u & 0x80000000u) ? ~u : (u | 0x80000000u);
;           if (key > t0 + qi || key < LEAD) u = 0u;
;           sc[i][qi] = u;
;         }
;         if (more) {
; #pragma unroll
;           for (int j = 0; j < 8; ++j) *(u32x4*)(wb + (lrow + 8 * j) * 144 + lpc * 16) = st[j];
.LBB0_735:
	s_or_b64 exec, exec, s[2:3]
	ds_read_b128 v[4:7], v210 offset:16384
	ds_read_b128 v[102:105], v210 offset:16416
	s_waitcnt vmcnt(8)
	ds_read_b128 v[8:11], v210 offset:20992
	ds_read_b128 v[212:215], v210 offset:21024
	ds_read_b128 v[216:219], v210 offset:16448
	ds_read_b128 v[220:223], v210 offset:16480
	ds_read_b128 v[224:227], v210 offset:21056
	ds_read_b128 v[228:231], v210 offset:21088
	s_waitcnt lgkmcnt(7)
	v_mfma_f32_32x32x16_bf16 v[20:35], v[64:67], v[4:7], 0
	s_sub_i32 s2, 0x209d, s23
	s_sub_i32 s10, 0x209e, s23
	s_waitcnt lgkmcnt(5)
	v_mfma_f32_32x32x16_bf16 v[4:19], v[64:67], v[8:11], 0
	v_mfma_f32_32x32x16_bf16 v[20:35], v[60:63], v[102:105], v[20:35]
	v_lshl_or_b32 v104, v108, 6, v101
	v_cmp_gt_i32_e32 vcc, s25, v104
	v_cmp_lt_i32_e64 s[6:7], s24, v104
	v_cmp_lt_i32_e64 s[2:3], s2, v104
	v_cmp_lt_i32_e64 s[14:15], s10, v104
	v_cmp_lt_i32_e64 s[10:11], s22, v104
	s_waitcnt lgkmcnt(4)
	v_mfma_f32_32x32x16_bf16 v[4:19], v[60:63], v[212:215], v[4:19]
	s_waitcnt lgkmcnt(3)
	v_mfma_f32_32x32x16_bf16 v[20:35], v[56:59], v[216:219], v[20:35]
	s_waitcnt lgkmcnt(1)
	v_mfma_f32_32x32x16_bf16 v[4:19], v[56:59], v[224:227], v[4:19]
	v_mfma_f32_32x32x16_bf16 v[20:35], v[52:55], v[220:223], v[20:35]
	s_waitcnt lgkmcnt(0)
	v_mfma_f32_32x32x16_bf16 v[4:19], v[52:55], v[228:231], v[4:19]
	s_nop 9
	v_max_f32_e32 v102, 0, v20
	v_max_f32_e32 v20, 0, v22
	v_max_f32_e32 v103, 0, v4
	v_pk_fma_f32 v[102:103], v[48:49], v[102:103], 0 op_sel_hi:[0,1,0]
	v_max_f32_e32 v4, 0, v21
	v_max_f32_e32 v5, 0, v5
	v_pk_fma_f32 v[4:5], v[48:49], v[4:5], v[102:103] op_sel:[1,0,0]
	v_max_f32_e32 v21, 0, v6
	v_pk_fma_f32 v[4:5], v[50:51], v[20:21], v[4:5] op_sel_hi:[0,1,1]
	v_max_f32_e32 v6, 0, v23
	v_max_f32_e32 v7, 0, v7
	v_mov_b32_e32 v20, v51
	v_pk_fma_f32 v[4:5], v[20:21], v[6:7], v[4:5] op_sel_hi:[0,1,1]
	v_mov_b32_e32 v6, v5
	v_max_f32_e32 v20, 0, v24
	v_max_f32_e32 v21, 0, v8
	v_max_f32_e32 v8, 0, v25
	v_pk_fma_f32 v[20:21], v[44:45], v[20:21], 0 op_sel_hi:[0,1,0]
	v_max_f32_e32 v9, 0, v9
	v_pk_fma_f32 v[8:9], v[44:45], v[8:9], v[20:21] op_sel:[1,0,0]
	v_max_f32_e32 v20, 0, v26
	v_max_f32_e32 v21, 0, v10
	v_max_f32_e32 v10, 0, v27
	v_pk_fma_f32 v[8:9], v[46:47], v[20:21], v[8:9] op_sel_hi:[0,1,1]
	v_max_f32_e32 v11, 0, v11
	v_mov_b32_e32 v20, v47
	v_pk_fma_f32 v[8:9], v[20:21], v[10:11], v[8:9] op_sel_hi:[0,1,1]
	v_mov_b32_e32 v7, v9
	s_nop 1
	v_permlane32_swap_b32_e32 v8, v7
	v_permlane32_swap_b32_e32 v4, v6
	v_mov_b32_e32 v5, v8
	v_pk_add_f32 v[4:5], v[4:5], v[6:7]
	v_max_f32_e32 v6, 0, v28
	v_max_f32_e32 v7, 0, v12
	v_pk_fma_f32 v[6:7], v[40:41], v[6:7], 0 op_sel_hi:[0,1,0]
	v_max_f32_e32 v8, 0, v29
	v_max_f32_e32 v9, 0, v13
	v_pk_fma_f32 v[6:7], v[40:41], v[8:9], v[6:7] op_sel:[1,0,0]
	v_max_f32_e32 v8, 0, v30
	v_max_f32_e32 v9, 0, v14
	v_pk_fma_f32 v[6:7], v[42:43], v[8:9], v[6:7] op_sel_hi:[0,1,1]
	v_max_f32_e32 v8, 0, v31
	v_max_f32_e32 v9, 0, v15
	v_mov_b32_e32 v10, v43
	v_pk_fma_f32 v[6:7], v[10:11], v[8:9], v[6:7] op_sel_hi:[0,1,1]
	v_mov_b32_e32 v8, v7
	v_max_f32_e32 v10, 0, v32
	v_max_f32_e32 v11, 0, v16
	v_max_f32_e32 v12, 0, v33
	v_pk_fma_f32 v[10:11], v[36:37], v[10:11], 0 op_sel_hi:[0,1,0]
	v_max_f32_e32 v13, 0, v17
	v_pk_fma_f32 v[10:11], v[36:37], v[12:13], v[10:11] op_sel:[1,0,0]
	v_max_f32_e32 v12, 0, v34
	v_max_f32_e32 v13, 0, v18
	v_pk_fma_f32 v[10:11], v[38:39], v[12:13], v[10:11] op_sel_hi:[0,1,1]
	v_max_f32_e32 v12, 0, v35
	v_max_f32_e32 v13, 0, v19
	v_mov_b32_e32 v14, v39
	v_pk_fma_f32 v[10:11], v[14:15], v[12:13], v[10:11] op_sel_hi:[0,1,1]
	v_mov_b32_e32 v9, v11
	s_nop 1
	v_permlane32_swap_b32_e32 v10, v9
	v_permlane32_swap_b32_e32 v6, v8
	v_mov_b32_e32 v7, v10
	v_pk_add_f32 v[6:7], v[6:7], v[8:9]
	v_pk_add_f32 v[4:5], v[4:5], 0 op_sel_hi:[1,0]
	v_pk_add_f32 v[6:7], v[6:7], 0 op_sel_hi:[1,0]
	v_cmp_gt_i32_e64 s[4:5], 0, v4
	v_cmp_gt_i32_e64 s[8:9], 0, v5
	v_cmp_gt_i32_e64 s[12:13], 0, v6
	v_cmp_gt_i32_e64 s[16:17], 0, v7
	s_and_saveexec_b64 s[20:21], s[0:1]
	s_cbranch_execz .LBB0_737
	v_mad_u32_u24 v8, v209, s57, v2
	s_waitcnt vmcnt(0)
	ds_write_b128 v8, v[68:71] offset:16384
	ds_write_b128 v8, v[72:75] offset:17536
	ds_write_b128 v8, v[76:79] offset:18688
	ds_write_b128 v8, v[80:83] offset:19840
	ds_write_b128 v8, v[84:87] offset:20992
	ds_write_b128 v8, v[88:91] offset:22144
	ds_write_b128 v8, v[92:95] offset:23296
	ds_write_b128 v8, v[96:99] offset:24448

; #define MFMA32(a, b, c) __builtin_amdgcn_mfma_f32_32x32x16_bf16((a), (b), (c), 0, 0, 0)
; DI void topk_job(const Params& p, int b, int t0, char* lds) {
;     ...
;         bf16x8 b0[4], b1[4];
; #pragma unroll
;         for (int ks = 0; ks < 4; ++ks) {
;           b0[ks] = *(const bf16x8*)(wb + r * 144 + ks * 32 + h * 16);
;           b1[ks] = *(const bf16x8*)(wb + (32 + r) * 144 + ks * 32 + h * 16);
;         }
;         __builtin_amdgcn_sched_barrier(0);
;         f32x16 a0, a1;
; #pragma unroll
;         for (int e = 0; e < 16; ++e) { a0[e] = 0.f; a1[e] = 0.f; }
; #pragma unroll
;         for (int ks = 0; ks < 4; ++ks) { a0 = MFMA32(af[ks], b0[ks], a0); a1 = MFMA32(af[ks], b1[ks], a1); }
;         const int key = c * 64 + lane;
; #pragma unroll
;         for (int qi = 0; qi < 4; ++qi) {
;           f32x2 pp2 = {0.f, 0.f};
; #pragma unroll
;           for (int e = 0; e < 4; ++e) {
;             const f32x2 rl = {fmaxf(a0[4 * qi + e], 0.f), fmaxf(a1[4 * qi + e], 0.f)};
;             const f32x2 wv = {iw[qi][e], iw[qi][e]};
;             pp2 += rl * wv;
;           }
;           const float p0 = pp2[0], p1 = pp2[1];
;           const u32x2 sw = __builtin_amdgcn_permlane32_swap(__float_as_uint(p0), __float_as_uint(p1), false, false);
;           float mine = __uint_as_float(sw[0]) + __uint_as_float(sw[1]);
;           mine += 0.0f;
;           unsigned u = __float_as_uint(mine);
;           u = (u & 0x80000000u) ? ~u : (u | 0x80000000u);
;           if (key > t0 + qi || key < LEAD) u = 0u;
;           sc[i][qi] = u;
;         }
;         if (more) {
; #pragma unroll
;           for (int j = 0; j < 8; ++j) *(u32x4*)(wb + (lrow + 8 * j) * 144 + lpc * 16) = st[j];
.LBB0_741:
	s_or_b64 exec, exec, s[2:3]
	ds_read_b128 v[4:7], v210 offset:16384
	ds_read_b128 v[212:215], v210 offset:16416
	s_waitcnt vmcnt(8)
	ds_read_b128 v[8:11], v210 offset:20992
	ds_read_b128 v[216:219], v210 offset:21024
	ds_read_b128 v[220:223], v210 offset:16448
	ds_read_b128 v[224:227], v210 offset:16480
	ds_read_b128 v[228:231], v210 offset:21056
	ds_read_b128 v[232:235], v210 offset:21088
	s_waitcnt lgkmcnt(7)
	v_mfma_f32_32x32x16_bf16 v[20:35], v[64:67], v[4:7], 0
	v_lshl_or_b32 v105, v106, 6, v101
	s_sub_i32 s2, 0x209d, s23
	s_sub_i32 s10, 0x209e, s23
	v_cmp_gt_i32_e32 vcc, s25, v105
	v_cmp_lt_i32_e64 s[6:7], s24, v105
	v_cmp_lt_i32_e64 s[2:3], s2, v105
	v_cmp_lt_i32_e64 s[14:15], s10, v105
	s_waitcnt lgkmcnt(5)
	v_mfma_f32_32x32x16_bf16 v[4:19], v[64:67], v[8:11], 0
	v_cmp_lt_i32_e64 s[10:11], s22, v105
	v_mfma_f32_32x32x16_bf16 v[20:35], v[60:63], v[212:215], v[20:35]
	s_waitcnt lgkmcnt(4)
	v_mfma_f32_32x32x16_bf16 v[4:19], v[60:63], v[216:219], v[4:19]
	s_waitcnt lgkmcnt(3)
	v_mfma_f32_32x32x16_bf16 v[20:35], v[56:59], v[220:223], v[20:35]
	s_waitcnt lgkmcnt(1)
	v_mfma_f32_32x32x16_bf16 v[4:19], v[56:59], v[228:231], v[4:19]
	v_mfma_f32_32x32x16_bf16 v[20:35], v[52:55], v[224:227], v[20:35]
	s_waitcnt lgkmcnt(0)
	v_mfma_f32_32x32x16_bf16 v[4:19], v[52:55], v[232:235], v[4:19]
	s_nop 9
	v_max_f32_e32 v102, 0, v20
	v_max_f32_e32 v20, 0, v22
	v_max_f32_e32 v103, 0, v4
	v_pk_fma_f32 v[102:103], v[48:49], v[102:103], 0 op_sel_hi:[0,1,0]
	v_max_f32_e32 v4, 0, v21
	v_max_f32_e32 v5, 0, v5
	v_pk_fma_f32 v[4:5], v[48:49], v[4:5], v[102:103] op_sel:[1,0,0]
	v_max_f32_e32 v21, 0, v6
	v_pk_fma_f32 v[4:5], v[50:51], v[20:21], v[4:5] op_sel_hi:[0,1,1]
	v_max_f32_e32 v6, 0, v23
	v_max_f32_e32 v7, 0, v7
	v_mov_b32_e32 v20, v51
	v_pk_fma_f32 v[4:5], v[20:21], v[6:7], v[4:5] op_sel_hi:[0,1,1]
	v_mov_b32_e32 v6, v5
	v_max_f32_e32 v20, 0, v24
	v_max_f32_e32 v21, 0, v8
	v_max_f32_e32 v8, 0, v25
	v_pk_fma_f32 v[20:21], v[44:45], v[20:21], 0 op_sel_hi:[0,1,0]
	v_max_f32_e32 v9, 0, v9
	v_pk_fma_f32 v[8:9], v[44:45], v[8:9], v[20:21] op_sel:[1,0,0]
	v_max_f32_e32 v20, 0, v26
	v_max_f32_e32 v21, 0, v10
	v_max_f32_e32 v10, 0, v27
	v_pk_fma_f32 v[8:9], v[46:47], v[20:21], v[8:9] op_sel_hi:[0,1,1]
	v_max_f32_e32 v11, 0, v11
	v_mov_b32_e32 v20, v47
	v_pk_fma_f32 v[8:9], v[20:21], v[10:11], v[8:9] op_sel_hi:[0,1,1]
	v_mov_b32_e32 v7, v9
	s_nop 1
	v_permlane32_swap_b32_e32 v8, v7
	v_permlane32_swap_b32_e32 v4, v6
	v_mov_b32_e32 v5, v8
	v_pk_add_f32 v[4:5], v[4:5], v[6:7]
	v_max_f32_e32 v6, 0, v28
	v_max_f32_e32 v7, 0, v12
	v_pk_fma_f32 v[6:7], v[40:41], v[6:7], 0 op_sel_hi:[0,1,0]
	v_max_f32_e32 v8, 0, v29
	v_max_f32_e32 v9, 0, v13
	v_pk_fma_f32 v[6:7], v[40:41], v[8:9], v[6:7] op_sel:[1,0,0]
	v_max_f32_e32 v8, 0, v30
	v_max_f32_e32 v9, 0, v14
	v_pk_fma_f32 v[6:7], v[42:43], v[8:9], v[6:7] op_sel_hi:[0,1,1]
	v_max_f32_e32 v8, 0, v31
	v_max_f32_e32 v9, 0, v15
	v_mov_b32_e32 v10, v43
	v_pk_fma_f32 v[6:7], v[10:11], v[8:9], v[6:7] op_sel_hi:[0,1,1]
	v_mov_b32_e32 v8, v7
	v_max_f32_e32 v10, 0, v32
	v_max_f32_e32 v11, 0, v16
	v_max_f32_e32 v12, 0, v33
	v_pk_fma_f32 v[10:11], v[36:37], v[10:11], 0 op_sel_hi:[0,1,0]
	v_max_f32_e32 v13, 0, v17
	v_pk_fma_f32 v[10:11], v[36:37], v[12:13], v[10:11] op_sel:[1,0,0]
	v_max_f32_e32 v12, 0, v34
	v_max_f32_e32 v13, 0, v18
	v_pk_fma_f32 v[10:11], v[38:39], v[12:13], v[10:11] op_sel_hi:[0,1,1]
	v_max_f32_e32 v12, 0, v35
	v_max_f32_e32 v13, 0, v19
	v_mov_b32_e32 v14, v39
	v_pk_fma_f32 v[10:11], v[14:15], v[12:13], v[10:11] op_sel_hi:[0,1,1]
	v_mov_b32_e32 v9, v11
	s_nop 1
	v_permlane32_swap_b32_e32 v10, v9
	v_permlane32_swap_b32_e32 v6, v8
	v_mov_b32_e32 v7, v10
	v_pk_add_f32 v[6:7], v[6:7], v[8:9]
	v_pk_add_f32 v[4:5], v[4:5], 0 op_sel_hi:[1,0]
	v_pk_add_f32 v[6:7], v[6:7], 0 op_sel_hi:[1,0]
	v_cmp_gt_i32_e64 s[4:5], 0, v4
	v_cmp_gt_i32_e64 s[8:9], 0, v5
	v_cmp_gt_i32_e64 s[12:13], 0, v6
	v_cmp_gt_i32_e64 s[16:17], 0, v7
	s_and_saveexec_b64 s[20:21], s[0:1]
	s_cbranch_execz .LBB0_743
	v_mad_u32_u24 v8, v209, s57, v2
	s_waitcnt vmcnt(0)
	ds_write_b128 v8, v[68:71] offset:16384
	ds_write_b128 v8, v[72:75] offset:17536
	ds_write_b128 v8, v[76:79] offset:18688
	ds_write_b128 v8, v[80:83] offset:19840
	ds_write_b128 v8, v[84:87] offset:20992
	ds_write_b128 v8, v[88:91] offset:22144
	ds_write_b128 v8, v[92:95] offset:23296
	ds_write_b128 v8, v[96:99] offset:24448

; #define MFMA32(a, b, c) __builtin_amdgcn_mfma_f32_32x32x16_bf16((a), (b), (c), 0, 0, 0)
; DI void topk_job(const Params& p, int b, int t0, char* lds) {
;     ...
;         bf16x8 b0[4], b1[4];
; #pragma unroll
;         for (int ks = 0; ks < 4; ++ks) {
;           b0[ks] = *(const bf16x8*)(wb + r * 144 + ks * 32 + h * 16);
;           b1[ks] = *(const bf16x8*)(wb + (32 + r) * 144 + ks * 32 + h * 16);
;         }
;         __builtin_amdgcn_sched_barrier(0);
;         f32x16 a0, a1;
; #pragma unroll
;         for (int e = 0; e < 16; ++e) { a0[e] = 0.f; a1[e] = 0.f; }
; #pragma unroll
;         for (int ks = 0; ks < 4; ++ks) { a0 = MFMA32(af[ks], b0[ks], a0); a1 = MFMA32(af[ks], b1[ks], a1); }
;         const int key = c * 64 + lane;
; #pragma unroll
;         for (int qi = 0; qi < 4; ++qi) {
;           f32x2 pp2 = {0.f, 0.f};
; #pragma unroll
;           for (int e = 0; e < 4; ++e) {
;             const f32x2 rl = {fmaxf(a0[4 * qi + e], 0.f), fmaxf(a1[4 * qi + e], 0.f)};
;             const f32x2 wv = {iw[qi][e], iw[qi][e]};
;             pp2 += rl * wv;
;           }
;           const float p0 = pp2[0], p1 = pp2[1];
;           const u32x2 sw = __builtin_amdgcn_permlane32_swap(__float_as_uint(p0), __float_as_uint(p1), false, false);
;           float mine = __uint_as_float(sw[0]) + __uint_as_float(sw[1]);
;           mine += 0.0f;
;           unsigned u = __float_as_uint(mine);
;           u = (u & 0x80000000u) ? ~u : (u | 0x80000000u);
;           if (key > t0 + qi || key < LEAD) u = 0u;
;           sc[i][qi] = u;
;         }
;         if (more) {
; #pragma unroll
;           for (int j = 0; j < 8; ++j) *(u32x4*)(wb + (lrow + 8 * j) * 144 + lpc * 16) = st[j];
.LBB0_747:
	s_or_b64 exec, exec, s[2:3]
	ds_read_b128 v[4:7], v210 offset:16384
	ds_read_b128 v[212:215], v210 offset:16416
	s_waitcnt vmcnt(8)
	ds_read_b128 v[8:11], v210 offset:20992
	ds_read_b128 v[216:219], v210 offset:21024
	ds_read_b128 v[220:223], v210 offset:16448
	ds_read_b128 v[224:227], v210 offset:16480
	ds_read_b128 v[228:231], v210 offset:21056
	ds_read_b128 v[232:235], v210 offset:21088
	s_waitcnt lgkmcnt(7)
	v_mfma_f32_32x32x16_bf16 v[20:35], v[64:67], v[4:7], 0
	v_lshl_or_b32 v103, v104, 6, v101
	s_sub_i32 s2, 0x209d, s23
	s_sub_i32 s10, 0x209e, s23
	v_cmp_gt_i32_e32 vcc, s25, v103
	v_cmp_lt_i32_e64 s[6:7], s24, v103
	v_cmp_lt_i32_e64 s[2:3], s2, v103
	v_cmp_lt_i32_e64 s[14:15], s10, v103
	s_waitcnt lgkmcnt(5)
	v_mfma_f32_32x32x16_bf16 v[4:19], v[64:67], v[8:11], 0
	v_cmp_lt_i32_e64 s[10:11], s22, v103
	v_mfma_f32_32x32x16_bf16 v[20:35], v[60:63], v[212:215], v[20:35]
	s_waitcnt lgkmcnt(4)
	v_mfma_f32_32x32x16_bf16 v[4:19], v[60:63], v[216:219], v[4:19]
	s_waitcnt lgkmcnt(3)
	v_mfma_f32_32x32x16_bf16 v[20:35], v[56:59], v[220:223], v[20:35]
	s_waitcnt lgkmcnt(1)
	v_mfma_f32_32x32x16_bf16 v[4:19], v[56:59], v[228:231], v[4:19]
	v_mfma_f32_32x32x16_bf16 v[20:35], v[52:55], v[224:227], v[20:35]
	s_waitcnt lgkmcnt(0)
	v_mfma_f32_32x32x16_bf16 v[4:19], v[52:55], v[232:235], v[4:19]
	s_nop 9
	v_max_f32_e32 v212, 0, v20
	v_max_f32_e32 v20, 0, v22
	v_max_f32_e32 v213, 0, v4
	v_pk_fma_f32 v[212:213], v[48:49], v[212:213], 0 op_sel_hi:[0,1,0]
	v_max_f32_e32 v4, 0, v21
	v_max_f32_e32 v5, 0, v5
	v_pk_fma_f32 v[4:5], v[48:49], v[4:5], v[212:213] op_sel:[1,0,0]
	v_max_f32_e32 v21, 0, v6
	v_pk_fma_f32 v[4:5], v[50:51], v[20:21], v[4:5] op_sel_hi:[0,1,1]
	v_max_f32_e32 v6, 0, v23
	v_max_f32_e32 v7, 0, v7
	v_mov_b32_e32 v20, v51
	v_pk_fma_f32 v[4:5], v[20:21], v[6:7], v[4:5] op_sel_hi:[0,1,1]
	v_mov_b32_e32 v6, v5
	v_max_f32_e32 v20, 0, v24
	v_max_f32_e32 v21, 0, v8
	v_max_f32_e32 v8, 0, v25
	v_pk_fma_f32 v[20:21], v[44:45], v[20:21], 0 op_sel_hi:[0,1,0]
	v_max_f32_e32 v9, 0, v9
	v_pk_fma_f32 v[8:9], v[44:45], v[8:9], v[20:21] op_sel:[1,0,0]
	v_max_f32_e32 v20, 0, v26
	v_max_f32_e32 v21, 0, v10
	v_max_f32_e32 v10, 0, v27
	v_pk_fma_f32 v[8:9], v[46:47], v[20:21], v[8:9] op_sel_hi:[0,1,1]
	v_max_f32_e32 v11, 0, v11
	v_mov_b32_e32 v20, v47
	v_pk_fma_f32 v[8:9], v[20:21], v[10:11], v[8:9] op_sel_hi:[0,1,1]
	v_mov_b32_e32 v7, v9
	s_nop 1
	v_permlane32_swap_b32_e32 v8, v7
	v_permlane32_swap_b32_e32 v4, v6
	v_mov_b32_e32 v5, v8
	v_pk_add_f32 v[4:5], v[4:5], v[6:7]
	v_max_f32_e32 v6, 0, v28
	v_max_f32_e32 v7, 0, v12
	v_pk_fma_f32 v[6:7], v[40:41], v[6:7], 0 op_sel_hi:[0,1,0]
	v_max_f32_e32 v8, 0, v29
	v_max_f32_e32 v9, 0, v13
	v_pk_fma_f32 v[6:7], v[40:41], v[8:9], v[6:7] op_sel:[1,0,0]
	v_max_f32_e32 v8, 0, v30
	v_max_f32_e32 v9, 0, v14
	v_pk_fma_f32 v[6:7], v[42:43], v[8:9], v[6:7] op_sel_hi:[0,1,1]
	v_max_f32_e32 v8, 0, v31
	v_max_f32_e32 v9, 0, v15
	v_mov_b32_e32 v10, v43
	v_pk_fma_f32 v[6:7], v[10:11], v[8:9], v[6:7] op_sel_hi:[0,1,1]
	v_mov_b32_e32 v8, v7
	v_max_f32_e32 v10, 0, v32
	v_max_f32_e32 v11, 0, v16
	v_max_f32_e32 v12, 0, v33
	v_pk_fma_f32 v[10:11], v[36:37], v[10:11], 0 op_sel_hi:[0,1,0]
	v_max_f32_e32 v13, 0, v17
	v_pk_fma_f32 v[10:11], v[36:37], v[12:13], v[10:11] op_sel:[1,0,0]
	v_max_f32_e32 v12, 0, v34
	v_max_f32_e32 v13, 0, v18
	v_pk_fma_f32 v[10:11], v[38:39], v[12:13], v[10:11] op_sel_hi:[0,1,1]
	v_max_f32_e32 v12, 0, v35
	v_max_f32_e32 v13, 0, v19
	v_mov_b32_e32 v14, v39
	v_pk_fma_f32 v[10:11], v[14:15], v[12:13], v[10:11] op_sel_hi:[0,1,1]
	v_mov_b32_e32 v9, v11
	s_nop 1
	v_permlane32_swap_b32_e32 v10, v9
	v_permlane32_swap_b32_e32 v6, v8
	v_mov_b32_e32 v7, v10
	v_pk_add_f32 v[6:7], v[6:7], v[8:9]
	v_pk_add_f32 v[4:5], v[4:5], 0 op_sel_hi:[1,0]
	v_pk_add_f32 v[6:7], v[6:7], 0 op_sel_hi:[1,0]
	v_cmp_gt_i32_e64 s[4:5], 0, v4
	v_cmp_gt_i32_e64 s[8:9], 0, v5
	v_cmp_gt_i32_e64 s[12:13], 0, v6
	v_cmp_gt_i32_e64 s[16:17], 0, v7
	s_and_saveexec_b64 s[20:21], s[0:1]
	s_cbranch_execz .LBB0_749
	v_mad_u32_u24 v8, v209, s57, v2
	s_waitcnt vmcnt(0)
	ds_write_b128 v8, v[68:71] offset:16384
	ds_write_b128 v8, v[72:75] offset:17536
	ds_write_b128 v8, v[76:79] offset:18688
	ds_write_b128 v8, v[80:83] offset:19840
	ds_write_b128 v8, v[84:87] offset:20992
	ds_write_b128 v8, v[88:91] offset:22144
	ds_write_b128 v8, v[92:95] offset:23296
	ds_write_b128 v8, v[96:99] offset:24448

; #define MFMA32(a, b, c) __builtin_amdgcn_mfma_f32_32x32x16_bf16((a), (b), (c), 0, 0, 0)
; DI void topk_job(const Params& p, int b, int t0, char* lds) {
;     ...
;         bf16x8 b0[4], b1[4];
; #pragma unroll
;         for (int ks = 0; ks < 4; ++ks) {
;           b0[ks] = *(const bf16x8*)(wb + r * 144 + ks * 32 + h * 16);
;           b1[ks] = *(const bf16x8*)(wb + (32 + r) * 144 + ks * 32 + h * 16);
;         }
;         __builtin_amdgcn_sched_barrier(0);
;         f32x16 a0, a1;
; #pragma unroll
;         for (int e = 0; e < 16; ++e) { a0[e] = 0.f; a1[e] = 0.f; }
; #pragma unroll
;         for (int ks = 0; ks < 4; ++ks) { a0 = MFMA32(af[ks], b0[ks], a0); a1 = MFMA32(af[ks], b1[ks], a1); }
;         const int key = c * 64 + lane;
; #pragma unroll
;         for (int qi = 0; qi < 4; ++qi) {
;           f32x2 pp2 = {0.f, 0.f};
; #pragma unroll
;           for (int e = 0; e < 4; ++e) {
;             const f32x2 rl = {fmaxf(a0[4 * qi + e], 0.f), fmaxf(a1[4 * qi + e], 0.f)};
;             const f32x2 wv = {iw[qi][e], iw[qi][e]};
;             pp2 += rl * wv;
;           }
;           const float p0 = pp2[0], p1 = pp2[1];
;           const u32x2 sw = __builtin_amdgcn_permlane32_swap(__float_as_uint(p0), __float_as_uint(p1), false, false);
;           float mine = __uint_as_float(sw[0]) + __uint_as_float(sw[1]);
;           mine += 0.0f;
;           unsigned u = __float_as_uint(mine);
;           u = (u & 0x80000000u) ? ~u : (u | 0x80000000u);
;           if (key > t0 + qi || key < LEAD) u = 0u;
;           sc[i][qi] = u;
;         }
;         if (more) {
; #pragma unroll
;           for (int j = 0; j < 8; ++j) *(u32x4*)(wb + (lrow + 8 * j) * 144 + lpc * 16) = st[j];
.LBB0_753:
	s_or_b64 exec, exec, s[2:3]
	ds_read_b128 v[4:7], v210 offset:16384
	ds_read_b128 v[212:215], v210 offset:16416
	ds_read_b128 v[8:11], v210 offset:20992
	ds_read_b128 v[216:219], v210 offset:21024
	ds_read_b128 v[220:223], v210 offset:16448
	ds_read_b128 v[224:227], v210 offset:16480
	ds_read_b128 v[228:231], v210 offset:21056
	ds_read_b128 v[232:235], v210 offset:21088
	s_waitcnt lgkmcnt(7)
	v_mfma_f32_32x32x16_bf16 v[20:35], v[64:67], v[4:7], 0
	s_sub_i32 s2, 0x209d, s23
	s_sub_i32 s10, 0x209e, s23
	s_waitcnt lgkmcnt(5)
	v_mfma_f32_32x32x16_bf16 v[4:19], v[64:67], v[8:11], 0
	v_mfma_f32_32x32x16_bf16 v[20:35], v[60:63], v[212:215], v[20:35]
	s_waitcnt lgkmcnt(4)
	v_mfma_f32_32x32x16_bf16 v[4:19], v[60:63], v[216:219], v[4:19]
	s_waitcnt lgkmcnt(3)
	v_mfma_f32_32x32x16_bf16 v[20:35], v[56:59], v[220:223], v[20:35]
	s_waitcnt lgkmcnt(1)
	v_mfma_f32_32x32x16_bf16 v[4:19], v[56:59], v[228:231], v[4:19]
	v_lshl_or_b32 v56, v102, 6, v101
	v_cmp_gt_i32_e32 vcc, s25, v56
	v_cmp_lt_i32_e64 s[6:7], s24, v56
	v_cmp_lt_i32_e64 s[2:3], s2, v56
	v_cmp_lt_i32_e64 s[14:15], s10, v56
	v_cmp_lt_i32_e64 s[10:11], s22, v56
	v_mfma_f32_32x32x16_bf16 v[20:35], v[52:55], v[224:227], v[20:35]
	s_waitcnt lgkmcnt(0)
	v_mfma_f32_32x32x16_bf16 v[4:19], v[52:55], v[232:235], v[4:19]
	s_nop 9
	v_max_f32_e32 v0, 0, v20
	s_nop 0
	v_max_f32_e32 v1, 0, v4
	v_pk_fma_f32 v[0:1], v[48:49], v[0:1], 0 op_sel_hi:[0,1,0]
	v_max_f32_e32 v4, 0, v21
	v_max_f32_e32 v5, 0, v5
	v_pk_fma_f32 v[0:1], v[48:49], v[4:5], v[0:1] op_sel:[1,0,0]
	v_max_f32_e32 v4, 0, v22
	v_max_f32_e32 v5, 0, v6
	v_pk_fma_f32 v[0:1], v[50:51], v[4:5], v[0:1] op_sel_hi:[0,1,1]
	v_max_f32_e32 v4, 0, v23
	v_max_f32_e32 v5, 0, v7
	v_mov_b32_e32 v6, v51
	v_pk_fma_f32 v[0:1], v[6:7], v[4:5], v[0:1] op_sel_hi:[0,1,1]
	v_mov_b32_e32 v4, v1
	v_max_f32_e32 v6, 0, v24
	v_max_f32_e32 v7, 0, v8
	v_max_f32_e32 v8, 0, v25
	v_pk_fma_f32 v[6:7], v[44:45], v[6:7], 0 op_sel_hi:[0,1,0]
	v_max_f32_e32 v9, 0, v9
	v_pk_fma_f32 v[6:7], v[44:45], v[8:9], v[6:7] op_sel:[1,0,0]
	v_max_f32_e32 v8, 0, v26
	v_max_f32_e32 v9, 0, v10
	v_pk_fma_f32 v[6:7], v[46:47], v[8:9], v[6:7] op_sel_hi:[0,1,1]
	v_max_f32_e32 v8, 0, v27
	v_max_f32_e32 v9, 0, v11
	v_mov_b32_e32 v10, v47
	v_pk_fma_f32 v[6:7], v[10:11], v[8:9], v[6:7] op_sel_hi:[0,1,1]
	v_mov_b32_e32 v5, v7
	s_nop 1
	v_permlane32_swap_b32_e32 v6, v5
	v_permlane32_swap_b32_e32 v0, v4
	v_mov_b32_e32 v1, v6
	v_pk_add_f32 v[0:1], v[0:1], v[4:5]
	v_max_f32_e32 v4, 0, v28
	v_max_f32_e32 v5, 0, v12
	v_pk_fma_f32 v[4:5], v[40:41], v[4:5], 0 op_sel_hi:[0,1,0]
	v_max_f32_e32 v6, 0, v29
	v_max_f32_e32 v7, 0, v13
	v_pk_fma_f32 v[4:5], v[40:41], v[6:7], v[4:5] op_sel:[1,0,0]
	v_max_f32_e32 v6, 0, v30
	v_max_f32_e32 v7, 0, v14
	v_pk_fma_f32 v[4:5], v[42:43], v[6:7], v[4:5] op_sel_hi:[0,1,1]
	v_max_f32_e32 v6, 0, v31
	v_max_f32_e32 v7, 0, v15
	v_mov_b32_e32 v8, v43
	v_pk_fma_f32 v[4:5], v[8:9], v[6:7], v[4:5] op_sel_hi:[0,1,1]
	v_mov_b32_e32 v6, v5
	v_max_f32_e32 v8, 0, v32
	v_max_f32_e32 v9, 0, v16
	v_max_f32_e32 v10, 0, v33
	v_pk_fma_f32 v[8:9], v[36:37], v[8:9], 0 op_sel_hi:[0,1,0]
	v_max_f32_e32 v11, 0, v17
	v_pk_fma_f32 v[8:9], v[36:37], v[10:11], v[8:9] op_sel:[1,0,0]
	v_max_f32_e32 v10, 0, v34
	v_max_f32_e32 v11, 0, v18
	v_pk_fma_f32 v[8:9], v[38:39], v[10:11], v[8:9] op_sel_hi:[0,1,1]
	v_max_f32_e32 v10, 0, v35
	v_max_f32_e32 v11, 0, v19
	v_mov_b32_e32 v12, v39
	v_pk_fma_f32 v[8:9], v[12:13], v[10:11], v[8:9] op_sel_hi:[0,1,1]
	v_mov_b32_e32 v7, v9
	s_nop 1
	v_permlane32_swap_b32_e32 v8, v7
	v_permlane32_swap_b32_e32 v4, v6
	v_mov_b32_e32 v5, v8
	v_pk_add_f32 v[4:5], v[4:5], v[6:7]
	v_pk_add_f32 v[0:1], v[0:1], 0 op_sel_hi:[1,0]
	v_pk_add_f32 v[4:5], v[4:5], 0 op_sel_hi:[1,0]
	v_cmp_gt_i32_e64 s[4:5], 0, v0
	v_cmp_gt_i32_e64 s[8:9], 0, v1
	v_cmp_gt_i32_e64 s[12:13], 0, v4
	v_cmp_gt_i32_e64 s[16:17], 0, v5
	s_and_saveexec_b64 s[20:21], s[0:1]
	s_cbranch_execz .LBB0_755
	v_mad_u32_u24 v2, v209, s57, v2
	ds_write_b128 v2, v[68:71] offset:16384
	ds_write_b128 v2, v[72:75] offset:17536
	ds_write_b128 v2, v[76:79] offset:18688
	ds_write_b128 v2, v[80:83] offset:19840
	ds_write_b128 v2, v[84:87] offset:20992
	ds_write_b128 v2, v[88:91] offset:22144
	ds_write_b128 v2, v[92:95] offset:23296
	ds_write_b128 v2, v[96:99] offset:24448

; DI void topk_job(const Params& p, int b, int t0, char* lds) {
;     ...
;   int* ng = (int*)(lds + 256);
;   unsigned long long* mg = (unsigned long long*)(lds + 1024);
;   unsigned long long* me = mg + 4 * 132;
;   int* bg = (int*)(me + 4 * 132);
;   int* be = bg + 4 * 132;
;   unsigned T[4];
;   {
;     unsigned* hist = (unsigned*)(lds + 16384);
;     int* sel = (int*)(lds + 512);
;     unsigned pref[4] = {0u, 0u, 0u, 0u};
;     int chi[4] = {0, 0, 0, 0};
;     bool few[4] = {false, false, false, false};
;     __syncthreads();
;     bool small = false;
;     int nb[4] = {0, 0, 0, 0};
; #pragma unroll
;     for (int pass = 0; pass < 3; ++pass) {
;       if (pass == 2) {
;         small = true;
; #pragma unroll
;         for (int q = 0; q < 4; ++q) small = small && (few[q] || nb[q] <= 64);
;         if (small) break;
;       }
;       {
;         const u32x4 z = {0u, 0u, 0u, 0u};
; #pragma unroll
;         for (int j = 0; j < 8; ++j) ((u32x4*)hist)[tid + 512 * j] = z;
;       }
;       __syncthreads();
; #pragma unroll
;       for (int i = 0; i < 17; ++i) {
; #pragma unroll
;         for (int q = 0; q < 4; ++q) {
;           const unsigned u = sc[i][q];
;           bool part; unsigned bin;
;           if (pass == 0) { part = (u != 0u); bin = (u >> 22) + (lane & 3) * 1024; }
;           else if (pass == 1) { part = (u != 0u) && ((u >> 22) == pref[q]) && !few[q]; bin = ((u >> 12) & 1023u) + (lane & 3) * 1024; }
;           else { part = (u != 0u) && ((u >> 12) == pref[q]) && !few[q]; bin = u & 4095u; }
;           if (part) atomicAdd(hist + q * 4096 + bin, 1u);
;         }
;       }
.LBB0_756:
	v_writelane_b32 v237, s46, 9
	s_nop 1
	v_writelane_b32 v237, s47, 10
	v_writelane_b32 v237, s44, 11
	s_nop 1
	v_writelane_b32 v237, s45, 12
	v_writelane_b32 v237, s42, 13
	s_nop 1
	v_writelane_b32 v237, s43, 14
	v_writelane_b32 v237, s40, 15
	s_nop 1
	v_writelane_b32 v237, s41, 16
	v_writelane_b32 v237, s36, 17
	s_nop 1
	v_writelane_b32 v237, s37, 18
	v_writelane_b32 v237, s34, 19
	s_nop 1
	v_writelane_b32 v237, s35, 20
	v_writelane_b32 v237, s30, 21
	s_nop 1
	v_writelane_b32 v237, s31, 22
	v_writelane_b32 v237, s28, 23
	s_nop 1
	v_writelane_b32 v237, s29, 24
	s_or_b64 exec, exec, s[18:19]
	s_waitcnt vmcnt(0) lgkmcnt(0)
	v_lshrrev_b32_e32 v0, 6, v100
	s_mov_b32 s3, s90
	v_readfirstlane_b32 s2, v0
	s_lshl_b32 s4, s87, 1
	s_and_b32 s4, s4, 0x3ffc
	s_sub_i32 s4, 0x209c, s4
	s_bitcmp1_b32 s87, 0
	s_cselect_b32 s5, 0x2100, 0
	s_add_i32 s4, s4, s5
	v_readlane_b32 s6, v240, 13
	v_readlane_b32 s7, v240, 14
	s_lshl_b32 s5, s4, 9
	s_add_u32 s40, s6, s5
	s_addc_u32 s41, s7, 0
	s_add_u32 s42, s40, 0x200
	s_addc_u32 s43, s41, 0
	s_add_u32 s44, s42, 0x200
	s_addc_u32 s45, s43, 0
	s_add_u32 s46, s44, 0x200
	s_addc_u32 s47, s45, 0
	s_mov_b32 s16, 0x55555555
	s_mov_b32 s17, 0x55555555
	s_mov_b32 s18, 0x33333333
	s_mov_b32 s19, 0x33333333
	s_mov_b32 s20, 0xf0f0f0f
	s_mov_b32 s21, 0xf0f0f0f
	s_mov_b32 s22, 0xff00ff
	s_mov_b32 s23, 0xff00ff
	s_mov_b32 s24, 0xffff
	s_mov_b32 s25, 0xffff
	s_mov_b32 s26, 0xffffffff
	s_mov_b32 s27, 0
	v_mov_b32_e32 v20, 1
	v_and_b32_e32 v0, 3, v101
	v_lshlrev_b32_e32 v0, 12, v0
	v_add_u32_e32 v21, 0x4000, v0
	v_add_u32_e32 v25, 0x14000, v0
	v_mov_b32_e32 v29, 0x4000
	v_add_u32_e32 v22, 0x8000, v0
	v_add_u32_e32 v26, 0x18000, v0
	v_mov_b32_e32 v30, 0x8000
	v_add_u32_e32 v23, 0xc000, v0
	v_add_u32_e32 v27, 0x1c000, v0
	v_mov_b32_e32 v31, 0xc000
	v_add_u32_e32 v24, 0x10000, v0
	v_add_u32_e32 v28, 0x20000, v0
	v_mov_b32_e32 v32, 0x10000
	s_movk_i32 s85, 0x100
	s_mov_b32 s56, 0
	s_mov_b32 s58, 0
	v_lshlrev_b32_e32 v75, 2, v100
	v_add_u32_e32 v75, 0x2800, v75
	v_lshlrev_b32_e32 v76, 1, v100
	v_add_u32_e32 v76, 0x800, v76
	s_barrier
	v_mov_b32_e32 v4, 0
	v_mov_b32_e32 v5, 0
	v_mov_b32_e32 v6, 0
	v_mov_b32_e32 v7, 0
	v_lshlrev_b32_e32 v0, 4, v100
	v_add_u32_e32 v0, 0x4000, v0
	v_add_u32_e32 v1, 0x10000, v0
	ds_write_b128 v0, v[4:7]
	ds_write_b128 v0, v[4:7] offset:8192
	ds_write_b128 v0, v[4:7] offset:16384
	ds_write_b128 v0, v[4:7] offset:24576
	ds_write_b128 v0, v[4:7] offset:32768
	ds_write_b128 v0, v[4:7] offset:40960
	ds_write_b128 v0, v[4:7] offset:49152
	ds_write_b128 v0, v[4:7] offset:57344
	ds_write_b128 v1, v[4:7]
	ds_write_b128 v1, v[4:7] offset:8192
	ds_write_b128 v1, v[4:7] offset:16384
	ds_write_b128 v1, v[4:7] offset:24576
	ds_write_b128 v1, v[4:7] offset:32768
	ds_write_b128 v1, v[4:7] offset:40960
	ds_write_b128 v1, v[4:7] offset:49152
	ds_write_b128 v1, v[4:7] offset:57344
	v_mov_b32_e32 v2, -1
	v_lshlrev_b32_e32 v0, 2, v100
	ds_write_b32 v0, v2 offset:8192
	s_waitcnt lgkmcnt(0)
	s_barrier
	s_add_i32 s28, s2, 1
	s_cmp_gt_u32 s28, s3
	s_cbranch_scc1 .Ltk_p0_done_1
	v_lshrrev_b32_e32 v0, 22, v208
	v_lshl_add_u32 v0, v0, 2, v21
	ds_add_u32 v0, v20
	v_lshrrev_b32_e32 v1, 22, v175
	v_lshl_add_u32 v1, v1, 2, v22
	ds_add_u32 v1, v20
	v_lshrrev_b32_e32 v4, 22, v161
	v_lshl_add_u32 v4, v4, 2, v23
	ds_add_u32 v4, v20
	v_lshrrev_b32_e32 v5, 22, v138
	v_lshl_add_u32 v5, v5, 2, v24
	ds_add_u32 v5, v20
	s_add_i32 s28, s28, 8
	s_cmp_gt_u32 s28, s3
	s_cbranch_scc1 .Ltk_p0_done_1
	v_lshrrev_b32_e32 v0, 22, v207
	v_lshl_add_u32 v0, v0, 2, v21
	ds_add_u32 v0, v20
	v_lshrrev_b32_e32 v1, 22, v173
	v_lshl_add_u32 v1, v1, 2, v22
	ds_add_u32 v1, v20
	v_lshrrev_b32_e32 v4, 22, v159
	v_lshl_add_u32 v4, v4, 2, v23
	ds_add_u32 v4, v20
	v_lshrrev_b32_e32 v5, 22, v135
	v_lshl_add_u32 v5, v5, 2, v24
	ds_add_u32 v5, v20
	s_add_i32 s28, s28, 8
	s_cmp_gt_u32 s28, s3
	s_cbranch_scc1 .Ltk_p0_done_1
	v_lshrrev_b32_e32 v0, 22, v187
	v_lshl_add_u32 v0, v0, 2, v21
	ds_add_u32 v0, v20
	v_lshrrev_b32_e32 v1, 22, v172
	v_lshl_add_u32 v1, v1, 2, v22
	ds_add_u32 v1, v20
	v_lshrrev_b32_e32 v4, 22, v158
	v_lshl_add_u32 v4, v4, 2, v23
	ds_add_u32 v4, v20
	v_lshrrev_b32_e32 v5, 22, v133
	v_lshl_add_u32 v5, v5, 2, v24
	ds_add_u32 v5, v20
	s_add_i32 s28, s28, 8
	s_cmp_gt_u32 s28, s3
	s_cbranch_scc1 .Ltk_p0_done_1
	v_lshrrev_b32_e32 v0, 22, v186
	v_lshl_add_u32 v0, v0, 2, v21
	ds_add_u32 v0, v20
	v_lshrrev_b32_e32 v1, 22, v171
	v_lshl_add_u32 v1, v1, 2, v22
	ds_add_u32 v1, v20
	v_lshrrev_b32_e32 v4, 22, v153
	v_lshl_add_u32 v4, v4, 2, v23
	ds_add_u32 v4, v20
	v_lshrrev_b32_e32 v5, 22, v129
	v_lshl_add_u32 v5, v5, 2, v24
	ds_add_u32 v5, v20
	s_add_i32 s28, s28, 8
	s_cmp_gt_u32 s28, s3
	s_cbranch_scc1 .Ltk_p0_done_1
	v_lshrrev_b32_e32 v0, 22, v185
	v_lshl_add_u32 v0, v0, 2, v21
	ds_add_u32 v0, v20
	v_lshrrev_b32_e32 v1, 22, v170
	v_lshl_add_u32 v1, v1, 2, v22
	ds_add_u32 v1, v20
	v_lshrrev_b32_e32 v4, 22, v150
	v_lshl_add_u32 v4, v4, 2, v23
	ds_add_u32 v4, v20
	v_lshrrev_b32_e32 v5, 22, v127
	v_lshl_add_u32 v5, v5, 2, v24
	ds_add_u32 v5, v20
	s_add_i32 s28, s28, 8
	s_cmp_gt_u32 s28, s3
	s_cbranch_scc1 .Ltk_p0_done_1
; DI void topk_job(const Params& p, int b, int t0, char* lds) {
;     ...
; #pragma unroll
;       for (int i = 0; i < 17; ++i) {
; #pragma unroll
;         for (int q = 0; q < 4; ++q) {
;           const unsigned u = sc[i][q];
;           bool part; unsigned bin;
;           if (pass == 0) { part = (u != 0u); bin = (u >> 22) + (lane & 3) * 1024; }
;           else if (pass == 1) { part = (u != 0u) && ((u >> 22) == pref[q]) && !few[q]; bin = ((u >> 12) & 1023u) + (lane & 3) * 1024; }
;           else { part = (u != 0u) && ((u >> 12) == pref[q]) && !few[q]; bin = u & 4095u; }
;           if (part) atomicAdd(hist + q * 4096 + bin, 1u);
;         }
;       }
	v_lshrrev_b32_e32 v0, 22, v184
	v_lshl_add_u32 v0, v0, 2, v21
	ds_add_u32 v0, v20
	v_lshrrev_b32_e32 v1, 22, v168
	v_lshl_add_u32 v1, v1, 2, v22
	ds_add_u32 v1, v20
	v_lshrrev_b32_e32 v4, 22, v149
	v_lshl_add_u32 v4, v4, 2, v23
	ds_add_u32 v4, v20
	v_lshrrev_b32_e32 v5, 22, v125
	v_lshl_add_u32 v5, v5, 2, v24
	ds_add_u32 v5, v20
	s_add_i32 s28, s28, 8
	s_cmp_gt_u32 s28, s3
	s_cbranch_scc1 .Ltk_p0_done_1
	v_lshrrev_b32_e32 v0, 22, v183
	v_lshl_add_u32 v0, v0, 2, v21
	ds_add_u32 v0, v20
	v_lshrrev_b32_e32 v1, 22, v167
	v_lshl_add_u32 v1, v1, 2, v22
	ds_add_u32 v1, v20
	v_lshrrev_b32_e32 v4, 22, v147
	v_lshl_add_u32 v4, v4, 2, v23
	ds_add_u32 v4, v20
	v_lshrrev_b32_e32 v5, 22, v123
	v_lshl_add_u32 v5, v5, 2, v24
	ds_add_u32 v5, v20
	s_add_i32 s28, s28, 8
	s_cmp_gt_u32 s28, s3
	s_cbranch_scc1 .Ltk_p0_done_1
	v_lshrrev_b32_e32 v0, 22, v182
	v_lshl_add_u32 v0, v0, 2, v21
	ds_add_u32 v0, v20
	v_lshrrev_b32_e32 v1, 22, v166
	v_lshl_add_u32 v1, v1, 2, v22
	ds_add_u32 v1, v20
	v_lshrrev_b32_e32 v4, 22, v146
	v_lshl_add_u32 v4, v4, 2, v23
	ds_add_u32 v4, v20
	v_lshrrev_b32_e32 v5, 22, v121
	v_lshl_add_u32 v5, v5, 2, v24
	ds_add_u32 v5, v20
	s_add_i32 s28, s28, 8
	s_cmp_gt_u32 s28, s3
	s_cbranch_scc1 .Ltk_p0_done_1
	v_lshrrev_b32_e32 v0, 22, v181
	v_lshl_add_u32 v0, v0, 2, v21
	ds_add_u32 v0, v20
	v_lshrrev_b32_e32 v1, 22, v165
	v_lshl_add_u32 v1, v1, 2, v22
	ds_add_u32 v1, v20
	v_lshrrev_b32_e32 v4, 22, v145
	v_lshl_add_u32 v4, v4, 2, v23
	ds_add_u32 v4, v20
	v_lshrrev_b32_e32 v5, 22, v119
	v_lshl_add_u32 v5, v5, 2, v24
	ds_add_u32 v5, v20
	s_add_i32 s28, s28, 8
	s_cmp_gt_u32 s28, s3
	s_cbranch_scc1 .Ltk_p0_done_1
	v_lshrrev_b32_e32 v0, 22, v180
	v_lshl_add_u32 v0, v0, 2, v21
	ds_add_u32 v0, v20
	v_lshrrev_b32_e32 v1, 22, v164
	v_lshl_add_u32 v1, v1, 2, v22
	ds_add_u32 v1, v20
	v_lshrrev_b32_e32 v4, 22, v143
	v_lshl_add_u32 v4, v4, 2, v23
	ds_add_u32 v4, v20
	v_lshrrev_b32_e32 v5, 22, v115
	v_lshl_add_u32 v5, v5, 2, v24
	ds_add_u32 v5, v20
	s_add_i32 s28, s28, 8
	s_cmp_gt_u32 s28, s3
	s_cbranch_scc1 .Ltk_p0_done_1
	v_lshrrev_b32_e32 v0, 22, v179
	v_lshl_add_u32 v0, v0, 2, v21
	ds_add_u32 v0, v20
	v_lshrrev_b32_e32 v1, 22, v163
	v_lshl_add_u32 v1, v1, 2, v22
	ds_add_u32 v1, v20
	v_lshrrev_b32_e32 v4, 22, v142
	v_lshl_add_u32 v4, v4, 2, v23
	ds_add_u32 v4, v20
	v_lshrrev_b32_e32 v5, 22, v113
	v_lshl_add_u32 v5, v5, 2, v24
	ds_add_u32 v5, v20
	s_add_i32 s28, s28, 8
	s_cmp_gt_u32 s28, s3
	s_cbranch_scc1 .Ltk_p0_done_1
	v_lshrrev_b32_e32 v0, 22, v178
	v_lshl_add_u32 v0, v0, 2, v21
	ds_add_u32 v0, v20
	v_lshrrev_b32_e32 v1, 22, v162
	v_lshl_add_u32 v1, v1, 2, v22
	ds_add_u32 v1, v20
	v_lshrrev_b32_e32 v4, 22, v141
	v_lshl_add_u32 v4, v4, 2, v23
	ds_add_u32 v4, v20
	v_lshrrev_b32_e32 v5, 22, v111
	v_lshl_add_u32 v5, v5, 2, v24
	ds_add_u32 v5, v20
	s_add_i32 s28, s28, 8
	s_cmp_gt_u32 s28, s3
	s_cbranch_scc1 .Ltk_p0_done_1
	v_lshrrev_b32_e32 v0, 22, v177
	v_lshl_add_u32 v0, v0, 2, v21
	ds_add_u32 v0, v20
	v_lshrrev_b32_e32 v1, 22, v160
	v_lshl_add_u32 v1, v1, 2, v22
	ds_add_u32 v1, v20
	v_lshrrev_b32_e32 v4, 22, v140
	v_lshl_add_u32 v4, v4, 2, v23
	ds_add_u32 v4, v20
	v_lshrrev_b32_e32 v5, 22, v109
	v_lshl_add_u32 v5, v5, 2, v24
	ds_add_u32 v5, v20
	s_add_i32 s28, s28, 8
	s_cmp_gt_u32 s28, s3
	s_cbranch_scc1 .Ltk_p0_done_1
	v_lshrrev_b32_e32 v0, 22, v176
	v_lshl_add_u32 v0, v0, 2, v21
	ds_add_u32 v0, v20
	v_lshrrev_b32_e32 v1, 22, v151
	v_lshl_add_u32 v1, v1, 2, v22
	ds_add_u32 v1, v20
	v_lshrrev_b32_e32 v4, 22, v139
	v_lshl_add_u32 v4, v4, 2, v23
	ds_add_u32 v4, v20
	v_lshrrev_b32_e32 v5, 22, v107
	v_lshl_add_u32 v5, v5, 2, v24
	ds_add_u32 v5, v20
	s_add_i32 s28, s28, 8
	s_cmp_gt_u32 s28, s3
	s_cbranch_scc1 .Ltk_p0_done_1
	v_lshrrev_b32_e32 v0, 22, v174
	v_lshl_add_u32 v0, v0, 2, v21
	ds_add_u32 v0, v20
	v_lshrrev_b32_e32 v1, 22, v148
	v_lshl_add_u32 v1, v1, 2, v22
	ds_add_u32 v1, v20
	v_lshrrev_b32_e32 v4, 22, v131
	v_lshl_add_u32 v4, v4, 2, v23
	ds_add_u32 v4, v20
	v_lshrrev_b32_e32 v5, 22, v105
	v_lshl_add_u32 v5, v5, 2, v24
	ds_add_u32 v5, v20
	s_add_i32 s28, s28, 8
	s_cmp_gt_u32 s28, s3
	s_cbranch_scc1 .Ltk_p0_done_1
	v_lshrrev_b32_e32 v0, 22, v169
	v_lshl_add_u32 v0, v0, 2, v21
	ds_add_u32 v0, v20
	v_lshrrev_b32_e32 v1, 22, v144
	v_lshl_add_u32 v1, v1, 2, v22
	ds_add_u32 v1, v20
	v_lshrrev_b32_e32 v4, 22, v117
	v_lshl_add_u32 v4, v4, 2, v23
	ds_add_u32 v4, v20
	v_lshrrev_b32_e32 v5, 22, v103
	v_lshl_add_u32 v5, v5, 2, v24
	ds_add_u32 v5, v20
	s_add_i32 s28, s28, 8
	s_cmp_gt_u32 s28, s3
	s_cbranch_scc1 .Ltk_p0_done_1
	v_lshrrev_b32_e32 v0, 22, v19
	v_lshl_add_u32 v0, v0, 2, v21
	ds_add_u32 v0, v20
	v_lshrrev_b32_e32 v1, 22, v18
	v_lshl_add_u32 v1, v1, 2, v22
	ds_add_u32 v1, v20
	v_lshrrev_b32_e32 v4, 22, v17
	v_lshl_add_u32 v4, v4, 2, v23
	ds_add_u32 v4, v20
	v_lshrrev_b32_e32 v5, 22, v16
	v_lshl_add_u32 v5, v5, 2, v24
	ds_add_u32 v5, v20

; DI void topk_job(const Params& p, int b, int t0, char* lds) {
;     ...
;       {
;         const u32x4 z = {0u, 0u, 0u, 0u};
; #pragma unroll
;         for (int j = 0; j < 8; ++j) ((u32x4*)hist)[tid + 512 * j] = z;
;       }
;       __syncthreads();
; #pragma unroll
;       for (int i = 0; i < 17; ++i) {
; #pragma unroll
;         for (int q = 0; q < 4; ++q) {
;           const unsigned u = sc[i][q];
;           bool part; unsigned bin;
;           if (pass == 0) { part = (u != 0u); bin = (u >> 22) + (lane & 3) * 1024; }
;           else if (pass == 1) { part = (u != 0u) && ((u >> 22) == pref[q]) && !few[q]; bin = ((u >> 12) & 1023u) + (lane & 3) * 1024; }
;           else { part = (u != 0u) && ((u >> 12) == pref[q]) && !few[q]; bin = u & 4095u; }
;           if (part) atomicAdd(hist + q * 4096 + bin, 1u);
;         }
;       }
;     ...
;       __syncthreads();
; #pragma unroll
;       for (int q = 0; q < 4; ++q) {
;         if (!few[q]) {
;           pref[q] = (pref[q] << (pass < 2 ? 10 : 12)) | (unsigned)sel[q * 4 + 0];
;           chi[q] = sel[q * 4 + 1];
;           nb[q] = sel[q * 4 + 3];
;           if (pass == 0) few[q] = sel[q * 4 + 2] != 0;
;         }
;       }
.Ltk_scan_end_2:
	s_waitcnt lgkmcnt(0)
	s_barrier
	ds_read_b128 v[4:7], v3 offset:512
	ds_read_b128 v[8:11], v3 offset:528
	s_waitcnt lgkmcnt(0)
	v_readfirstlane_b32 s8, v4
	v_readfirstlane_b32 s9, v6
	v_readfirstlane_b32 s10, v8
	v_readfirstlane_b32 s11, v10
	v_mov_b32_e32 v4, 0
	v_mov_b32_e32 v5, 0
	v_mov_b32_e32 v6, 0
	v_mov_b32_e32 v7, 0
	v_lshlrev_b32_e32 v0, 4, v100
	v_add_u32_e32 v0, 0x4000, v0
	ds_write_b128 v0, v[4:7]
	ds_write_b128 v0, v[4:7] offset:8192
	ds_write_b128 v0, v[4:7] offset:16384
	ds_write_b128 v0, v[4:7] offset:24576
	ds_write_b128 v0, v[4:7] offset:32768
	ds_write_b128 v0, v[4:7] offset:40960
	ds_write_b128 v0, v[4:7] offset:49152
	ds_write_b128 v0, v[4:7] offset:57344
	s_add_i32 s28, s2, 1
	s_cmp_gt_u32 s28, s3
	s_cbranch_scc1 .Ltk_p1_done_6
	v_lshrrev_b32_e32 v0, 22, v208
	v_cmp_eq_u32_e32 vcc, s8, v0
	v_bfe_u32 v8, v208, 12, 10
	v_lshl_add_u32 v8, v8, 2, v25
	v_cndmask_b32_e32 v8, v75, v8, vcc
	ds_add_u32 v8, v20
	v_lshrrev_b32_e32 v1, 22, v175
	v_cmp_eq_u32_e32 vcc, s9, v1
	v_bfe_u32 v9, v175, 12, 10
	v_lshl_add_u32 v9, v9, 2, v26
	v_cndmask_b32_e32 v9, v75, v9, vcc
	ds_add_u32 v9, v20
	v_lshrrev_b32_e32 v4, 22, v161
	v_cmp_eq_u32_e32 vcc, s10, v4
	v_bfe_u32 v10, v161, 12, 10
	v_lshl_add_u32 v10, v10, 2, v27
	v_cndmask_b32_e32 v10, v75, v10, vcc
	ds_add_u32 v10, v20
	v_lshrrev_b32_e32 v5, 22, v138
	v_cmp_eq_u32_e32 vcc, s11, v5
	v_bfe_u32 v11, v138, 12, 10
	v_lshl_add_u32 v11, v11, 2, v28
	v_cndmask_b32_e32 v11, v75, v11, vcc
	ds_add_u32 v11, v20
	s_add_i32 s28, s28, 8
	s_cmp_gt_u32 s28, s3
	s_cbranch_scc1 .Ltk_p1_done_6
	v_lshrrev_b32_e32 v0, 22, v207
	v_cmp_eq_u32_e32 vcc, s8, v0
	v_bfe_u32 v8, v207, 12, 10
	v_lshl_add_u32 v8, v8, 2, v25
	v_cndmask_b32_e32 v8, v75, v8, vcc
	ds_add_u32 v8, v20
	v_lshrrev_b32_e32 v1, 22, v173
	v_cmp_eq_u32_e32 vcc, s9, v1
	v_bfe_u32 v9, v173, 12, 10
	v_lshl_add_u32 v9, v9, 2, v26
	v_cndmask_b32_e32 v9, v75, v9, vcc
	ds_add_u32 v9, v20
	v_lshrrev_b32_e32 v4, 22, v159
	v_cmp_eq_u32_e32 vcc, s10, v4
	v_bfe_u32 v10, v159, 12, 10
	v_lshl_add_u32 v10, v10, 2, v27
	v_cndmask_b32_e32 v10, v75, v10, vcc
	ds_add_u32 v10, v20
	v_lshrrev_b32_e32 v5, 22, v135
	v_cmp_eq_u32_e32 vcc, s11, v5
	v_bfe_u32 v11, v135, 12, 10
	v_lshl_add_u32 v11, v11, 2, v28
	v_cndmask_b32_e32 v11, v75, v11, vcc
	ds_add_u32 v11, v20
	s_add_i32 s28, s28, 8
	s_cmp_gt_u32 s28, s3
	s_cbranch_scc1 .Ltk_p1_done_6
	v_lshrrev_b32_e32 v0, 22, v187
	v_cmp_eq_u32_e32 vcc, s8, v0
	v_bfe_u32 v8, v187, 12, 10
	v_lshl_add_u32 v8, v8, 2, v25
	v_cndmask_b32_e32 v8, v75, v8, vcc
	ds_add_u32 v8, v20
	v_lshrrev_b32_e32 v1, 22, v172
	v_cmp_eq_u32_e32 vcc, s9, v1
	v_bfe_u32 v9, v172, 12, 10
	v_lshl_add_u32 v9, v9, 2, v26
	v_cndmask_b32_e32 v9, v75, v9, vcc
	ds_add_u32 v9, v20
	v_lshrrev_b32_e32 v4, 22, v158
	v_cmp_eq_u32_e32 vcc, s10, v4
	v_bfe_u32 v10, v158, 12, 10
	v_lshl_add_u32 v10, v10, 2, v27
	v_cndmask_b32_e32 v10, v75, v10, vcc
	ds_add_u32 v10, v20
	v_lshrrev_b32_e32 v5, 22, v133
	v_cmp_eq_u32_e32 vcc, s11, v5
	v_bfe_u32 v11, v133, 12, 10
	v_lshl_add_u32 v11, v11, 2, v28
	v_cndmask_b32_e32 v11, v75, v11, vcc
	ds_add_u32 v11, v20
	s_add_i32 s28, s28, 8
	s_cmp_gt_u32 s28, s3
	s_cbranch_scc1 .Ltk_p1_done_6
	v_lshrrev_b32_e32 v0, 22, v186
	v_cmp_eq_u32_e32 vcc, s8, v0
	v_bfe_u32 v8, v186, 12, 10
	v_lshl_add_u32 v8, v8, 2, v25
	v_cndmask_b32_e32 v8, v75, v8, vcc
	ds_add_u32 v8, v20
	v_lshrrev_b32_e32 v1, 22, v171
	v_cmp_eq_u32_e32 vcc, s9, v1
	v_bfe_u32 v9, v171, 12, 10
	v_lshl_add_u32 v9, v9, 2, v26
	v_cndmask_b32_e32 v9, v75, v9, vcc
	ds_add_u32 v9, v20
	v_lshrrev_b32_e32 v4, 22, v153
	v_cmp_eq_u32_e32 vcc, s10, v4
	v_bfe_u32 v10, v153, 12, 10
	v_lshl_add_u32 v10, v10, 2, v27
	v_cndmask_b32_e32 v10, v75, v10, vcc
	ds_add_u32 v10, v20
	v_lshrrev_b32_e32 v5, 22, v129
	v_cmp_eq_u32_e32 vcc, s11, v5
	v_bfe_u32 v11, v129, 12, 10
	v_lshl_add_u32 v11, v11, 2, v28
	v_cndmask_b32_e32 v11, v75, v11, vcc
	ds_add_u32 v11, v20
	s_add_i32 s28, s28, 8
	s_cmp_gt_u32 s28, s3
	s_cbranch_scc1 .Ltk_p1_done_6
	v_lshrrev_b32_e32 v0, 22, v185
	v_cmp_eq_u32_e32 vcc, s8, v0
	v_bfe_u32 v8, v185, 12, 10
	v_lshl_add_u32 v8, v8, 2, v25
	v_cndmask_b32_e32 v8, v75, v8, vcc
	ds_add_u32 v8, v20
	v_lshrrev_b32_e32 v1, 22, v170
	v_cmp_eq_u32_e32 vcc, s9, v1
	v_bfe_u32 v9, v170, 12, 10
	v_lshl_add_u32 v9, v9, 2, v26
	v_cndmask_b32_e32 v9, v75, v9, vcc
	ds_add_u32 v9, v20
	v_lshrrev_b32_e32 v4, 22, v150
	v_cmp_eq_u32_e32 vcc, s10, v4
	v_bfe_u32 v10, v150, 12, 10
	v_lshl_add_u32 v10, v10, 2, v27
	v_cndmask_b32_e32 v10, v75, v10, vcc
	ds_add_u32 v10, v20
	v_lshrrev_b32_e32 v5, 22, v127
	v_cmp_eq_u32_e32 vcc, s11, v5
	v_bfe_u32 v11, v127, 12, 10
	v_lshl_add_u32 v11, v11, 2, v28
	v_cndmask_b32_e32 v11, v75, v11, vcc
	ds_add_u32 v11, v20
	s_add_i32 s28, s28, 8
	s_cmp_gt_u32 s28, s3
	s_cbranch_scc1 .Ltk_p1_done_6
	v_lshrrev_b32_e32 v0, 22, v184
	v_cmp_eq_u32_e32 vcc, s8, v0
	v_bfe_u32 v8, v184, 12, 10
	v_lshl_add_u32 v8, v8, 2, v25
	v_cndmask_b32_e32 v8, v75, v8, vcc
	ds_add_u32 v8, v20
	v_lshrrev_b32_e32 v1, 22, v168
	v_cmp_eq_u32_e32 vcc, s9, v1
	v_bfe_u32 v9, v168, 12, 10
	v_lshl_add_u32 v9, v9, 2, v26
	v_cndmask_b32_e32 v9, v75, v9, vcc
	ds_add_u32 v9, v20
	v_lshrrev_b32_e32 v4, 22, v149
	v_cmp_eq_u32_e32 vcc, s10, v4
	v_bfe_u32 v10, v149, 12, 10
	v_lshl_add_u32 v10, v10, 2, v27
	v_cndmask_b32_e32 v10, v75, v10, vcc
	ds_add_u32 v10, v20
	v_lshrrev_b32_e32 v5, 22, v125
	v_cmp_eq_u32_e32 vcc, s11, v5
	v_bfe_u32 v11, v125, 12, 10
	v_lshl_add_u32 v11, v11, 2, v28
	v_cndmask_b32_e32 v11, v75, v11, vcc
	ds_add_u32 v11, v20
	s_add_i32 s28, s28, 8
	s_cmp_gt_u32 s28, s3
	s_cbranch_scc1 .Ltk_p1_done_6
; DI void topk_job(const Params& p, int b, int t0, char* lds) {
;     ...
; #pragma unroll
;       for (int i = 0; i < 17; ++i) {
; #pragma unroll
;         for (int q = 0; q < 4; ++q) {
;           const unsigned u = sc[i][q];
;           bool part; unsigned bin;
;           if (pass == 0) { part = (u != 0u); bin = (u >> 22) + (lane & 3) * 1024; }
;           else if (pass == 1) { part = (u != 0u) && ((u >> 22) == pref[q]) && !few[q]; bin = ((u >> 12) & 1023u) + (lane & 3) * 1024; }
;           else { part = (u != 0u) && ((u >> 12) == pref[q]) && !few[q]; bin = u & 4095u; }
;           if (part) atomicAdd(hist + q * 4096 + bin, 1u);
;         }
;       }
	v_lshrrev_b32_e32 v0, 22, v183
	v_cmp_eq_u32_e32 vcc, s8, v0
	v_bfe_u32 v8, v183, 12, 10
	v_lshl_add_u32 v8, v8, 2, v25
	v_cndmask_b32_e32 v8, v75, v8, vcc
	ds_add_u32 v8, v20
	v_lshrrev_b32_e32 v1, 22, v167
	v_cmp_eq_u32_e32 vcc, s9, v1
	v_bfe_u32 v9, v167, 12, 10
	v_lshl_add_u32 v9, v9, 2, v26
	v_cndmask_b32_e32 v9, v75, v9, vcc
	ds_add_u32 v9, v20
	v_lshrrev_b32_e32 v4, 22, v147
	v_cmp_eq_u32_e32 vcc, s10, v4
	v_bfe_u32 v10, v147, 12, 10
	v_lshl_add_u32 v10, v10, 2, v27
	v_cndmask_b32_e32 v10, v75, v10, vcc
	ds_add_u32 v10, v20
	v_lshrrev_b32_e32 v5, 22, v123
	v_cmp_eq_u32_e32 vcc, s11, v5
	v_bfe_u32 v11, v123, 12, 10
	v_lshl_add_u32 v11, v11, 2, v28
	v_cndmask_b32_e32 v11, v75, v11, vcc
	ds_add_u32 v11, v20
	s_add_i32 s28, s28, 8
	s_cmp_gt_u32 s28, s3
	s_cbranch_scc1 .Ltk_p1_done_6
	v_lshrrev_b32_e32 v0, 22, v182
	v_cmp_eq_u32_e32 vcc, s8, v0
	v_bfe_u32 v8, v182, 12, 10
	v_lshl_add_u32 v8, v8, 2, v25
	v_cndmask_b32_e32 v8, v75, v8, vcc
	ds_add_u32 v8, v20
	v_lshrrev_b32_e32 v1, 22, v166
	v_cmp_eq_u32_e32 vcc, s9, v1
	v_bfe_u32 v9, v166, 12, 10
	v_lshl_add_u32 v9, v9, 2, v26
	v_cndmask_b32_e32 v9, v75, v9, vcc
	ds_add_u32 v9, v20
	v_lshrrev_b32_e32 v4, 22, v146
	v_cmp_eq_u32_e32 vcc, s10, v4
	v_bfe_u32 v10, v146, 12, 10
	v_lshl_add_u32 v10, v10, 2, v27
	v_cndmask_b32_e32 v10, v75, v10, vcc
	ds_add_u32 v10, v20
	v_lshrrev_b32_e32 v5, 22, v121
	v_cmp_eq_u32_e32 vcc, s11, v5
	v_bfe_u32 v11, v121, 12, 10
	v_lshl_add_u32 v11, v11, 2, v28
	v_cndmask_b32_e32 v11, v75, v11, vcc
	ds_add_u32 v11, v20
	s_add_i32 s28, s28, 8
	s_cmp_gt_u32 s28, s3
	s_cbranch_scc1 .Ltk_p1_done_6
	v_lshrrev_b32_e32 v0, 22, v181
	v_cmp_eq_u32_e32 vcc, s8, v0
	v_bfe_u32 v8, v181, 12, 10
	v_lshl_add_u32 v8, v8, 2, v25
	v_cndmask_b32_e32 v8, v75, v8, vcc
	ds_add_u32 v8, v20
	v_lshrrev_b32_e32 v1, 22, v165
	v_cmp_eq_u32_e32 vcc, s9, v1
	v_bfe_u32 v9, v165, 12, 10
	v_lshl_add_u32 v9, v9, 2, v26
	v_cndmask_b32_e32 v9, v75, v9, vcc
	ds_add_u32 v9, v20
	v_lshrrev_b32_e32 v4, 22, v145
	v_cmp_eq_u32_e32 vcc, s10, v4
	v_bfe_u32 v10, v145, 12, 10
	v_lshl_add_u32 v10, v10, 2, v27
	v_cndmask_b32_e32 v10, v75, v10, vcc
	ds_add_u32 v10, v20
	v_lshrrev_b32_e32 v5, 22, v119
	v_cmp_eq_u32_e32 vcc, s11, v5
	v_bfe_u32 v11, v119, 12, 10
	v_lshl_add_u32 v11, v11, 2, v28
	v_cndmask_b32_e32 v11, v75, v11, vcc
	ds_add_u32 v11, v20
	s_add_i32 s28, s28, 8
	s_cmp_gt_u32 s28, s3
	s_cbranch_scc1 .Ltk_p1_done_6
	v_lshrrev_b32_e32 v0, 22, v180
	v_cmp_eq_u32_e32 vcc, s8, v0
	v_bfe_u32 v8, v180, 12, 10
	v_lshl_add_u32 v8, v8, 2, v25
	v_cndmask_b32_e32 v8, v75, v8, vcc
	ds_add_u32 v8, v20
	v_lshrrev_b32_e32 v1, 22, v164
	v_cmp_eq_u32_e32 vcc, s9, v1
	v_bfe_u32 v9, v164, 12, 10
	v_lshl_add_u32 v9, v9, 2, v26
	v_cndmask_b32_e32 v9, v75, v9, vcc
	ds_add_u32 v9, v20
	v_lshrrev_b32_e32 v4, 22, v143
	v_cmp_eq_u32_e32 vcc, s10, v4
	v_bfe_u32 v10, v143, 12, 10
	v_lshl_add_u32 v10, v10, 2, v27
	v_cndmask_b32_e32 v10, v75, v10, vcc
	ds_add_u32 v10, v20
	v_lshrrev_b32_e32 v5, 22, v115
	v_cmp_eq_u32_e32 vcc, s11, v5
	v_bfe_u32 v11, v115, 12, 10
	v_lshl_add_u32 v11, v11, 2, v28
	v_cndmask_b32_e32 v11, v75, v11, vcc
	ds_add_u32 v11, v20
	s_add_i32 s28, s28, 8
	s_cmp_gt_u32 s28, s3
	s_cbranch_scc1 .Ltk_p1_done_6
	v_lshrrev_b32_e32 v0, 22, v179
	v_cmp_eq_u32_e32 vcc, s8, v0
	v_bfe_u32 v8, v179, 12, 10
	v_lshl_add_u32 v8, v8, 2, v25
	v_cndmask_b32_e32 v8, v75, v8, vcc
	ds_add_u32 v8, v20
	v_lshrrev_b32_e32 v1, 22, v163
	v_cmp_eq_u32_e32 vcc, s9, v1
	v_bfe_u32 v9, v163, 12, 10
	v_lshl_add_u32 v9, v9, 2, v26
	v_cndmask_b32_e32 v9, v75, v9, vcc
	ds_add_u32 v9, v20
	v_lshrrev_b32_e32 v4, 22, v142
	v_cmp_eq_u32_e32 vcc, s10, v4
	v_bfe_u32 v10, v142, 12, 10
	v_lshl_add_u32 v10, v10, 2, v27
	v_cndmask_b32_e32 v10, v75, v10, vcc
	ds_add_u32 v10, v20
	v_lshrrev_b32_e32 v5, 22, v113
	v_cmp_eq_u32_e32 vcc, s11, v5
	v_bfe_u32 v11, v113, 12, 10
	v_lshl_add_u32 v11, v11, 2, v28
	v_cndmask_b32_e32 v11, v75, v11, vcc
	ds_add_u32 v11, v20
	s_add_i32 s28, s28, 8
	s_cmp_gt_u32 s28, s3
	s_cbranch_scc1 .Ltk_p1_done_6
; DI void topk_job(const Params& p, int b, int t0, char* lds) {
;     ...
; #pragma unroll
;       for (int i = 0; i < 17; ++i) {
; #pragma unroll
;         for (int q = 0; q < 4; ++q) {
;           const unsigned u = sc[i][q];
;           bool part; unsigned bin;
;           if (pass == 0) { part = (u != 0u); bin = (u >> 22) + (lane & 3) * 1024; }
;           else if (pass == 1) { part = (u != 0u) && ((u >> 22) == pref[q]) && !few[q]; bin = ((u >> 12) & 1023u) + (lane & 3) * 1024; }
;           else { part = (u != 0u) && ((u >> 12) == pref[q]) && !few[q]; bin = u & 4095u; }
;           if (part) atomicAdd(hist + q * 4096 + bin, 1u);
;         }
;       }
	v_lshrrev_b32_e32 v0, 22, v178
	v_cmp_eq_u32_e32 vcc, s8, v0
	v_bfe_u32 v8, v178, 12, 10
	v_lshl_add_u32 v8, v8, 2, v25
	v_cndmask_b32_e32 v8, v75, v8, vcc
	ds_add_u32 v8, v20
	v_lshrrev_b32_e32 v1, 22, v162
	v_cmp_eq_u32_e32 vcc, s9, v1
	v_bfe_u32 v9, v162, 12, 10
	v_lshl_add_u32 v9, v9, 2, v26
	v_cndmask_b32_e32 v9, v75, v9, vcc
	ds_add_u32 v9, v20
	v_lshrrev_b32_e32 v4, 22, v141
	v_cmp_eq_u32_e32 vcc, s10, v4
	v_bfe_u32 v10, v141, 12, 10
	v_lshl_add_u32 v10, v10, 2, v27
	v_cndmask_b32_e32 v10, v75, v10, vcc
	ds_add_u32 v10, v20
	v_lshrrev_b32_e32 v5, 22, v111
	v_cmp_eq_u32_e32 vcc, s11, v5
	v_bfe_u32 v11, v111, 12, 10
	v_lshl_add_u32 v11, v11, 2, v28
	v_cndmask_b32_e32 v11, v75, v11, vcc
	ds_add_u32 v11, v20
	s_add_i32 s28, s28, 8
	s_cmp_gt_u32 s28, s3
	s_cbranch_scc1 .Ltk_p1_done_6
	v_lshrrev_b32_e32 v0, 22, v177
	v_cmp_eq_u32_e32 vcc, s8, v0
	v_bfe_u32 v8, v177, 12, 10
	v_lshl_add_u32 v8, v8, 2, v25
	v_cndmask_b32_e32 v8, v75, v8, vcc
	ds_add_u32 v8, v20
	v_lshrrev_b32_e32 v1, 22, v160
	v_cmp_eq_u32_e32 vcc, s9, v1
	v_bfe_u32 v9, v160, 12, 10
	v_lshl_add_u32 v9, v9, 2, v26
	v_cndmask_b32_e32 v9, v75, v9, vcc
	ds_add_u32 v9, v20
	v_lshrrev_b32_e32 v4, 22, v140
	v_cmp_eq_u32_e32 vcc, s10, v4
	v_bfe_u32 v10, v140, 12, 10
	v_lshl_add_u32 v10, v10, 2, v27
	v_cndmask_b32_e32 v10, v75, v10, vcc
	ds_add_u32 v10, v20
	v_lshrrev_b32_e32 v5, 22, v109
	v_cmp_eq_u32_e32 vcc, s11, v5
	v_bfe_u32 v11, v109, 12, 10
	v_lshl_add_u32 v11, v11, 2, v28
	v_cndmask_b32_e32 v11, v75, v11, vcc
	ds_add_u32 v11, v20
	s_add_i32 s28, s28, 8
	s_cmp_gt_u32 s28, s3
	s_cbranch_scc1 .Ltk_p1_done_6
	v_lshrrev_b32_e32 v0, 22, v176
	v_cmp_eq_u32_e32 vcc, s8, v0
	v_bfe_u32 v8, v176, 12, 10
	v_lshl_add_u32 v8, v8, 2, v25
	v_cndmask_b32_e32 v8, v75, v8, vcc
	ds_add_u32 v8, v20
	v_lshrrev_b32_e32 v1, 22, v151
	v_cmp_eq_u32_e32 vcc, s9, v1
	v_bfe_u32 v9, v151, 12, 10
	v_lshl_add_u32 v9, v9, 2, v26
	v_cndmask_b32_e32 v9, v75, v9, vcc
	ds_add_u32 v9, v20
	v_lshrrev_b32_e32 v4, 22, v139
	v_cmp_eq_u32_e32 vcc, s10, v4
	v_bfe_u32 v10, v139, 12, 10
	v_lshl_add_u32 v10, v10, 2, v27
	v_cndmask_b32_e32 v10, v75, v10, vcc
	ds_add_u32 v10, v20
	v_lshrrev_b32_e32 v5, 22, v107
	v_cmp_eq_u32_e32 vcc, s11, v5
	v_bfe_u32 v11, v107, 12, 10
	v_lshl_add_u32 v11, v11, 2, v28
	v_cndmask_b32_e32 v11, v75, v11, vcc
	ds_add_u32 v11, v20
	s_add_i32 s28, s28, 8
	s_cmp_gt_u32 s28, s3
	s_cbranch_scc1 .Ltk_p1_done_6
	v_lshrrev_b32_e32 v0, 22, v174
	v_cmp_eq_u32_e32 vcc, s8, v0
	v_bfe_u32 v8, v174, 12, 10
	v_lshl_add_u32 v8, v8, 2, v25
	v_cndmask_b32_e32 v8, v75, v8, vcc
	ds_add_u32 v8, v20
	v_lshrrev_b32_e32 v1, 22, v148
	v_cmp_eq_u32_e32 vcc, s9, v1
	v_bfe_u32 v9, v148, 12, 10
	v_lshl_add_u32 v9, v9, 2, v26
	v_cndmask_b32_e32 v9, v75, v9, vcc
	ds_add_u32 v9, v20
	v_lshrrev_b32_e32 v4, 22, v131
	v_cmp_eq_u32_e32 vcc, s10, v4
	v_bfe_u32 v10, v131, 12, 10
	v_lshl_add_u32 v10, v10, 2, v27
	v_cndmask_b32_e32 v10, v75, v10, vcc
	ds_add_u32 v10, v20
	v_lshrrev_b32_e32 v5, 22, v105
	v_cmp_eq_u32_e32 vcc, s11, v5
	v_bfe_u32 v11, v105, 12, 10
	v_lshl_add_u32 v11, v11, 2, v28
	v_cndmask_b32_e32 v11, v75, v11, vcc
	ds_add_u32 v11, v20
	s_add_i32 s28, s28, 8
	s_cmp_gt_u32 s28, s3
	s_cbranch_scc1 .Ltk_p1_done_6
	v_lshrrev_b32_e32 v0, 22, v169
	v_cmp_eq_u32_e32 vcc, s8, v0
	v_bfe_u32 v8, v169, 12, 10
	v_lshl_add_u32 v8, v8, 2, v25
	v_cndmask_b32_e32 v8, v75, v8, vcc
	ds_add_u32 v8, v20
	v_lshrrev_b32_e32 v1, 22, v144
	v_cmp_eq_u32_e32 vcc, s9, v1
	v_bfe_u32 v9, v144, 12, 10
	v_lshl_add_u32 v9, v9, 2, v26
	v_cndmask_b32_e32 v9, v75, v9, vcc
	ds_add_u32 v9, v20
	v_lshrrev_b32_e32 v4, 22, v117
	v_cmp_eq_u32_e32 vcc, s10, v4
	v_bfe_u32 v10, v117, 12, 10
	v_lshl_add_u32 v10, v10, 2, v27
	v_cndmask_b32_e32 v10, v75, v10, vcc
	ds_add_u32 v10, v20
	v_lshrrev_b32_e32 v5, 22, v103
	v_cmp_eq_u32_e32 vcc, s11, v5
	v_bfe_u32 v11, v103, 12, 10
	v_lshl_add_u32 v11, v11, 2, v28
	v_cndmask_b32_e32 v11, v75, v11, vcc
	ds_add_u32 v11, v20
	s_add_i32 s28, s28, 8
	s_cmp_gt_u32 s28, s3
	s_cbranch_scc1 .Ltk_p1_done_6
	v_lshrrev_b32_e32 v0, 22, v19
	v_cmp_eq_u32_e32 vcc, s8, v0
	v_bfe_u32 v8, v19, 12, 10
	v_lshl_add_u32 v8, v8, 2, v25
	v_cndmask_b32_e32 v8, v75, v8, vcc
	ds_add_u32 v8, v20
	v_lshrrev_b32_e32 v1, 22, v18
	v_cmp_eq_u32_e32 vcc, s9, v1
	v_bfe_u32 v9, v18, 12, 10
	v_lshl_add_u32 v9, v9, 2, v26
	v_cndmask_b32_e32 v9, v75, v9, vcc
	ds_add_u32 v9, v20
	v_lshrrev_b32_e32 v4, 22, v17
	v_cmp_eq_u32_e32 vcc, s10, v4
	v_bfe_u32 v10, v17, 12, 10
	v_lshl_add_u32 v10, v10, 2, v27
	v_cndmask_b32_e32 v10, v75, v10, vcc
	ds_add_u32 v10, v20
	v_lshrrev_b32_e32 v5, 22, v16
	v_cmp_eq_u32_e32 vcc, s11, v5
	v_bfe_u32 v11, v16, 12, 10
	v_lshl_add_u32 v11, v11, 2, v28
	v_cndmask_b32_e32 v11, v75, v11, vcc
	ds_add_u32 v11, v20

; DI void topk_job(const Params& p, int b, int t0, char* lds) {
;     ...
; #pragma unroll
;       for (int i = 0; i < 17; ++i) {
; #pragma unroll
;         for (int q = 0; q < 4; ++q) {
;           const unsigned u = sc[i][q];
;           bool part; unsigned bin;
;           if (pass == 0) { part = (u != 0u); bin = (u >> 22) + (lane & 3) * 1024; }
;           else if (pass == 1) { part = (u != 0u) && ((u >> 22) == pref[q]) && !few[q]; bin = ((u >> 12) & 1023u) + (lane & 3) * 1024; }
;           else { part = (u != 0u) && ((u >> 12) == pref[q]) && !few[q]; bin = u & 4095u; }
;           if (part) atomicAdd(hist + q * 4096 + bin, 1u);
;         }
;       }
;     ...
;       __syncthreads();
; #pragma unroll
;       for (int q = 0; q < 4; ++q) {
;         if (!few[q]) {
;           pref[q] = (pref[q] << (pass < 2 ? 10 : 12)) | (unsigned)sel[q * 4 + 0];
;           chi[q] = sel[q * 4 + 1];
;           nb[q] = sel[q * 4 + 3];
;           if (pass == 0) few[q] = sel[q * 4 + 2] != 0;
;         }
;       }
.Ltk_scan_end_7:
	s_waitcnt lgkmcnt(0)
	s_barrier
	ds_read_b128 v[4:7], v3 offset:512
	ds_read_b128 v[8:11], v3 offset:528
	s_waitcnt lgkmcnt(0)
	v_readfirstlane_b32 s8, v4
	v_readfirstlane_b32 s9, v6
	v_readfirstlane_b32 s10, v8
	v_readfirstlane_b32 s11, v10
	s_add_i32 s28, s2, 1
	s_cmp_gt_u32 s28, s3
	s_cbranch_scc1 .Ltk_p2_done_11
	v_lshrrev_b32_e32 v0, 12, v208
	v_cmp_eq_u32_e32 vcc, s8, v0
	s_cbranch_vccz .Ltk_p2s_12
	v_and_b32_e32 v8, 0xfff, v208
	v_lshl_add_u32 v8, v8, 2, v29
	v_cndmask_b32_e32 v8, v75, v8, vcc
	ds_add_u32 v8, v20
.Ltk_p2s_12:
	v_lshrrev_b32_e32 v1, 12, v175
	v_cmp_eq_u32_e32 vcc, s9, v1
	s_cbranch_vccz .Ltk_p2s_13
	v_and_b32_e32 v9, 0xfff, v175
	v_lshl_add_u32 v9, v9, 2, v30
	v_cndmask_b32_e32 v9, v75, v9, vcc
	ds_add_u32 v9, v20
.Ltk_p2s_13:
	v_lshrrev_b32_e32 v4, 12, v161
	v_cmp_eq_u32_e32 vcc, s10, v4
	s_cbranch_vccz .Ltk_p2s_14
	v_and_b32_e32 v10, 0xfff, v161
	v_lshl_add_u32 v10, v10, 2, v31
	v_cndmask_b32_e32 v10, v75, v10, vcc
	ds_add_u32 v10, v20
.Ltk_p2s_14:
	v_lshrrev_b32_e32 v5, 12, v138
	v_cmp_eq_u32_e32 vcc, s11, v5
	s_cbranch_vccz .Ltk_p2s_15
	v_and_b32_e32 v11, 0xfff, v138
	v_lshl_add_u32 v11, v11, 2, v32
	v_cndmask_b32_e32 v11, v75, v11, vcc
	ds_add_u32 v11, v20
.Ltk_p2s_15:
	s_add_i32 s28, s28, 8
	s_cmp_gt_u32 s28, s3
	s_cbranch_scc1 .Ltk_p2_done_11
	v_lshrrev_b32_e32 v0, 12, v207
	v_cmp_eq_u32_e32 vcc, s8, v0
	s_cbranch_vccz .Ltk_p2s_16
	v_and_b32_e32 v8, 0xfff, v207
	v_lshl_add_u32 v8, v8, 2, v29
	v_cndmask_b32_e32 v8, v75, v8, vcc
	ds_add_u32 v8, v20
.Ltk_p2s_16:
	v_lshrrev_b32_e32 v1, 12, v173
	v_cmp_eq_u32_e32 vcc, s9, v1
	s_cbranch_vccz .Ltk_p2s_17
	v_and_b32_e32 v9, 0xfff, v173
	v_lshl_add_u32 v9, v9, 2, v30
	v_cndmask_b32_e32 v9, v75, v9, vcc
	ds_add_u32 v9, v20
.Ltk_p2s_17:
	v_lshrrev_b32_e32 v4, 12, v159
	v_cmp_eq_u32_e32 vcc, s10, v4
	s_cbranch_vccz .Ltk_p2s_18
	v_and_b32_e32 v10, 0xfff, v159
	v_lshl_add_u32 v10, v10, 2, v31
	v_cndmask_b32_e32 v10, v75, v10, vcc
	ds_add_u32 v10, v20
.Ltk_p2s_18:
	v_lshrrev_b32_e32 v5, 12, v135
	v_cmp_eq_u32_e32 vcc, s11, v5
	s_cbranch_vccz .Ltk_p2s_19
	v_and_b32_e32 v11, 0xfff, v135
	v_lshl_add_u32 v11, v11, 2, v32
	v_cndmask_b32_e32 v11, v75, v11, vcc
	ds_add_u32 v11, v20
.Ltk_p2s_19:
	s_add_i32 s28, s28, 8
	s_cmp_gt_u32 s28, s3
	s_cbranch_scc1 .Ltk_p2_done_11
	v_lshrrev_b32_e32 v0, 12, v187
	v_cmp_eq_u32_e32 vcc, s8, v0
	s_cbranch_vccz .Ltk_p2s_20
	v_and_b32_e32 v8, 0xfff, v187
	v_lshl_add_u32 v8, v8, 2, v29
	v_cndmask_b32_e32 v8, v75, v8, vcc
	ds_add_u32 v8, v20
.Ltk_p2s_20:
	v_lshrrev_b32_e32 v1, 12, v172
	v_cmp_eq_u32_e32 vcc, s9, v1
	s_cbranch_vccz .Ltk_p2s_21
	v_and_b32_e32 v9, 0xfff, v172
	v_lshl_add_u32 v9, v9, 2, v30
	v_cndmask_b32_e32 v9, v75, v9, vcc
	ds_add_u32 v9, v20
.Ltk_p2s_21:
	v_lshrrev_b32_e32 v4, 12, v158
	v_cmp_eq_u32_e32 vcc, s10, v4
	s_cbranch_vccz .Ltk_p2s_22
	v_and_b32_e32 v10, 0xfff, v158
	v_lshl_add_u32 v10, v10, 2, v31
	v_cndmask_b32_e32 v10, v75, v10, vcc
	ds_add_u32 v10, v20
.Ltk_p2s_22:
	v_lshrrev_b32_e32 v5, 12, v133
	v_cmp_eq_u32_e32 vcc, s11, v5
	s_cbranch_vccz .Ltk_p2s_23
	v_and_b32_e32 v11, 0xfff, v133
	v_lshl_add_u32 v11, v11, 2, v32
	v_cndmask_b32_e32 v11, v75, v11, vcc
	ds_add_u32 v11, v20
.Ltk_p2s_23:
	s_add_i32 s28, s28, 8
	s_cmp_gt_u32 s28, s3
	s_cbranch_scc1 .Ltk_p2_done_11
	v_lshrrev_b32_e32 v0, 12, v186
	v_cmp_eq_u32_e32 vcc, s8, v0
	s_cbranch_vccz .Ltk_p2s_24
	v_and_b32_e32 v8, 0xfff, v186
	v_lshl_add_u32 v8, v8, 2, v29
	v_cndmask_b32_e32 v8, v75, v8, vcc
	ds_add_u32 v8, v20
.Ltk_p2s_24:
	v_lshrrev_b32_e32 v1, 12, v171
	v_cmp_eq_u32_e32 vcc, s9, v1
	s_cbranch_vccz .Ltk_p2s_25
	v_and_b32_e32 v9, 0xfff, v171
	v_lshl_add_u32 v9, v9, 2, v30
	v_cndmask_b32_e32 v9, v75, v9, vcc
	ds_add_u32 v9, v20
.Ltk_p2s_25:
	v_lshrrev_b32_e32 v4, 12, v153
	v_cmp_eq_u32_e32 vcc, s10, v4
	s_cbranch_vccz .Ltk_p2s_26
	v_and_b32_e32 v10, 0xfff, v153
	v_lshl_add_u32 v10, v10, 2, v31
	v_cndmask_b32_e32 v10, v75, v10, vcc
	ds_add_u32 v10, v20
.Ltk_p2s_26:
	v_lshrrev_b32_e32 v5, 12, v129
	v_cmp_eq_u32_e32 vcc, s11, v5
	s_cbranch_vccz .Ltk_p2s_27
	v_and_b32_e32 v11, 0xfff, v129
	v_lshl_add_u32 v11, v11, 2, v32
	v_cndmask_b32_e32 v11, v75, v11, vcc
	ds_add_u32 v11, v20
.Ltk_p2s_27:
	s_add_i32 s28, s28, 8
	s_cmp_gt_u32 s28, s3
	s_cbranch_scc1 .Ltk_p2_done_11
	v_lshrrev_b32_e32 v0, 12, v185
	v_cmp_eq_u32_e32 vcc, s8, v0
	s_cbranch_vccz .Ltk_p2s_28
	v_and_b32_e32 v8, 0xfff, v185
	v_lshl_add_u32 v8, v8, 2, v29
	v_cndmask_b32_e32 v8, v75, v8, vcc
	ds_add_u32 v8, v20
.Ltk_p2s_28:
	v_lshrrev_b32_e32 v1, 12, v170
	v_cmp_eq_u32_e32 vcc, s9, v1
	s_cbranch_vccz .Ltk_p2s_29
	v_and_b32_e32 v9, 0xfff, v170
	v_lshl_add_u32 v9, v9, 2, v30
	v_cndmask_b32_e32 v9, v75, v9, vcc
	ds_add_u32 v9, v20
.Ltk_p2s_29:
	v_lshrrev_b32_e32 v4, 12, v150
	v_cmp_eq_u32_e32 vcc, s10, v4
	s_cbranch_vccz .Ltk_p2s_30
	v_and_b32_e32 v10, 0xfff, v150
	v_lshl_add_u32 v10, v10, 2, v31
	v_cndmask_b32_e32 v10, v75, v10, vcc
	ds_add_u32 v10, v20
.Ltk_p2s_30:
	v_lshrrev_b32_e32 v5, 12, v127
	v_cmp_eq_u32_e32 vcc, s11, v5
	s_cbranch_vccz .Ltk_p2s_31
	v_and_b32_e32 v11, 0xfff, v127
	v_lshl_add_u32 v11, v11, 2, v32
	v_cndmask_b32_e32 v11, v75, v11, vcc
	ds_add_u32 v11, v20
.Ltk_p2s_31:
	s_add_i32 s28, s28, 8
	s_cmp_gt_u32 s28, s3
	s_cbranch_scc1 .Ltk_p2_done_11
	v_lshrrev_b32_e32 v0, 12, v184
	v_cmp_eq_u32_e32 vcc, s8, v0
	s_cbranch_vccz .Ltk_p2s_32
	v_and_b32_e32 v8, 0xfff, v184
	v_lshl_add_u32 v8, v8, 2, v29
	v_cndmask_b32_e32 v8, v75, v8, vcc
	ds_add_u32 v8, v20
.Ltk_p2s_32:
	v_lshrrev_b32_e32 v1, 12, v168
	v_cmp_eq_u32_e32 vcc, s9, v1
	s_cbranch_vccz .Ltk_p2s_33
	v_and_b32_e32 v9, 0xfff, v168
	v_lshl_add_u32 v9, v9, 2, v30
	v_cndmask_b32_e32 v9, v75, v9, vcc
	ds_add_u32 v9, v20
; DI void topk_job(const Params& p, int b, int t0, char* lds) {
;     ...
; #pragma unroll
;       for (int i = 0; i < 17; ++i) {
; #pragma unroll
;         for (int q = 0; q < 4; ++q) {
;           const unsigned u = sc[i][q];
;           bool part; unsigned bin;
;           if (pass == 0) { part = (u != 0u); bin = (u >> 22) + (lane & 3) * 1024; }
;           else if (pass == 1) { part = (u != 0u) && ((u >> 22) == pref[q]) && !few[q]; bin = ((u >> 12) & 1023u) + (lane & 3) * 1024; }
;           else { part = (u != 0u) && ((u >> 12) == pref[q]) && !few[q]; bin = u & 4095u; }
;           if (part) atomicAdd(hist + q * 4096 + bin, 1u);
;         }
;       }
.Ltk_p2s_33:
	v_lshrrev_b32_e32 v4, 12, v149
	v_cmp_eq_u32_e32 vcc, s10, v4
	s_cbranch_vccz .Ltk_p2s_34
	v_and_b32_e32 v10, 0xfff, v149
	v_lshl_add_u32 v10, v10, 2, v31
	v_cndmask_b32_e32 v10, v75, v10, vcc
	ds_add_u32 v10, v20
.Ltk_p2s_34:
	v_lshrrev_b32_e32 v5, 12, v125
	v_cmp_eq_u32_e32 vcc, s11, v5
	s_cbranch_vccz .Ltk_p2s_35
	v_and_b32_e32 v11, 0xfff, v125
	v_lshl_add_u32 v11, v11, 2, v32
	v_cndmask_b32_e32 v11, v75, v11, vcc
	ds_add_u32 v11, v20
.Ltk_p2s_35:
	s_add_i32 s28, s28, 8
	s_cmp_gt_u32 s28, s3
	s_cbranch_scc1 .Ltk_p2_done_11
	v_lshrrev_b32_e32 v0, 12, v183
	v_cmp_eq_u32_e32 vcc, s8, v0
	s_cbranch_vccz .Ltk_p2s_36
	v_and_b32_e32 v8, 0xfff, v183
	v_lshl_add_u32 v8, v8, 2, v29
	v_cndmask_b32_e32 v8, v75, v8, vcc
	ds_add_u32 v8, v20
.Ltk_p2s_36:
	v_lshrrev_b32_e32 v1, 12, v167
	v_cmp_eq_u32_e32 vcc, s9, v1
	s_cbranch_vccz .Ltk_p2s_37
	v_and_b32_e32 v9, 0xfff, v167
	v_lshl_add_u32 v9, v9, 2, v30
	v_cndmask_b32_e32 v9, v75, v9, vcc
	ds_add_u32 v9, v20
.Ltk_p2s_37:
	v_lshrrev_b32_e32 v4, 12, v147
	v_cmp_eq_u32_e32 vcc, s10, v4
	s_cbranch_vccz .Ltk_p2s_38
	v_and_b32_e32 v10, 0xfff, v147
	v_lshl_add_u32 v10, v10, 2, v31
	v_cndmask_b32_e32 v10, v75, v10, vcc
	ds_add_u32 v10, v20
.Ltk_p2s_38:
	v_lshrrev_b32_e32 v5, 12, v123
	v_cmp_eq_u32_e32 vcc, s11, v5
	s_cbranch_vccz .Ltk_p2s_39
	v_and_b32_e32 v11, 0xfff, v123
	v_lshl_add_u32 v11, v11, 2, v32
	v_cndmask_b32_e32 v11, v75, v11, vcc
	ds_add_u32 v11, v20
.Ltk_p2s_39:
	s_add_i32 s28, s28, 8
	s_cmp_gt_u32 s28, s3
	s_cbranch_scc1 .Ltk_p2_done_11
	v_lshrrev_b32_e32 v0, 12, v182
	v_cmp_eq_u32_e32 vcc, s8, v0
	s_cbranch_vccz .Ltk_p2s_40
	v_and_b32_e32 v8, 0xfff, v182
	v_lshl_add_u32 v8, v8, 2, v29
	v_cndmask_b32_e32 v8, v75, v8, vcc
	ds_add_u32 v8, v20
.Ltk_p2s_40:
	v_lshrrev_b32_e32 v1, 12, v166
	v_cmp_eq_u32_e32 vcc, s9, v1
	s_cbranch_vccz .Ltk_p2s_41
	v_and_b32_e32 v9, 0xfff, v166
	v_lshl_add_u32 v9, v9, 2, v30
	v_cndmask_b32_e32 v9, v75, v9, vcc
	ds_add_u32 v9, v20
.Ltk_p2s_41:
	v_lshrrev_b32_e32 v4, 12, v146
	v_cmp_eq_u32_e32 vcc, s10, v4
	s_cbranch_vccz .Ltk_p2s_42
	v_and_b32_e32 v10, 0xfff, v146
	v_lshl_add_u32 v10, v10, 2, v31
	v_cndmask_b32_e32 v10, v75, v10, vcc
	ds_add_u32 v10, v20
.Ltk_p2s_42:
	v_lshrrev_b32_e32 v5, 12, v121
	v_cmp_eq_u32_e32 vcc, s11, v5
	s_cbranch_vccz .Ltk_p2s_43
	v_and_b32_e32 v11, 0xfff, v121
	v_lshl_add_u32 v11, v11, 2, v32
	v_cndmask_b32_e32 v11, v75, v11, vcc
	ds_add_u32 v11, v20
.Ltk_p2s_43:
	s_add_i32 s28, s28, 8
	s_cmp_gt_u32 s28, s3
	s_cbranch_scc1 .Ltk_p2_done_11
	v_lshrrev_b32_e32 v0, 12, v181
	v_cmp_eq_u32_e32 vcc, s8, v0
	s_cbranch_vccz .Ltk_p2s_44
	v_and_b32_e32 v8, 0xfff, v181
	v_lshl_add_u32 v8, v8, 2, v29
	v_cndmask_b32_e32 v8, v75, v8, vcc
	ds_add_u32 v8, v20
.Ltk_p2s_44:
	v_lshrrev_b32_e32 v1, 12, v165
	v_cmp_eq_u32_e32 vcc, s9, v1
	s_cbranch_vccz .Ltk_p2s_45
	v_and_b32_e32 v9, 0xfff, v165
	v_lshl_add_u32 v9, v9, 2, v30
	v_cndmask_b32_e32 v9, v75, v9, vcc
	ds_add_u32 v9, v20
.Ltk_p2s_45:
	v_lshrrev_b32_e32 v4, 12, v145
	v_cmp_eq_u32_e32 vcc, s10, v4
	s_cbranch_vccz .Ltk_p2s_46
	v_and_b32_e32 v10, 0xfff, v145
	v_lshl_add_u32 v10, v10, 2, v31
	v_cndmask_b32_e32 v10, v75, v10, vcc
	ds_add_u32 v10, v20
.Ltk_p2s_46:
	v_lshrrev_b32_e32 v5, 12, v119
	v_cmp_eq_u32_e32 vcc, s11, v5
	s_cbranch_vccz .Ltk_p2s_47
	v_and_b32_e32 v11, 0xfff, v119
	v_lshl_add_u32 v11, v11, 2, v32
	v_cndmask_b32_e32 v11, v75, v11, vcc
	ds_add_u32 v11, v20
.Ltk_p2s_47:
	s_add_i32 s28, s28, 8
	s_cmp_gt_u32 s28, s3
	s_cbranch_scc1 .Ltk_p2_done_11
	v_lshrrev_b32_e32 v0, 12, v180
	v_cmp_eq_u32_e32 vcc, s8, v0
	s_cbranch_vccz .Ltk_p2s_48
	v_and_b32_e32 v8, 0xfff, v180
	v_lshl_add_u32 v8, v8, 2, v29
	v_cndmask_b32_e32 v8, v75, v8, vcc
	ds_add_u32 v8, v20
.Ltk_p2s_48:
	v_lshrrev_b32_e32 v1, 12, v164
	v_cmp_eq_u32_e32 vcc, s9, v1
	s_cbranch_vccz .Ltk_p2s_49
	v_and_b32_e32 v9, 0xfff, v164
	v_lshl_add_u32 v9, v9, 2, v30
	v_cndmask_b32_e32 v9, v75, v9, vcc
	ds_add_u32 v9, v20
.Ltk_p2s_49:
	v_lshrrev_b32_e32 v4, 12, v143
	v_cmp_eq_u32_e32 vcc, s10, v4
	s_cbranch_vccz .Ltk_p2s_50
	v_and_b32_e32 v10, 0xfff, v143
	v_lshl_add_u32 v10, v10, 2, v31
	v_cndmask_b32_e32 v10, v75, v10, vcc
	ds_add_u32 v10, v20
.Ltk_p2s_50:
	v_lshrrev_b32_e32 v5, 12, v115
	v_cmp_eq_u32_e32 vcc, s11, v5
	s_cbranch_vccz .Ltk_p2s_51
	v_and_b32_e32 v11, 0xfff, v115
	v_lshl_add_u32 v11, v11, 2, v32
	v_cndmask_b32_e32 v11, v75, v11, vcc
	ds_add_u32 v11, v20
.Ltk_p2s_51:
	s_add_i32 s28, s28, 8
	s_cmp_gt_u32 s28, s3
	s_cbranch_scc1 .Ltk_p2_done_11
	v_lshrrev_b32_e32 v0, 12, v179
	v_cmp_eq_u32_e32 vcc, s8, v0
	s_cbranch_vccz .Ltk_p2s_52
	v_and_b32_e32 v8, 0xfff, v179
	v_lshl_add_u32 v8, v8, 2, v29
	v_cndmask_b32_e32 v8, v75, v8, vcc
	ds_add_u32 v8, v20
.Ltk_p2s_52:
	v_lshrrev_b32_e32 v1, 12, v163
	v_cmp_eq_u32_e32 vcc, s9, v1
	s_cbranch_vccz .Ltk_p2s_53
	v_and_b32_e32 v9, 0xfff, v163
	v_lshl_add_u32 v9, v9, 2, v30
	v_cndmask_b32_e32 v9, v75, v9, vcc
	ds_add_u32 v9, v20
.Ltk_p2s_53:
	v_lshrrev_b32_e32 v4, 12, v142
	v_cmp_eq_u32_e32 vcc, s10, v4
	s_cbranch_vccz .Ltk_p2s_54
	v_and_b32_e32 v10, 0xfff, v142
	v_lshl_add_u32 v10, v10, 2, v31
	v_cndmask_b32_e32 v10, v75, v10, vcc
	ds_add_u32 v10, v20
.Ltk_p2s_54:
	v_lshrrev_b32_e32 v5, 12, v113
	v_cmp_eq_u32_e32 vcc, s11, v5
	s_cbranch_vccz .Ltk_p2s_55
	v_and_b32_e32 v11, 0xfff, v113
	v_lshl_add_u32 v11, v11, 2, v32
	v_cndmask_b32_e32 v11, v75, v11, vcc
	ds_add_u32 v11, v20
.Ltk_p2s_55:
	s_add_i32 s28, s28, 8
	s_cmp_gt_u32 s28, s3
	s_cbranch_scc1 .Ltk_p2_done_11
	v_lshrrev_b32_e32 v0, 12, v178
	v_cmp_eq_u32_e32 vcc, s8, v0
	s_cbranch_vccz .Ltk_p2s_56
	v_and_b32_e32 v8, 0xfff, v178
	v_lshl_add_u32 v8, v8, 2, v29
	v_cndmask_b32_e32 v8, v75, v8, vcc
	ds_add_u32 v8, v20
; DI void topk_job(const Params& p, int b, int t0, char* lds) {
;     ...
; #pragma unroll
;       for (int i = 0; i < 17; ++i) {
; #pragma unroll
;         for (int q = 0; q < 4; ++q) {
;           const unsigned u = sc[i][q];
;           bool part; unsigned bin;
;           if (pass == 0) { part = (u != 0u); bin = (u >> 22) + (lane & 3) * 1024; }
;           else if (pass == 1) { part = (u != 0u) && ((u >> 22) == pref[q]) && !few[q]; bin = ((u >> 12) & 1023u) + (lane & 3) * 1024; }
;           else { part = (u != 0u) && ((u >> 12) == pref[q]) && !few[q]; bin = u & 4095u; }
;           if (part) atomicAdd(hist + q * 4096 + bin, 1u);
;         }
;       }
.Ltk_p2s_56:
	v_lshrrev_b32_e32 v1, 12, v162
	v_cmp_eq_u32_e32 vcc, s9, v1
	s_cbranch_vccz .Ltk_p2s_57
	v_and_b32_e32 v9, 0xfff, v162
	v_lshl_add_u32 v9, v9, 2, v30
	v_cndmask_b32_e32 v9, v75, v9, vcc
	ds_add_u32 v9, v20
.Ltk_p2s_57:
	v_lshrrev_b32_e32 v4, 12, v141
	v_cmp_eq_u32_e32 vcc, s10, v4
	s_cbranch_vccz .Ltk_p2s_58
	v_and_b32_e32 v10, 0xfff, v141
	v_lshl_add_u32 v10, v10, 2, v31
	v_cndmask_b32_e32 v10, v75, v10, vcc
	ds_add_u32 v10, v20
.Ltk_p2s_58:
	v_lshrrev_b32_e32 v5, 12, v111
	v_cmp_eq_u32_e32 vcc, s11, v5
	s_cbranch_vccz .Ltk_p2s_59
	v_and_b32_e32 v11, 0xfff, v111
	v_lshl_add_u32 v11, v11, 2, v32
	v_cndmask_b32_e32 v11, v75, v11, vcc
	ds_add_u32 v11, v20
.Ltk_p2s_59:
	s_add_i32 s28, s28, 8
	s_cmp_gt_u32 s28, s3
	s_cbranch_scc1 .Ltk_p2_done_11
	v_lshrrev_b32_e32 v0, 12, v177
	v_cmp_eq_u32_e32 vcc, s8, v0
	s_cbranch_vccz .Ltk_p2s_60
	v_and_b32_e32 v8, 0xfff, v177
	v_lshl_add_u32 v8, v8, 2, v29
	v_cndmask_b32_e32 v8, v75, v8, vcc
	ds_add_u32 v8, v20
.Ltk_p2s_60:
	v_lshrrev_b32_e32 v1, 12, v160
	v_cmp_eq_u32_e32 vcc, s9, v1
	s_cbranch_vccz .Ltk_p2s_61
	v_and_b32_e32 v9, 0xfff, v160
	v_lshl_add_u32 v9, v9, 2, v30
	v_cndmask_b32_e32 v9, v75, v9, vcc
	ds_add_u32 v9, v20
.Ltk_p2s_61:
	v_lshrrev_b32_e32 v4, 12, v140
	v_cmp_eq_u32_e32 vcc, s10, v4
	s_cbranch_vccz .Ltk_p2s_62
	v_and_b32_e32 v10, 0xfff, v140
	v_lshl_add_u32 v10, v10, 2, v31
	v_cndmask_b32_e32 v10, v75, v10, vcc
	ds_add_u32 v10, v20
.Ltk_p2s_62:
	v_lshrrev_b32_e32 v5, 12, v109
	v_cmp_eq_u32_e32 vcc, s11, v5
	s_cbranch_vccz .Ltk_p2s_63
	v_and_b32_e32 v11, 0xfff, v109
	v_lshl_add_u32 v11, v11, 2, v32
	v_cndmask_b32_e32 v11, v75, v11, vcc
	ds_add_u32 v11, v20
.Ltk_p2s_63:
	s_add_i32 s28, s28, 8
	s_cmp_gt_u32 s28, s3
	s_cbranch_scc1 .Ltk_p2_done_11
	v_lshrrev_b32_e32 v0, 12, v176
	v_cmp_eq_u32_e32 vcc, s8, v0
	s_cbranch_vccz .Ltk_p2s_64
	v_and_b32_e32 v8, 0xfff, v176
	v_lshl_add_u32 v8, v8, 2, v29
	v_cndmask_b32_e32 v8, v75, v8, vcc
	ds_add_u32 v8, v20
.Ltk_p2s_64:
	v_lshrrev_b32_e32 v1, 12, v151
	v_cmp_eq_u32_e32 vcc, s9, v1
	s_cbranch_vccz .Ltk_p2s_65
	v_and_b32_e32 v9, 0xfff, v151
	v_lshl_add_u32 v9, v9, 2, v30
	v_cndmask_b32_e32 v9, v75, v9, vcc
	ds_add_u32 v9, v20
.Ltk_p2s_65:
	v_lshrrev_b32_e32 v4, 12, v139
	v_cmp_eq_u32_e32 vcc, s10, v4
	s_cbranch_vccz .Ltk_p2s_66
	v_and_b32_e32 v10, 0xfff, v139
	v_lshl_add_u32 v10, v10, 2, v31
	v_cndmask_b32_e32 v10, v75, v10, vcc
	ds_add_u32 v10, v20
.Ltk_p2s_66:
	v_lshrrev_b32_e32 v5, 12, v107
	v_cmp_eq_u32_e32 vcc, s11, v5
	s_cbranch_vccz .Ltk_p2s_67
	v_and_b32_e32 v11, 0xfff, v107
	v_lshl_add_u32 v11, v11, 2, v32
	v_cndmask_b32_e32 v11, v75, v11, vcc
	ds_add_u32 v11, v20
.Ltk_p2s_67:
	s_add_i32 s28, s28, 8
	s_cmp_gt_u32 s28, s3
	s_cbranch_scc1 .Ltk_p2_done_11
	v_lshrrev_b32_e32 v0, 12, v174
	v_cmp_eq_u32_e32 vcc, s8, v0
	s_cbranch_vccz .Ltk_p2s_68
	v_and_b32_e32 v8, 0xfff, v174
	v_lshl_add_u32 v8, v8, 2, v29
	v_cndmask_b32_e32 v8, v75, v8, vcc
	ds_add_u32 v8, v20
.Ltk_p2s_68:
	v_lshrrev_b32_e32 v1, 12, v148
	v_cmp_eq_u32_e32 vcc, s9, v1
	s_cbranch_vccz .Ltk_p2s_69
	v_and_b32_e32 v9, 0xfff, v148
	v_lshl_add_u32 v9, v9, 2, v30
	v_cndmask_b32_e32 v9, v75, v9, vcc
	ds_add_u32 v9, v20
.Ltk_p2s_69:
	v_lshrrev_b32_e32 v4, 12, v131
	v_cmp_eq_u32_e32 vcc, s10, v4
	s_cbranch_vccz .Ltk_p2s_70
	v_and_b32_e32 v10, 0xfff, v131
	v_lshl_add_u32 v10, v10, 2, v31
	v_cndmask_b32_e32 v10, v75, v10, vcc
	ds_add_u32 v10, v20
.Ltk_p2s_70:
	v_lshrrev_b32_e32 v5, 12, v105
	v_cmp_eq_u32_e32 vcc, s11, v5
	s_cbranch_vccz .Ltk_p2s_71
	v_and_b32_e32 v11, 0xfff, v105
	v_lshl_add_u32 v11, v11, 2, v32
	v_cndmask_b32_e32 v11, v75, v11, vcc
	ds_add_u32 v11, v20
.Ltk_p2s_71:
	s_add_i32 s28, s28, 8
	s_cmp_gt_u32 s28, s3
	s_cbranch_scc1 .Ltk_p2_done_11
	v_lshrrev_b32_e32 v0, 12, v169
	v_cmp_eq_u32_e32 vcc, s8, v0
	s_cbranch_vccz .Ltk_p2s_72
	v_and_b32_e32 v8, 0xfff, v169
	v_lshl_add_u32 v8, v8, 2, v29
	v_cndmask_b32_e32 v8, v75, v8, vcc
	ds_add_u32 v8, v20
.Ltk_p2s_72:
	v_lshrrev_b32_e32 v1, 12, v144
	v_cmp_eq_u32_e32 vcc, s9, v1
	s_cbranch_vccz .Ltk_p2s_73
	v_and_b32_e32 v9, 0xfff, v144
	v_lshl_add_u32 v9, v9, 2, v30
	v_cndmask_b32_e32 v9, v75, v9, vcc
	ds_add_u32 v9, v20
.Ltk_p2s_73:
	v_lshrrev_b32_e32 v4, 12, v117
	v_cmp_eq_u32_e32 vcc, s10, v4
	s_cbranch_vccz .Ltk_p2s_74
	v_and_b32_e32 v10, 0xfff, v117
	v_lshl_add_u32 v10, v10, 2, v31
	v_cndmask_b32_e32 v10, v75, v10, vcc
	ds_add_u32 v10, v20
.Ltk_p2s_74:
	v_lshrrev_b32_e32 v5, 12, v103
	v_cmp_eq_u32_e32 vcc, s11, v5
	s_cbranch_vccz .Ltk_p2s_75
	v_and_b32_e32 v11, 0xfff, v103
	v_lshl_add_u32 v11, v11, 2, v32
	v_cndmask_b32_e32 v11, v75, v11, vcc
	ds_add_u32 v11, v20
.Ltk_p2s_75:
	s_add_i32 s28, s28, 8
	s_cmp_gt_u32 s28, s3
	s_cbranch_scc1 .Ltk_p2_done_11
	v_lshrrev_b32_e32 v0, 12, v19
	v_cmp_eq_u32_e32 vcc, s8, v0
	s_cbranch_vccz .Ltk_p2s_76
	v_and_b32_e32 v8, 0xfff, v19
	v_lshl_add_u32 v8, v8, 2, v29
	v_cndmask_b32_e32 v8, v75, v8, vcc
	ds_add_u32 v8, v20
.Ltk_p2s_76:
	v_lshrrev_b32_e32 v1, 12, v18
	v_cmp_eq_u32_e32 vcc, s9, v1
	s_cbranch_vccz .Ltk_p2s_77
	v_and_b32_e32 v9, 0xfff, v18
	v_lshl_add_u32 v9, v9, 2, v30
	v_cndmask_b32_e32 v9, v75, v9, vcc
	ds_add_u32 v9, v20
.Ltk_p2s_77:
	v_lshrrev_b32_e32 v4, 12, v17
	v_cmp_eq_u32_e32 vcc, s10, v4
	s_cbranch_vccz .Ltk_p2s_78
	v_and_b32_e32 v10, 0xfff, v17
	v_lshl_add_u32 v10, v10, 2, v31
	v_cndmask_b32_e32 v10, v75, v10, vcc
	ds_add_u32 v10, v20
.Ltk_p2s_78:
	v_lshrrev_b32_e32 v5, 12, v16
	v_cmp_eq_u32_e32 vcc, s11, v5
	s_cbranch_vccz .Ltk_p2s_79
	v_and_b32_e32 v11, 0xfff, v16
	v_lshl_add_u32 v11, v11, 2, v32
	v_cndmask_b32_e32 v11, v75, v11, vcc
	ds_add_u32 v11, v20
; DI void topk_job(const Params& p, int b, int t0, char* lds) {
;     ...
;       __syncthreads();
;       if (w < 4) {
;         const int q = w;
;         const unsigned* hq = hist + q * 4096;
;         const int need = 256 - chi[q];
;         int G = 0;
;         if (pass < 2) {
; #pragma unroll
;           for (int rep = 0; rep < 4; ++rep)
; #pragma unroll
;             for (int j = 0; j < 16; ++j) G += (int)hq[rep * 1024 + 16 * lane + ((j + lane) & 15)];
;         } else {
; #pragma unroll 8
;           for (int j = 0; j < 64; ++j) G += (int)hq[64 * lane + ((j + lane) & 63)];
;         }
.Ltk_p2s_79:
.Ltk_p2_done_11:
	s_waitcnt lgkmcnt(0)
	s_barrier
	s_cmp_gt_u32 s2, 3
	s_cbranch_scc1 .Ltk_scan_end_80
	s_lshl_b32 s84, s2, 14
	s_add_i32 s84, s84, 0x4000
	s_cmp_eq_u32 s56, 1
	s_cbranch_scc1 .Ltk_scan_few_81
	v_lshlrev_b32_e32 v33, 8, v101
	v_add_u32_e32 v33, s84, v33
	v_mov_b32_e32 v66, 0
	v_add_u32_e32 v0, 0, v101
	v_and_b32_e32 v0, 63, v0
	v_lshl_add_u32 v34, v0, 2, v33
	ds_read_b32 v50, v34
	v_add_u32_e32 v0, 1, v101
	v_and_b32_e32 v0, 63, v0
	v_lshl_add_u32 v35, v0, 2, v33
	ds_read_b32 v51, v35
	v_add_u32_e32 v0, 2, v101
	v_and_b32_e32 v0, 63, v0
	v_lshl_add_u32 v36, v0, 2, v33
	ds_read_b32 v52, v36
	v_add_u32_e32 v0, 3, v101
	v_and_b32_e32 v0, 63, v0
	v_lshl_add_u32 v37, v0, 2, v33
	ds_read_b32 v53, v37
	v_add_u32_e32 v0, 4, v101
	v_and_b32_e32 v0, 63, v0
	v_lshl_add_u32 v38, v0, 2, v33
	ds_read_b32 v54, v38
	v_add_u32_e32 v0, 5, v101
	v_and_b32_e32 v0, 63, v0
	v_lshl_add_u32 v39, v0, 2, v33
	ds_read_b32 v55, v39
	v_add_u32_e32 v0, 6, v101
	v_and_b32_e32 v0, 63, v0
	v_lshl_add_u32 v40, v0, 2, v33
	ds_read_b32 v56, v40
	v_add_u32_e32 v0, 7, v101
	v_and_b32_e32 v0, 63, v0
	v_lshl_add_u32 v41, v0, 2, v33
	ds_read_b32 v57, v41
	v_add_u32_e32 v0, 8, v101
	v_and_b32_e32 v0, 63, v0
	v_lshl_add_u32 v42, v0, 2, v33
	ds_read_b32 v58, v42
	v_add_u32_e32 v0, 9, v101
	v_and_b32_e32 v0, 63, v0
	v_lshl_add_u32 v43, v0, 2, v33
	ds_read_b32 v59, v43
	v_add_u32_e32 v0, 10, v101
	v_and_b32_e32 v0, 63, v0
	v_lshl_add_u32 v44, v0, 2, v33
	ds_read_b32 v60, v44
	v_add_u32_e32 v0, 11, v101
	v_and_b32_e32 v0, 63, v0
	v_lshl_add_u32 v45, v0, 2, v33
	ds_read_b32 v61, v45
	v_add_u32_e32 v0, 12, v101
	v_and_b32_e32 v0, 63, v0
	v_lshl_add_u32 v46, v0, 2, v33
	ds_read_b32 v62, v46
	v_add_u32_e32 v0, 13, v101
	v_and_b32_e32 v0, 63, v0
	v_lshl_add_u32 v47, v0, 2, v33
	ds_read_b32 v63, v47
	v_add_u32_e32 v0, 14, v101
	v_and_b32_e32 v0, 63, v0
	v_lshl_add_u32 v48, v0, 2, v33
	ds_read_b32 v64, v48
	v_add_u32_e32 v0, 15, v101
	v_and_b32_e32 v0, 63, v0
	v_lshl_add_u32 v49, v0, 2, v33
	ds_read_b32 v65, v49
	s_waitcnt lgkmcnt(0)
	v_add3_u32 v66, v66, v50, v51
	v_add3_u32 v66, v66, v52, v53
	v_add3_u32 v66, v66, v54, v55
	v_add3_u32 v66, v66, v56, v57
	v_add3_u32 v66, v66, v58, v59
	v_add3_u32 v66, v66, v60, v61
	v_add3_u32 v66, v66, v62, v63
	v_add3_u32 v66, v66, v64, v65
	v_add_u32_e32 v0, 16, v101
	v_and_b32_e32 v0, 63, v0
	v_lshl_add_u32 v34, v0, 2, v33
	ds_read_b32 v50, v34
	v_add_u32_e32 v0, 17, v101
	v_and_b32_e32 v0, 63, v0
	v_lshl_add_u32 v35, v0, 2, v33
	ds_read_b32 v51, v35
	v_add_u32_e32 v0, 18, v101
	v_and_b32_e32 v0, 63, v0
	v_lshl_add_u32 v36, v0, 2, v33
	ds_read_b32 v52, v36
	v_add_u32_e32 v0, 19, v101
	v_and_b32_e32 v0, 63, v0
	v_lshl_add_u32 v37, v0, 2, v33
	ds_read_b32 v53, v37
	v_add_u32_e32 v0, 20, v101
	v_and_b32_e32 v0, 63, v0
	v_lshl_add_u32 v38, v0, 2, v33
	ds_read_b32 v54, v38
	v_add_u32_e32 v0, 21, v101
	v_and_b32_e32 v0, 63, v0
	v_lshl_add_u32 v39, v0, 2, v33
	ds_read_b32 v55, v39
	v_add_u32_e32 v0, 22, v101
	v_and_b32_e32 v0, 63, v0
	v_lshl_add_u32 v40, v0, 2, v33
	ds_read_b32 v56, v40
	v_add_u32_e32 v0, 23, v101
	v_and_b32_e32 v0, 63, v0
	v_lshl_add_u32 v41, v0, 2, v33
	ds_read_b32 v57, v41
	v_add_u32_e32 v0, 24, v101
	v_and_b32_e32 v0, 63, v0
	v_lshl_add_u32 v42, v0, 2, v33
	ds_read_b32 v58, v42
	v_add_u32_e32 v0, 25, v101
	v_and_b32_e32 v0, 63, v0
	v_lshl_add_u32 v43, v0, 2, v33
	ds_read_b32 v59, v43
	v_add_u32_e32 v0, 26, v101
	v_and_b32_e32 v0, 63, v0
	v_lshl_add_u32 v44, v0, 2, v33
	ds_read_b32 v60, v44
	v_add_u32_e32 v0, 27, v101
	v_and_b32_e32 v0, 63, v0
	v_lshl_add_u32 v45, v0, 2, v33
	ds_read_b32 v61, v45
	v_add_u32_e32 v0, 28, v101
	v_and_b32_e32 v0, 63, v0
	v_lshl_add_u32 v46, v0, 2, v33
	ds_read_b32 v62, v46
	v_add_u32_e32 v0, 29, v101
	v_and_b32_e32 v0, 63, v0
	v_lshl_add_u32 v47, v0, 2, v33
	ds_read_b32 v63, v47
	v_add_u32_e32 v0, 30, v101
	v_and_b32_e32 v0, 63, v0
	v_lshl_add_u32 v48, v0, 2, v33
	ds_read_b32 v64, v48
	v_add_u32_e32 v0, 31, v101
	v_and_b32_e32 v0, 63, v0
	v_lshl_add_u32 v49, v0, 2, v33
	ds_read_b32 v65, v49
	s_waitcnt lgkmcnt(0)
; template <int CTRL> DI int dpp_movi(int v) { return __builtin_amdgcn_mov_dpp(v, CTRL, 0xF, 0xF, true); }
; template <bool UP> DI int wscan(int v, int lane, int& total) {
;   int acc = v, tot = v, o;
;   o = dpp_movi<0xB1>(tot);  if (((lane & 1) != 0) == UP) acc += o;  tot += o;
;   o = dpp_movi<0x4E>(tot);  if (((lane & 2) != 0) == UP) acc += o;  tot += o;
;   o = dpp_movi<0x141>(tot); if (((lane & 4) != 0) == UP) acc += o;  tot += o;
;   o = dpp_movi<0x140>(tot); if (((lane & 8) != 0) == UP) acc += o;  tot += o;
;   u32x2 r = __builtin_amdgcn_permlane16_swap((unsigned)tot, (unsigned)tot, false, false);
;   o = (int)((lane & 16) ? r[0] : r[1]); if (((lane & 16) != 0) == UP) acc += o; tot += o;
;   r = __builtin_amdgcn_permlane32_swap((unsigned)tot, (unsigned)tot, false, false);
;   o = (int)((lane & 32) ? r[0] : r[1]); if (((lane & 32) != 0) == UP) acc += o; tot += o;
;   total = tot;
;   return acc;
; }
; DI void topk_job(const Params& p, int b, int t0, char* lds) {
;     ...
;           for (int j = 0; j < 64; ++j) G += (int)hq[64 * lane + ((j + lane) & 63)];
;         }
;         int S = G;
;         { int tt; S = wscan<false>(S, lane, tt); }
;         const unsigned long long mk = __ballot(S >= need);
;         int B = 0, cg2 = 0, fw = 0, nbin = 0;
;         if (mk == 0ull) {
;           fw = 1;
;         } else {
;           const int ks = 63 - __clzll(mk);
;           const int above = (ks < 63) ? __builtin_amdgcn_readlane(S, ks + 1) : 0;
	v_add3_u32 v66, v66, v50, v51
	v_add3_u32 v66, v66, v52, v53
	v_add3_u32 v66, v66, v54, v55
	v_add3_u32 v66, v66, v56, v57
	v_add3_u32 v66, v66, v58, v59
	v_add3_u32 v66, v66, v60, v61
	v_add3_u32 v66, v66, v62, v63
	v_add3_u32 v66, v66, v64, v65
	v_add_u32_e32 v0, 32, v101
	v_and_b32_e32 v0, 63, v0
	v_lshl_add_u32 v34, v0, 2, v33
	ds_read_b32 v50, v34
	v_add_u32_e32 v0, 33, v101
	v_and_b32_e32 v0, 63, v0
	v_lshl_add_u32 v35, v0, 2, v33
	ds_read_b32 v51, v35
	v_add_u32_e32 v0, 34, v101
	v_and_b32_e32 v0, 63, v0
	v_lshl_add_u32 v36, v0, 2, v33
	ds_read_b32 v52, v36
	v_add_u32_e32 v0, 35, v101
	v_and_b32_e32 v0, 63, v0
	v_lshl_add_u32 v37, v0, 2, v33
	ds_read_b32 v53, v37
	v_add_u32_e32 v0, 36, v101
	v_and_b32_e32 v0, 63, v0
	v_lshl_add_u32 v38, v0, 2, v33
	ds_read_b32 v54, v38
	v_add_u32_e32 v0, 37, v101
	v_and_b32_e32 v0, 63, v0
	v_lshl_add_u32 v39, v0, 2, v33
	ds_read_b32 v55, v39
	v_add_u32_e32 v0, 38, v101
	v_and_b32_e32 v0, 63, v0
	v_lshl_add_u32 v40, v0, 2, v33
	ds_read_b32 v56, v40
	v_add_u32_e32 v0, 39, v101
	v_and_b32_e32 v0, 63, v0
	v_lshl_add_u32 v41, v0, 2, v33
	ds_read_b32 v57, v41
	v_add_u32_e32 v0, 40, v101
	v_and_b32_e32 v0, 63, v0
	v_lshl_add_u32 v42, v0, 2, v33
	ds_read_b32 v58, v42
	v_add_u32_e32 v0, 41, v101
	v_and_b32_e32 v0, 63, v0
	v_lshl_add_u32 v43, v0, 2, v33
	ds_read_b32 v59, v43
	v_add_u32_e32 v0, 42, v101
	v_and_b32_e32 v0, 63, v0
	v_lshl_add_u32 v44, v0, 2, v33
	ds_read_b32 v60, v44
	v_add_u32_e32 v0, 43, v101
	v_and_b32_e32 v0, 63, v0
	v_lshl_add_u32 v45, v0, 2, v33
	ds_read_b32 v61, v45
	v_add_u32_e32 v0, 44, v101
	v_and_b32_e32 v0, 63, v0
	v_lshl_add_u32 v46, v0, 2, v33
	ds_read_b32 v62, v46
	v_add_u32_e32 v0, 45, v101
	v_and_b32_e32 v0, 63, v0
	v_lshl_add_u32 v47, v0, 2, v33
	ds_read_b32 v63, v47
	v_add_u32_e32 v0, 46, v101
	v_and_b32_e32 v0, 63, v0
	v_lshl_add_u32 v48, v0, 2, v33
	ds_read_b32 v64, v48
	v_add_u32_e32 v0, 47, v101
	v_and_b32_e32 v0, 63, v0
	v_lshl_add_u32 v49, v0, 2, v33
	ds_read_b32 v65, v49
	s_waitcnt lgkmcnt(0)
	v_add3_u32 v66, v66, v50, v51
	v_add3_u32 v66, v66, v52, v53
	v_add3_u32 v66, v66, v54, v55
	v_add3_u32 v66, v66, v56, v57
	v_add3_u32 v66, v66, v58, v59
	v_add3_u32 v66, v66, v60, v61
	v_add3_u32 v66, v66, v62, v63
	v_add3_u32 v66, v66, v64, v65
	v_add_u32_e32 v0, 48, v101
	v_and_b32_e32 v0, 63, v0
	v_lshl_add_u32 v34, v0, 2, v33
	ds_read_b32 v50, v34
	v_add_u32_e32 v0, 49, v101
	v_and_b32_e32 v0, 63, v0
	v_lshl_add_u32 v35, v0, 2, v33
	ds_read_b32 v51, v35
	v_add_u32_e32 v0, 50, v101
	v_and_b32_e32 v0, 63, v0
	v_lshl_add_u32 v36, v0, 2, v33
	ds_read_b32 v52, v36
	v_add_u32_e32 v0, 51, v101
	v_and_b32_e32 v0, 63, v0
	v_lshl_add_u32 v37, v0, 2, v33
	ds_read_b32 v53, v37
	v_add_u32_e32 v0, 52, v101
	v_and_b32_e32 v0, 63, v0
	v_lshl_add_u32 v38, v0, 2, v33
	ds_read_b32 v54, v38
	v_add_u32_e32 v0, 53, v101
	v_and_b32_e32 v0, 63, v0
	v_lshl_add_u32 v39, v0, 2, v33
	ds_read_b32 v55, v39
	v_add_u32_e32 v0, 54, v101
	v_and_b32_e32 v0, 63, v0
	v_lshl_add_u32 v40, v0, 2, v33
	ds_read_b32 v56, v40
	v_add_u32_e32 v0, 55, v101
	v_and_b32_e32 v0, 63, v0
	v_lshl_add_u32 v41, v0, 2, v33
	ds_read_b32 v57, v41
	v_add_u32_e32 v0, 56, v101
	v_and_b32_e32 v0, 63, v0
	v_lshl_add_u32 v42, v0, 2, v33
	ds_read_b32 v58, v42
	v_add_u32_e32 v0, 57, v101
	v_and_b32_e32 v0, 63, v0
	v_lshl_add_u32 v43, v0, 2, v33
	ds_read_b32 v59, v43
	v_add_u32_e32 v0, 58, v101
	v_and_b32_e32 v0, 63, v0
	v_lshl_add_u32 v44, v0, 2, v33
	ds_read_b32 v60, v44
	v_add_u32_e32 v0, 59, v101
	v_and_b32_e32 v0, 63, v0
	v_lshl_add_u32 v45, v0, 2, v33
	ds_read_b32 v61, v45
	v_add_u32_e32 v0, 60, v101
	v_and_b32_e32 v0, 63, v0
	v_lshl_add_u32 v46, v0, 2, v33
	ds_read_b32 v62, v46
	v_add_u32_e32 v0, 61, v101
	v_and_b32_e32 v0, 63, v0
	v_lshl_add_u32 v47, v0, 2, v33
	ds_read_b32 v63, v47
	v_add_u32_e32 v0, 62, v101
	v_and_b32_e32 v0, 63, v0
	v_lshl_add_u32 v48, v0, 2, v33
	ds_read_b32 v64, v48
	v_add_u32_e32 v0, 63, v101
	v_and_b32_e32 v0, 63, v0
	v_lshl_add_u32 v49, v0, 2, v33
	ds_read_b32 v65, v49
	s_waitcnt lgkmcnt(0)
	v_add3_u32 v66, v66, v50, v51
	v_add3_u32 v66, v66, v52, v53
	v_add3_u32 v66, v66, v54, v55
	v_add3_u32 v66, v66, v56, v57
	v_add3_u32 v66, v66, v58, v59
	v_add3_u32 v66, v66, v60, v61
	v_add3_u32 v66, v66, v62, v63
	v_add3_u32 v66, v66, v64, v65
	s_nop 1
	v_add_u32_dpp v68, v66, v66 quad_perm:[1,0,3,2] row_mask:0xf bank_mask:0xf bound_ctrl:1
	v_cndmask_b32_e64 v67, v66, v68, s[16:17]
	s_nop 1
	v_mov_b32_dpp v69, v68 quad_perm:[2,3,0,1] row_mask:0xf bank_mask:0xf bound_ctrl:1
	v_add_u32_e32 v68, v68, v69
	v_cndmask_b32_e64 v70, 0, v69, s[18:19]
	v_add_u32_e32 v67, v67, v70
	s_nop 0
	v_mov_b32_dpp v69, v68 row_half_mirror row_mask:0xf bank_mask:0xf bound_ctrl:1
	v_add_u32_e32 v68, v68, v69
	v_cndmask_b32_e64 v70, 0, v69, s[20:21]
	v_add_u32_e32 v67, v67, v70
	s_nop 0
	v_mov_b32_dpp v69, v68 row_mirror row_mask:0xf bank_mask:0xf bound_ctrl:1
	v_add_u32_e32 v68, v68, v69
	v_cndmask_b32_e64 v70, 0, v69, s[22:23]
	v_add_u32_e32 v67, v67, v70
	v_mov_b32_e32 v71, v68
	v_mov_b32_e32 v72, v68
	s_nop 1
	v_permlane16_swap_b32_e32 v71, v72
	v_cndmask_b32_e64 v69, v71, v72, s[24:25]
	v_add_u32_e32 v68, v68, v69
	v_cndmask_b32_e64 v70, 0, v69, s[24:25]
	v_add_u32_e32 v67, v67, v70
	v_mov_b32_e32 v71, v68
	v_mov_b32_e32 v72, v68
	s_nop 1
	v_permlane32_swap_b32_e32 v71, v72
	v_cndmask_b32_e64 v69, v71, v72, s[26:27]
	v_cndmask_b32_e64 v70, 0, v69, s[26:27]
	v_add_u32_e32 v67, v67, v70
	v_cmp_le_u32_e64 s[30:31], s85, v67
	s_cmp_eq_u64 s[30:31], 0
	s_cbranch_scc1 .Ltk_scan_few_81
	s_flbit_i32_b64 s88, s[30:31]
	s_sub_i32 s88, 63, s88
	s_mov_b32 s90, 0
	s_cmp_eq_u32 s88, 63
	s_cbranch_scc1 .Ltk_noabove_83
	s_add_i32 s4, s88, 1
	s_nop 0
	v_readlane_b32 s90, v67, s4

; DI void topk_job(const Params& p, int b, int t0, char* lds) {
;     ...
;   const unsigned long long lt = (1ull << lane) - 1ull;
; #pragma unroll
;   for (int i = 0; i < 17; ++i) {
;     const int c = 1 + w + 8 * i;
;     if (c <= cmax) {
;       const int key = c * 64 + lane;
; #pragma unroll
;       for (int q = 0; q < 4; ++q) {
;         u16* out = p.IDX + (size_t)(b * PP + t0 + q) * 256;
;         const bool gt = sc[i][q] > T[q];
;         const bool eq = (sc[i][q] == T[q]) && (T[q] != 0u);
;         const unsigned long long m1 = __ballot(gt), m2 = __ballot(eq);
;         if ((m1 | m2) != 0ull) {
;           const unsigned bb = baseb[q * 132 + c];
;           if (gt) out[(int)(bb & 0xffffu) + __popcll(m1 & lt)] = (u16)key;
;           if (eq) { const int pos = ng[q] + (int)(bb >> 16) + __popcll(m2 & lt); if (pos < 256) out[pos] = (u16)key; }
;         }
;       }
;     }
;   }
.Ltk_pfx_end_85:
	s_waitcnt lgkmcnt(0)
	s_barrier
	ds_read_b128 v[4:7], v3 offset:256
	s_movk_i32 s84, 0x100
	s_waitcnt lgkmcnt(0)
	v_readfirstlane_b32 s48, v4
	v_readfirstlane_b32 s49, v5
	v_readfirstlane_b32 s50, v6
	v_readfirstlane_b32 s51, v7
	s_add_i32 s28, s2, 1
	s_cmp_gt_u32 s28, s3
	s_cbranch_scc1 .Ltk_scat_done_87
	s_lshl_b32 s29, s28, 2
	s_addk_i32 s29, 0x1000
	v_mov_b32_e32 v11, s29
	ds_read_b32 v12, v11
	ds_read_b32 v13, v11 offset:544
	ds_read_b32 v14, v11 offset:1088
	ds_read_b32 v15, v11 offset:1632
	v_lshl_add_u32 v6, s28, 6, v101
	v_cmp_lt_u32_e64 s[68:69], s12, v208
	v_cmp_eq_u32_e32 vcc, s12, v208
	s_waitcnt lgkmcnt(3)
	v_and_b32_e32 v0, 0xffff, v12
	v_mbcnt_lo_u32_b32 v7, s68, 0
	v_mbcnt_hi_u32_b32 v7, s69, v7
	v_add_lshl_u32 v0, v0, v7, 1
	v_cndmask_b32_e64 v0, v76, v0, s[68:69]
	ds_write_b16 v0, v6 offset:8192
	s_cbranch_vccz .Ltk_noeq_88
	s_cmp_eq_u32 s12, 0
	s_cbranch_scc1 .Ltk_noeq_88
	v_mbcnt_lo_u32_b32 v8, vcc_lo, 0
	v_mbcnt_hi_u32_b32 v8, vcc_hi, v8
	v_lshrrev_b32_e32 v1, 16, v12
	v_add3_u32 v1, v1, v8, s48
	v_cmp_gt_u32_e64 s[72:73], s84, v1
	v_lshlrev_b32_e32 v1, 1, v1
	s_and_b64 s[72:73], s[72:73], vcc
	s_nop 0
	v_cndmask_b32_e64 v1, v76, v1, s[72:73]
	ds_write_b16 v1, v6 offset:8192
.Ltk_noeq_88:
	v_cmp_lt_u32_e64 s[68:69], s13, v175
	v_cmp_eq_u32_e32 vcc, s13, v175
	s_waitcnt lgkmcnt(2)
	v_and_b32_e32 v0, 0xffff, v13
	v_mbcnt_lo_u32_b32 v7, s68, 0
	v_mbcnt_hi_u32_b32 v7, s69, v7
	v_add_lshl_u32 v0, v0, v7, 1
	v_cndmask_b32_e64 v0, v76, v0, s[68:69]
	ds_write_b16 v0, v6 offset:8704
	s_cbranch_vccz .Ltk_noeq_89
	s_cmp_eq_u32 s13, 0
	s_cbranch_scc1 .Ltk_noeq_89
	v_mbcnt_lo_u32_b32 v8, vcc_lo, 0
	v_mbcnt_hi_u32_b32 v8, vcc_hi, v8
	v_lshrrev_b32_e32 v1, 16, v13
	v_add3_u32 v1, v1, v8, s49
	v_cmp_gt_u32_e64 s[72:73], s84, v1
	v_lshlrev_b32_e32 v1, 1, v1
	s_and_b64 s[72:73], s[72:73], vcc
	s_nop 0
	v_cndmask_b32_e64 v1, v76, v1, s[72:73]
	ds_write_b16 v1, v6 offset:8704
.Ltk_noeq_89:
	v_cmp_lt_u32_e64 s[68:69], s14, v161
	v_cmp_eq_u32_e32 vcc, s14, v161
	s_waitcnt lgkmcnt(1)
	v_and_b32_e32 v0, 0xffff, v14
	v_mbcnt_lo_u32_b32 v7, s68, 0
	v_mbcnt_hi_u32_b32 v7, s69, v7
	v_add_lshl_u32 v0, v0, v7, 1
	v_cndmask_b32_e64 v0, v76, v0, s[68:69]
	ds_write_b16 v0, v6 offset:9216
	s_cbranch_vccz .Ltk_noeq_90
	s_cmp_eq_u32 s14, 0
	s_cbranch_scc1 .Ltk_noeq_90
	v_mbcnt_lo_u32_b32 v8, vcc_lo, 0
	v_mbcnt_hi_u32_b32 v8, vcc_hi, v8
	v_lshrrev_b32_e32 v1, 16, v14
	v_add3_u32 v1, v1, v8, s50
	v_cmp_gt_u32_e64 s[72:73], s84, v1
	v_lshlrev_b32_e32 v1, 1, v1
	s_and_b64 s[72:73], s[72:73], vcc
	s_nop 0
	v_cndmask_b32_e64 v1, v76, v1, s[72:73]
	ds_write_b16 v1, v6 offset:9216
.Ltk_noeq_90:
	v_cmp_lt_u32_e64 s[68:69], s15, v138
	v_cmp_eq_u32_e32 vcc, s15, v138
	s_waitcnt lgkmcnt(0)
	v_and_b32_e32 v0, 0xffff, v15
	v_mbcnt_lo_u32_b32 v7, s68, 0
	v_mbcnt_hi_u32_b32 v7, s69, v7
	v_add_lshl_u32 v0, v0, v7, 1
	v_cndmask_b32_e64 v0, v76, v0, s[68:69]
	ds_write_b16 v0, v6 offset:9728
	s_cbranch_vccz .Ltk_noeq_91
	s_cmp_eq_u32 s15, 0
	s_cbranch_scc1 .Ltk_noeq_91
	v_mbcnt_lo_u32_b32 v8, vcc_lo, 0
	v_mbcnt_hi_u32_b32 v8, vcc_hi, v8
	v_lshrrev_b32_e32 v1, 16, v15
	v_add3_u32 v1, v1, v8, s51
	v_cmp_gt_u32_e64 s[72:73], s84, v1
	v_lshlrev_b32_e32 v1, 1, v1
	s_and_b64 s[72:73], s[72:73], vcc
	s_nop 0
	v_cndmask_b32_e64 v1, v76, v1, s[72:73]
	ds_write_b16 v1, v6 offset:9728
.Ltk_noeq_91:
	s_add_i32 s28, s28, 8
	s_cmp_gt_u32 s28, s3
	s_cbranch_scc1 .Ltk_scat_done_87
	s_lshl_b32 s29, s28, 2
	s_addk_i32 s29, 0x1000
	v_mov_b32_e32 v11, s29
	ds_read_b32 v12, v11
	ds_read_b32 v13, v11 offset:544
	ds_read_b32 v14, v11 offset:1088
	ds_read_b32 v15, v11 offset:1632
	v_lshl_add_u32 v6, s28, 6, v101
	v_cmp_lt_u32_e64 s[68:69], s12, v207
	v_cmp_eq_u32_e32 vcc, s12, v207
	s_waitcnt lgkmcnt(3)
	v_and_b32_e32 v0, 0xffff, v12
	v_mbcnt_lo_u32_b32 v7, s68, 0
	v_mbcnt_hi_u32_b32 v7, s69, v7
	v_add_lshl_u32 v0, v0, v7, 1
	v_cndmask_b32_e64 v0, v76, v0, s[68:69]
	ds_write_b16 v0, v6 offset:8192
	s_cbranch_vccz .Ltk_noeq_92
	s_cmp_eq_u32 s12, 0
	s_cbranch_scc1 .Ltk_noeq_92
	v_mbcnt_lo_u32_b32 v8, vcc_lo, 0
	v_mbcnt_hi_u32_b32 v8, vcc_hi, v8
	v_lshrrev_b32_e32 v1, 16, v12
	v_add3_u32 v1, v1, v8, s48
	v_cmp_gt_u32_e64 s[72:73], s84, v1
	v_lshlrev_b32_e32 v1, 1, v1
	s_and_b64 s[72:73], s[72:73], vcc
	s_nop 0
	v_cndmask_b32_e64 v1, v76, v1, s[72:73]
	ds_write_b16 v1, v6 offset:8192
.Ltk_noeq_92:
	v_cmp_lt_u32_e64 s[68:69], s13, v173
	v_cmp_eq_u32_e32 vcc, s13, v173
	s_waitcnt lgkmcnt(2)
	v_and_b32_e32 v0, 0xffff, v13
	v_mbcnt_lo_u32_b32 v7, s68, 0
	v_mbcnt_hi_u32_b32 v7, s69, v7
	v_add_lshl_u32 v0, v0, v7, 1
	v_cndmask_b32_e64 v0, v76, v0, s[68:69]
	ds_write_b16 v0, v6 offset:8704
	s_cbranch_vccz .Ltk_noeq_93
	s_cmp_eq_u32 s13, 0
	s_cbranch_scc1 .Ltk_noeq_93
	v_mbcnt_lo_u32_b32 v8, vcc_lo, 0
	v_mbcnt_hi_u32_b32 v8, vcc_hi, v8
	v_lshrrev_b32_e32 v1, 16, v13
	v_add3_u32 v1, v1, v8, s49
	v_cmp_gt_u32_e64 s[72:73], s84, v1
	v_lshlrev_b32_e32 v1, 1, v1
	s_and_b64 s[72:73], s[72:73], vcc
	s_nop 0
	v_cndmask_b32_e64 v1, v76, v1, s[72:73]
	ds_write_b16 v1, v6 offset:8704
.Ltk_noeq_93:
	v_cmp_lt_u32_e64 s[68:69], s14, v159
	v_cmp_eq_u32_e32 vcc, s14, v159
	s_waitcnt lgkmcnt(1)
	v_and_b32_e32 v0, 0xffff, v14
	v_mbcnt_lo_u32_b32 v7, s68, 0
	v_mbcnt_hi_u32_b32 v7, s69, v7
	v_add_lshl_u32 v0, v0, v7, 1
	v_cndmask_b32_e64 v0, v76, v0, s[68:69]
	ds_write_b16 v0, v6 offset:9216
	s_cbranch_vccz .Ltk_noeq_94
	s_cmp_eq_u32 s14, 0
	s_cbranch_scc1 .Ltk_noeq_94
	v_mbcnt_lo_u32_b32 v8, vcc_lo, 0
	v_mbcnt_hi_u32_b32 v8, vcc_hi, v8
	v_lshrrev_b32_e32 v1, 16, v14
	v_add3_u32 v1, v1, v8, s50
	v_cmp_gt_u32_e64 s[72:73], s84, v1
	v_lshlrev_b32_e32 v1, 1, v1
	s_and_b64 s[72:73], s[72:73], vcc
	s_nop 0
	v_cndmask_b32_e64 v1, v76, v1, s[72:73]
	ds_write_b16 v1, v6 offset:9216
; DI void topk_job(const Params& p, int b, int t0, char* lds) {
;     ...
;   const unsigned long long lt = (1ull << lane) - 1ull;
; #pragma unroll
;   for (int i = 0; i < 17; ++i) {
;     const int c = 1 + w + 8 * i;
;     if (c <= cmax) {
;       const int key = c * 64 + lane;
; #pragma unroll
;       for (int q = 0; q < 4; ++q) {
;         u16* out = p.IDX + (size_t)(b * PP + t0 + q) * 256;
;         const bool gt = sc[i][q] > T[q];
;         const bool eq = (sc[i][q] == T[q]) && (T[q] != 0u);
;         const unsigned long long m1 = __ballot(gt), m2 = __ballot(eq);
;         if ((m1 | m2) != 0ull) {
;           const unsigned bb = baseb[q * 132 + c];
;           if (gt) out[(int)(bb & 0xffffu) + __popcll(m1 & lt)] = (u16)key;
;           if (eq) { const int pos = ng[q] + (int)(bb >> 16) + __popcll(m2 & lt); if (pos < 256) out[pos] = (u16)key; }
;         }
;       }
;     }
;   }
.Ltk_noeq_94:
	v_cmp_lt_u32_e64 s[68:69], s15, v135
	v_cmp_eq_u32_e32 vcc, s15, v135
	s_waitcnt lgkmcnt(0)
	v_and_b32_e32 v0, 0xffff, v15
	v_mbcnt_lo_u32_b32 v7, s68, 0
	v_mbcnt_hi_u32_b32 v7, s69, v7
	v_add_lshl_u32 v0, v0, v7, 1
	v_cndmask_b32_e64 v0, v76, v0, s[68:69]
	ds_write_b16 v0, v6 offset:9728
	s_cbranch_vccz .Ltk_noeq_95
	s_cmp_eq_u32 s15, 0
	s_cbranch_scc1 .Ltk_noeq_95
	v_mbcnt_lo_u32_b32 v8, vcc_lo, 0
	v_mbcnt_hi_u32_b32 v8, vcc_hi, v8
	v_lshrrev_b32_e32 v1, 16, v15
	v_add3_u32 v1, v1, v8, s51
	v_cmp_gt_u32_e64 s[72:73], s84, v1
	v_lshlrev_b32_e32 v1, 1, v1
	s_and_b64 s[72:73], s[72:73], vcc
	s_nop 0
	v_cndmask_b32_e64 v1, v76, v1, s[72:73]
	ds_write_b16 v1, v6 offset:9728
.Ltk_noeq_95:
	s_add_i32 s28, s28, 8
	s_cmp_gt_u32 s28, s3
	s_cbranch_scc1 .Ltk_scat_done_87
	s_lshl_b32 s29, s28, 2
	s_addk_i32 s29, 0x1000
	v_mov_b32_e32 v11, s29
	ds_read_b32 v12, v11
	ds_read_b32 v13, v11 offset:544
	ds_read_b32 v14, v11 offset:1088
	ds_read_b32 v15, v11 offset:1632
	v_lshl_add_u32 v6, s28, 6, v101
	v_cmp_lt_u32_e64 s[68:69], s12, v187
	v_cmp_eq_u32_e32 vcc, s12, v187
	s_waitcnt lgkmcnt(3)
	v_and_b32_e32 v0, 0xffff, v12
	v_mbcnt_lo_u32_b32 v7, s68, 0
	v_mbcnt_hi_u32_b32 v7, s69, v7
	v_add_lshl_u32 v0, v0, v7, 1
	v_cndmask_b32_e64 v0, v76, v0, s[68:69]
	ds_write_b16 v0, v6 offset:8192
	s_cbranch_vccz .Ltk_noeq_96
	s_cmp_eq_u32 s12, 0
	s_cbranch_scc1 .Ltk_noeq_96
	v_mbcnt_lo_u32_b32 v8, vcc_lo, 0
	v_mbcnt_hi_u32_b32 v8, vcc_hi, v8
	v_lshrrev_b32_e32 v1, 16, v12
	v_add3_u32 v1, v1, v8, s48
	v_cmp_gt_u32_e64 s[72:73], s84, v1
	v_lshlrev_b32_e32 v1, 1, v1
	s_and_b64 s[72:73], s[72:73], vcc
	s_nop 0
	v_cndmask_b32_e64 v1, v76, v1, s[72:73]
	ds_write_b16 v1, v6 offset:8192
.Ltk_noeq_96:
	v_cmp_lt_u32_e64 s[68:69], s13, v172
	v_cmp_eq_u32_e32 vcc, s13, v172
	s_waitcnt lgkmcnt(2)
	v_and_b32_e32 v0, 0xffff, v13
	v_mbcnt_lo_u32_b32 v7, s68, 0
	v_mbcnt_hi_u32_b32 v7, s69, v7
	v_add_lshl_u32 v0, v0, v7, 1
	v_cndmask_b32_e64 v0, v76, v0, s[68:69]
	ds_write_b16 v0, v6 offset:8704
	s_cbranch_vccz .Ltk_noeq_97
	s_cmp_eq_u32 s13, 0
	s_cbranch_scc1 .Ltk_noeq_97
	v_mbcnt_lo_u32_b32 v8, vcc_lo, 0
	v_mbcnt_hi_u32_b32 v8, vcc_hi, v8
	v_lshrrev_b32_e32 v1, 16, v13
	v_add3_u32 v1, v1, v8, s49
	v_cmp_gt_u32_e64 s[72:73], s84, v1
	v_lshlrev_b32_e32 v1, 1, v1
	s_and_b64 s[72:73], s[72:73], vcc
	s_nop 0
	v_cndmask_b32_e64 v1, v76, v1, s[72:73]
	ds_write_b16 v1, v6 offset:8704
.Ltk_noeq_97:
	v_cmp_lt_u32_e64 s[68:69], s14, v158
	v_cmp_eq_u32_e32 vcc, s14, v158
	s_waitcnt lgkmcnt(1)
	v_and_b32_e32 v0, 0xffff, v14
	v_mbcnt_lo_u32_b32 v7, s68, 0
	v_mbcnt_hi_u32_b32 v7, s69, v7
	v_add_lshl_u32 v0, v0, v7, 1
	v_cndmask_b32_e64 v0, v76, v0, s[68:69]
	ds_write_b16 v0, v6 offset:9216
	s_cbranch_vccz .Ltk_noeq_98
	s_cmp_eq_u32 s14, 0
	s_cbranch_scc1 .Ltk_noeq_98
	v_mbcnt_lo_u32_b32 v8, vcc_lo, 0
	v_mbcnt_hi_u32_b32 v8, vcc_hi, v8
	v_lshrrev_b32_e32 v1, 16, v14
	v_add3_u32 v1, v1, v8, s50
	v_cmp_gt_u32_e64 s[72:73], s84, v1
	v_lshlrev_b32_e32 v1, 1, v1
	s_and_b64 s[72:73], s[72:73], vcc
	s_nop 0
	v_cndmask_b32_e64 v1, v76, v1, s[72:73]
	ds_write_b16 v1, v6 offset:9216
.Ltk_noeq_98:
	v_cmp_lt_u32_e64 s[68:69], s15, v133
	v_cmp_eq_u32_e32 vcc, s15, v133
	s_waitcnt lgkmcnt(0)
	v_and_b32_e32 v0, 0xffff, v15
	v_mbcnt_lo_u32_b32 v7, s68, 0
	v_mbcnt_hi_u32_b32 v7, s69, v7
	v_add_lshl_u32 v0, v0, v7, 1
	v_cndmask_b32_e64 v0, v76, v0, s[68:69]
	ds_write_b16 v0, v6 offset:9728
	s_cbranch_vccz .Ltk_noeq_99
	s_cmp_eq_u32 s15, 0
	s_cbranch_scc1 .Ltk_noeq_99
	v_mbcnt_lo_u32_b32 v8, vcc_lo, 0
	v_mbcnt_hi_u32_b32 v8, vcc_hi, v8
	v_lshrrev_b32_e32 v1, 16, v15
	v_add3_u32 v1, v1, v8, s51
	v_cmp_gt_u32_e64 s[72:73], s84, v1
	v_lshlrev_b32_e32 v1, 1, v1
	s_and_b64 s[72:73], s[72:73], vcc
	s_nop 0
	v_cndmask_b32_e64 v1, v76, v1, s[72:73]
	ds_write_b16 v1, v6 offset:9728
.Ltk_noeq_99:
	s_add_i32 s28, s28, 8
	s_cmp_gt_u32 s28, s3
	s_cbranch_scc1 .Ltk_scat_done_87
	s_lshl_b32 s29, s28, 2
	s_addk_i32 s29, 0x1000
	v_mov_b32_e32 v11, s29
	ds_read_b32 v12, v11
	ds_read_b32 v13, v11 offset:544
	ds_read_b32 v14, v11 offset:1088
	ds_read_b32 v15, v11 offset:1632
	v_lshl_add_u32 v6, s28, 6, v101
	v_cmp_lt_u32_e64 s[68:69], s12, v186
	v_cmp_eq_u32_e32 vcc, s12, v186
	s_waitcnt lgkmcnt(3)
	v_and_b32_e32 v0, 0xffff, v12
	v_mbcnt_lo_u32_b32 v7, s68, 0
	v_mbcnt_hi_u32_b32 v7, s69, v7
	v_add_lshl_u32 v0, v0, v7, 1
	v_cndmask_b32_e64 v0, v76, v0, s[68:69]
	ds_write_b16 v0, v6 offset:8192
	s_cbranch_vccz .Ltk_noeq_100
	s_cmp_eq_u32 s12, 0
	s_cbranch_scc1 .Ltk_noeq_100
	v_mbcnt_lo_u32_b32 v8, vcc_lo, 0
	v_mbcnt_hi_u32_b32 v8, vcc_hi, v8
	v_lshrrev_b32_e32 v1, 16, v12
	v_add3_u32 v1, v1, v8, s48
	v_cmp_gt_u32_e64 s[72:73], s84, v1
	v_lshlrev_b32_e32 v1, 1, v1
	s_and_b64 s[72:73], s[72:73], vcc
	s_nop 0
	v_cndmask_b32_e64 v1, v76, v1, s[72:73]
	ds_write_b16 v1, v6 offset:8192
.Ltk_noeq_100:
	v_cmp_lt_u32_e64 s[68:69], s13, v171
	v_cmp_eq_u32_e32 vcc, s13, v171
	s_waitcnt lgkmcnt(2)
	v_and_b32_e32 v0, 0xffff, v13
	v_mbcnt_lo_u32_b32 v7, s68, 0
	v_mbcnt_hi_u32_b32 v7, s69, v7
	v_add_lshl_u32 v0, v0, v7, 1
	v_cndmask_b32_e64 v0, v76, v0, s[68:69]
	ds_write_b16 v0, v6 offset:8704
	s_cbranch_vccz .Ltk_noeq_101
	s_cmp_eq_u32 s13, 0
	s_cbranch_scc1 .Ltk_noeq_101
	v_mbcnt_lo_u32_b32 v8, vcc_lo, 0
	v_mbcnt_hi_u32_b32 v8, vcc_hi, v8
	v_lshrrev_b32_e32 v1, 16, v13
	v_add3_u32 v1, v1, v8, s49
	v_cmp_gt_u32_e64 s[72:73], s84, v1
	v_lshlrev_b32_e32 v1, 1, v1
	s_and_b64 s[72:73], s[72:73], vcc
	s_nop 0
	v_cndmask_b32_e64 v1, v76, v1, s[72:73]
	ds_write_b16 v1, v6 offset:8704
; DI void topk_job(const Params& p, int b, int t0, char* lds) {
;     ...
;   const unsigned long long lt = (1ull << lane) - 1ull;
; #pragma unroll
;   for (int i = 0; i < 17; ++i) {
;     const int c = 1 + w + 8 * i;
;     if (c <= cmax) {
;       const int key = c * 64 + lane;
; #pragma unroll
;       for (int q = 0; q < 4; ++q) {
;         u16* out = p.IDX + (size_t)(b * PP + t0 + q) * 256;
;         const bool gt = sc[i][q] > T[q];
;         const bool eq = (sc[i][q] == T[q]) && (T[q] != 0u);
;         const unsigned long long m1 = __ballot(gt), m2 = __ballot(eq);
;         if ((m1 | m2) != 0ull) {
;           const unsigned bb = baseb[q * 132 + c];
;           if (gt) out[(int)(bb & 0xffffu) + __popcll(m1 & lt)] = (u16)key;
;           if (eq) { const int pos = ng[q] + (int)(bb >> 16) + __popcll(m2 & lt); if (pos < 256) out[pos] = (u16)key; }
;         }
;       }
;     }
;   }
.Ltk_noeq_101:
	v_cmp_lt_u32_e64 s[68:69], s14, v153
	v_cmp_eq_u32_e32 vcc, s14, v153
	s_waitcnt lgkmcnt(1)
	v_and_b32_e32 v0, 0xffff, v14
	v_mbcnt_lo_u32_b32 v7, s68, 0
	v_mbcnt_hi_u32_b32 v7, s69, v7
	v_add_lshl_u32 v0, v0, v7, 1
	v_cndmask_b32_e64 v0, v76, v0, s[68:69]
	ds_write_b16 v0, v6 offset:9216
	s_cbranch_vccz .Ltk_noeq_102
	s_cmp_eq_u32 s14, 0
	s_cbranch_scc1 .Ltk_noeq_102
	v_mbcnt_lo_u32_b32 v8, vcc_lo, 0
	v_mbcnt_hi_u32_b32 v8, vcc_hi, v8
	v_lshrrev_b32_e32 v1, 16, v14
	v_add3_u32 v1, v1, v8, s50
	v_cmp_gt_u32_e64 s[72:73], s84, v1
	v_lshlrev_b32_e32 v1, 1, v1
	s_and_b64 s[72:73], s[72:73], vcc
	s_nop 0
	v_cndmask_b32_e64 v1, v76, v1, s[72:73]
	ds_write_b16 v1, v6 offset:9216
.Ltk_noeq_102:
	v_cmp_lt_u32_e64 s[68:69], s15, v129
	v_cmp_eq_u32_e32 vcc, s15, v129
	s_waitcnt lgkmcnt(0)
	v_and_b32_e32 v0, 0xffff, v15
	v_mbcnt_lo_u32_b32 v7, s68, 0
	v_mbcnt_hi_u32_b32 v7, s69, v7
	v_add_lshl_u32 v0, v0, v7, 1
	v_cndmask_b32_e64 v0, v76, v0, s[68:69]
	ds_write_b16 v0, v6 offset:9728
	s_cbranch_vccz .Ltk_noeq_103
	s_cmp_eq_u32 s15, 0
	s_cbranch_scc1 .Ltk_noeq_103
	v_mbcnt_lo_u32_b32 v8, vcc_lo, 0
	v_mbcnt_hi_u32_b32 v8, vcc_hi, v8
	v_lshrrev_b32_e32 v1, 16, v15
	v_add3_u32 v1, v1, v8, s51
	v_cmp_gt_u32_e64 s[72:73], s84, v1
	v_lshlrev_b32_e32 v1, 1, v1
	s_and_b64 s[72:73], s[72:73], vcc
	s_nop 0
	v_cndmask_b32_e64 v1, v76, v1, s[72:73]
	ds_write_b16 v1, v6 offset:9728
.Ltk_noeq_103:
	s_add_i32 s28, s28, 8
	s_cmp_gt_u32 s28, s3
	s_cbranch_scc1 .Ltk_scat_done_87
	s_lshl_b32 s29, s28, 2
	s_addk_i32 s29, 0x1000
	v_mov_b32_e32 v11, s29
	ds_read_b32 v12, v11
	ds_read_b32 v13, v11 offset:544
	ds_read_b32 v14, v11 offset:1088
	ds_read_b32 v15, v11 offset:1632
	v_lshl_add_u32 v6, s28, 6, v101
	v_cmp_lt_u32_e64 s[68:69], s12, v185
	v_cmp_eq_u32_e32 vcc, s12, v185
	s_waitcnt lgkmcnt(3)
	v_and_b32_e32 v0, 0xffff, v12
	v_mbcnt_lo_u32_b32 v7, s68, 0
	v_mbcnt_hi_u32_b32 v7, s69, v7
	v_add_lshl_u32 v0, v0, v7, 1
	v_cndmask_b32_e64 v0, v76, v0, s[68:69]
	ds_write_b16 v0, v6 offset:8192
	s_cbranch_vccz .Ltk_noeq_104
	s_cmp_eq_u32 s12, 0
	s_cbranch_scc1 .Ltk_noeq_104
	v_mbcnt_lo_u32_b32 v8, vcc_lo, 0
	v_mbcnt_hi_u32_b32 v8, vcc_hi, v8
	v_lshrrev_b32_e32 v1, 16, v12
	v_add3_u32 v1, v1, v8, s48
	v_cmp_gt_u32_e64 s[72:73], s84, v1
	v_lshlrev_b32_e32 v1, 1, v1
	s_and_b64 s[72:73], s[72:73], vcc
	s_nop 0
	v_cndmask_b32_e64 v1, v76, v1, s[72:73]
	ds_write_b16 v1, v6 offset:8192
.Ltk_noeq_104:
	v_cmp_lt_u32_e64 s[68:69], s13, v170
	v_cmp_eq_u32_e32 vcc, s13, v170
	s_waitcnt lgkmcnt(2)
	v_and_b32_e32 v0, 0xffff, v13
	v_mbcnt_lo_u32_b32 v7, s68, 0
	v_mbcnt_hi_u32_b32 v7, s69, v7
	v_add_lshl_u32 v0, v0, v7, 1
	v_cndmask_b32_e64 v0, v76, v0, s[68:69]
	ds_write_b16 v0, v6 offset:8704
	s_cbranch_vccz .Ltk_noeq_105
	s_cmp_eq_u32 s13, 0
	s_cbranch_scc1 .Ltk_noeq_105
	v_mbcnt_lo_u32_b32 v8, vcc_lo, 0
	v_mbcnt_hi_u32_b32 v8, vcc_hi, v8
	v_lshrrev_b32_e32 v1, 16, v13
	v_add3_u32 v1, v1, v8, s49
	v_cmp_gt_u32_e64 s[72:73], s84, v1
	v_lshlrev_b32_e32 v1, 1, v1
	s_and_b64 s[72:73], s[72:73], vcc
	s_nop 0
	v_cndmask_b32_e64 v1, v76, v1, s[72:73]
	ds_write_b16 v1, v6 offset:8704
.Ltk_noeq_105:
	v_cmp_lt_u32_e64 s[68:69], s14, v150
	v_cmp_eq_u32_e32 vcc, s14, v150
	s_waitcnt lgkmcnt(1)
	v_and_b32_e32 v0, 0xffff, v14
	v_mbcnt_lo_u32_b32 v7, s68, 0
	v_mbcnt_hi_u32_b32 v7, s69, v7
	v_add_lshl_u32 v0, v0, v7, 1
	v_cndmask_b32_e64 v0, v76, v0, s[68:69]
	ds_write_b16 v0, v6 offset:9216
	s_cbranch_vccz .Ltk_noeq_106
	s_cmp_eq_u32 s14, 0
	s_cbranch_scc1 .Ltk_noeq_106
	v_mbcnt_lo_u32_b32 v8, vcc_lo, 0
	v_mbcnt_hi_u32_b32 v8, vcc_hi, v8
	v_lshrrev_b32_e32 v1, 16, v14
	v_add3_u32 v1, v1, v8, s50
	v_cmp_gt_u32_e64 s[72:73], s84, v1
	v_lshlrev_b32_e32 v1, 1, v1
	s_and_b64 s[72:73], s[72:73], vcc
	s_nop 0
	v_cndmask_b32_e64 v1, v76, v1, s[72:73]
	ds_write_b16 v1, v6 offset:9216
.Ltk_noeq_106:
	v_cmp_lt_u32_e64 s[68:69], s15, v127
	v_cmp_eq_u32_e32 vcc, s15, v127
	s_waitcnt lgkmcnt(0)
	v_and_b32_e32 v0, 0xffff, v15
	v_mbcnt_lo_u32_b32 v7, s68, 0
	v_mbcnt_hi_u32_b32 v7, s69, v7
	v_add_lshl_u32 v0, v0, v7, 1
	v_cndmask_b32_e64 v0, v76, v0, s[68:69]
	ds_write_b16 v0, v6 offset:9728
	s_cbranch_vccz .Ltk_noeq_107
	s_cmp_eq_u32 s15, 0
	s_cbranch_scc1 .Ltk_noeq_107
	v_mbcnt_lo_u32_b32 v8, vcc_lo, 0
	v_mbcnt_hi_u32_b32 v8, vcc_hi, v8
	v_lshrrev_b32_e32 v1, 16, v15
	v_add3_u32 v1, v1, v8, s51
	v_cmp_gt_u32_e64 s[72:73], s84, v1
	v_lshlrev_b32_e32 v1, 1, v1
	s_and_b64 s[72:73], s[72:73], vcc
	s_nop 0
	v_cndmask_b32_e64 v1, v76, v1, s[72:73]
	ds_write_b16 v1, v6 offset:9728
.Ltk_noeq_107:
	s_add_i32 s28, s28, 8
	s_cmp_gt_u32 s28, s3
	s_cbranch_scc1 .Ltk_scat_done_87
	s_lshl_b32 s29, s28, 2
	s_addk_i32 s29, 0x1000
	v_mov_b32_e32 v11, s29
	ds_read_b32 v12, v11
	ds_read_b32 v13, v11 offset:544
	ds_read_b32 v14, v11 offset:1088
	ds_read_b32 v15, v11 offset:1632
	v_lshl_add_u32 v6, s28, 6, v101
	v_cmp_lt_u32_e64 s[68:69], s12, v184
	v_cmp_eq_u32_e32 vcc, s12, v184
	s_waitcnt lgkmcnt(3)
	v_and_b32_e32 v0, 0xffff, v12
	v_mbcnt_lo_u32_b32 v7, s68, 0
	v_mbcnt_hi_u32_b32 v7, s69, v7
	v_add_lshl_u32 v0, v0, v7, 1
	v_cndmask_b32_e64 v0, v76, v0, s[68:69]
	ds_write_b16 v0, v6 offset:8192
	s_cbranch_vccz .Ltk_noeq_108
	s_cmp_eq_u32 s12, 0
	s_cbranch_scc1 .Ltk_noeq_108
	v_mbcnt_lo_u32_b32 v8, vcc_lo, 0
	v_mbcnt_hi_u32_b32 v8, vcc_hi, v8
	v_lshrrev_b32_e32 v1, 16, v12
	v_add3_u32 v1, v1, v8, s48
	v_cmp_gt_u32_e64 s[72:73], s84, v1
	v_lshlrev_b32_e32 v1, 1, v1
	s_and_b64 s[72:73], s[72:73], vcc
	s_nop 0
	v_cndmask_b32_e64 v1, v76, v1, s[72:73]
	ds_write_b16 v1, v6 offset:8192
; DI void topk_job(const Params& p, int b, int t0, char* lds) {
;     ...
;   const unsigned long long lt = (1ull << lane) - 1ull;
; #pragma unroll
;   for (int i = 0; i < 17; ++i) {
;     const int c = 1 + w + 8 * i;
;     if (c <= cmax) {
;       const int key = c * 64 + lane;
; #pragma unroll
;       for (int q = 0; q < 4; ++q) {
;         u16* out = p.IDX + (size_t)(b * PP + t0 + q) * 256;
;         const bool gt = sc[i][q] > T[q];
;         const bool eq = (sc[i][q] == T[q]) && (T[q] != 0u);
;         const unsigned long long m1 = __ballot(gt), m2 = __ballot(eq);
;         if ((m1 | m2) != 0ull) {
;           const unsigned bb = baseb[q * 132 + c];
;           if (gt) out[(int)(bb & 0xffffu) + __popcll(m1 & lt)] = (u16)key;
;           if (eq) { const int pos = ng[q] + (int)(bb >> 16) + __popcll(m2 & lt); if (pos < 256) out[pos] = (u16)key; }
;         }
;       }
;     }
;   }
.Ltk_noeq_108:
	v_cmp_lt_u32_e64 s[68:69], s13, v168
	v_cmp_eq_u32_e32 vcc, s13, v168
	s_waitcnt lgkmcnt(2)
	v_and_b32_e32 v0, 0xffff, v13
	v_mbcnt_lo_u32_b32 v7, s68, 0
	v_mbcnt_hi_u32_b32 v7, s69, v7
	v_add_lshl_u32 v0, v0, v7, 1
	v_cndmask_b32_e64 v0, v76, v0, s[68:69]
	ds_write_b16 v0, v6 offset:8704
	s_cbranch_vccz .Ltk_noeq_109
	s_cmp_eq_u32 s13, 0
	s_cbranch_scc1 .Ltk_noeq_109
	v_mbcnt_lo_u32_b32 v8, vcc_lo, 0
	v_mbcnt_hi_u32_b32 v8, vcc_hi, v8
	v_lshrrev_b32_e32 v1, 16, v13
	v_add3_u32 v1, v1, v8, s49
	v_cmp_gt_u32_e64 s[72:73], s84, v1
	v_lshlrev_b32_e32 v1, 1, v1
	s_and_b64 s[72:73], s[72:73], vcc
	s_nop 0
	v_cndmask_b32_e64 v1, v76, v1, s[72:73]
	ds_write_b16 v1, v6 offset:8704
.Ltk_noeq_109:
	v_cmp_lt_u32_e64 s[68:69], s14, v149
	v_cmp_eq_u32_e32 vcc, s14, v149
	s_waitcnt lgkmcnt(1)
	v_and_b32_e32 v0, 0xffff, v14
	v_mbcnt_lo_u32_b32 v7, s68, 0
	v_mbcnt_hi_u32_b32 v7, s69, v7
	v_add_lshl_u32 v0, v0, v7, 1
	v_cndmask_b32_e64 v0, v76, v0, s[68:69]
	ds_write_b16 v0, v6 offset:9216
	s_cbranch_vccz .Ltk_noeq_110
	s_cmp_eq_u32 s14, 0
	s_cbranch_scc1 .Ltk_noeq_110
	v_mbcnt_lo_u32_b32 v8, vcc_lo, 0
	v_mbcnt_hi_u32_b32 v8, vcc_hi, v8
	v_lshrrev_b32_e32 v1, 16, v14
	v_add3_u32 v1, v1, v8, s50
	v_cmp_gt_u32_e64 s[72:73], s84, v1
	v_lshlrev_b32_e32 v1, 1, v1
	s_and_b64 s[72:73], s[72:73], vcc
	s_nop 0
	v_cndmask_b32_e64 v1, v76, v1, s[72:73]
	ds_write_b16 v1, v6 offset:9216
.Ltk_noeq_110:
	v_cmp_lt_u32_e64 s[68:69], s15, v125
	v_cmp_eq_u32_e32 vcc, s15, v125
	s_waitcnt lgkmcnt(0)
	v_and_b32_e32 v0, 0xffff, v15
	v_mbcnt_lo_u32_b32 v7, s68, 0
	v_mbcnt_hi_u32_b32 v7, s69, v7
	v_add_lshl_u32 v0, v0, v7, 1
	v_cndmask_b32_e64 v0, v76, v0, s[68:69]
	ds_write_b16 v0, v6 offset:9728
	s_cbranch_vccz .Ltk_noeq_111
	s_cmp_eq_u32 s15, 0
	s_cbranch_scc1 .Ltk_noeq_111
	v_mbcnt_lo_u32_b32 v8, vcc_lo, 0
	v_mbcnt_hi_u32_b32 v8, vcc_hi, v8
	v_lshrrev_b32_e32 v1, 16, v15
	v_add3_u32 v1, v1, v8, s51
	v_cmp_gt_u32_e64 s[72:73], s84, v1
	v_lshlrev_b32_e32 v1, 1, v1
	s_and_b64 s[72:73], s[72:73], vcc
	s_nop 0
	v_cndmask_b32_e64 v1, v76, v1, s[72:73]
	ds_write_b16 v1, v6 offset:9728
.Ltk_noeq_111:
	s_add_i32 s28, s28, 8
	s_cmp_gt_u32 s28, s3
	s_cbranch_scc1 .Ltk_scat_done_87
	s_lshl_b32 s29, s28, 2
	s_addk_i32 s29, 0x1000
	v_mov_b32_e32 v11, s29
	ds_read_b32 v12, v11
	ds_read_b32 v13, v11 offset:544
	ds_read_b32 v14, v11 offset:1088
	ds_read_b32 v15, v11 offset:1632
	v_lshl_add_u32 v6, s28, 6, v101
	v_cmp_lt_u32_e64 s[68:69], s12, v183
	v_cmp_eq_u32_e32 vcc, s12, v183
	s_waitcnt lgkmcnt(3)
	v_and_b32_e32 v0, 0xffff, v12
	v_mbcnt_lo_u32_b32 v7, s68, 0
	v_mbcnt_hi_u32_b32 v7, s69, v7
	v_add_lshl_u32 v0, v0, v7, 1
	v_cndmask_b32_e64 v0, v76, v0, s[68:69]
	ds_write_b16 v0, v6 offset:8192
	s_cbranch_vccz .Ltk_noeq_112
	s_cmp_eq_u32 s12, 0
	s_cbranch_scc1 .Ltk_noeq_112
	v_mbcnt_lo_u32_b32 v8, vcc_lo, 0
	v_mbcnt_hi_u32_b32 v8, vcc_hi, v8
	v_lshrrev_b32_e32 v1, 16, v12
	v_add3_u32 v1, v1, v8, s48
	v_cmp_gt_u32_e64 s[72:73], s84, v1
	v_lshlrev_b32_e32 v1, 1, v1
	s_and_b64 s[72:73], s[72:73], vcc
	s_nop 0
	v_cndmask_b32_e64 v1, v76, v1, s[72:73]
	ds_write_b16 v1, v6 offset:8192
.Ltk_noeq_112:
	v_cmp_lt_u32_e64 s[68:69], s13, v167
	v_cmp_eq_u32_e32 vcc, s13, v167
	s_waitcnt lgkmcnt(2)
	v_and_b32_e32 v0, 0xffff, v13
	v_mbcnt_lo_u32_b32 v7, s68, 0
	v_mbcnt_hi_u32_b32 v7, s69, v7
	v_add_lshl_u32 v0, v0, v7, 1
	v_cndmask_b32_e64 v0, v76, v0, s[68:69]
	ds_write_b16 v0, v6 offset:8704
	s_cbranch_vccz .Ltk_noeq_113
	s_cmp_eq_u32 s13, 0
	s_cbranch_scc1 .Ltk_noeq_113
	v_mbcnt_lo_u32_b32 v8, vcc_lo, 0
	v_mbcnt_hi_u32_b32 v8, vcc_hi, v8
	v_lshrrev_b32_e32 v1, 16, v13
	v_add3_u32 v1, v1, v8, s49
	v_cmp_gt_u32_e64 s[72:73], s84, v1
	v_lshlrev_b32_e32 v1, 1, v1
	s_and_b64 s[72:73], s[72:73], vcc
	s_nop 0
	v_cndmask_b32_e64 v1, v76, v1, s[72:73]
	ds_write_b16 v1, v6 offset:8704
.Ltk_noeq_113:
	v_cmp_lt_u32_e64 s[68:69], s14, v147
	v_cmp_eq_u32_e32 vcc, s14, v147
	s_waitcnt lgkmcnt(1)
	v_and_b32_e32 v0, 0xffff, v14
	v_mbcnt_lo_u32_b32 v7, s68, 0
	v_mbcnt_hi_u32_b32 v7, s69, v7
	v_add_lshl_u32 v0, v0, v7, 1
	v_cndmask_b32_e64 v0, v76, v0, s[68:69]
	ds_write_b16 v0, v6 offset:9216
	s_cbranch_vccz .Ltk_noeq_114
	s_cmp_eq_u32 s14, 0
	s_cbranch_scc1 .Ltk_noeq_114
	v_mbcnt_lo_u32_b32 v8, vcc_lo, 0
	v_mbcnt_hi_u32_b32 v8, vcc_hi, v8
	v_lshrrev_b32_e32 v1, 16, v14
	v_add3_u32 v1, v1, v8, s50
	v_cmp_gt_u32_e64 s[72:73], s84, v1
	v_lshlrev_b32_e32 v1, 1, v1
	s_and_b64 s[72:73], s[72:73], vcc
	s_nop 0
	v_cndmask_b32_e64 v1, v76, v1, s[72:73]
	ds_write_b16 v1, v6 offset:9216
.Ltk_noeq_114:
	v_cmp_lt_u32_e64 s[68:69], s15, v123
	v_cmp_eq_u32_e32 vcc, s15, v123
	s_waitcnt lgkmcnt(0)
	v_and_b32_e32 v0, 0xffff, v15
	v_mbcnt_lo_u32_b32 v7, s68, 0
	v_mbcnt_hi_u32_b32 v7, s69, v7
	v_add_lshl_u32 v0, v0, v7, 1
	v_cndmask_b32_e64 v0, v76, v0, s[68:69]
	ds_write_b16 v0, v6 offset:9728
	s_cbranch_vccz .Ltk_noeq_115
	s_cmp_eq_u32 s15, 0
	s_cbranch_scc1 .Ltk_noeq_115
	v_mbcnt_lo_u32_b32 v8, vcc_lo, 0
	v_mbcnt_hi_u32_b32 v8, vcc_hi, v8
	v_lshrrev_b32_e32 v1, 16, v15
	v_add3_u32 v1, v1, v8, s51
	v_cmp_gt_u32_e64 s[72:73], s84, v1
	v_lshlrev_b32_e32 v1, 1, v1
	s_and_b64 s[72:73], s[72:73], vcc
	s_nop 0
	v_cndmask_b32_e64 v1, v76, v1, s[72:73]
	ds_write_b16 v1, v6 offset:9728
; DI void topk_job(const Params& p, int b, int t0, char* lds) {
;     ...
;   const unsigned long long lt = (1ull << lane) - 1ull;
; #pragma unroll
;   for (int i = 0; i < 17; ++i) {
;     const int c = 1 + w + 8 * i;
;     if (c <= cmax) {
;       const int key = c * 64 + lane;
; #pragma unroll
;       for (int q = 0; q < 4; ++q) {
;         u16* out = p.IDX + (size_t)(b * PP + t0 + q) * 256;
;         const bool gt = sc[i][q] > T[q];
;         const bool eq = (sc[i][q] == T[q]) && (T[q] != 0u);
;         const unsigned long long m1 = __ballot(gt), m2 = __ballot(eq);
;         if ((m1 | m2) != 0ull) {
;           const unsigned bb = baseb[q * 132 + c];
;           if (gt) out[(int)(bb & 0xffffu) + __popcll(m1 & lt)] = (u16)key;
;           if (eq) { const int pos = ng[q] + (int)(bb >> 16) + __popcll(m2 & lt); if (pos < 256) out[pos] = (u16)key; }
;         }
;       }
;     }
;   }
.Ltk_noeq_115:
	s_add_i32 s28, s28, 8
	s_cmp_gt_u32 s28, s3
	s_cbranch_scc1 .Ltk_scat_done_87
	s_lshl_b32 s29, s28, 2
	s_addk_i32 s29, 0x1000
	v_mov_b32_e32 v11, s29
	ds_read_b32 v12, v11
	ds_read_b32 v13, v11 offset:544
	ds_read_b32 v14, v11 offset:1088
	ds_read_b32 v15, v11 offset:1632
	v_lshl_add_u32 v6, s28, 6, v101
	v_cmp_lt_u32_e64 s[68:69], s12, v182
	v_cmp_eq_u32_e32 vcc, s12, v182
	s_waitcnt lgkmcnt(3)
	v_and_b32_e32 v0, 0xffff, v12
	v_mbcnt_lo_u32_b32 v7, s68, 0
	v_mbcnt_hi_u32_b32 v7, s69, v7
	v_add_lshl_u32 v0, v0, v7, 1
	v_cndmask_b32_e64 v0, v76, v0, s[68:69]
	ds_write_b16 v0, v6 offset:8192
	s_cbranch_vccz .Ltk_noeq_116
	s_cmp_eq_u32 s12, 0
	s_cbranch_scc1 .Ltk_noeq_116
	v_mbcnt_lo_u32_b32 v8, vcc_lo, 0
	v_mbcnt_hi_u32_b32 v8, vcc_hi, v8
	v_lshrrev_b32_e32 v1, 16, v12
	v_add3_u32 v1, v1, v8, s48
	v_cmp_gt_u32_e64 s[72:73], s84, v1
	v_lshlrev_b32_e32 v1, 1, v1
	s_and_b64 s[72:73], s[72:73], vcc
	s_nop 0
	v_cndmask_b32_e64 v1, v76, v1, s[72:73]
	ds_write_b16 v1, v6 offset:8192
.Ltk_noeq_116:
	v_cmp_lt_u32_e64 s[68:69], s13, v166
	v_cmp_eq_u32_e32 vcc, s13, v166
	s_waitcnt lgkmcnt(2)
	v_and_b32_e32 v0, 0xffff, v13
	v_mbcnt_lo_u32_b32 v7, s68, 0
	v_mbcnt_hi_u32_b32 v7, s69, v7
	v_add_lshl_u32 v0, v0, v7, 1
	v_cndmask_b32_e64 v0, v76, v0, s[68:69]
	ds_write_b16 v0, v6 offset:8704
	s_cbranch_vccz .Ltk_noeq_117
	s_cmp_eq_u32 s13, 0
	s_cbranch_scc1 .Ltk_noeq_117
	v_mbcnt_lo_u32_b32 v8, vcc_lo, 0
	v_mbcnt_hi_u32_b32 v8, vcc_hi, v8
	v_lshrrev_b32_e32 v1, 16, v13
	v_add3_u32 v1, v1, v8, s49
	v_cmp_gt_u32_e64 s[72:73], s84, v1
	v_lshlrev_b32_e32 v1, 1, v1
	s_and_b64 s[72:73], s[72:73], vcc
	s_nop 0
	v_cndmask_b32_e64 v1, v76, v1, s[72:73]
	ds_write_b16 v1, v6 offset:8704
.Ltk_noeq_117:
	v_cmp_lt_u32_e64 s[68:69], s14, v146
	v_cmp_eq_u32_e32 vcc, s14, v146
	s_waitcnt lgkmcnt(1)
	v_and_b32_e32 v0, 0xffff, v14
	v_mbcnt_lo_u32_b32 v7, s68, 0
	v_mbcnt_hi_u32_b32 v7, s69, v7
	v_add_lshl_u32 v0, v0, v7, 1
	v_cndmask_b32_e64 v0, v76, v0, s[68:69]
	ds_write_b16 v0, v6 offset:9216
	s_cbranch_vccz .Ltk_noeq_118
	s_cmp_eq_u32 s14, 0
	s_cbranch_scc1 .Ltk_noeq_118
	v_mbcnt_lo_u32_b32 v8, vcc_lo, 0
	v_mbcnt_hi_u32_b32 v8, vcc_hi, v8
	v_lshrrev_b32_e32 v1, 16, v14
	v_add3_u32 v1, v1, v8, s50
	v_cmp_gt_u32_e64 s[72:73], s84, v1
	v_lshlrev_b32_e32 v1, 1, v1
	s_and_b64 s[72:73], s[72:73], vcc
	s_nop 0
	v_cndmask_b32_e64 v1, v76, v1, s[72:73]
	ds_write_b16 v1, v6 offset:9216
.Ltk_noeq_118:
	v_cmp_lt_u32_e64 s[68:69], s15, v121
	v_cmp_eq_u32_e32 vcc, s15, v121
	s_waitcnt lgkmcnt(0)
	v_and_b32_e32 v0, 0xffff, v15
	v_mbcnt_lo_u32_b32 v7, s68, 0
	v_mbcnt_hi_u32_b32 v7, s69, v7
	v_add_lshl_u32 v0, v0, v7, 1
	v_cndmask_b32_e64 v0, v76, v0, s[68:69]
	ds_write_b16 v0, v6 offset:9728
	s_cbranch_vccz .Ltk_noeq_119
	s_cmp_eq_u32 s15, 0
	s_cbranch_scc1 .Ltk_noeq_119
	v_mbcnt_lo_u32_b32 v8, vcc_lo, 0
	v_mbcnt_hi_u32_b32 v8, vcc_hi, v8
	v_lshrrev_b32_e32 v1, 16, v15
	v_add3_u32 v1, v1, v8, s51
	v_cmp_gt_u32_e64 s[72:73], s84, v1
	v_lshlrev_b32_e32 v1, 1, v1
	s_and_b64 s[72:73], s[72:73], vcc
	s_nop 0
	v_cndmask_b32_e64 v1, v76, v1, s[72:73]
	ds_write_b16 v1, v6 offset:9728
.Ltk_noeq_119:
	s_add_i32 s28, s28, 8
	s_cmp_gt_u32 s28, s3
	s_cbranch_scc1 .Ltk_scat_done_87
	s_lshl_b32 s29, s28, 2
	s_addk_i32 s29, 0x1000
	v_mov_b32_e32 v11, s29
	ds_read_b32 v12, v11
	ds_read_b32 v13, v11 offset:544
	ds_read_b32 v14, v11 offset:1088
	ds_read_b32 v15, v11 offset:1632
	v_lshl_add_u32 v6, s28, 6, v101
	v_cmp_lt_u32_e64 s[68:69], s12, v181
	v_cmp_eq_u32_e32 vcc, s12, v181
	s_waitcnt lgkmcnt(3)
	v_and_b32_e32 v0, 0xffff, v12
	v_mbcnt_lo_u32_b32 v7, s68, 0
	v_mbcnt_hi_u32_b32 v7, s69, v7
	v_add_lshl_u32 v0, v0, v7, 1
	v_cndmask_b32_e64 v0, v76, v0, s[68:69]
	ds_write_b16 v0, v6 offset:8192
	s_cbranch_vccz .Ltk_noeq_120
	s_cmp_eq_u32 s12, 0
	s_cbranch_scc1 .Ltk_noeq_120
	v_mbcnt_lo_u32_b32 v8, vcc_lo, 0
	v_mbcnt_hi_u32_b32 v8, vcc_hi, v8
	v_lshrrev_b32_e32 v1, 16, v12
	v_add3_u32 v1, v1, v8, s48
	v_cmp_gt_u32_e64 s[72:73], s84, v1
	v_lshlrev_b32_e32 v1, 1, v1
	s_and_b64 s[72:73], s[72:73], vcc
	s_nop 0
	v_cndmask_b32_e64 v1, v76, v1, s[72:73]
	ds_write_b16 v1, v6 offset:8192
.Ltk_noeq_120:
	v_cmp_lt_u32_e64 s[68:69], s13, v165
	v_cmp_eq_u32_e32 vcc, s13, v165
	s_waitcnt lgkmcnt(2)
	v_and_b32_e32 v0, 0xffff, v13
	v_mbcnt_lo_u32_b32 v7, s68, 0
	v_mbcnt_hi_u32_b32 v7, s69, v7
	v_add_lshl_u32 v0, v0, v7, 1
	v_cndmask_b32_e64 v0, v76, v0, s[68:69]
	ds_write_b16 v0, v6 offset:8704
	s_cbranch_vccz .Ltk_noeq_121
	s_cmp_eq_u32 s13, 0
	s_cbranch_scc1 .Ltk_noeq_121
	v_mbcnt_lo_u32_b32 v8, vcc_lo, 0
	v_mbcnt_hi_u32_b32 v8, vcc_hi, v8
	v_lshrrev_b32_e32 v1, 16, v13
	v_add3_u32 v1, v1, v8, s49
	v_cmp_gt_u32_e64 s[72:73], s84, v1
	v_lshlrev_b32_e32 v1, 1, v1
	s_and_b64 s[72:73], s[72:73], vcc
	s_nop 0
	v_cndmask_b32_e64 v1, v76, v1, s[72:73]
	ds_write_b16 v1, v6 offset:8704
.Ltk_noeq_121:
	v_cmp_lt_u32_e64 s[68:69], s14, v145
	v_cmp_eq_u32_e32 vcc, s14, v145
	s_waitcnt lgkmcnt(1)
	v_and_b32_e32 v0, 0xffff, v14
	v_mbcnt_lo_u32_b32 v7, s68, 0
	v_mbcnt_hi_u32_b32 v7, s69, v7
	v_add_lshl_u32 v0, v0, v7, 1
	v_cndmask_b32_e64 v0, v76, v0, s[68:69]
	ds_write_b16 v0, v6 offset:9216
	s_cbranch_vccz .Ltk_noeq_122
	s_cmp_eq_u32 s14, 0
	s_cbranch_scc1 .Ltk_noeq_122
	v_mbcnt_lo_u32_b32 v8, vcc_lo, 0
	v_mbcnt_hi_u32_b32 v8, vcc_hi, v8
	v_lshrrev_b32_e32 v1, 16, v14
	v_add3_u32 v1, v1, v8, s50
	v_cmp_gt_u32_e64 s[72:73], s84, v1
	v_lshlrev_b32_e32 v1, 1, v1
	s_and_b64 s[72:73], s[72:73], vcc
	s_nop 0
	v_cndmask_b32_e64 v1, v76, v1, s[72:73]
	ds_write_b16 v1, v6 offset:9216
; DI void topk_job(const Params& p, int b, int t0, char* lds) {
;     ...
;   const unsigned long long lt = (1ull << lane) - 1ull;
; #pragma unroll
;   for (int i = 0; i < 17; ++i) {
;     const int c = 1 + w + 8 * i;
;     if (c <= cmax) {
;       const int key = c * 64 + lane;
; #pragma unroll
;       for (int q = 0; q < 4; ++q) {
;         u16* out = p.IDX + (size_t)(b * PP + t0 + q) * 256;
;         const bool gt = sc[i][q] > T[q];
;         const bool eq = (sc[i][q] == T[q]) && (T[q] != 0u);
;         const unsigned long long m1 = __ballot(gt), m2 = __ballot(eq);
;         if ((m1 | m2) != 0ull) {
;           const unsigned bb = baseb[q * 132 + c];
;           if (gt) out[(int)(bb & 0xffffu) + __popcll(m1 & lt)] = (u16)key;
;           if (eq) { const int pos = ng[q] + (int)(bb >> 16) + __popcll(m2 & lt); if (pos < 256) out[pos] = (u16)key; }
;         }
;       }
;     }
;   }
.Ltk_noeq_122:
	v_cmp_lt_u32_e64 s[68:69], s15, v119
	v_cmp_eq_u32_e32 vcc, s15, v119
	s_waitcnt lgkmcnt(0)
	v_and_b32_e32 v0, 0xffff, v15
	v_mbcnt_lo_u32_b32 v7, s68, 0
	v_mbcnt_hi_u32_b32 v7, s69, v7
	v_add_lshl_u32 v0, v0, v7, 1
	v_cndmask_b32_e64 v0, v76, v0, s[68:69]
	ds_write_b16 v0, v6 offset:9728
	s_cbranch_vccz .Ltk_noeq_123
	s_cmp_eq_u32 s15, 0
	s_cbranch_scc1 .Ltk_noeq_123
	v_mbcnt_lo_u32_b32 v8, vcc_lo, 0
	v_mbcnt_hi_u32_b32 v8, vcc_hi, v8
	v_lshrrev_b32_e32 v1, 16, v15
	v_add3_u32 v1, v1, v8, s51
	v_cmp_gt_u32_e64 s[72:73], s84, v1
	v_lshlrev_b32_e32 v1, 1, v1
	s_and_b64 s[72:73], s[72:73], vcc
	s_nop 0
	v_cndmask_b32_e64 v1, v76, v1, s[72:73]
	ds_write_b16 v1, v6 offset:9728
.Ltk_noeq_123:
	s_add_i32 s28, s28, 8
	s_cmp_gt_u32 s28, s3
	s_cbranch_scc1 .Ltk_scat_done_87
	s_lshl_b32 s29, s28, 2
	s_addk_i32 s29, 0x1000
	v_mov_b32_e32 v11, s29
	ds_read_b32 v12, v11
	ds_read_b32 v13, v11 offset:544
	ds_read_b32 v14, v11 offset:1088
	ds_read_b32 v15, v11 offset:1632
	v_lshl_add_u32 v6, s28, 6, v101
	v_cmp_lt_u32_e64 s[68:69], s12, v180
	v_cmp_eq_u32_e32 vcc, s12, v180
	s_waitcnt lgkmcnt(3)
	v_and_b32_e32 v0, 0xffff, v12
	v_mbcnt_lo_u32_b32 v7, s68, 0
	v_mbcnt_hi_u32_b32 v7, s69, v7
	v_add_lshl_u32 v0, v0, v7, 1
	v_cndmask_b32_e64 v0, v76, v0, s[68:69]
	ds_write_b16 v0, v6 offset:8192
	s_cbranch_vccz .Ltk_noeq_124
	s_cmp_eq_u32 s12, 0
	s_cbranch_scc1 .Ltk_noeq_124
	v_mbcnt_lo_u32_b32 v8, vcc_lo, 0
	v_mbcnt_hi_u32_b32 v8, vcc_hi, v8
	v_lshrrev_b32_e32 v1, 16, v12
	v_add3_u32 v1, v1, v8, s48
	v_cmp_gt_u32_e64 s[72:73], s84, v1
	v_lshlrev_b32_e32 v1, 1, v1
	s_and_b64 s[72:73], s[72:73], vcc
	s_nop 0
	v_cndmask_b32_e64 v1, v76, v1, s[72:73]
	ds_write_b16 v1, v6 offset:8192
.Ltk_noeq_124:
	v_cmp_lt_u32_e64 s[68:69], s13, v164
	v_cmp_eq_u32_e32 vcc, s13, v164
	s_waitcnt lgkmcnt(2)
	v_and_b32_e32 v0, 0xffff, v13
	v_mbcnt_lo_u32_b32 v7, s68, 0
	v_mbcnt_hi_u32_b32 v7, s69, v7
	v_add_lshl_u32 v0, v0, v7, 1
	v_cndmask_b32_e64 v0, v76, v0, s[68:69]
	ds_write_b16 v0, v6 offset:8704
	s_cbranch_vccz .Ltk_noeq_125
	s_cmp_eq_u32 s13, 0
	s_cbranch_scc1 .Ltk_noeq_125
	v_mbcnt_lo_u32_b32 v8, vcc_lo, 0
	v_mbcnt_hi_u32_b32 v8, vcc_hi, v8
	v_lshrrev_b32_e32 v1, 16, v13
	v_add3_u32 v1, v1, v8, s49
	v_cmp_gt_u32_e64 s[72:73], s84, v1
	v_lshlrev_b32_e32 v1, 1, v1
	s_and_b64 s[72:73], s[72:73], vcc
	s_nop 0
	v_cndmask_b32_e64 v1, v76, v1, s[72:73]
	ds_write_b16 v1, v6 offset:8704
.Ltk_noeq_125:
	v_cmp_lt_u32_e64 s[68:69], s14, v143
	v_cmp_eq_u32_e32 vcc, s14, v143
	s_waitcnt lgkmcnt(1)
	v_and_b32_e32 v0, 0xffff, v14
	v_mbcnt_lo_u32_b32 v7, s68, 0
	v_mbcnt_hi_u32_b32 v7, s69, v7
	v_add_lshl_u32 v0, v0, v7, 1
	v_cndmask_b32_e64 v0, v76, v0, s[68:69]
	ds_write_b16 v0, v6 offset:9216
	s_cbranch_vccz .Ltk_noeq_126
	s_cmp_eq_u32 s14, 0
	s_cbranch_scc1 .Ltk_noeq_126
	v_mbcnt_lo_u32_b32 v8, vcc_lo, 0
	v_mbcnt_hi_u32_b32 v8, vcc_hi, v8
	v_lshrrev_b32_e32 v1, 16, v14
	v_add3_u32 v1, v1, v8, s50
	v_cmp_gt_u32_e64 s[72:73], s84, v1
	v_lshlrev_b32_e32 v1, 1, v1
	s_and_b64 s[72:73], s[72:73], vcc
	s_nop 0
	v_cndmask_b32_e64 v1, v76, v1, s[72:73]
	ds_write_b16 v1, v6 offset:9216
.Ltk_noeq_126:
	v_cmp_lt_u32_e64 s[68:69], s15, v115
	v_cmp_eq_u32_e32 vcc, s15, v115
	s_waitcnt lgkmcnt(0)
	v_and_b32_e32 v0, 0xffff, v15
	v_mbcnt_lo_u32_b32 v7, s68, 0
	v_mbcnt_hi_u32_b32 v7, s69, v7
	v_add_lshl_u32 v0, v0, v7, 1
	v_cndmask_b32_e64 v0, v76, v0, s[68:69]
	ds_write_b16 v0, v6 offset:9728
	s_cbranch_vccz .Ltk_noeq_127
	s_cmp_eq_u32 s15, 0
	s_cbranch_scc1 .Ltk_noeq_127
	v_mbcnt_lo_u32_b32 v8, vcc_lo, 0
	v_mbcnt_hi_u32_b32 v8, vcc_hi, v8
	v_lshrrev_b32_e32 v1, 16, v15
	v_add3_u32 v1, v1, v8, s51
	v_cmp_gt_u32_e64 s[72:73], s84, v1
	v_lshlrev_b32_e32 v1, 1, v1
	s_and_b64 s[72:73], s[72:73], vcc
	s_nop 0
	v_cndmask_b32_e64 v1, v76, v1, s[72:73]
	ds_write_b16 v1, v6 offset:9728
.Ltk_noeq_127:
	s_add_i32 s28, s28, 8
	s_cmp_gt_u32 s28, s3
	s_cbranch_scc1 .Ltk_scat_done_87
	s_lshl_b32 s29, s28, 2
	s_addk_i32 s29, 0x1000
	v_mov_b32_e32 v11, s29
	ds_read_b32 v12, v11
	ds_read_b32 v13, v11 offset:544
	ds_read_b32 v14, v11 offset:1088
	ds_read_b32 v15, v11 offset:1632
	v_lshl_add_u32 v6, s28, 6, v101
	v_cmp_lt_u32_e64 s[68:69], s12, v179
	v_cmp_eq_u32_e32 vcc, s12, v179
	s_waitcnt lgkmcnt(3)
	v_and_b32_e32 v0, 0xffff, v12
	v_mbcnt_lo_u32_b32 v7, s68, 0
	v_mbcnt_hi_u32_b32 v7, s69, v7
	v_add_lshl_u32 v0, v0, v7, 1
	v_cndmask_b32_e64 v0, v76, v0, s[68:69]
	ds_write_b16 v0, v6 offset:8192
	s_cbranch_vccz .Ltk_noeq_128
	s_cmp_eq_u32 s12, 0
	s_cbranch_scc1 .Ltk_noeq_128
	v_mbcnt_lo_u32_b32 v8, vcc_lo, 0
	v_mbcnt_hi_u32_b32 v8, vcc_hi, v8
	v_lshrrev_b32_e32 v1, 16, v12
	v_add3_u32 v1, v1, v8, s48
	v_cmp_gt_u32_e64 s[72:73], s84, v1
	v_lshlrev_b32_e32 v1, 1, v1
	s_and_b64 s[72:73], s[72:73], vcc
	s_nop 0
	v_cndmask_b32_e64 v1, v76, v1, s[72:73]
	ds_write_b16 v1, v6 offset:8192
.Ltk_noeq_128:
	v_cmp_lt_u32_e64 s[68:69], s13, v163
	v_cmp_eq_u32_e32 vcc, s13, v163
	s_waitcnt lgkmcnt(2)
	v_and_b32_e32 v0, 0xffff, v13
	v_mbcnt_lo_u32_b32 v7, s68, 0
	v_mbcnt_hi_u32_b32 v7, s69, v7
	v_add_lshl_u32 v0, v0, v7, 1
	v_cndmask_b32_e64 v0, v76, v0, s[68:69]
	ds_write_b16 v0, v6 offset:8704
	s_cbranch_vccz .Ltk_noeq_129
	s_cmp_eq_u32 s13, 0
	s_cbranch_scc1 .Ltk_noeq_129
	v_mbcnt_lo_u32_b32 v8, vcc_lo, 0
	v_mbcnt_hi_u32_b32 v8, vcc_hi, v8
	v_lshrrev_b32_e32 v1, 16, v13
	v_add3_u32 v1, v1, v8, s49
	v_cmp_gt_u32_e64 s[72:73], s84, v1
	v_lshlrev_b32_e32 v1, 1, v1
	s_and_b64 s[72:73], s[72:73], vcc
	s_nop 0
	v_cndmask_b32_e64 v1, v76, v1, s[72:73]
	ds_write_b16 v1, v6 offset:8704
; DI void topk_job(const Params& p, int b, int t0, char* lds) {
;     ...
;   const unsigned long long lt = (1ull << lane) - 1ull;
; #pragma unroll
;   for (int i = 0; i < 17; ++i) {
;     const int c = 1 + w + 8 * i;
;     if (c <= cmax) {
;       const int key = c * 64 + lane;
; #pragma unroll
;       for (int q = 0; q < 4; ++q) {
;         u16* out = p.IDX + (size_t)(b * PP + t0 + q) * 256;
;         const bool gt = sc[i][q] > T[q];
;         const bool eq = (sc[i][q] == T[q]) && (T[q] != 0u);
;         const unsigned long long m1 = __ballot(gt), m2 = __ballot(eq);
;         if ((m1 | m2) != 0ull) {
;           const unsigned bb = baseb[q * 132 + c];
;           if (gt) out[(int)(bb & 0xffffu) + __popcll(m1 & lt)] = (u16)key;
;           if (eq) { const int pos = ng[q] + (int)(bb >> 16) + __popcll(m2 & lt); if (pos < 256) out[pos] = (u16)key; }
;         }
;       }
;     }
;   }
.Ltk_noeq_129:
	v_cmp_lt_u32_e64 s[68:69], s14, v142
	v_cmp_eq_u32_e32 vcc, s14, v142
	s_waitcnt lgkmcnt(1)
	v_and_b32_e32 v0, 0xffff, v14
	v_mbcnt_lo_u32_b32 v7, s68, 0
	v_mbcnt_hi_u32_b32 v7, s69, v7
	v_add_lshl_u32 v0, v0, v7, 1
	v_cndmask_b32_e64 v0, v76, v0, s[68:69]
	ds_write_b16 v0, v6 offset:9216
	s_cbranch_vccz .Ltk_noeq_130
	s_cmp_eq_u32 s14, 0
	s_cbranch_scc1 .Ltk_noeq_130
	v_mbcnt_lo_u32_b32 v8, vcc_lo, 0
	v_mbcnt_hi_u32_b32 v8, vcc_hi, v8
	v_lshrrev_b32_e32 v1, 16, v14
	v_add3_u32 v1, v1, v8, s50
	v_cmp_gt_u32_e64 s[72:73], s84, v1
	v_lshlrev_b32_e32 v1, 1, v1
	s_and_b64 s[72:73], s[72:73], vcc
	s_nop 0
	v_cndmask_b32_e64 v1, v76, v1, s[72:73]
	ds_write_b16 v1, v6 offset:9216
.Ltk_noeq_130:
	v_cmp_lt_u32_e64 s[68:69], s15, v113
	v_cmp_eq_u32_e32 vcc, s15, v113
	s_waitcnt lgkmcnt(0)
	v_and_b32_e32 v0, 0xffff, v15
	v_mbcnt_lo_u32_b32 v7, s68, 0
	v_mbcnt_hi_u32_b32 v7, s69, v7
	v_add_lshl_u32 v0, v0, v7, 1
	v_cndmask_b32_e64 v0, v76, v0, s[68:69]
	ds_write_b16 v0, v6 offset:9728
	s_cbranch_vccz .Ltk_noeq_131
	s_cmp_eq_u32 s15, 0
	s_cbranch_scc1 .Ltk_noeq_131
	v_mbcnt_lo_u32_b32 v8, vcc_lo, 0
	v_mbcnt_hi_u32_b32 v8, vcc_hi, v8
	v_lshrrev_b32_e32 v1, 16, v15
	v_add3_u32 v1, v1, v8, s51
	v_cmp_gt_u32_e64 s[72:73], s84, v1
	v_lshlrev_b32_e32 v1, 1, v1
	s_and_b64 s[72:73], s[72:73], vcc
	s_nop 0
	v_cndmask_b32_e64 v1, v76, v1, s[72:73]
	ds_write_b16 v1, v6 offset:9728
.Ltk_noeq_131:
	s_add_i32 s28, s28, 8
	s_cmp_gt_u32 s28, s3
	s_cbranch_scc1 .Ltk_scat_done_87
	s_lshl_b32 s29, s28, 2
	s_addk_i32 s29, 0x1000
	v_mov_b32_e32 v11, s29
	ds_read_b32 v12, v11
	ds_read_b32 v13, v11 offset:544
	ds_read_b32 v14, v11 offset:1088
	ds_read_b32 v15, v11 offset:1632
	v_lshl_add_u32 v6, s28, 6, v101
	v_cmp_lt_u32_e64 s[68:69], s12, v178
	v_cmp_eq_u32_e32 vcc, s12, v178
	s_waitcnt lgkmcnt(3)
	v_and_b32_e32 v0, 0xffff, v12
	v_mbcnt_lo_u32_b32 v7, s68, 0
	v_mbcnt_hi_u32_b32 v7, s69, v7
	v_add_lshl_u32 v0, v0, v7, 1
	v_cndmask_b32_e64 v0, v76, v0, s[68:69]
	ds_write_b16 v0, v6 offset:8192
	s_cbranch_vccz .Ltk_noeq_132
	s_cmp_eq_u32 s12, 0
	s_cbranch_scc1 .Ltk_noeq_132
	v_mbcnt_lo_u32_b32 v8, vcc_lo, 0
	v_mbcnt_hi_u32_b32 v8, vcc_hi, v8
	v_lshrrev_b32_e32 v1, 16, v12
	v_add3_u32 v1, v1, v8, s48
	v_cmp_gt_u32_e64 s[72:73], s84, v1
	v_lshlrev_b32_e32 v1, 1, v1
	s_and_b64 s[72:73], s[72:73], vcc
	s_nop 0
	v_cndmask_b32_e64 v1, v76, v1, s[72:73]
	ds_write_b16 v1, v6 offset:8192
.Ltk_noeq_132:
	v_cmp_lt_u32_e64 s[68:69], s13, v162
	v_cmp_eq_u32_e32 vcc, s13, v162
	s_waitcnt lgkmcnt(2)
	v_and_b32_e32 v0, 0xffff, v13
	v_mbcnt_lo_u32_b32 v7, s68, 0
	v_mbcnt_hi_u32_b32 v7, s69, v7
	v_add_lshl_u32 v0, v0, v7, 1
	v_cndmask_b32_e64 v0, v76, v0, s[68:69]
	ds_write_b16 v0, v6 offset:8704
	s_cbranch_vccz .Ltk_noeq_133
	s_cmp_eq_u32 s13, 0
	s_cbranch_scc1 .Ltk_noeq_133
	v_mbcnt_lo_u32_b32 v8, vcc_lo, 0
	v_mbcnt_hi_u32_b32 v8, vcc_hi, v8
	v_lshrrev_b32_e32 v1, 16, v13
	v_add3_u32 v1, v1, v8, s49
	v_cmp_gt_u32_e64 s[72:73], s84, v1
	v_lshlrev_b32_e32 v1, 1, v1
	s_and_b64 s[72:73], s[72:73], vcc
	s_nop 0
	v_cndmask_b32_e64 v1, v76, v1, s[72:73]
	ds_write_b16 v1, v6 offset:8704
.Ltk_noeq_133:
	v_cmp_lt_u32_e64 s[68:69], s14, v141
	v_cmp_eq_u32_e32 vcc, s14, v141
	s_waitcnt lgkmcnt(1)
	v_and_b32_e32 v0, 0xffff, v14
	v_mbcnt_lo_u32_b32 v7, s68, 0
	v_mbcnt_hi_u32_b32 v7, s69, v7
	v_add_lshl_u32 v0, v0, v7, 1
	v_cndmask_b32_e64 v0, v76, v0, s[68:69]
	ds_write_b16 v0, v6 offset:9216
	s_cbranch_vccz .Ltk_noeq_134
	s_cmp_eq_u32 s14, 0
	s_cbranch_scc1 .Ltk_noeq_134
	v_mbcnt_lo_u32_b32 v8, vcc_lo, 0
	v_mbcnt_hi_u32_b32 v8, vcc_hi, v8
	v_lshrrev_b32_e32 v1, 16, v14
	v_add3_u32 v1, v1, v8, s50
	v_cmp_gt_u32_e64 s[72:73], s84, v1
	v_lshlrev_b32_e32 v1, 1, v1
	s_and_b64 s[72:73], s[72:73], vcc
	s_nop 0
	v_cndmask_b32_e64 v1, v76, v1, s[72:73]
	ds_write_b16 v1, v6 offset:9216
.Ltk_noeq_134:
	v_cmp_lt_u32_e64 s[68:69], s15, v111
	v_cmp_eq_u32_e32 vcc, s15, v111
	s_waitcnt lgkmcnt(0)
	v_and_b32_e32 v0, 0xffff, v15
	v_mbcnt_lo_u32_b32 v7, s68, 0
	v_mbcnt_hi_u32_b32 v7, s69, v7
	v_add_lshl_u32 v0, v0, v7, 1
	v_cndmask_b32_e64 v0, v76, v0, s[68:69]
	ds_write_b16 v0, v6 offset:9728
	s_cbranch_vccz .Ltk_noeq_135
	s_cmp_eq_u32 s15, 0
	s_cbranch_scc1 .Ltk_noeq_135
	v_mbcnt_lo_u32_b32 v8, vcc_lo, 0
	v_mbcnt_hi_u32_b32 v8, vcc_hi, v8
	v_lshrrev_b32_e32 v1, 16, v15
	v_add3_u32 v1, v1, v8, s51
	v_cmp_gt_u32_e64 s[72:73], s84, v1
	v_lshlrev_b32_e32 v1, 1, v1
	s_and_b64 s[72:73], s[72:73], vcc
	s_nop 0
	v_cndmask_b32_e64 v1, v76, v1, s[72:73]
	ds_write_b16 v1, v6 offset:9728
.Ltk_noeq_135:
	s_add_i32 s28, s28, 8
	s_cmp_gt_u32 s28, s3
	s_cbranch_scc1 .Ltk_scat_done_87
	s_lshl_b32 s29, s28, 2
	s_addk_i32 s29, 0x1000
	v_mov_b32_e32 v11, s29
	ds_read_b32 v12, v11
	ds_read_b32 v13, v11 offset:544
	ds_read_b32 v14, v11 offset:1088
	ds_read_b32 v15, v11 offset:1632
	v_lshl_add_u32 v6, s28, 6, v101
	v_cmp_lt_u32_e64 s[68:69], s12, v177
	v_cmp_eq_u32_e32 vcc, s12, v177
	s_waitcnt lgkmcnt(3)
	v_and_b32_e32 v0, 0xffff, v12
	v_mbcnt_lo_u32_b32 v7, s68, 0
	v_mbcnt_hi_u32_b32 v7, s69, v7
	v_add_lshl_u32 v0, v0, v7, 1
	v_cndmask_b32_e64 v0, v76, v0, s[68:69]
	ds_write_b16 v0, v6 offset:8192
	s_cbranch_vccz .Ltk_noeq_136
	s_cmp_eq_u32 s12, 0
	s_cbranch_scc1 .Ltk_noeq_136
	v_mbcnt_lo_u32_b32 v8, vcc_lo, 0
	v_mbcnt_hi_u32_b32 v8, vcc_hi, v8
	v_lshrrev_b32_e32 v1, 16, v12
	v_add3_u32 v1, v1, v8, s48
	v_cmp_gt_u32_e64 s[72:73], s84, v1
	v_lshlrev_b32_e32 v1, 1, v1
	s_and_b64 s[72:73], s[72:73], vcc
	s_nop 0
	v_cndmask_b32_e64 v1, v76, v1, s[72:73]
	ds_write_b16 v1, v6 offset:8192
; DI void topk_job(const Params& p, int b, int t0, char* lds) {
;     ...
;   const unsigned long long lt = (1ull << lane) - 1ull;
; #pragma unroll
;   for (int i = 0; i < 17; ++i) {
;     const int c = 1 + w + 8 * i;
;     if (c <= cmax) {
;       const int key = c * 64 + lane;
; #pragma unroll
;       for (int q = 0; q < 4; ++q) {
;         u16* out = p.IDX + (size_t)(b * PP + t0 + q) * 256;
;         const bool gt = sc[i][q] > T[q];
;         const bool eq = (sc[i][q] == T[q]) && (T[q] != 0u);
;         const unsigned long long m1 = __ballot(gt), m2 = __ballot(eq);
;         if ((m1 | m2) != 0ull) {
;           const unsigned bb = baseb[q * 132 + c];
;           if (gt) out[(int)(bb & 0xffffu) + __popcll(m1 & lt)] = (u16)key;
;           if (eq) { const int pos = ng[q] + (int)(bb >> 16) + __popcll(m2 & lt); if (pos < 256) out[pos] = (u16)key; }
;         }
;       }
;     }
;   }
.Ltk_noeq_136:
	v_cmp_lt_u32_e64 s[68:69], s13, v160
	v_cmp_eq_u32_e32 vcc, s13, v160
	s_waitcnt lgkmcnt(2)
	v_and_b32_e32 v0, 0xffff, v13
	v_mbcnt_lo_u32_b32 v7, s68, 0
	v_mbcnt_hi_u32_b32 v7, s69, v7
	v_add_lshl_u32 v0, v0, v7, 1
	v_cndmask_b32_e64 v0, v76, v0, s[68:69]
	ds_write_b16 v0, v6 offset:8704
	s_cbranch_vccz .Ltk_noeq_137
	s_cmp_eq_u32 s13, 0
	s_cbranch_scc1 .Ltk_noeq_137
	v_mbcnt_lo_u32_b32 v8, vcc_lo, 0
	v_mbcnt_hi_u32_b32 v8, vcc_hi, v8
	v_lshrrev_b32_e32 v1, 16, v13
	v_add3_u32 v1, v1, v8, s49
	v_cmp_gt_u32_e64 s[72:73], s84, v1
	v_lshlrev_b32_e32 v1, 1, v1
	s_and_b64 s[72:73], s[72:73], vcc
	s_nop 0
	v_cndmask_b32_e64 v1, v76, v1, s[72:73]
	ds_write_b16 v1, v6 offset:8704
.Ltk_noeq_137:
	v_cmp_lt_u32_e64 s[68:69], s14, v140
	v_cmp_eq_u32_e32 vcc, s14, v140
	s_waitcnt lgkmcnt(1)
	v_and_b32_e32 v0, 0xffff, v14
	v_mbcnt_lo_u32_b32 v7, s68, 0
	v_mbcnt_hi_u32_b32 v7, s69, v7
	v_add_lshl_u32 v0, v0, v7, 1
	v_cndmask_b32_e64 v0, v76, v0, s[68:69]
	ds_write_b16 v0, v6 offset:9216
	s_cbranch_vccz .Ltk_noeq_138
	s_cmp_eq_u32 s14, 0
	s_cbranch_scc1 .Ltk_noeq_138
	v_mbcnt_lo_u32_b32 v8, vcc_lo, 0
	v_mbcnt_hi_u32_b32 v8, vcc_hi, v8
	v_lshrrev_b32_e32 v1, 16, v14
	v_add3_u32 v1, v1, v8, s50
	v_cmp_gt_u32_e64 s[72:73], s84, v1
	v_lshlrev_b32_e32 v1, 1, v1
	s_and_b64 s[72:73], s[72:73], vcc
	s_nop 0
	v_cndmask_b32_e64 v1, v76, v1, s[72:73]
	ds_write_b16 v1, v6 offset:9216
.Ltk_noeq_138:
	v_cmp_lt_u32_e64 s[68:69], s15, v109
	v_cmp_eq_u32_e32 vcc, s15, v109
	s_waitcnt lgkmcnt(0)
	v_and_b32_e32 v0, 0xffff, v15
	v_mbcnt_lo_u32_b32 v7, s68, 0
	v_mbcnt_hi_u32_b32 v7, s69, v7
	v_add_lshl_u32 v0, v0, v7, 1
	v_cndmask_b32_e64 v0, v76, v0, s[68:69]
	ds_write_b16 v0, v6 offset:9728
	s_cbranch_vccz .Ltk_noeq_139
	s_cmp_eq_u32 s15, 0
	s_cbranch_scc1 .Ltk_noeq_139
	v_mbcnt_lo_u32_b32 v8, vcc_lo, 0
	v_mbcnt_hi_u32_b32 v8, vcc_hi, v8
	v_lshrrev_b32_e32 v1, 16, v15
	v_add3_u32 v1, v1, v8, s51
	v_cmp_gt_u32_e64 s[72:73], s84, v1
	v_lshlrev_b32_e32 v1, 1, v1
	s_and_b64 s[72:73], s[72:73], vcc
	s_nop 0
	v_cndmask_b32_e64 v1, v76, v1, s[72:73]
	ds_write_b16 v1, v6 offset:9728
.Ltk_noeq_139:
	s_add_i32 s28, s28, 8
	s_cmp_gt_u32 s28, s3
	s_cbranch_scc1 .Ltk_scat_done_87
	s_lshl_b32 s29, s28, 2
	s_addk_i32 s29, 0x1000
	v_mov_b32_e32 v11, s29
	ds_read_b32 v12, v11
	ds_read_b32 v13, v11 offset:544
	ds_read_b32 v14, v11 offset:1088
	ds_read_b32 v15, v11 offset:1632
	v_lshl_add_u32 v6, s28, 6, v101
	v_cmp_lt_u32_e64 s[68:69], s12, v176
	v_cmp_eq_u32_e32 vcc, s12, v176
	s_waitcnt lgkmcnt(3)
	v_and_b32_e32 v0, 0xffff, v12
	v_mbcnt_lo_u32_b32 v7, s68, 0
	v_mbcnt_hi_u32_b32 v7, s69, v7
	v_add_lshl_u32 v0, v0, v7, 1
	v_cndmask_b32_e64 v0, v76, v0, s[68:69]
	ds_write_b16 v0, v6 offset:8192
	s_cbranch_vccz .Ltk_noeq_140
	s_cmp_eq_u32 s12, 0
	s_cbranch_scc1 .Ltk_noeq_140
	v_mbcnt_lo_u32_b32 v8, vcc_lo, 0
	v_mbcnt_hi_u32_b32 v8, vcc_hi, v8
	v_lshrrev_b32_e32 v1, 16, v12
	v_add3_u32 v1, v1, v8, s48
	v_cmp_gt_u32_e64 s[72:73], s84, v1
	v_lshlrev_b32_e32 v1, 1, v1
	s_and_b64 s[72:73], s[72:73], vcc
	s_nop 0
	v_cndmask_b32_e64 v1, v76, v1, s[72:73]
	ds_write_b16 v1, v6 offset:8192
.Ltk_noeq_140:
	v_cmp_lt_u32_e64 s[68:69], s13, v151
	v_cmp_eq_u32_e32 vcc, s13, v151
	s_waitcnt lgkmcnt(2)
	v_and_b32_e32 v0, 0xffff, v13
	v_mbcnt_lo_u32_b32 v7, s68, 0
	v_mbcnt_hi_u32_b32 v7, s69, v7
	v_add_lshl_u32 v0, v0, v7, 1
	v_cndmask_b32_e64 v0, v76, v0, s[68:69]
	ds_write_b16 v0, v6 offset:8704
	s_cbranch_vccz .Ltk_noeq_141
	s_cmp_eq_u32 s13, 0
	s_cbranch_scc1 .Ltk_noeq_141
	v_mbcnt_lo_u32_b32 v8, vcc_lo, 0
	v_mbcnt_hi_u32_b32 v8, vcc_hi, v8
	v_lshrrev_b32_e32 v1, 16, v13
	v_add3_u32 v1, v1, v8, s49
	v_cmp_gt_u32_e64 s[72:73], s84, v1
	v_lshlrev_b32_e32 v1, 1, v1
	s_and_b64 s[72:73], s[72:73], vcc
	s_nop 0
	v_cndmask_b32_e64 v1, v76, v1, s[72:73]
	ds_write_b16 v1, v6 offset:8704
.Ltk_noeq_141:
	v_cmp_lt_u32_e64 s[68:69], s14, v139
	v_cmp_eq_u32_e32 vcc, s14, v139
	s_waitcnt lgkmcnt(1)
	v_and_b32_e32 v0, 0xffff, v14
	v_mbcnt_lo_u32_b32 v7, s68, 0
	v_mbcnt_hi_u32_b32 v7, s69, v7
	v_add_lshl_u32 v0, v0, v7, 1
	v_cndmask_b32_e64 v0, v76, v0, s[68:69]
	ds_write_b16 v0, v6 offset:9216
	s_cbranch_vccz .Ltk_noeq_142
	s_cmp_eq_u32 s14, 0
	s_cbranch_scc1 .Ltk_noeq_142
	v_mbcnt_lo_u32_b32 v8, vcc_lo, 0
	v_mbcnt_hi_u32_b32 v8, vcc_hi, v8
	v_lshrrev_b32_e32 v1, 16, v14
	v_add3_u32 v1, v1, v8, s50
	v_cmp_gt_u32_e64 s[72:73], s84, v1
	v_lshlrev_b32_e32 v1, 1, v1
	s_and_b64 s[72:73], s[72:73], vcc
	s_nop 0
	v_cndmask_b32_e64 v1, v76, v1, s[72:73]
	ds_write_b16 v1, v6 offset:9216
.Ltk_noeq_142:
	v_cmp_lt_u32_e64 s[68:69], s15, v107
	v_cmp_eq_u32_e32 vcc, s15, v107
	s_waitcnt lgkmcnt(0)
	v_and_b32_e32 v0, 0xffff, v15
	v_mbcnt_lo_u32_b32 v7, s68, 0
	v_mbcnt_hi_u32_b32 v7, s69, v7
	v_add_lshl_u32 v0, v0, v7, 1
	v_cndmask_b32_e64 v0, v76, v0, s[68:69]
	ds_write_b16 v0, v6 offset:9728
	s_cbranch_vccz .Ltk_noeq_143
	s_cmp_eq_u32 s15, 0
	s_cbranch_scc1 .Ltk_noeq_143
	v_mbcnt_lo_u32_b32 v8, vcc_lo, 0
	v_mbcnt_hi_u32_b32 v8, vcc_hi, v8
	v_lshrrev_b32_e32 v1, 16, v15
	v_add3_u32 v1, v1, v8, s51
	v_cmp_gt_u32_e64 s[72:73], s84, v1
	v_lshlrev_b32_e32 v1, 1, v1
	s_and_b64 s[72:73], s[72:73], vcc
	s_nop 0
	v_cndmask_b32_e64 v1, v76, v1, s[72:73]
	ds_write_b16 v1, v6 offset:9728
; DI void topk_job(const Params& p, int b, int t0, char* lds) {
;     ...
; #pragma unroll
;   for (int i = 0; i < 17; ++i) {
;     const int c = 1 + w + 8 * i;
;     if (c <= cmax) {
;       const int key = c * 64 + lane;
; #pragma unroll
;       for (int q = 0; q < 4; ++q) {
;         u16* out = p.IDX + (size_t)(b * PP + t0 + q) * 256;
;         const bool gt = sc[i][q] > T[q];
;         const bool eq = (sc[i][q] == T[q]) && (T[q] != 0u);
;         const unsigned long long m1 = __ballot(gt), m2 = __ballot(eq);
;         if ((m1 | m2) != 0ull) {
;           const unsigned bb = baseb[q * 132 + c];
;           if (gt) out[(int)(bb & 0xffffu) + __popcll(m1 & lt)] = (u16)key;
;           if (eq) { const int pos = ng[q] + (int)(bb >> 16) + __popcll(m2 & lt); if (pos < 256) out[pos] = (u16)key; }
;         }
;       }
;     }
;   }
.Ltk_noeq_143:
	s_add_i32 s28, s28, 8
	s_cmp_gt_u32 s28, s3
	s_cbranch_scc1 .Ltk_scat_done_87
	s_lshl_b32 s29, s28, 2
	s_addk_i32 s29, 0x1000
	v_mov_b32_e32 v11, s29
	ds_read_b32 v12, v11
	ds_read_b32 v13, v11 offset:544
	ds_read_b32 v14, v11 offset:1088
	ds_read_b32 v15, v11 offset:1632
	v_lshl_add_u32 v6, s28, 6, v101
	v_cmp_lt_u32_e64 s[68:69], s12, v174
	v_cmp_eq_u32_e32 vcc, s12, v174
	s_waitcnt lgkmcnt(3)
	v_and_b32_e32 v0, 0xffff, v12
	v_mbcnt_lo_u32_b32 v7, s68, 0
	v_mbcnt_hi_u32_b32 v7, s69, v7
	v_add_lshl_u32 v0, v0, v7, 1
	v_cndmask_b32_e64 v0, v76, v0, s[68:69]
	ds_write_b16 v0, v6 offset:8192
	s_cbranch_vccz .Ltk_noeq_144
	s_cmp_eq_u32 s12, 0
	s_cbranch_scc1 .Ltk_noeq_144
	v_mbcnt_lo_u32_b32 v8, vcc_lo, 0
	v_mbcnt_hi_u32_b32 v8, vcc_hi, v8
	v_lshrrev_b32_e32 v1, 16, v12
	v_add3_u32 v1, v1, v8, s48
	v_cmp_gt_u32_e64 s[72:73], s84, v1
	v_lshlrev_b32_e32 v1, 1, v1
	s_and_b64 s[72:73], s[72:73], vcc
	s_nop 0
	v_cndmask_b32_e64 v1, v76, v1, s[72:73]
	ds_write_b16 v1, v6 offset:8192
.Ltk_noeq_144:
	v_cmp_lt_u32_e64 s[68:69], s13, v148
	v_cmp_eq_u32_e32 vcc, s13, v148
	s_waitcnt lgkmcnt(2)
	v_and_b32_e32 v0, 0xffff, v13
	v_mbcnt_lo_u32_b32 v7, s68, 0
	v_mbcnt_hi_u32_b32 v7, s69, v7
	v_add_lshl_u32 v0, v0, v7, 1
	v_cndmask_b32_e64 v0, v76, v0, s[68:69]
	ds_write_b16 v0, v6 offset:8704
	s_cbranch_vccz .Ltk_noeq_145
	s_cmp_eq_u32 s13, 0
	s_cbranch_scc1 .Ltk_noeq_145
	v_mbcnt_lo_u32_b32 v8, vcc_lo, 0
	v_mbcnt_hi_u32_b32 v8, vcc_hi, v8
	v_lshrrev_b32_e32 v1, 16, v13
	v_add3_u32 v1, v1, v8, s49
	v_cmp_gt_u32_e64 s[72:73], s84, v1
	v_lshlrev_b32_e32 v1, 1, v1
	s_and_b64 s[72:73], s[72:73], vcc
	s_nop 0
	v_cndmask_b32_e64 v1, v76, v1, s[72:73]
	ds_write_b16 v1, v6 offset:8704
.Ltk_noeq_145:
	v_cmp_lt_u32_e64 s[68:69], s14, v131
	v_cmp_eq_u32_e32 vcc, s14, v131
	s_waitcnt lgkmcnt(1)
	v_and_b32_e32 v0, 0xffff, v14
	v_mbcnt_lo_u32_b32 v7, s68, 0
	v_mbcnt_hi_u32_b32 v7, s69, v7
	v_add_lshl_u32 v0, v0, v7, 1
	v_cndmask_b32_e64 v0, v76, v0, s[68:69]
	ds_write_b16 v0, v6 offset:9216
	s_cbranch_vccz .Ltk_noeq_146
	s_cmp_eq_u32 s14, 0
	s_cbranch_scc1 .Ltk_noeq_146
	v_mbcnt_lo_u32_b32 v8, vcc_lo, 0
	v_mbcnt_hi_u32_b32 v8, vcc_hi, v8
	v_lshrrev_b32_e32 v1, 16, v14
	v_add3_u32 v1, v1, v8, s50
	v_cmp_gt_u32_e64 s[72:73], s84, v1
	v_lshlrev_b32_e32 v1, 1, v1
	s_and_b64 s[72:73], s[72:73], vcc
	s_nop 0
	v_cndmask_b32_e64 v1, v76, v1, s[72:73]
	ds_write_b16 v1, v6 offset:9216
.Ltk_noeq_146:
	v_cmp_lt_u32_e64 s[68:69], s15, v105
	v_cmp_eq_u32_e32 vcc, s15, v105
	s_waitcnt lgkmcnt(0)
	v_and_b32_e32 v0, 0xffff, v15
	v_mbcnt_lo_u32_b32 v7, s68, 0
	v_mbcnt_hi_u32_b32 v7, s69, v7
	v_add_lshl_u32 v0, v0, v7, 1
	v_cndmask_b32_e64 v0, v76, v0, s[68:69]
	ds_write_b16 v0, v6 offset:9728
	s_cbranch_vccz .Ltk_noeq_147
	s_cmp_eq_u32 s15, 0
	s_cbranch_scc1 .Ltk_noeq_147
	v_mbcnt_lo_u32_b32 v8, vcc_lo, 0
	v_mbcnt_hi_u32_b32 v8, vcc_hi, v8
	v_lshrrev_b32_e32 v1, 16, v15
	v_add3_u32 v1, v1, v8, s51
	v_cmp_gt_u32_e64 s[72:73], s84, v1
	v_lshlrev_b32_e32 v1, 1, v1
	s_and_b64 s[72:73], s[72:73], vcc
	s_nop 0
	v_cndmask_b32_e64 v1, v76, v1, s[72:73]
	ds_write_b16 v1, v6 offset:9728
.Ltk_noeq_147:
	s_add_i32 s28, s28, 8
	s_cmp_gt_u32 s28, s3
	s_cbranch_scc1 .Ltk_scat_done_87
	s_lshl_b32 s29, s28, 2
	s_addk_i32 s29, 0x1000
	v_mov_b32_e32 v11, s29
	ds_read_b32 v12, v11
	ds_read_b32 v13, v11 offset:544
	ds_read_b32 v14, v11 offset:1088
	ds_read_b32 v15, v11 offset:1632
	v_lshl_add_u32 v6, s28, 6, v101
	v_cmp_lt_u32_e64 s[68:69], s12, v169
	v_cmp_eq_u32_e32 vcc, s12, v169
	s_waitcnt lgkmcnt(3)
	v_and_b32_e32 v0, 0xffff, v12
	v_mbcnt_lo_u32_b32 v7, s68, 0
	v_mbcnt_hi_u32_b32 v7, s69, v7
	v_add_lshl_u32 v0, v0, v7, 1
	v_cndmask_b32_e64 v0, v76, v0, s[68:69]
	ds_write_b16 v0, v6 offset:8192
	s_cbranch_vccz .Ltk_noeq_148
	s_cmp_eq_u32 s12, 0
	s_cbranch_scc1 .Ltk_noeq_148
	v_mbcnt_lo_u32_b32 v8, vcc_lo, 0
	v_mbcnt_hi_u32_b32 v8, vcc_hi, v8
	v_lshrrev_b32_e32 v1, 16, v12
	v_add3_u32 v1, v1, v8, s48
	v_cmp_gt_u32_e64 s[72:73], s84, v1
	v_lshlrev_b32_e32 v1, 1, v1
	s_and_b64 s[72:73], s[72:73], vcc
	s_nop 0
	v_cndmask_b32_e64 v1, v76, v1, s[72:73]
	ds_write_b16 v1, v6 offset:8192
.Ltk_noeq_148:
	v_cmp_lt_u32_e64 s[68:69], s13, v144
	v_cmp_eq_u32_e32 vcc, s13, v144
	s_waitcnt lgkmcnt(2)
	v_and_b32_e32 v0, 0xffff, v13
	v_mbcnt_lo_u32_b32 v7, s68, 0
	v_mbcnt_hi_u32_b32 v7, s69, v7
	v_add_lshl_u32 v0, v0, v7, 1
	v_cndmask_b32_e64 v0, v76, v0, s[68:69]
	ds_write_b16 v0, v6 offset:8704
	s_cbranch_vccz .Ltk_noeq_149
	s_cmp_eq_u32 s13, 0
	s_cbranch_scc1 .Ltk_noeq_149
	v_mbcnt_lo_u32_b32 v8, vcc_lo, 0
	v_mbcnt_hi_u32_b32 v8, vcc_hi, v8
	v_lshrrev_b32_e32 v1, 16, v13
	v_add3_u32 v1, v1, v8, s49
	v_cmp_gt_u32_e64 s[72:73], s84, v1
	v_lshlrev_b32_e32 v1, 1, v1
	s_and_b64 s[72:73], s[72:73], vcc
	s_nop 0
	v_cndmask_b32_e64 v1, v76, v1, s[72:73]
	ds_write_b16 v1, v6 offset:8704
.Ltk_noeq_149:
	v_cmp_lt_u32_e64 s[68:69], s14, v117
	v_cmp_eq_u32_e32 vcc, s14, v117
	s_waitcnt lgkmcnt(1)
	v_and_b32_e32 v0, 0xffff, v14
	v_mbcnt_lo_u32_b32 v7, s68, 0
	v_mbcnt_hi_u32_b32 v7, s69, v7
	v_add_lshl_u32 v0, v0, v7, 1
	v_cndmask_b32_e64 v0, v76, v0, s[68:69]
	ds_write_b16 v0, v6 offset:9216
	s_cbranch_vccz .Ltk_noeq_150
	s_cmp_eq_u32 s14, 0
	s_cbranch_scc1 .Ltk_noeq_150
	v_mbcnt_lo_u32_b32 v8, vcc_lo, 0
	v_mbcnt_hi_u32_b32 v8, vcc_hi, v8
	v_lshrrev_b32_e32 v1, 16, v14
	v_add3_u32 v1, v1, v8, s50
	v_cmp_gt_u32_e64 s[72:73], s84, v1
	v_lshlrev_b32_e32 v1, 1, v1
	s_and_b64 s[72:73], s[72:73], vcc
	s_nop 0
	v_cndmask_b32_e64 v1, v76, v1, s[72:73]
	ds_write_b16 v1, v6 offset:9216
; DI void topk_job(const Params& p, int b, int t0, char* lds) {
;     ...
; #pragma unroll
;   for (int i = 0; i < 17; ++i) {
;     const int c = 1 + w + 8 * i;
;     if (c <= cmax) {
;       const int key = c * 64 + lane;
; #pragma unroll
;       for (int q = 0; q < 4; ++q) {
;         u16* out = p.IDX + (size_t)(b * PP + t0 + q) * 256;
;         const bool gt = sc[i][q] > T[q];
;         const bool eq = (sc[i][q] == T[q]) && (T[q] != 0u);
;         const unsigned long long m1 = __ballot(gt), m2 = __ballot(eq);
;         if ((m1 | m2) != 0ull) {
;           const unsigned bb = baseb[q * 132 + c];
;           if (gt) out[(int)(bb & 0xffffu) + __popcll(m1 & lt)] = (u16)key;
;           if (eq) { const int pos = ng[q] + (int)(bb >> 16) + __popcll(m2 & lt); if (pos < 256) out[pos] = (u16)key; }
;         }
;       }
;     }
;   }
; #pragma unroll
;   for (int q = 0; q < 4; ++q) {
;     if (T[q] == 0u) {
;       u16* out = p.IDX + (size_t)(b * PP + t0 + q) * 256;
;       if (tid < 256 && tid >= ng[q]) out[tid] = (u16)0xFFFF;
;     }
;   }
.Ltk_noeq_150:
	v_cmp_lt_u32_e64 s[68:69], s15, v103
	v_cmp_eq_u32_e32 vcc, s15, v103
	s_waitcnt lgkmcnt(0)
	v_and_b32_e32 v0, 0xffff, v15
	v_mbcnt_lo_u32_b32 v7, s68, 0
	v_mbcnt_hi_u32_b32 v7, s69, v7
	v_add_lshl_u32 v0, v0, v7, 1
	v_cndmask_b32_e64 v0, v76, v0, s[68:69]
	ds_write_b16 v0, v6 offset:9728
	s_cbranch_vccz .Ltk_noeq_151
	s_cmp_eq_u32 s15, 0
	s_cbranch_scc1 .Ltk_noeq_151
	v_mbcnt_lo_u32_b32 v8, vcc_lo, 0
	v_mbcnt_hi_u32_b32 v8, vcc_hi, v8
	v_lshrrev_b32_e32 v1, 16, v15
	v_add3_u32 v1, v1, v8, s51
	v_cmp_gt_u32_e64 s[72:73], s84, v1
	v_lshlrev_b32_e32 v1, 1, v1
	s_and_b64 s[72:73], s[72:73], vcc
	s_nop 0
	v_cndmask_b32_e64 v1, v76, v1, s[72:73]
	ds_write_b16 v1, v6 offset:9728
.Ltk_noeq_151:
	s_add_i32 s28, s28, 8
	s_cmp_gt_u32 s28, s3
	s_cbranch_scc1 .Ltk_scat_done_87
	s_lshl_b32 s29, s28, 2
	s_addk_i32 s29, 0x1000
	v_mov_b32_e32 v11, s29
	ds_read_b32 v12, v11
	ds_read_b32 v13, v11 offset:544
	ds_read_b32 v14, v11 offset:1088
	ds_read_b32 v15, v11 offset:1632
	v_lshl_add_u32 v6, s28, 6, v101
	v_cmp_lt_u32_e64 s[68:69], s12, v19
	v_cmp_eq_u32_e32 vcc, s12, v19
	s_waitcnt lgkmcnt(3)
	v_and_b32_e32 v0, 0xffff, v12
	v_mbcnt_lo_u32_b32 v7, s68, 0
	v_mbcnt_hi_u32_b32 v7, s69, v7
	v_add_lshl_u32 v0, v0, v7, 1
	v_cndmask_b32_e64 v0, v76, v0, s[68:69]
	ds_write_b16 v0, v6 offset:8192
	s_cbranch_vccz .Ltk_noeq_152
	s_cmp_eq_u32 s12, 0
	s_cbranch_scc1 .Ltk_noeq_152
	v_mbcnt_lo_u32_b32 v8, vcc_lo, 0
	v_mbcnt_hi_u32_b32 v8, vcc_hi, v8
	v_lshrrev_b32_e32 v1, 16, v12
	v_add3_u32 v1, v1, v8, s48
	v_cmp_gt_u32_e64 s[72:73], s84, v1
	v_lshlrev_b32_e32 v1, 1, v1
	s_and_b64 s[72:73], s[72:73], vcc
	s_nop 0
	v_cndmask_b32_e64 v1, v76, v1, s[72:73]
	ds_write_b16 v1, v6 offset:8192
.Ltk_noeq_152:
	v_cmp_lt_u32_e64 s[68:69], s13, v18
	v_cmp_eq_u32_e32 vcc, s13, v18
	s_waitcnt lgkmcnt(2)
	v_and_b32_e32 v0, 0xffff, v13
	v_mbcnt_lo_u32_b32 v7, s68, 0
	v_mbcnt_hi_u32_b32 v7, s69, v7
	v_add_lshl_u32 v0, v0, v7, 1
	v_cndmask_b32_e64 v0, v76, v0, s[68:69]
	ds_write_b16 v0, v6 offset:8704
	s_cbranch_vccz .Ltk_noeq_153
	s_cmp_eq_u32 s13, 0
	s_cbranch_scc1 .Ltk_noeq_153
	v_mbcnt_lo_u32_b32 v8, vcc_lo, 0
	v_mbcnt_hi_u32_b32 v8, vcc_hi, v8
	v_lshrrev_b32_e32 v1, 16, v13
	v_add3_u32 v1, v1, v8, s49
	v_cmp_gt_u32_e64 s[72:73], s84, v1
	v_lshlrev_b32_e32 v1, 1, v1
	s_and_b64 s[72:73], s[72:73], vcc
	s_nop 0
	v_cndmask_b32_e64 v1, v76, v1, s[72:73]
	ds_write_b16 v1, v6 offset:8704
.Ltk_noeq_153:
	v_cmp_lt_u32_e64 s[68:69], s14, v17
	v_cmp_eq_u32_e32 vcc, s14, v17
	s_waitcnt lgkmcnt(1)
	v_and_b32_e32 v0, 0xffff, v14
	v_mbcnt_lo_u32_b32 v7, s68, 0
	v_mbcnt_hi_u32_b32 v7, s69, v7
	v_add_lshl_u32 v0, v0, v7, 1
	v_cndmask_b32_e64 v0, v76, v0, s[68:69]
	ds_write_b16 v0, v6 offset:9216
	s_cbranch_vccz .Ltk_noeq_154
	s_cmp_eq_u32 s14, 0
	s_cbranch_scc1 .Ltk_noeq_154
	v_mbcnt_lo_u32_b32 v8, vcc_lo, 0
	v_mbcnt_hi_u32_b32 v8, vcc_hi, v8
	v_lshrrev_b32_e32 v1, 16, v14
	v_add3_u32 v1, v1, v8, s50
	v_cmp_gt_u32_e64 s[72:73], s84, v1
	v_lshlrev_b32_e32 v1, 1, v1
	s_and_b64 s[72:73], s[72:73], vcc
	s_nop 0
	v_cndmask_b32_e64 v1, v76, v1, s[72:73]
	ds_write_b16 v1, v6 offset:9216
.Ltk_noeq_154:
	v_cmp_lt_u32_e64 s[68:69], s15, v16
	v_cmp_eq_u32_e32 vcc, s15, v16
	s_waitcnt lgkmcnt(0)
	v_and_b32_e32 v0, 0xffff, v15
	v_mbcnt_lo_u32_b32 v7, s68, 0
	v_mbcnt_hi_u32_b32 v7, s69, v7
	v_add_lshl_u32 v0, v0, v7, 1
	v_cndmask_b32_e64 v0, v76, v0, s[68:69]
	ds_write_b16 v0, v6 offset:9728
	s_cbranch_vccz .Ltk_noeq_155
	s_cmp_eq_u32 s15, 0
	s_cbranch_scc1 .Ltk_noeq_155
	v_mbcnt_lo_u32_b32 v8, vcc_lo, 0
	v_mbcnt_hi_u32_b32 v8, vcc_hi, v8
	v_lshrrev_b32_e32 v1, 16, v15
	v_add3_u32 v1, v1, v8, s51
	v_cmp_gt_u32_e64 s[72:73], s84, v1
	v_lshlrev_b32_e32 v1, 1, v1
	s_and_b64 s[72:73], s[72:73], vcc
	s_nop 0
	v_cndmask_b32_e64 v1, v76, v1, s[72:73]
	ds_write_b16 v1, v6 offset:9728
.Ltk_noeq_155:
.Ltk_scat_done_87:
	s_waitcnt lgkmcnt(0)
	s_barrier
	s_cmp_gt_u32 s2, 1
	s_cbranch_scc1 .Ltk_copy_end_156
	v_lshlrev_b32_e32 v0, 4, v100
	ds_read_b128 v[4:7], v0 offset:8192
	s_waitcnt lgkmcnt(0)
	global_store_dwordx4 v0, v[4:7], s[40:41]
.Ltk_copy_end_156:
.Ltk_restore:
	v_readlane_b32 s6, v240, 7
	v_readlane_b32 s7, v240, 8
	v_readlane_b32 s8, v240, 9
	v_readlane_b32 s9, v240, 10
	v_readlane_b32 s10, v240, 11
	v_readlane_b32 s11, v240, 12
	v_readlane_b32 s12, v240, 13
	v_readlane_b32 s13, v240, 14
	v_readlane_b32 s17, v240, 10
	v_readlane_b32 s20, v240, 13
	v_readlane_b32 s22, v240, 15
	v_readlane_b32 s23, v240, 16
	v_readlane_b32 s27, v238, 63
	v_readlane_b32 s34, v238, 57
	v_readlane_b32 s35, v238, 58
	v_readlane_b32 s36, v237, 2
	v_readlane_b32 s50, v238, 59
	v_readlane_b32 s91, v238, 41
	v_readlane_b32 s92, v238, 37
	v_readlane_b32 s93, v238, 38
	v_readlane_b32 s94, v238, 39
	v_readlane_b32 s95, v238, 40
	v_readlane_b32 s96, v238, 42
	s_movk_i32 s57, 0x90
	s_mov_b64 s[64:65], s[66:67]
	s_mov_b32 s89, 0x7f800000
	s_branch .LBB0_609
